# GLA phases: LDS reads software-pipelined (renamed temporaries, reads hoisted up to 5 generations ahead, lgkmcnt recomputed)
# speedup vs baseline: 1.0022x; 1.0022x over previous
.LBB0_464:
	s_waitcnt lgkmcnt(0)
	ds_read_b128 v[94:97], v149 offset:6144
	ds_read_b128 v[98:101], v149 offset:6160
	s_waitcnt vmcnt(5)
	v_lshlrev_b32_e32 v102, 16, v22
	v_and_b32_e32 v103, 0xffff0000, v22
	s_add_i32 s46, s47, s46
	s_waitcnt lgkmcnt(1)
	v_mul_f32_e32 v94, 0xbfb8aa3b, v94
	v_mul_f32_e32 v95, 0xbfb8aa3b, v95
	v_exp_f32_e32 v94, v94
	v_exp_f32_e32 v95, v95
	v_mul_f32_e32 v22, 0xbfb8aa3b, v96
	v_exp_f32_e32 v96, v22
	v_mul_f32_e32 v22, 0xbfb8aa3b, v97
	v_exp_f32_e32 v97, v22
	v_pk_mul_f32 v[94:95], v[94:95], v[102:103]
	s_add_i32 s83, s83, 1
	v_cvt_pk_bf16_f32 v22, v94, v95
	v_lshlrev_b32_e32 v94, 16, v23
	v_and_b32_e32 v95, 0xffff0000, v23
	s_waitcnt lgkmcnt(0)
	v_mul_f32_e32 v23, 0xbfb8aa3b, v98
	v_pk_mul_f32 v[94:95], v[96:97], v[94:95]
	v_exp_f32_e32 v96, v23
	v_mul_f32_e32 v23, 0xbfb8aa3b, v99
	v_exp_f32_e32 v97, v23
	v_cvt_pk_bf16_f32 v23, v94, v95
	v_lshlrev_b32_e32 v94, 16, v24
	v_and_b32_e32 v95, 0xffff0000, v24
	v_mul_f32_e32 v24, 0xbfb8aa3b, v100
	v_pk_mul_f32 v[94:95], v[96:97], v[94:95]
	v_exp_f32_e32 v96, v24
	v_mul_f32_e32 v24, 0xbfb8aa3b, v101
	v_exp_f32_e32 v97, v24
	v_cvt_pk_bf16_f32 v24, v94, v95
	v_lshlrev_b32_e32 v94, 16, v25
	v_and_b32_e32 v95, 0xffff0000, v25
	v_pk_mul_f32 v[94:95], v[96:97], v[94:95]
	s_waitcnt vmcnt(4)
	v_lshlrev_b32_e32 v98, 16, v6
	v_cvt_pk_bf16_f32 v25, v94, v95
	ds_write_b128 v150, v[22:25] offset:56320
	ds_read_b128 v[232:235], v151 offset:6144
	ds_read_b128 v[94:97], v151 offset:6160
	v_and_b32_e32 v99, 0xffff0000, v6
	s_mul_i32 s53, s46, 0x1800
	s_mul_hi_i32 s52, s46, 0x1800
	s_waitcnt lgkmcnt(1)
	v_mul_f32_e32 v22, 0xbfb8aa3b, v232
	v_mul_f32_e32 v23, 0xbfb8aa3b, v233
	v_exp_f32_e32 v22, v22
	v_exp_f32_e32 v23, v23
	v_mul_f32_e32 v6, 0xbfb8aa3b, v234
	v_exp_f32_e32 v24, v6
	v_mul_f32_e32 v6, 0xbfb8aa3b, v235
	v_exp_f32_e32 v25, v6
	v_pk_mul_f32 v[22:23], v[22:23], v[98:99]
	s_add_u32 s50, s80, s53
	v_cvt_pk_bf16_f32 v6, v22, v23
	v_lshlrev_b32_e32 v22, 16, v7
	v_and_b32_e32 v23, 0xffff0000, v7
	s_waitcnt lgkmcnt(0)
	v_mul_f32_e32 v7, 0xbfb8aa3b, v94
	v_pk_mul_f32 v[22:23], v[24:25], v[22:23]
	v_exp_f32_e32 v24, v7
	v_mul_f32_e32 v7, 0xbfb8aa3b, v95
	v_exp_f32_e32 v25, v7
	v_cvt_pk_bf16_f32 v7, v22, v23
	v_lshlrev_b32_e32 v22, 16, v8
	v_and_b32_e32 v23, 0xffff0000, v8
	v_mul_f32_e32 v8, 0xbfb8aa3b, v96
	v_pk_mul_f32 v[22:23], v[24:25], v[22:23]
	v_exp_f32_e32 v24, v8
	v_mul_f32_e32 v8, 0xbfb8aa3b, v97
	v_exp_f32_e32 v25, v8
	v_cvt_pk_bf16_f32 v8, v22, v23
	v_lshlrev_b32_e32 v22, 16, v9
	v_and_b32_e32 v23, 0xffff0000, v9
	v_pk_mul_f32 v[22:23], v[24:25], v[22:23]
	s_addc_u32 s51, s81, s52
	v_cvt_pk_bf16_f32 v9, v22, v23
	ds_write_b128 v152, v[6:9] offset:56320
	s_waitcnt vmcnt(3)
	ds_write_b128 v153, v[2:5]
	s_waitcnt vmcnt(2)
	ds_write_b128 v155, v[10:13]
	s_waitcnt vmcnt(1)
	ds_write_b128 v153, v[14:17] offset:16896
	s_waitcnt vmcnt(0)
	ds_write_b128 v156, v[18:21]
	v_lshl_add_u64 v[2:3], s[50:51], 0, v[112:113]
	s_add_u32 s50, s38, s53
	s_addc_u32 s51, s39, s52
	s_add_u32 s50, s50, s76
	s_addc_u32 s51, s51, 0
	s_add_u32 s50, s50, 0xad20800
	global_load_dwordx4 v[22:25], v[2:3], off offset:1024
	v_add_co_u32_e32 v2, vcc, s63, v2
	s_addc_u32 s51, s51, 0
	s_nop 0
	v_addc_co_u32_e32 v3, vcc, 0, v3, vcc
	v_lshl_add_u64 v[18:19], s[50:51], 0, v[114:115]
	v_add_co_u32_e32 v10, vcc, s64, v18
	global_load_dwordx4 v[6:9], v[2:3], off offset:1024
	s_nop 0
	v_addc_co_u32_e32 v11, vcc, 0, v19, vcc
	v_add_co_u32_e32 v14, vcc, s63, v18
	global_load_dwordx4 v[2:5], v[18:19], off
	s_nop 0
	v_addc_co_u32_e32 v15, vcc, 0, v19, vcc
	v_add_co_u32_e32 v18, vcc, s65, v18
	global_load_dwordx4 v[10:13], v[10:11], off
	s_nop 0
	v_addc_co_u32_e32 v19, vcc, 0, v19, vcc
	global_load_dwordx4 v[14:17], v[14:15], off
	v_lshl_add_u32 v167, s87, 9, v128
	global_load_dwordx4 v[18:21], v[18:19], off
	s_waitcnt lgkmcnt(0)
	s_barrier
	s_waitcnt lgkmcnt(0)
	ds_read_b64_tr_b16 v[96:97], v158 offset:57408
	ds_read_b64_tr_b16 v[94:95], v158 offset:56320
	ds_read_b64_tr_b16 v[108:109], v157 offset:2112
	ds_read_b64_tr_b16 v[106:107], v157
	ds_read_b64_tr_b16 v[102:103], v157 offset:32
	ds_read_b64_tr_b16 v[104:105], v157 offset:2144
	ds_read_b64_tr_b16 v[232:233], v158 offset:65024
	ds_read_b64_tr_b16 v[234:235], v159 offset:57408
	ds_read_b64_tr_b16 v[98:99], v157 offset:16896
	ds_read_b64_tr_b16 v[100:101], v157 offset:19008
	s_waitcnt lgkmcnt(6)
	v_mfma_f32_16x16x32_bf16 v[70:73], v[94:97], v[106:109], v[70:73]
	s_nop 0
	s_nop 0
	s_nop 0
	s_cmp_eq_u32 s43, s83
	s_waitcnt lgkmcnt(4)
	v_mfma_f32_16x16x32_bf16 v[74:77], v[94:97], v[102:105], v[74:77]
	ds_read_b64_tr_b16 v[94:95], v157 offset:16928
	ds_read_b64_tr_b16 v[96:97], v157 offset:19040
	ds_read_b64_tr_b16 v[172:173], v158 offset:56352
	ds_read_b64_tr_b16 v[174:175], v158 offset:57440
	ds_read_b64_tr_b16 v[238:239], v159 offset:57440
	ds_read_b64_tr_b16 v[236:237], v158 offset:65056
	ds_read_b64_tr_b16 v[244:245], v158 offset:56384
	ds_read_b64_tr_b16 v[246:247], v158 offset:57472
	ds_read_b64_tr_b16 v[248:249], v158 offset:65088
	ds_read_b64_tr_b16 v[250:251], v159 offset:57472
	ds_read_b64_tr_b16 v[252:253], v158 offset:56416
	ds_read_b64_tr_b16 v[254:255], v158 offset:57504
	s_nop 0
	s_nop 0
	s_nop 0
	s_nop 0
	s_nop 0
	s_waitcnt lgkmcnt(12)
	v_mfma_f32_16x16x32_bf16 v[70:73], v[232:235], v[98:101], v[70:73]
	s_waitcnt lgkmcnt(10)
	v_mfma_f32_16x16x32_bf16 v[74:77], v[232:235], v[94:97], v[74:77]
	ds_read_b64_tr_b16 v[232:233], v158 offset:65120
	ds_read_b64_tr_b16 v[234:235], v159 offset:57504
	s_nop 0
	s_nop 0
	s_waitcnt lgkmcnt(10)
	v_mfma_f32_16x16x32_bf16 v[58:61], v[172:175], v[106:109], v[58:61]
	v_mfma_f32_16x16x32_bf16 v[82:85], v[172:175], v[102:105], v[82:85]
	s_waitcnt lgkmcnt(8)
	v_mfma_f32_16x16x32_bf16 v[58:61], v[236:239], v[98:101], v[58:61]
	v_mfma_f32_16x16x32_bf16 v[82:85], v[236:239], v[94:97], v[82:85]
	ds_read_b64_tr_b16 v[236:237], v158 offset:56448
	ds_read_b64_tr_b16 v[238:239], v158 offset:57536
	s_nop 0
	s_nop 0
	s_waitcnt lgkmcnt(8)
	v_mfma_f32_16x16x32_bf16 v[66:69], v[244:247], v[106:109], v[66:69]
	v_mfma_f32_16x16x32_bf16 v[78:81], v[244:247], v[102:105], v[78:81]
	ds_read_b64_tr_b16 v[244:245], v158 offset:65152
	ds_read_b64_tr_b16 v[246:247], v159 offset:57536
	s_nop 0
	s_nop 0
	s_waitcnt lgkmcnt(8)
	v_mfma_f32_16x16x32_bf16 v[66:69], v[248:251], v[98:101], v[66:69]
	v_mfma_f32_16x16x32_bf16 v[78:81], v[248:251], v[94:97], v[78:81]
	ds_read_b64_tr_b16 v[248:249], v158 offset:56480
	ds_read_b64_tr_b16 v[250:251], v158 offset:57568
	s_nop 0
	s_nop 0
	s_waitcnt lgkmcnt(8)
	v_mfma_f32_16x16x32_bf16 v[62:65], v[252:255], v[106:109], v[62:65]
	v_mfma_f32_16x16x32_bf16 v[86:89], v[252:255], v[102:105], v[86:89]
	ds_read_b64_tr_b16 v[252:253], v158 offset:65184
	ds_read_b64_tr_b16 v[254:255], v159 offset:57568
	s_nop 0
	s_nop 0
	s_waitcnt lgkmcnt(8)
	v_mfma_f32_16x16x32_bf16 v[62:65], v[232:235], v[98:101], v[62:65]
	v_mfma_f32_16x16x32_bf16 v[86:89], v[232:235], v[94:97], v[86:89]
	ds_read_b64_tr_b16 v[232:233], v158 offset:56512
	ds_read_b64_tr_b16 v[234:235], v158 offset:57600
	s_nop 0
	s_nop 0
	s_waitcnt lgkmcnt(8)
	v_mfma_f32_16x16x32_bf16 v[38:41], v[236:239], v[106:109], v[38:41]
	v_mfma_f32_16x16x32_bf16 v[50:53], v[236:239], v[102:105], v[50:53]
	ds_read_b64_tr_b16 v[236:237], v158 offset:65216
	ds_read_b64_tr_b16 v[238:239], v159 offset:57600
	s_nop 0
	s_nop 0
	s_waitcnt lgkmcnt(8)
	v_mfma_f32_16x16x32_bf16 v[38:41], v[244:247], v[98:101], v[38:41]
	v_mfma_f32_16x16x32_bf16 v[50:53], v[244:247], v[94:97], v[50:53]
	ds_read_b64_tr_b16 v[244:245], v158 offset:56544
	ds_read_b64_tr_b16 v[246:247], v158 offset:57632
	s_nop 0
	s_nop 0
	s_waitcnt lgkmcnt(8)
	v_mfma_f32_16x16x32_bf16 v[30:33], v[248:251], v[106:109], v[30:33]
	v_mfma_f32_16x16x32_bf16 v[54:57], v[248:251], v[102:105], v[54:57]
	s_nop 0
	s_nop 0
	s_waitcnt lgkmcnt(6)
	v_mfma_f32_16x16x32_bf16 v[30:33], v[252:255], v[98:101], v[30:33]
	v_mfma_f32_16x16x32_bf16 v[54:57], v[252:255], v[94:97], v[54:57]
	s_nop 0
	s_nop 0
	s_waitcnt lgkmcnt(4)
	v_mfma_f32_16x16x32_bf16 v[42:45], v[232:235], v[106:109], v[42:45]
	v_mfma_f32_16x16x32_bf16 v[46:49], v[232:235], v[102:105], v[46:49]
	s_nop 0
	s_nop 0
	s_waitcnt lgkmcnt(2)
	v_mfma_f32_16x16x32_bf16 v[42:45], v[236:239], v[98:101], v[42:45]
	v_mfma_f32_16x16x32_bf16 v[46:49], v[236:239], v[94:97], v[46:49]
	s_nop 0
	s_nop 0
	s_waitcnt lgkmcnt(0)
	v_mfma_f32_16x16x32_bf16 v[34:37], v[244:247], v[106:109], v[34:37]
	ds_read_b64_tr_b16 v[106:107], v158 offset:65248
	ds_read_b64_tr_b16 v[108:109], v159 offset:57632
	ds_read_b128 v[168:171], v167 offset:4096
	ds_read_b128 v[248:251], v167 offset:4160
	ds_read_b128 v[252:255], v167 offset:4224
	ds_read_b128 v[232:235], v167 offset:4288
	ds_read_b128 v[236:239], v167 offset:4352
	v_mfma_f32_16x16x32_bf16 v[102:105], v[244:247], v[102:105], v[26:29]
	ds_read_b128 v[244:247], v167 offset:4416
	s_nop 0
	s_waitcnt lgkmcnt(6)
	v_mfma_f32_16x16x32_bf16 v[26:29], v[106:109], v[98:101], v[34:37]
	s_nop 1
	s_waitcnt lgkmcnt(5)
	v_mul_f32_e32 v34, 0x3fb8aa3b, v168
	v_exp_f32_e32 v98, v34
	v_mul_f32_e32 v34, 0x3fb8aa3b, v169
	v_exp_f32_e32 v99, v34
	v_mul_f32_e32 v34, 0x3fb8aa3b, v170
	v_exp_f32_e32 v100, v34
	v_mul_f32_e32 v34, 0x3fb8aa3b, v171
	v_exp_f32_e32 v101, v34
	s_nop 0
	v_mfma_f32_16x16x32_bf16 v[94:97], v[106:109], v[94:97], v[102:105]
	v_mul_f32_e64 v70, v70, v98
	v_mul_f32_e64 v71, v71, v99
	v_pk_mul_f32 v[74:75], v[74:75], v[98:99]
	v_pk_mul_f32 v[72:73], v[72:73], v[100:101]
	s_waitcnt lgkmcnt(4)
	v_mul_f32_e32 v34, 0x3fb8aa3b, v248
	v_exp_f32_e32 v102, v34
	v_mul_f32_e32 v34, 0x3fb8aa3b, v249
	v_exp_f32_e32 v103, v34
	v_mul_f32_e32 v34, 0x3fb8aa3b, v250
	v_exp_f32_e32 v104, v34
	v_mul_f32_e32 v34, 0x3fb8aa3b, v251
	ds_read_b128 v[248:251], v167 offset:4480
	v_exp_f32_e32 v105, v34
	s_nop 0
	v_pk_mul_f32 v[76:77], v[76:77], v[100:101]
	v_pk_mul_f32 v[58:59], v[58:59], v[102:103]
	v_pk_mul_f32 v[82:83], v[82:83], v[102:103]
	v_pk_mul_f32 v[60:61], v[60:61], v[104:105]
	s_waitcnt lgkmcnt(4)
	v_mul_f32_e32 v34, 0x3fb8aa3b, v252
	v_exp_f32_e32 v98, v34
	v_mul_f32_e32 v34, 0x3fb8aa3b, v253
	v_exp_f32_e32 v99, v34
	v_mul_f32_e32 v34, 0x3fb8aa3b, v254
	v_exp_f32_e32 v100, v34
	v_mul_f32_e32 v34, 0x3fb8aa3b, v255
	ds_read_b128 v[252:255], v167 offset:4544
	v_exp_f32_e32 v101, v34
	s_nop 0
	v_pk_mul_f32 v[84:85], v[84:85], v[104:105]
	v_pk_mul_f32 v[66:67], v[66:67], v[98:99]
	v_pk_mul_f32 v[78:79], v[78:79], v[98:99]
	v_pk_mul_f32 v[68:69], v[68:69], v[100:101]
	s_waitcnt lgkmcnt(4)
	v_mul_f32_e32 v34, 0x3fb8aa3b, v232
	v_exp_f32_e32 v102, v34
	v_mul_f32_e32 v34, 0x3fb8aa3b, v233
	v_exp_f32_e32 v103, v34
	v_mul_f32_e32 v34, 0x3fb8aa3b, v234
	v_exp_f32_e32 v104, v34
	v_mul_f32_e32 v34, 0x3fb8aa3b, v235
	v_exp_f32_e32 v105, v34
	s_nop 0
	v_pk_mul_f32 v[80:81], v[80:81], v[100:101]
	v_pk_mul_f32 v[62:63], v[62:63], v[102:103]
	v_pk_mul_f32 v[86:87], v[86:87], v[102:103]
	v_pk_mul_f32 v[64:65], v[64:65], v[104:105]
	s_waitcnt lgkmcnt(3)
	v_mul_f32_e32 v34, 0x3fb8aa3b, v236
	v_exp_f32_e32 v98, v34
	v_mul_f32_e32 v34, 0x3fb8aa3b, v237
	v_exp_f32_e32 v99, v34
	v_mul_f32_e32 v34, 0x3fb8aa3b, v238
	v_exp_f32_e32 v100, v34
	v_mul_f32_e32 v34, 0x3fb8aa3b, v239
	v_exp_f32_e32 v101, v34
	s_nop 0
	v_pk_mul_f32 v[88:89], v[88:89], v[104:105]
	v_pk_mul_f32 v[38:39], v[38:39], v[98:99]
	v_pk_mul_f32 v[50:51], v[50:51], v[98:99]
	v_pk_mul_f32 v[40:41], v[40:41], v[100:101]
	s_waitcnt lgkmcnt(2)
	v_mul_f32_e32 v34, 0x3fb8aa3b, v244
	v_exp_f32_e32 v102, v34
	v_mul_f32_e32 v34, 0x3fb8aa3b, v245
	v_exp_f32_e32 v103, v34
	v_mul_f32_e32 v34, 0x3fb8aa3b, v246
	v_exp_f32_e32 v104, v34
	v_mul_f32_e32 v34, 0x3fb8aa3b, v247
	v_exp_f32_e32 v105, v34
	s_nop 0
	v_pk_mul_f32 v[52:53], v[52:53], v[100:101]
	v_pk_mul_f32 v[30:31], v[30:31], v[102:103]
	v_pk_mul_f32 v[54:55], v[54:55], v[102:103]
	v_pk_mul_f32 v[32:33], v[32:33], v[104:105]
	s_waitcnt lgkmcnt(1)
	v_mul_f32_e32 v34, 0x3fb8aa3b, v248
	v_exp_f32_e32 v98, v34
	v_mul_f32_e32 v34, 0x3fb8aa3b, v249
	v_exp_f32_e32 v99, v34
	v_mul_f32_e32 v34, 0x3fb8aa3b, v250
	v_exp_f32_e32 v100, v34
	v_mul_f32_e32 v34, 0x3fb8aa3b, v251
	v_exp_f32_e32 v101, v34
	s_nop 0
	v_pk_mul_f32 v[56:57], v[56:57], v[104:105]
	v_pk_mul_f32 v[42:43], v[42:43], v[98:99]
	v_pk_mul_f32 v[44:45], v[44:45], v[100:101]
	v_pk_mul_f32 v[48:49], v[48:49], v[100:101]
	s_waitcnt lgkmcnt(0)
	v_mul_f32_e32 v34, 0x3fb8aa3b, v252
	v_exp_f32_e32 v102, v34
	v_mul_f32_e32 v34, 0x3fb8aa3b, v253
	v_mul_f32_e32 v35, 0x3fb8aa3b, v254
	v_exp_f32_e32 v104, v35
	v_mul_f32_e32 v35, 0x3fb8aa3b, v255
	v_exp_f32_e32 v105, v35
	v_exp_f32_e32 v103, v34
	v_pk_mul_f32 v[46:47], v[46:47], v[98:99]
	v_pk_mul_f32 v[36:37], v[28:29], v[104:105]
	v_pk_mul_f32 v[34:35], v[26:27], v[102:103]
	v_pk_mul_f32 v[28:29], v[96:97], v[104:105]
	v_pk_mul_f32 v[26:27], v[94:95], v[102:103]
	s_waitcnt lgkmcnt(0)
	s_cbranch_scc1 .LBB0_480
.LBB0_465:
	s_and_b32 s87, s83, 1
	s_cmp_eq_u32 s87, 0
	s_cselect_b64 s[50:51], -1, 0
	s_and_b64 s[30:31], s[50:51], exec
	s_cselect_b32 s30, 0xf0, s67
	v_add3_u32 v98, s30, v126, v133
	s_waitcnt lgkmcnt(0)
	ds_read2_b32 v[100:101], v98 offset1:4
	ds_read2_b32 v[102:103], v98 offset0:8 offset1:12
	ds_read2_b32 v[104:105], v98 offset0:64 offset1:68
	ds_read2_b32 v[108:109], v98 offset0:128 offset1:132
	ds_read2_b32 v[232:233], v98 offset0:72 offset1:76
	ds_read2_b32 v[236:237], v98 offset0:136 offset1:140
	ds_read2_b32 v[244:245], v98 offset0:192 offset1:196
	ds_read2_b32 v[248:249], v98 offset0:200 offset1:204
	s_mov_b64 s[52:53], -1
	s_waitcnt lgkmcnt(7)
	v_mfma_f32_16x16x4_f32 v[94:97], v100, v166, 0
	s_andn2_b64 vcc, exec, s[48:49]
	v_mfma_f32_16x16x4_f32 v[94:97], v101, v165, v[94:97]
	s_waitcnt lgkmcnt(6)
	v_mfma_f32_16x16x4_f32 v[94:97], v102, v164, v[94:97]
	v_mfma_f32_16x16x4_f32 v[94:97], v103, v163, v[94:97]
	s_waitcnt lgkmcnt(5)
	v_mfma_f32_16x16x4_f32 v[100:103], v104, v166, 0
	s_nop 7
	v_add_f32_e32 v94, v162, v94
	v_min_f32_e32 v99, 0, v94
	v_mul_f32_e64 v94, |v94|, s68
	v_exp_f32_e32 v94, v94
	v_add_f32_e32 v95, v162, v95
	v_add_f32_e32 v96, v162, v96
	v_add_f32_e32 v97, v162, v97
	v_add_f32_e32 v94, 1.0, v94
	v_log_f32_e32 v94, v94
	v_mfma_f32_16x16x4_f32 v[100:103], v105, v165, v[100:103]
	s_nop 0
	v_fmac_f32_e32 v99, 0xbf317218, v94
	v_mul_f32_e32 v94, 0x3d800000, v99
	v_min_f32_e32 v99, 0, v95
	v_mul_f32_e64 v95, |v95|, s68
	v_exp_f32_e32 v95, v95
	s_waitcnt lgkmcnt(3)
	v_mfma_f32_16x16x4_f32 v[100:103], v232, v164, v[100:103]
	v_add_f32_e32 v95, 1.0, v95
	v_log_f32_e32 v95, v95
	s_nop 0
	v_fmac_f32_e32 v99, 0xbf317218, v95
	v_mul_f32_e32 v95, 0x3d800000, v99
	v_min_f32_e32 v99, 0, v96
	v_mul_f32_e64 v96, |v96|, s68
	v_exp_f32_e32 v96, v96
	v_mfma_f32_16x16x4_f32 v[100:103], v233, v163, v[100:103]
	v_add_f32_e32 v96, 1.0, v96
	v_log_f32_e32 v96, v96
	s_nop 0
	v_fmac_f32_e32 v99, 0xbf317218, v96
	v_mul_f32_e32 v96, 0x3d800000, v99
	v_min_f32_e32 v99, 0, v97
	v_mul_f32_e64 v97, |v97|, s68
	v_exp_f32_e32 v97, v97
	v_mfma_f32_16x16x4_f32 v[104:107], v108, v166, 0
	v_add_f32_e32 v97, 1.0, v97
	v_log_f32_e32 v97, v97
	s_nop 0
	v_fmac_f32_e32 v99, 0xbf317218, v97
	v_mul_f32_e32 v97, 0x3d800000, v99
	v_add_f32_e32 v99, v162, v100
	v_min_f32_e32 v100, 0, v99
	v_mul_f32_e64 v99, |v99|, s68
	v_exp_f32_e32 v99, v99
	v_mfma_f32_16x16x4_f32 v[104:107], v109, v165, v[104:107]
	s_nop 0
	v_add_f32_e32 v99, 1.0, v99
	v_log_f32_e32 v99, v99
	s_nop 0
	v_fmac_f32_e32 v100, 0xbf317218, v99
	v_mul_f32_e32 v99, 0x3d800000, v100
	v_add_f32_e32 v100, v162, v101
	v_min_f32_e32 v101, 0, v100
	v_mul_f32_e64 v100, |v100|, s68
	v_exp_f32_e32 v100, v100
	s_waitcnt lgkmcnt(2)
	v_mfma_f32_16x16x4_f32 v[104:107], v236, v164, v[104:107]
	v_add_f32_e32 v100, 1.0, v100
	v_log_f32_e32 v100, v100
	s_nop 0
	v_fmac_f32_e32 v101, 0xbf317218, v100
	v_mul_f32_e32 v100, 0x3d800000, v101
	v_add_f32_e32 v101, v162, v102
	v_min_f32_e32 v102, 0, v101
	v_mul_f32_e64 v101, |v101|, s68
	v_exp_f32_e32 v101, v101
	v_mfma_f32_16x16x4_f32 v[104:107], v237, v163, v[104:107]
	s_nop 0
	v_add_f32_e32 v101, 1.0, v101
	v_log_f32_e32 v101, v101
	s_nop 0
	v_fmac_f32_e32 v102, 0xbf317218, v101
	v_mul_f32_e32 v101, 0x3d800000, v102
	v_add_f32_e32 v102, v162, v103
	v_min_f32_e32 v103, 0, v102
	v_mul_f32_e64 v102, |v102|, s68
	v_exp_f32_e32 v102, v102
	s_waitcnt lgkmcnt(1)
	v_mfma_f32_16x16x4_f32 v[168:171], v244, v166, 0
	v_add_f32_e32 v102, 1.0, v102
	v_log_f32_e32 v102, v102
	s_nop 0
	v_fmac_f32_e32 v103, 0xbf317218, v102
	v_mul_f32_e32 v102, 0x3d800000, v103
	v_add_f32_e32 v103, v162, v104
	v_min_f32_e32 v104, 0, v103
	v_mul_f32_e64 v103, |v103|, s68
	v_exp_f32_e32 v103, v103
	v_mfma_f32_16x16x4_f32 v[168:171], v245, v165, v[168:171]
	s_nop 0
	v_add_f32_e32 v103, 1.0, v103
	v_log_f32_e32 v103, v103
	s_nop 0
	v_fmac_f32_e32 v104, 0xbf317218, v103
	v_mul_f32_e32 v103, 0x3d800000, v104
	v_add_f32_e32 v104, v162, v105
	v_min_f32_e32 v105, 0, v104
	v_mul_f32_e64 v104, |v104|, s68
	v_exp_f32_e32 v104, v104
	s_waitcnt lgkmcnt(0)
	v_mfma_f32_16x16x4_f32 v[168:171], v248, v164, v[168:171]
	v_add_f32_e32 v104, 1.0, v104
	v_log_f32_e32 v104, v104
	s_nop 0
	v_fmac_f32_e32 v105, 0xbf317218, v104
	v_mul_f32_e32 v104, 0x3d800000, v105
	v_add_f32_e32 v105, v162, v106
	v_min_f32_e32 v106, 0, v105
	v_mul_f32_e64 v105, |v105|, s68
	v_exp_f32_e32 v105, v105
	v_mfma_f32_16x16x4_f32 v[168:171], v249, v163, v[168:171]
	v_add_f32_e32 v105, 1.0, v105
	v_log_f32_e32 v105, v105
	s_nop 0
	v_fmac_f32_e32 v106, 0xbf317218, v105
	v_mul_f32_e32 v105, 0x3d800000, v106
	v_add_f32_e32 v106, v162, v107
	v_min_f32_e32 v107, 0, v106
	v_mul_f32_e64 v106, |v106|, s68
	v_exp_f32_e32 v106, v106
	s_nop 0
	v_add_f32_e32 v98, v162, v168
	v_add_f32_e32 v106, 1.0, v106
	v_log_f32_e32 v106, v106
	s_nop 0
	v_fmac_f32_e32 v107, 0xbf317218, v106
	v_mul_f32_e32 v106, 0x3d800000, v107
	v_min_f32_e32 v107, 0, v98
	v_mul_f32_e64 v98, |v98|, s68
	v_exp_f32_e32 v98, v98
	s_nop 0
	v_add_f32_e32 v98, 1.0, v98
	v_log_f32_e32 v98, v98
	s_nop 0
	v_fmac_f32_e32 v107, 0xbf317218, v98
	v_mul_f32_e32 v98, 0x3d800000, v107
	v_add_f32_e32 v107, v162, v169
	v_min_f32_e32 v108, 0, v107
	v_mul_f32_e64 v107, |v107|, s68
	v_exp_f32_e32 v107, v107
	s_nop 0
	v_add_f32_e32 v107, 1.0, v107
	v_log_f32_e32 v107, v107
	s_nop 0
	v_fmac_f32_e32 v108, 0xbf317218, v107
	v_mul_f32_e32 v107, 0x3d800000, v108
	v_add_f32_e32 v108, v162, v170
	v_min_f32_e32 v109, 0, v108
	v_mul_f32_e64 v108, |v108|, s68
	v_exp_f32_e32 v108, v108
	s_nop 0
	v_add_f32_e32 v108, 1.0, v108
	v_log_f32_e32 v108, v108
	s_nop 0
	v_fmac_f32_e32 v109, 0xbf317218, v108
	v_add_f32_e32 v108, v162, v171
	v_mul_f32_e32 v167, 0x3d800000, v109
	v_min_f32_e32 v109, 0, v108
	v_mul_f32_e64 v108, |v108|, s68
	v_exp_f32_e32 v108, v108
	s_nop 0
	v_add_f32_e32 v108, 1.0, v108
	v_log_f32_e32 v108, v108
	s_nop 0
	v_fmac_f32_e32 v109, 0xbf317218, v108
	v_cndmask_b32_e64 v108, 0, 1, s[48:49]
	v_mul_f32_e32 v182, 0x3d800000, v109
	v_cmp_ne_u32_e64 s[30:31], 1, v108
	s_waitcnt lgkmcnt(0)
	s_cbranch_vccnz .LBB0_467
	v_add_f32_e32 v108, 0, v182
	v_add_f32_e32 v109, v167, v108
	v_add_f32_e32 v168, v107, v109
	v_add_f32_e32 v169, v98, v168
	v_add_f32_e32 v170, v106, v169
	v_add_f32_e32 v171, v105, v170
	v_add_f32_e32 v172, v104, v171
	v_add_f32_e32 v173, v103, v172
	v_add_f32_e32 v174, v102, v173
	v_add_f32_e32 v175, v101, v174
	v_add_f32_e32 v176, v100, v175
	v_add_f32_e32 v177, v99, v176
	v_add_f32_e32 v178, v97, v177
	v_add_f32_e32 v179, v96, v178
	v_add_f32_e32 v180, v95, v179
	v_add_f32_e32 v181, v94, v180
	s_mov_b64 s[52:53], 0

.LBB0_480:
	v_add3_u32 v108, s67, v126, v133
	s_waitcnt lgkmcnt(0)
	ds_read2_b32 v[94:95], v108 offset1:4
	ds_read2_b32 v[232:233], v108 offset0:8 offset1:12
	ds_read2_b32 v[234:235], v108 offset0:64 offset1:68
	ds_read2_b32 v[236:237], v108 offset0:72 offset1:76
	ds_read2_b32 v[244:245], v108 offset0:128 offset1:132
	ds_read2_b32 v[248:249], v108 offset0:136 offset1:140
	ds_read2_b32 v[252:253], v108 offset0:192 offset1:196
	s_and_b64 vcc, exec, s[30:31]
	s_mov_b64 s[46:47], -1
	s_waitcnt lgkmcnt(6)
	v_mfma_f32_16x16x4_f32 v[90:93], v94, v166, 0
	v_mfma_f32_16x16x4_f32 v[90:93], v95, v165, v[90:93]
	s_waitcnt lgkmcnt(5)
	v_mfma_f32_16x16x4_f32 v[90:93], v232, v164, v[90:93]
	s_waitcnt lgkmcnt(4)
	v_mfma_f32_16x16x4_f32 v[94:97], v234, v166, 0
	v_mfma_f32_16x16x4_f32 v[90:93], v233, v163, v[90:93]
	s_nop 9
	v_add_f32_e32 v98, v162, v92
	v_add_f32_e32 v99, v162, v93
	v_mfma_f32_16x16x4_f32 v[92:95], v235, v165, v[94:97]
	v_mul_f32_e64 v105, |v98|, s68
	v_exp_f32_e32 v96, v105
	v_add_f32_e32 v91, v162, v91
	v_add_f32_e32 v90, v162, v90
	v_min_f32_e32 v104, 0, v91
	v_add_f32_e32 v96, 1.0, v96
	v_log_f32_e32 v101, v96
	s_waitcnt lgkmcnt(3)
	v_mfma_f32_16x16x4_f32 v[94:97], v236, v164, v[92:95]
	v_mul_f32_e64 v91, |v91|, s68
	v_min_f32_e32 v100, 0, v90
	v_mul_f32_e64 v90, |v90|, s68
	v_exp_f32_e32 v91, v91
	v_mul_f32_e64 v92, |v99|, s68
	v_exp_f32_e32 v90, v90
	v_exp_f32_e32 v93, v92
	v_mfma_f32_16x16x4_f32 v[94:97], v237, v163, v[94:97]
	s_nop 0
	v_add_f32_e32 v91, 1.0, v91
	v_min_f32_e32 v92, 0, v98
	v_add_f32_e32 v90, 1.0, v90
	v_log_f32_e32 v91, v91
	v_add_f32_e32 v93, 1.0, v93
	v_log_f32_e32 v90, v90
	s_nop 2
	v_add_f32_e32 v94, v162, v94
	v_mul_f32_e64 v98, |v94|, s68
	v_exp_f32_e32 v98, v98
	v_log_f32_e32 v93, v93
	v_fmac_f32_e32 v104, 0xbf317218, v91
	v_min_f32_e32 v99, 0, v99
	v_add_f32_e32 v98, 1.0, v98
	v_add_f32_e32 v95, v162, v95
	v_fmac_f32_e32 v100, 0xbf317218, v90
	v_mul_f32_e32 v91, 0x3d800000, v104
	v_fmac_f32_e32 v99, 0xbf317218, v93
	v_log_f32_e32 v104, v98
	v_mul_f32_e64 v98, |v95|, s68
	v_mul_f32_e32 v90, 0x3d800000, v100
	v_fmac_f32_e32 v92, 0xbf317218, v101
	v_mul_f32_e32 v93, 0x3d800000, v99
	v_exp_f32_e32 v105, v98
	s_waitcnt lgkmcnt(2)
	v_mfma_f32_16x16x4_f32 v[98:101], v244, v166, 0
	v_min_f32_e32 v94, 0, v94
	v_fmac_f32_e32 v94, 0xbf317218, v104
	v_add_f32_e32 v102, 1.0, v105
	s_nop 0
	v_add_f32_e32 v106, v162, v96
	v_mul_f32_e64 v96, |v106|, s68
	v_exp_f32_e32 v96, v96
	v_mfma_f32_16x16x4_f32 v[98:101], v245, v165, v[98:101]
	v_log_f32_e32 v102, v102
	v_min_f32_e32 v95, 0, v95
	v_add_f32_e32 v96, 1.0, v96
	v_add_f32_e32 v103, v162, v97
	v_fmac_f32_e32 v95, 0xbf317218, v102
	v_log_f32_e32 v102, v96
	v_mul_f32_e32 v92, 0x3d800000, v92
	s_waitcnt lgkmcnt(1)
	v_mfma_f32_16x16x4_f32 v[96:99], v248, v164, v[98:101]
	s_nop 0
	v_mul_f32_e64 v100, |v103|, s68
	v_exp_f32_e32 v100, v100
	v_min_f32_e32 v104, 0, v106
	v_fmac_f32_e32 v104, 0xbf317218, v102
	s_nop 0
	v_add_f32_e32 v100, 1.0, v100
	v_log_f32_e32 v102, v100
	v_mfma_f32_16x16x4_f32 v[98:101], v249, v163, v[96:99]
	v_min_f32_e32 v103, 0, v103
	v_mul_f32_e32 v94, 0x3d800000, v94
	v_fmac_f32_e32 v103, 0xbf317218, v102
	v_mul_f32_e32 v95, 0x3d800000, v95
	s_nop 5
	v_add_f32_e32 v98, v162, v98
	v_mul_f32_e64 v96, |v98|, s68
	v_exp_f32_e32 v97, v96
	v_add_f32_e32 v99, v162, v99
	v_mul_f32_e32 v96, 0x3d800000, v104
	v_min_f32_e32 v98, 0, v98
	v_add_f32_e32 v97, 1.0, v97
	v_log_f32_e32 v102, v97
	v_mul_f32_e64 v97, |v99|, s68
	v_exp_f32_e32 v104, v97
	v_mul_f32_e32 v97, 0x3d800000, v103
	v_fmac_f32_e32 v98, 0xbf317218, v102
	v_min_f32_e32 v99, 0, v99
	v_add_f32_e32 v102, 1.0, v104
	v_log_f32_e32 v109, v102
	s_waitcnt lgkmcnt(0)
	v_mfma_f32_16x16x4_f32 v[102:105], v252, v166, 0
	v_add_f32_e32 v100, v162, v100
	v_min_f32_e32 v106, 0, v100
	v_fmac_f32_e32 v99, 0xbf317218, v109
	ds_read2_b32 v[108:109], v108 offset0:200 offset1:204
	v_mul_f32_e64 v100, |v100|, s68
	v_exp_f32_e32 v100, v100
	v_mul_f32_e32 v98, 0x3d800000, v98
	v_mfma_f32_16x16x4_f32 v[102:105], v253, v165, v[102:105]
	v_add_f32_e32 v107, v162, v101
	v_mul_f32_e64 v101, |v107|, s68
	v_add_f32_e32 v100, 1.0, v100
	v_exp_f32_e32 v165, v101
	v_log_f32_e32 v166, v100
	v_mul_f32_e32 v99, 0x3d800000, v99
	v_fmac_f32_e32 v106, 0xbf317218, v166
	s_waitcnt lgkmcnt(0)
	v_mfma_f32_16x16x4_f32 v[100:103], v108, v164, v[102:105]
	s_nop 0
	v_add_f32_e32 v104, 1.0, v165
	v_log_f32_e32 v104, v104
	v_min_f32_e32 v105, 0, v107
	v_mul_f32_e32 v168, 0x3d800000, v106
	v_fmac_f32_e32 v105, 0xbf317218, v104
	v_mul_f32_e32 v169, 0x3d800000, v105
	v_mfma_f32_16x16x4_f32 v[100:103], v109, v163, v[100:103]
	s_nop 9
	v_add_f32_e32 v100, v162, v100
	v_mul_f32_e64 v104, |v100|, s68
	v_exp_f32_e32 v104, v104
	v_add_f32_e32 v101, v162, v101
	v_mul_f32_e64 v105, |v101|, s68
	v_exp_f32_e32 v105, v105
	v_add_f32_e32 v104, 1.0, v104
	v_log_f32_e32 v104, v104
	v_min_f32_e32 v100, 0, v100
	v_add_f32_e32 v105, 1.0, v105
	v_log_f32_e32 v105, v105
	v_fmac_f32_e32 v100, 0xbf317218, v104
	v_mul_f32_e32 v170, 0x3d800000, v100
	v_min_f32_e32 v100, 0, v101
	v_fmac_f32_e32 v100, 0xbf317218, v105
	v_mul_f32_e32 v171, 0x3d800000, v100
	v_add_f32_e32 v100, v162, v102
	v_mul_f32_e64 v101, |v100|, s68
	v_exp_f32_e32 v101, v101
	v_add_f32_e32 v102, v162, v103
	v_mul_f32_e64 v103, |v102|, s68
	v_exp_f32_e32 v103, v103
	v_add_f32_e32 v101, 1.0, v101
	v_log_f32_e32 v101, v101
	v_min_f32_e32 v100, 0, v100
	v_add_f32_e32 v103, 1.0, v103
	v_log_f32_e32 v103, v103
	v_fmac_f32_e32 v100, 0xbf317218, v101
	v_mul_f32_e32 v172, 0x3d800000, v100
	v_min_f32_e32 v100, 0, v102
	v_fmac_f32_e32 v100, 0xbf317218, v103
	v_mul_f32_e32 v173, 0x3d800000, v100
	s_waitcnt lgkmcnt(0)
	s_cbranch_vccnz .LBB0_482
	v_add_f32_e32 v100, 0, v173
	v_add_f32_e32 v101, v172, v100
	v_add_f32_e32 v102, v171, v101
	v_add_f32_e32 v103, v170, v102
	v_add_f32_e32 v104, v169, v103
	v_add_f32_e32 v105, v168, v104
	v_add_f32_e32 v106, v99, v105
	v_add_f32_e32 v107, v98, v106
	v_add_f32_e32 v108, v97, v107
	v_add_f32_e32 v109, v96, v108
	v_add_f32_e32 v162, v95, v109
	v_add_f32_e32 v163, v94, v162
	v_add_f32_e32 v164, v93, v163
	v_add_f32_e32 v165, v92, v164
	v_add_f32_e32 v166, v91, v165
	v_add_f32_e32 v167, v90, v166
	s_mov_b64 s[46:47], 0

.LBB0_490:
	s_or_b64 exec, exec, s[30:31]
	s_waitcnt lgkmcnt(0)
	ds_read_b128 v[90:93], v149 offset:6144
	ds_read_b128 v[94:97], v149 offset:6160
	s_waitcnt vmcnt(5)
	v_lshlrev_b32_e32 v98, 16, v22
	v_and_b32_e32 v99, 0xffff0000, v22
	s_waitcnt lgkmcnt(1)
	v_mul_f32_e32 v90, 0xbfb8aa3b, v90
	v_mul_f32_e32 v91, 0xbfb8aa3b, v91
	v_exp_f32_e32 v90, v90
	v_exp_f32_e32 v91, v91
	v_mul_f32_e32 v22, 0xbfb8aa3b, v92
	v_exp_f32_e32 v92, v22
	v_mul_f32_e32 v22, 0xbfb8aa3b, v93
	v_exp_f32_e32 v93, v22
	v_pk_mul_f32 v[90:91], v[90:91], v[98:99]
	s_nop 0
	v_cvt_pk_bf16_f32 v22, v90, v91
	v_lshlrev_b32_e32 v90, 16, v23
	v_and_b32_e32 v91, 0xffff0000, v23
	s_waitcnt lgkmcnt(0)
	v_mul_f32_e32 v23, 0xbfb8aa3b, v94
	v_pk_mul_f32 v[90:91], v[92:93], v[90:91]
	v_exp_f32_e32 v92, v23
	v_mul_f32_e32 v23, 0xbfb8aa3b, v95
	v_exp_f32_e32 v93, v23
	v_cvt_pk_bf16_f32 v23, v90, v91
	v_lshlrev_b32_e32 v90, 16, v24
	v_and_b32_e32 v91, 0xffff0000, v24
	v_mul_f32_e32 v24, 0xbfb8aa3b, v96
	v_pk_mul_f32 v[90:91], v[92:93], v[90:91]
	v_exp_f32_e32 v92, v24
	v_mul_f32_e32 v24, 0xbfb8aa3b, v97
	v_exp_f32_e32 v93, v24
	v_cvt_pk_bf16_f32 v24, v90, v91
	v_lshlrev_b32_e32 v90, 16, v25
	v_and_b32_e32 v91, 0xffff0000, v25
	v_pk_mul_f32 v[90:91], v[92:93], v[90:91]
	s_waitcnt vmcnt(4)
	v_lshlrev_b32_e32 v94, 16, v6
	v_cvt_pk_bf16_f32 v25, v90, v91
	ds_write_b128 v150, v[22:25] offset:56320
	ds_read_b128 v[232:235], v151 offset:6144
	ds_read_b128 v[90:93], v151 offset:6160
	v_and_b32_e32 v95, 0xffff0000, v6
	s_waitcnt lgkmcnt(1)
	v_mul_f32_e32 v22, 0xbfb8aa3b, v232
	v_mul_f32_e32 v23, 0xbfb8aa3b, v233
	v_exp_f32_e32 v22, v22
	v_exp_f32_e32 v23, v23
	v_mul_f32_e32 v6, 0xbfb8aa3b, v234
	v_exp_f32_e32 v24, v6
	v_mul_f32_e32 v6, 0xbfb8aa3b, v235
	v_exp_f32_e32 v25, v6
	v_pk_mul_f32 v[22:23], v[22:23], v[94:95]
	s_nop 0
	v_cvt_pk_bf16_f32 v6, v22, v23
	v_lshlrev_b32_e32 v22, 16, v7
	v_and_b32_e32 v23, 0xffff0000, v7
	s_waitcnt lgkmcnt(0)
	v_mul_f32_e32 v7, 0xbfb8aa3b, v90
	v_pk_mul_f32 v[22:23], v[24:25], v[22:23]
	v_exp_f32_e32 v24, v7
	v_mul_f32_e32 v7, 0xbfb8aa3b, v91
	v_exp_f32_e32 v25, v7
	v_cvt_pk_bf16_f32 v7, v22, v23
	v_lshlrev_b32_e32 v22, 16, v8
	v_and_b32_e32 v23, 0xffff0000, v8
	v_mul_f32_e32 v8, 0xbfb8aa3b, v92
	v_pk_mul_f32 v[22:23], v[24:25], v[22:23]
	v_exp_f32_e32 v24, v8
	v_mul_f32_e32 v8, 0xbfb8aa3b, v93
	v_exp_f32_e32 v25, v8
	v_cvt_pk_bf16_f32 v8, v22, v23
	v_lshlrev_b32_e32 v22, 16, v9
	v_and_b32_e32 v23, 0xffff0000, v9
	v_pk_mul_f32 v[22:23], v[24:25], v[22:23]
	s_nop 0
	v_cvt_pk_bf16_f32 v9, v22, v23
	ds_write_b128 v152, v[6:9] offset:56320
	s_waitcnt vmcnt(3)
	ds_write_b128 v153, v[2:5]
	s_waitcnt vmcnt(2)
	ds_write_b128 v155, v[10:13]
	s_waitcnt vmcnt(1)
	ds_write_b128 v153, v[14:17] offset:16896
	s_waitcnt vmcnt(0)
	ds_write_b128 v156, v[18:21]
	s_waitcnt lgkmcnt(0)
	s_barrier
	s_waitcnt lgkmcnt(0)
	ds_read_b64_tr_b16 v[4:5], v158 offset:57408
	ds_read_b64_tr_b16 v[2:3], v158 offset:56320
	ds_read_b64_tr_b16 v[8:9], v157 offset:2112
	ds_read_b64_tr_b16 v[6:7], v157
	ds_read_b64_tr_b16 v[12:13], v157 offset:2144
	ds_read_b64_tr_b16 v[10:11], v157 offset:32
	ds_read_b64_tr_b16 v[14:15], v158 offset:56352
	ds_read_b64_tr_b16 v[18:19], v158 offset:56384
	ds_read_b64_tr_b16 v[22:23], v158 offset:56416
	ds_read_b64_tr_b16 v[16:17], v158 offset:57440
	ds_read_b64_tr_b16 v[20:21], v158 offset:57472
	ds_read_b64_tr_b16 v[24:25], v158 offset:57504
	ds_read_b64_tr_b16 v[232:233], v158 offset:65024
	ds_read_b64_tr_b16 v[234:235], v159 offset:57408
	ds_read_b64_tr_b16 v[94:95], v157 offset:16896
	ds_read_b64_tr_b16 v[96:97], v157 offset:19008
	ds_read_b64_tr_b16 v[100:101], v157 offset:19040
	ds_read_b64_tr_b16 v[98:99], v157 offset:16928
	ds_read_b64_tr_b16 v[236:237], v158 offset:65056
	ds_read_b64_tr_b16 v[102:103], v158 offset:65088
	ds_read_b64_tr_b16 v[106:107], v158 offset:65120
	ds_read_b64_tr_b16 v[238:239], v159 offset:57440
	ds_read_b64_tr_b16 v[104:105], v159 offset:57472
	ds_read_b64_tr_b16 v[108:109], v159 offset:57504
	ds_read_b64_tr_b16 v[244:245], v158 offset:56448
	ds_read_b64_tr_b16 v[246:247], v158 offset:57536
	s_waitcnt lgkmcnt(15)
	v_mfma_f32_16x16x32_bf16 v[58:61], v[14:17], v[6:9], v[58:61]
	v_mfma_f32_16x16x32_bf16 v[14:17], v[14:17], v[10:13], v[82:85]
	v_mfma_f32_16x16x32_bf16 v[70:73], v[2:5], v[6:9], v[70:73]
	v_mfma_f32_16x16x32_bf16 v[2:5], v[2:5], v[10:13], v[74:77]
	s_nop 2
	s_nop 0
	s_nop 0
	s_nop 0
	s_nop 0
	s_nop 0
	s_nop 0
	s_waitcnt lgkmcnt(4)
	v_mfma_f32_16x16x32_bf16 v[58:61], v[236:239], v[94:97], v[58:61]
	v_mfma_f32_16x16x32_bf16 v[14:17], v[236:239], v[98:101], v[14:17]
	s_nop 0
	s_nop 0
	v_mfma_f32_16x16x32_bf16 v[66:69], v[18:21], v[6:9], v[66:69]
	v_mfma_f32_16x16x32_bf16 v[18:21], v[18:21], v[10:13], v[78:81]
	ds_read_b64_tr_b16 v[78:79], v158 offset:56480
	ds_read_b64_tr_b16 v[82:83], v158 offset:56512
	v_mfma_f32_16x16x32_bf16 v[62:65], v[22:25], v[6:9], v[62:65]
	v_mfma_f32_16x16x32_bf16 v[22:25], v[22:25], v[10:13], v[86:89]
	ds_read_b64_tr_b16 v[86:87], v158 offset:56544
	ds_read_b64_tr_b16 v[80:81], v158 offset:57568
	ds_read_b64_tr_b16 v[84:85], v158 offset:57600
	ds_read_b64_tr_b16 v[88:89], v158 offset:57632
	ds_read_b64_tr_b16 v[90:91], v158 offset:65152
	ds_read_b64_tr_b16 v[92:93], v159 offset:57536
	ds_read_b64_tr_b16 v[248:249], v158 offset:65184
	s_nop 0
	s_nop 0
	s_nop 0
	s_nop 0
	s_nop 0
	s_nop 0
	s_nop 0
	s_waitcnt lgkmcnt(4)
	v_mfma_f32_16x16x32_bf16 v[42:45], v[82:85], v[6:9], v[42:45]
	v_mfma_f32_16x16x32_bf16 v[46:49], v[82:85], v[10:13], v[46:49]
	v_add_u32_e32 v82, s43, v128
	s_ashr_i32 s43, s42, 31
	s_lshl_b64 s[30:31], s[42:43], 17
	v_mfma_f32_16x16x32_bf16 v[70:73], v[232:235], v[94:97], v[70:73]
	v_mfma_f32_16x16x32_bf16 v[2:5], v[232:235], v[98:101], v[2:5]
	s_nop 0
	s_nop 0
	v_mfma_f32_16x16x32_bf16 v[66:69], v[102:105], v[94:97], v[66:69]
	v_mfma_f32_16x16x32_bf16 v[18:21], v[102:105], v[98:101], v[18:21]
	ds_read_b64_tr_b16 v[102:103], v158 offset:65216
	v_mfma_f32_16x16x32_bf16 v[62:65], v[106:109], v[94:97], v[62:65]
	v_mfma_f32_16x16x32_bf16 v[22:25], v[106:109], v[98:101], v[22:25]
	ds_read_b64_tr_b16 v[106:107], v158 offset:65248
	ds_read_b64_tr_b16 v[250:251], v159 offset:57568
	ds_read_b64_tr_b16 v[104:105], v159 offset:57600
	ds_read_b64_tr_b16 v[108:109], v159 offset:57632
	ds_read_b128 v[252:255], v82 offset:4096
	ds_read_b128 v[236:239], v82 offset:4160
	ds_read_b128 v[232:235], v82 offset:4224
	v_mfma_f32_16x16x32_bf16 v[38:41], v[244:247], v[6:9], v[38:41]
	v_mfma_f32_16x16x32_bf16 v[50:53], v[244:247], v[10:13], v[50:53]
	ds_read_b128 v[244:247], v82 offset:4288
	s_nop 0
	s_nop 0
	s_nop 0
	s_nop 0
	s_nop 0
	s_nop 0
	v_mfma_f32_16x16x32_bf16 v[54:57], v[78:81], v[10:13], v[54:57]
	s_waitcnt lgkmcnt(12)
	v_mfma_f32_16x16x32_bf16 v[10:13], v[86:89], v[10:13], v[26:29]
	s_nop 2
	s_nop 0
	v_mfma_f32_16x16x32_bf16 v[30:33], v[78:81], v[6:9], v[30:33]
	v_mfma_f32_16x16x32_bf16 v[6:9], v[86:89], v[6:9], v[34:37]
	s_nop 2
	s_nop 0
	s_waitcnt lgkmcnt(3)
	v_mul_f32_e32 v26, 0x3fb8aa3b, v252
	v_mfma_f32_16x16x32_bf16 v[30:33], v[248:251], v[94:97], v[30:33]
	s_waitcnt lgkmcnt(2)
	v_mul_f32_e32 v34, 0x3fb8aa3b, v236
	v_mfma_f32_16x16x32_bf16 v[54:57], v[248:251], v[98:101], v[54:57]
	ds_read_b128 v[248:251], v82 offset:4352
	v_exp_f32_e32 v74, v26
	v_mul_f32_e32 v26, 0x3fb8aa3b, v253
	v_mul_f32_e32 v27, 0x3fb8aa3b, v254
	v_exp_f32_e32 v76, v27
	v_mul_f32_e32 v27, 0x3fb8aa3b, v255
	ds_read_b128 v[252:255], v82 offset:4416
	v_exp_f32_e32 v77, v27
	v_exp_f32_e32 v75, v26
	v_mfma_f32_16x16x32_bf16 v[38:41], v[90:93], v[94:97], v[38:41]
	v_mul_f32_e64 v28, v72, v76
	v_mul_f32_e64 v29, v73, v77
	v_pk_mul_f32 v[4:5], v[4:5], v[76:77]
	v_exp_f32_e32 v76, v34
	v_mul_f32_e32 v34, 0x3fb8aa3b, v237
	v_mul_f32_e32 v35, 0x3fb8aa3b, v238
	v_exp_f32_e32 v78, v35
	v_mul_f32_e32 v35, 0x3fb8aa3b, v239
	ds_read_b128 v[236:239], v82 offset:4480
	v_exp_f32_e32 v79, v35
	v_exp_f32_e32 v77, v34
	s_nop 0
	v_pk_mul_f32 v[26:27], v[70:71], v[74:75]
	ds_read_b128 v[70:73], v82 offset:4544
	s_nop 0
	v_pk_mul_f32 v[2:3], v[2:3], v[74:75]
	v_pk_mul_f32 v[60:61], v[60:61], v[78:79]
	s_waitcnt lgkmcnt(5)
	v_mul_f32_e32 v34, 0x3fb8aa3b, v232
	v_exp_f32_e32 v74, v34
	v_mul_f32_e32 v34, 0x3fb8aa3b, v233
	v_mul_f32_e32 v35, 0x3fb8aa3b, v234
	v_exp_f32_e32 v75, v34
	v_exp_f32_e32 v80, v35
	v_mul_f32_e32 v35, 0x3fb8aa3b, v235
	v_exp_f32_e32 v81, v35
	v_pk_mul_f32 v[34:35], v[66:67], v[74:75]
	s_waitcnt lgkmcnt(4)
	v_mul_f32_e32 v66, 0x3fb8aa3b, v244
	v_mul_f32_e32 v67, 0x3fb8aa3b, v246
	v_pk_mul_f32 v[58:59], v[58:59], v[76:77]
	v_pk_mul_f32 v[16:17], v[16:17], v[78:79]
	v_pk_mul_f32 v[14:15], v[14:15], v[76:77]
	v_exp_f32_e32 v76, v66
	v_mul_f32_e32 v66, 0x3fb8aa3b, v245
	v_exp_f32_e32 v78, v67
	v_mul_f32_e32 v67, 0x3fb8aa3b, v247
	v_pk_mul_f32 v[36:37], v[68:69], v[80:81]
	v_exp_f32_e32 v79, v67
	v_exp_f32_e32 v77, v66
	s_nop 0
	s_nop 0
	v_pk_mul_f32 v[18:19], v[18:19], v[74:75]
	v_mfma_f32_16x16x32_bf16 v[50:53], v[90:93], v[98:101], v[50:53]
	v_mul_f32_e64 v64, v64, v78
	v_mul_f32_e64 v65, v65, v79
	s_waitcnt lgkmcnt(3)
	v_mul_f32_e32 v66, 0x3fb8aa3b, v248
	v_exp_f32_e32 v74, v66
	v_mul_f32_e32 v75, 0x3fb8aa3b, v249
	v_mul_f32_e32 v66, 0x3fb8aa3b, v250
	v_mul_f32_e32 v67, 0x3fb8aa3b, v251
	v_exp_f32_e32 v66, v66
	v_exp_f32_e32 v67, v67
	v_pk_mul_f32 v[62:63], v[62:63], v[76:77]
	v_pk_mul_f32 v[24:25], v[24:25], v[78:79]
	v_pk_mul_f32 v[22:23], v[22:23], v[76:77]
	v_pk_mul_f32 v[40:41], v[40:41], v[66:67]
	v_pk_mul_f32 v[52:53], v[52:53], v[66:67]
	s_waitcnt lgkmcnt(2)
	v_mul_f32_e32 v66, 0x3fb8aa3b, v252
	v_mul_f32_e32 v67, 0x3fb8aa3b, v254
	v_exp_f32_e32 v76, v66
	v_mul_f32_e32 v66, 0x3fb8aa3b, v253
	v_exp_f32_e32 v78, v67
	v_mul_f32_e32 v67, 0x3fb8aa3b, v255
	v_exp_f32_e32 v79, v67
	v_exp_f32_e32 v77, v66
	s_nop 0
	s_nop 0
	v_mfma_f32_16x16x32_bf16 v[42:45], v[102:105], v[94:97], v[42:45]
	v_mul_f32_e64 v20, v20, v80
	v_mul_f32_e64 v21, v21, v81
	v_exp_f32_e32 v75, v75
	s_waitcnt lgkmcnt(1)
	v_mul_f32_e32 v66, 0x3fb8aa3b, v236
	v_mul_f32_e32 v67, 0x3fb8aa3b, v237
	v_mfma_f32_16x16x32_bf16 v[46:49], v[102:105], v[98:101], v[46:49]
	v_exp_f32_e32 v66, v66
	v_exp_f32_e32 v67, v67
	v_pk_mul_f32 v[38:39], v[38:39], v[74:75]
	v_pk_mul_f32 v[50:51], v[50:51], v[74:75]
	v_mul_f32_e32 v68, 0x3fb8aa3b, v238
	v_pk_mul_f32 v[42:43], v[42:43], v[66:67]
	s_nop 1
	v_pk_mul_f32 v[46:47], v[46:47], v[66:67]
	v_lshl_add_u64 v[66:67], v[120:121], 0, s[30:31]
	s_movk_i32 s30, 0x2000
	global_store_dwordx4 v[66:67], v[26:29], off
	v_mul_f32_e32 v69, 0x3fb8aa3b, v239
	v_pk_mul_f32 v[32:33], v[32:33], v[78:79]
	v_add_co_u32_e32 v26, vcc, s30, v66
	s_movk_i32 s30, 0x4000
	s_nop 0
	v_addc_co_u32_e32 v27, vcc, 0, v67, vcc
	global_store_dwordx4 v[26:27], v[2:5], off
	v_pk_mul_f32 v[30:31], v[30:31], v[76:77]
	v_exp_f32_e32 v68, v68
	v_add_co_u32_e32 v2, vcc, s30, v66
	s_movk_i32 s30, 0x6000
	s_nop 0
	v_addc_co_u32_e32 v3, vcc, 0, v67, vcc
	global_store_dwordx4 v[2:3], v[58:61], off
	v_add_co_u32_e32 v2, vcc, s30, v66
	v_exp_f32_e32 v69, v69
	s_nop 0
	v_addc_co_u32_e32 v3, vcc, 0, v67, vcc
	global_store_dwordx4 v[2:3], v[14:17], off
	v_add_co_u32_e32 v2, vcc, s62, v66
	v_pk_mul_f32 v[56:57], v[56:57], v[78:79]
	s_nop 0
	v_addc_co_u32_e32 v3, vcc, 0, v67, vcc
	global_store_dwordx4 v[2:3], v[34:37], off
	v_add_co_u32_e32 v2, vcc, s69, v66
	v_pk_mul_f32 v[54:55], v[54:55], v[76:77]
	s_nop 0
	v_addc_co_u32_e32 v3, vcc, 0, v67, vcc
	global_store_dwordx4 v[2:3], v[18:21], off
	v_add_co_u32_e32 v2, vcc, s70, v66
	s_waitcnt lgkmcnt(0)
	v_mul_f32_e32 v70, 0x3fb8aa3b, v70
	v_addc_co_u32_e32 v3, vcc, 0, v67, vcc
	global_store_dwordx4 v[2:3], v[62:65], off
	v_add_co_u32_e32 v2, vcc, s71, v66
	v_mul_f32_e32 v71, 0x3fb8aa3b, v71
	s_nop 0
	v_addc_co_u32_e32 v3, vcc, 0, v67, vcc
	global_store_dwordx4 v[2:3], v[22:25], off
	v_add_co_u32_e32 v2, vcc, s72, v66
	v_mul_f32_e32 v72, 0x3fb8aa3b, v72
	s_nop 0
	v_addc_co_u32_e32 v3, vcc, 0, v67, vcc
	global_store_dwordx4 v[2:3], v[38:41], off
	v_add_co_u32_e32 v2, vcc, s66, v66
	v_mul_f32_e32 v73, 0x3fb8aa3b, v73
	s_nop 0
	v_addc_co_u32_e32 v3, vcc, 0, v67, vcc
	global_store_dwordx4 v[2:3], v[50:53], off
	v_add_co_u32_e32 v2, vcc, s73, v66
	v_mfma_f32_16x16x32_bf16 v[6:9], v[106:109], v[94:97], v[6:9]
	s_nop 0
	v_addc_co_u32_e32 v3, vcc, 0, v67, vcc
	global_store_dwordx4 v[2:3], v[30:33], off
	v_add_co_u32_e32 v2, vcc, s74, v66
	v_pk_mul_f32 v[44:45], v[44:45], v[68:69]
	s_nop 0
	v_addc_co_u32_e32 v3, vcc, 0, v67, vcc
	global_store_dwordx4 v[2:3], v[54:57], off
	v_add_co_u32_e32 v2, vcc, s64, v66
	v_exp_f32_e32 v70, v70
	v_exp_f32_e32 v72, v72
	v_exp_f32_e32 v73, v73
	v_exp_f32_e32 v71, v71
	v_addc_co_u32_e32 v3, vcc, 0, v67, vcc
	global_store_dwordx4 v[2:3], v[42:45], off
	v_add_co_u32_e32 v2, vcc, s75, v66
	v_mfma_f32_16x16x32_bf16 v[10:13], v[106:109], v[98:101], v[10:13]
	v_mul_f32_e64 v48, v48, v68
	v_mul_f32_e64 v49, v49, v69
	v_addc_co_u32_e32 v3, vcc, 0, v67, vcc
	global_store_dwordx4 v[2:3], v[46:49], off
	v_add_co_u32_e32 v2, vcc, 0x1c000, v66
	v_pk_mul_f32 v[8:9], v[8:9], v[72:73]
	v_pk_mul_f32 v[6:7], v[6:7], v[70:71]
	v_addc_co_u32_e32 v3, vcc, 0, v67, vcc
	global_store_dwordx4 v[2:3], v[6:9], off
	v_add_co_u32_e32 v2, vcc, 0x1e000, v66
	v_pk_mul_f32 v[12:13], v[12:13], v[72:73]
	v_pk_mul_f32 v[10:11], v[10:11], v[70:71]
	v_addc_co_u32_e32 v3, vcc, 0, v67, vcc
	global_store_dwordx4 v[2:3], v[10:13], off
	s_and_saveexec_b64 s[30:31], s[4:5]
	s_waitcnt lgkmcnt(0)
	s_cbranch_execz .LBB0_450
	v_mul_f32_e32 v1, 0x3fb8aa3b, v1
	v_exp_f32_e32 v1, v1
	s_lshl_b64 s[46:47], s[42:43], 9
	v_lshl_add_u64 v[2:3], v[118:119], 0, s[46:47]
	global_store_dword v[2:3], v1, off
	s_branch .LBB0_450

.LBB0_501:
	ds_read_b128 v[160:163], v149 offset:6144
	ds_read_b128 v[164:167], v149 offset:6160
	s_waitcnt vmcnt(6)
	v_lshlrev_b32_e32 v108, 16, v98
	v_and_b32_e32 v109, 0xffff0000, v98
	v_cvt_pk_bf16_f32 v180, v34, v35
	s_waitcnt lgkmcnt(1)
	v_mul_f32_e32 v1, 0xbfb8aa3b, v160
	v_mul_f32_e32 v107, 0xbfb8aa3b, v161
	v_exp_f32_e32 v168, v1
	v_exp_f32_e32 v169, v107
	v_mul_f32_e32 v1, 0xbfb8aa3b, v162
	v_exp_f32_e32 v170, v1
	v_mul_f32_e32 v1, 0xbfb8aa3b, v163
	v_exp_f32_e32 v171, v1
	s_waitcnt lgkmcnt(0)
	v_mul_f32_e32 v1, 0xbfb8aa3b, v164
	v_pk_mul_f32 v[108:109], v[168:169], v[108:109]
	v_exp_f32_e32 v168, v1
	v_mul_f32_e32 v1, 0xbfb8aa3b, v165
	v_exp_f32_e32 v169, v1
	v_cvt_pk_bf16_f32 v98, v108, v109
	v_lshlrev_b32_e32 v108, 16, v99
	v_and_b32_e32 v109, 0xffff0000, v99
	v_pk_mul_f32 v[108:109], v[170:171], v[108:109]
	v_mul_f32_e32 v1, 0xbfb8aa3b, v166
	v_cvt_pk_bf16_f32 v99, v108, v109
	v_lshlrev_b32_e32 v108, 16, v100
	v_and_b32_e32 v109, 0xffff0000, v100
	v_pk_mul_f32 v[108:109], v[168:169], v[108:109]
	v_exp_f32_e32 v168, v1
	v_mul_f32_e32 v1, 0xbfb8aa3b, v167
	v_exp_f32_e32 v169, v1
	v_cvt_pk_bf16_f32 v100, v108, v109
	v_lshlrev_b32_e32 v108, 16, v101
	v_and_b32_e32 v109, 0xffff0000, v101
	v_pk_mul_f32 v[108:109], v[168:169], v[108:109]
	v_mul_f32_e32 v1, 0x3fb8aa3b, v160
	v_cvt_pk_bf16_f32 v101, v108, v109
	v_exp_f32_e32 v108, v1
	v_mul_f32_e32 v1, 0x3fb8aa3b, v161
	v_exp_f32_e32 v109, v1
	ds_write_b128 v135, v[98:101] offset:56320
	v_lshlrev_b32_e32 v98, 16, v94
	v_and_b32_e32 v99, 0xffff0000, v94
	v_pk_mul_f32 v[100:101], v[108:109], s[40:41] op_sel_hi:[1,0]
	v_mul_f32_e32 v1, 0x3fb8aa3b, v162
	v_pk_mul_f32 v[98:99], v[100:101], v[98:99]
	v_exp_f32_e32 v100, v1
	v_mul_f32_e32 v1, 0x3fb8aa3b, v163
	v_exp_f32_e32 v101, v1
	v_cvt_pk_bf16_f32 v94, v98, v99
	v_lshlrev_b32_e32 v98, 16, v95
	v_and_b32_e32 v99, 0xffff0000, v95
	v_pk_mul_f32 v[100:101], v[100:101], s[40:41] op_sel_hi:[1,0]
	v_mul_f32_e32 v1, 0x3fb8aa3b, v164
	v_pk_mul_f32 v[98:99], v[100:101], v[98:99]
	v_exp_f32_e32 v100, v1
	v_mul_f32_e32 v1, 0x3fb8aa3b, v165
	v_exp_f32_e32 v101, v1
	v_cvt_pk_bf16_f32 v95, v98, v99
	v_lshlrev_b32_e32 v98, 16, v96
	v_and_b32_e32 v99, 0xffff0000, v96
	v_pk_mul_f32 v[100:101], v[100:101], s[40:41] op_sel_hi:[1,0]
	v_mul_f32_e32 v1, 0x3fb8aa3b, v166
	v_pk_mul_f32 v[98:99], v[100:101], v[98:99]
	v_exp_f32_e32 v100, v1
	v_mul_f32_e32 v1, 0x3fb8aa3b, v167
	v_exp_f32_e32 v101, v1
	v_cvt_pk_bf16_f32 v96, v98, v99
	v_lshlrev_b32_e32 v98, 16, v97
	v_and_b32_e32 v99, 0xffff0000, v97
	v_pk_mul_f32 v[100:101], v[100:101], s[40:41] op_sel_hi:[1,0]
	s_waitcnt vmcnt(4)
	v_lshlrev_b32_e32 v160, 16, v90
	v_pk_mul_f32 v[98:99], v[100:101], v[98:99]
	v_and_b32_e32 v161, 0xffff0000, v90
	v_cvt_pk_bf16_f32 v97, v98, v99
	ds_write_b128 v135, v[94:97] offset:38912
	ds_read_b128 v[94:97], v151 offset:6144
	ds_read_b128 v[98:101], v151 offset:6160
	v_cvt_pk_bf16_f32 v181, v36, v37
	v_cvt_pk_bf16_f32 v182, v30, v31
	v_cvt_pk_bf16_f32 v183, v32, v33
	s_waitcnt lgkmcnt(1)
	v_mul_f32_e32 v1, 0xbfb8aa3b, v94
	v_exp_f32_e32 v108, v1
	v_mul_f32_e32 v1, 0xbfb8aa3b, v95
	v_exp_f32_e32 v109, v1
	v_mul_f32_e32 v1, 0xbfb8aa3b, v96
	v_add_u32_e32 v107, 0xa800, v147
	s_add_u32 s46, s46, 0x60000
	v_pk_mul_f32 v[108:109], v[108:109], v[160:161]
	v_exp_f32_e32 v160, v1
	v_mul_f32_e32 v1, 0xbfb8aa3b, v97
	v_exp_f32_e32 v161, v1
	v_cvt_pk_bf16_f32 v90, v108, v109
	v_lshlrev_b32_e32 v108, 16, v91
	v_and_b32_e32 v109, 0xffff0000, v91
	s_waitcnt lgkmcnt(0)
	v_mul_f32_e32 v1, 0xbfb8aa3b, v98
	v_pk_mul_f32 v[108:109], v[160:161], v[108:109]
	v_exp_f32_e32 v160, v1
	v_mul_f32_e32 v1, 0xbfb8aa3b, v99
	v_exp_f32_e32 v161, v1
	v_cvt_pk_bf16_f32 v91, v108, v109
	v_lshlrev_b32_e32 v108, 16, v92
	v_and_b32_e32 v109, 0xffff0000, v92
	v_mul_f32_e32 v1, 0xbfb8aa3b, v100
	v_pk_mul_f32 v[108:109], v[160:161], v[108:109]
	v_exp_f32_e32 v160, v1
	v_mul_f32_e32 v1, 0xbfb8aa3b, v101
	v_exp_f32_e32 v161, v1
	v_mul_f32_e32 v1, 0x3fb8aa3b, v94
	v_exp_f32_e32 v94, v1
	v_mul_f32_e32 v1, 0x3fb8aa3b, v95
	v_exp_f32_e32 v95, v1
	v_cvt_pk_bf16_f32 v92, v108, v109
	v_lshlrev_b32_e32 v108, 16, v93
	v_and_b32_e32 v109, 0xffff0000, v93
	v_pk_mul_f32 v[108:109], v[160:161], v[108:109]
	v_mul_f32_e32 v1, 0x3fb8aa3b, v96
	v_cvt_pk_bf16_f32 v93, v108, v109
	ds_write_b128 v136, v[90:93] offset:56320
	v_lshlrev_b32_e32 v90, 16, v86
	v_and_b32_e32 v91, 0xffff0000, v86
	v_pk_mul_f32 v[92:93], v[94:95], s[40:41] op_sel_hi:[1,0]
	v_add_u32_e32 v108, 0xb800, v147
	v_pk_mul_f32 v[90:91], v[92:93], v[90:91]
	v_exp_f32_e32 v92, v1
	v_mul_f32_e32 v1, 0x3fb8aa3b, v97
	v_exp_f32_e32 v93, v1
	v_cvt_pk_bf16_f32 v86, v90, v91
	v_lshlrev_b32_e32 v90, 16, v87
	v_and_b32_e32 v91, 0xffff0000, v87
	v_pk_mul_f32 v[92:93], v[92:93], s[40:41] op_sel_hi:[1,0]
	v_mul_f32_e32 v1, 0x3fb8aa3b, v98
	v_pk_mul_f32 v[90:91], v[92:93], v[90:91]
	v_exp_f32_e32 v92, v1
	v_mul_f32_e32 v1, 0x3fb8aa3b, v99
	v_exp_f32_e32 v93, v1
	v_cvt_pk_bf16_f32 v87, v90, v91
	v_lshlrev_b32_e32 v90, 16, v88
	v_and_b32_e32 v91, 0xffff0000, v88
	v_pk_mul_f32 v[92:93], v[92:93], s[40:41] op_sel_hi:[1,0]
	v_mul_f32_e32 v1, 0x3fb8aa3b, v100
	v_pk_mul_f32 v[90:91], v[92:93], v[90:91]
	v_exp_f32_e32 v92, v1
	v_mul_f32_e32 v1, 0x3fb8aa3b, v101
	v_exp_f32_e32 v93, v1
	v_cvt_pk_bf16_f32 v88, v90, v91
	v_lshlrev_b32_e32 v90, 16, v89
	v_and_b32_e32 v91, 0xffff0000, v89
	v_pk_mul_f32 v[92:93], v[92:93], s[40:41] op_sel_hi:[1,0]
	v_add_u32_e32 v109, 0xc800, v147
	v_pk_mul_f32 v[90:91], v[92:93], v[90:91]
	s_addc_u32 s47, s47, 0
	v_cvt_pk_bf16_f32 v89, v90, v91
	ds_write_b128 v136, v[86:89] offset:38912
	s_waitcnt vmcnt(3)
	ds_write_b128 v153, v[70:73]
	s_waitcnt vmcnt(2)
	ds_write_b128 v155, v[74:77]
	s_waitcnt vmcnt(1)
	ds_write_b128 v153, v[78:81] offset:16896
	s_waitcnt vmcnt(0)
	ds_write_b128 v156, v[82:85]
	s_waitcnt lgkmcnt(0)
	s_barrier
	s_waitcnt lgkmcnt(0)
	ds_read_b128 v[70:73], v142 offset:56320
	ds_read_b128 v[232:235], v142 offset:56384
	ds_read_b128 v[236:239], v134 offset:38912
	ds_read_b128 v[82:85], v134 offset:38976
	ds_read_b128 v[86:89], v142 offset:56448
	ds_read_b128 v[244:247], v142 offset:56512
	ds_read_b128 v[90:93], v134 offset:39040
	ds_read_b128 v[94:97], v134 offset:39104
	s_waitcnt lgkmcnt(5)
	v_mfma_f32_16x16x32_bf16 v[70:73], v[70:73], v[236:239], 0
	s_add_i32 s30, s30, 64
	s_waitcnt lgkmcnt(4)
	v_mfma_f32_16x16x32_bf16 v[70:73], v[232:235], v[82:85], v[70:73]
	s_nop 0
	s_nop 0
	s_nop 0
	s_waitcnt lgkmcnt(1)
	v_mfma_f32_16x16x32_bf16 v[70:73], v[86:89], v[90:93], v[70:73]
	s_waitcnt lgkmcnt(0)
	v_mfma_f32_16x16x32_bf16 v[70:73], v[244:247], v[94:97], v[70:73]
	v_mov_b32_e32 v74, s59
	s_nop 6
	v_cndmask_b32_e64 v1, v70, v74, s[14:15]
	v_cndmask_b32_e64 v1, v1, v70, s[16:17]
	v_cndmask_b32_e64 v70, 0, v71, s[16:17]
	v_cndmask_b32_e64 v71, v72, 0, s[18:19]
	v_cndmask_b32_e64 v72, v73, 0, s[20:21]
	v_cvt_pk_bf16_f32 v70, v1, v70
	v_cvt_pk_bf16_f32 v71, v71, v72
	ds_write_b64 v143, v[70:71]
	ds_read_b128 v[248:251], v144 offset:56320
	ds_read_b128 v[252:255], v144 offset:56384
	ds_read_b128 v[78:81], v144 offset:56448
	ds_read_b128 v[74:77], v144 offset:56512
	s_waitcnt lgkmcnt(3)
	v_mfma_f32_16x16x32_bf16 v[70:73], v[248:251], v[236:239], 0
	s_nop 0
	s_waitcnt lgkmcnt(2)
	v_mfma_f32_16x16x32_bf16 v[70:73], v[252:255], v[82:85], v[70:73]
	s_nop 0
	s_waitcnt lgkmcnt(1)
	v_mfma_f32_16x16x32_bf16 v[70:73], v[78:81], v[90:93], v[70:73]
	s_waitcnt lgkmcnt(0)
	v_mfma_f32_16x16x32_bf16 v[70:73], v[74:77], v[94:97], v[70:73]
	v_mov_b32_e32 v74, s59
	s_nop 6
	v_cndmask_b32_e64 v1, v70, v74, s[22:23]
	v_cndmask_b32_e64 v1, v1, v70, s[24:25]
	v_cndmask_b32_e64 v70, 0, v71, s[24:25]
	v_cndmask_b32_e64 v71, v72, 0, s[26:27]
	v_cndmask_b32_e64 v72, v73, 0, s[28:29]
	v_cvt_pk_bf16_f32 v70, v1, v70
	v_cvt_pk_bf16_f32 v71, v71, v72
	ds_write_b64 v145, v[70:71]
	s_waitcnt lgkmcnt(0)
	s_barrier
	s_waitcnt lgkmcnt(0)
	ds_read_b64_tr_b16 v[76:77], v157 offset:2112
	ds_read_b64_tr_b16 v[74:75], v157
	ds_read_b64_tr_b16 v[80:81], v157 offset:2144
	ds_read_b64_tr_b16 v[78:79], v157 offset:32
	ds_read_b128 v[232:235], v146
	ds_read_b128 v[236:239], v146 offset:64
	ds_read_b64_tr_b16 v[82:83], v157 offset:16896
	ds_read_b64_tr_b16 v[84:85], v157 offset:19008
	ds_read_b64_tr_b16 v[72:73], v157 offset:19040
	ds_read_b64_tr_b16 v[70:71], v157 offset:16928
	ds_read_b128 v[244:247], v146 offset:2304
	ds_read_b128 v[248:251], v146 offset:2368
	ds_read_b128 v[252:255], v146 offset:4608
	s_waitcnt lgkmcnt(8)
	v_mfma_f32_16x16x32_bf16 v[90:93], v[74:77], v[232:235], 0
	s_nop 0
	s_nop 0
	v_add_u32_e32 v1, 0x9800, v147
	v_mfma_f32_16x16x32_bf16 v[94:97], v[78:81], v[232:235], 0
	ds_read_b128 v[232:235], v146 offset:4672
	s_nop 0
	s_nop 0
	s_waitcnt lgkmcnt(6)
	v_mfma_f32_16x16x32_bf16 v[90:93], v[82:85], v[236:239], v[90:93]
	s_waitcnt lgkmcnt(4)
	v_mfma_f32_16x16x32_bf16 v[86:89], v[70:73], v[236:239], v[94:97]
	ds_read_b128 v[236:239], v146 offset:6912
	s_nop 2
	s_nop 0
	s_nop 0
	s_waitcnt lgkmcnt(4)
	v_mfma_f32_16x16x32_bf16 v[160:163], v[74:77], v[244:247], 0
	v_mfma_f32_16x16x32_bf16 v[94:97], v[78:81], v[244:247], 0
	ds_read_b128 v[244:247], v146 offset:6976
	s_waitcnt lgkmcnt(4)
	v_mfma_f32_16x16x32_bf16 v[160:163], v[82:85], v[248:251], v[160:163]
	v_mfma_f32_16x16x32_bf16 v[94:97], v[70:73], v[248:251], v[94:97]
	ds_read2_b64 v[248:251], v1 offset1:4
	s_nop 0
	s_nop 0
	s_waitcnt lgkmcnt(4)
	v_mfma_f32_16x16x32_bf16 v[168:171], v[74:77], v[252:255], 0
	v_mfma_f32_16x16x32_bf16 v[98:101], v[78:81], v[252:255], 0
	ds_read2_b64 v[252:255], v1 offset0:8 offset1:12
	s_waitcnt lgkmcnt(4)
	v_mfma_f32_16x16x32_bf16 v[168:171], v[82:85], v[232:235], v[168:171]
	v_mfma_f32_16x16x32_bf16 v[98:101], v[70:73], v[232:235], v[98:101]
	ds_read2_b64 v[232:235], v107 offset0:32 offset1:36
	s_nop 0
	s_nop 0
	s_nop 0
	s_nop 0
	s_waitcnt lgkmcnt(4)
	v_mfma_f32_16x16x32_bf16 v[176:179], v[74:77], v[236:239], 0
	v_mfma_f32_16x16x32_bf16 v[164:167], v[78:81], v[236:239], 0
	ds_read2_b64 v[236:239], v108 offset0:64 offset1:68
	s_waitcnt lgkmcnt(4)
	v_mfma_f32_16x16x32_bf16 v[176:179], v[82:85], v[244:247], v[176:179]
	v_mfma_f32_16x16x32_bf16 v[164:167], v[70:73], v[244:247], v[164:167]
	ds_read2_b64 v[244:247], v109 offset0:96 offset1:100
	v_cvt_pk_bf16_f32 v172, v14, v15
	v_cvt_pk_bf16_f32 v173, v16, v17
	v_cvt_pk_bf16_f32 v174, v58, v59
	v_cvt_pk_bf16_f32 v175, v60, v61
	s_waitcnt lgkmcnt(4)
	v_mfma_f32_16x16x32_bf16 v[90:93], v[180:183], v[248:251], v[90:93]
	v_mfma_f32_16x16x32_bf16 v[86:89], v[172:175], v[248:251], v[86:89]
	ds_read2_b64 v[248:251], v107 offset0:40 offset1:44
	s_nop 0
	s_waitcnt lgkmcnt(3)
	v_mfma_f32_16x16x32_bf16 v[160:163], v[180:183], v[232:235], v[160:163]
	v_mfma_f32_16x16x32_bf16 v[94:97], v[172:175], v[232:235], v[94:97]
	ds_read2_b64 v[232:235], v108 offset0:72 offset1:76
	s_nop 0
	s_waitcnt lgkmcnt(3)
	v_mfma_f32_16x16x32_bf16 v[168:171], v[180:183], v[236:239], v[168:171]
	v_mfma_f32_16x16x32_bf16 v[98:101], v[172:175], v[236:239], v[98:101]
	ds_read2_b64 v[236:239], v109 offset0:104 offset1:108
	s_nop 0
	s_waitcnt lgkmcnt(3)
	v_mfma_f32_16x16x32_bf16 v[176:179], v[180:183], v[244:247], v[176:179]
	v_cvt_pk_bf16_f32 v180, v54, v55
	v_cvt_pk_bf16_f32 v181, v56, v57
	v_cvt_pk_bf16_f32 v182, v62, v63
	v_cvt_pk_bf16_f32 v183, v64, v65
	v_mfma_f32_16x16x32_bf16 v[164:167], v[172:175], v[244:247], v[164:167]
	ds_read2_b64 v[244:247], v1 offset0:16 offset1:20
	v_cvt_pk_bf16_f32 v172, v46, v47
	v_cvt_pk_bf16_f32 v173, v48, v49
	v_cvt_pk_bf16_f32 v174, v66, v67
	v_cvt_pk_bf16_f32 v175, v68, v69
	s_nop 0
	s_waitcnt lgkmcnt(3)
	v_mfma_f32_16x16x32_bf16 v[160:163], v[180:183], v[248:251], v[160:163]
	v_mfma_f32_16x16x32_bf16 v[94:97], v[172:175], v[248:251], v[94:97]
	ds_read2_b64 v[248:251], v107 offset0:48 offset1:52
	s_nop 0
	s_waitcnt lgkmcnt(3)
	v_mfma_f32_16x16x32_bf16 v[168:171], v[180:183], v[232:235], v[168:171]
	v_mfma_f32_16x16x32_bf16 v[98:101], v[172:175], v[232:235], v[98:101]
	ds_read2_b64 v[232:235], v108 offset0:80 offset1:84
	s_nop 0
	v_mfma_f32_16x16x32_bf16 v[90:93], v[180:183], v[252:255], v[90:93]
	v_mfma_f32_16x16x32_bf16 v[86:89], v[172:175], v[252:255], v[86:89]
	ds_read2_b64 v[252:255], v109 offset0:112 offset1:116
	s_nop 0
	s_waitcnt lgkmcnt(4)
	v_mfma_f32_16x16x32_bf16 v[176:179], v[180:183], v[236:239], v[176:179]
	v_cvt_pk_bf16_f32 v180, v22, v23
	v_cvt_pk_bf16_f32 v181, v24, v25
	v_cvt_pk_bf16_f32 v182, v18, v19
	v_cvt_pk_bf16_f32 v183, v20, v21
	v_mfma_f32_16x16x32_bf16 v[164:167], v[172:175], v[236:239], v[164:167]
	ds_read2_b64 v[236:239], v1 offset0:24 offset1:28
	v_cvt_pk_bf16_f32 v172, v10, v11
	v_cvt_pk_bf16_f32 v173, v12, v13
	v_cvt_pk_bf16_f32 v174, v50, v51
	v_cvt_pk_bf16_f32 v175, v52, v53
	s_nop 0
	s_waitcnt lgkmcnt(3)
	v_mfma_f32_16x16x32_bf16 v[160:163], v[180:183], v[248:251], v[160:163]
	v_mfma_f32_16x16x32_bf16 v[94:97], v[172:175], v[248:251], v[94:97]
	ds_read2_b64 v[248:251], v107 offset0:56 offset1:60
	s_nop 0
	s_waitcnt lgkmcnt(3)
	v_mfma_f32_16x16x32_bf16 v[168:171], v[180:183], v[232:235], v[168:171]
	v_mfma_f32_16x16x32_bf16 v[98:101], v[172:175], v[232:235], v[98:101]
	ds_read2_b64 v[232:235], v108 offset0:88 offset1:92
	s_nop 0
	v_mfma_f32_16x16x32_bf16 v[90:93], v[180:183], v[244:247], v[90:93]
	v_mfma_f32_16x16x32_bf16 v[86:89], v[172:175], v[244:247], v[86:89]
	ds_read2_b64 v[244:247], v109 offset0:120 offset1:124
	s_nop 0
	v_lshl_add_u32 v1, s79, 9, v128
	s_waitcnt lgkmcnt(4)
	v_mfma_f32_16x16x32_bf16 v[176:179], v[180:183], v[252:255], v[176:179]
	v_cvt_pk_bf16_f32 v180, v38, v39
	v_cvt_pk_bf16_f32 v181, v40, v41
	v_cvt_pk_bf16_f32 v182, v26, v27
	v_cvt_pk_bf16_f32 v183, v28, v29
	v_mfma_f32_16x16x32_bf16 v[164:167], v[172:175], v[252:255], v[164:167]
	ds_read_b64_tr_b16 v[254:255], v158 offset:57408
	ds_read_b64_tr_b16 v[252:253], v158 offset:56320
	v_cvt_pk_bf16_f32 v172, v42, v43
	v_cvt_pk_bf16_f32 v173, v44, v45
	v_cvt_pk_bf16_f32 v174, v6, v7
	v_cvt_pk_bf16_f32 v175, v8, v9
	s_nop 0
	s_waitcnt lgkmcnt(4)
	v_mfma_f32_16x16x32_bf16 v[160:163], v[180:183], v[248:251], v[160:163]
	v_mfma_f32_16x16x32_bf16 v[94:97], v[172:175], v[248:251], v[94:97]
	ds_read_b64_tr_b16 v[248:249], v158 offset:56352
	ds_read_b64_tr_b16 v[184:185], v158 offset:56384
	ds_read_b64_tr_b16 v[188:189], v158 offset:56416
	ds_read_b64_tr_b16 v[250:251], v158 offset:57440
	ds_read_b64_tr_b16 v[186:187], v158 offset:57472
	ds_read_b64_tr_b16 v[190:191], v158 offset:57504
	ds_read_b64_tr_b16 v[192:193], v158 offset:65024
	ds_read_b64_tr_b16 v[194:195], v159 offset:57408
	s_nop 0
	s_waitcnt lgkmcnt(11)
	v_mfma_f32_16x16x32_bf16 v[168:171], v[180:183], v[232:235], v[168:171]
	v_mfma_f32_16x16x32_bf16 v[98:101], v[172:175], v[232:235], v[98:101]
	ds_read_b64_tr_b16 v[232:233], v158 offset:65056
	ds_read_b64_tr_b16 v[196:197], v158 offset:65088
	ds_read_b64_tr_b16 v[200:201], v158 offset:65120
	ds_read_b64_tr_b16 v[234:235], v159 offset:57440
	ds_read_b64_tr_b16 v[198:199], v159 offset:57472
	ds_read_b64_tr_b16 v[202:203], v159 offset:57504
	s_nop 0
	v_mfma_f32_16x16x32_bf16 v[90:93], v[180:183], v[236:239], v[90:93]
	s_waitcnt lgkmcnt(15)
	v_mfma_f32_16x16x32_bf16 v[176:179], v[180:183], v[244:247], v[176:179]
	s_nop 0
	s_nop 0
	s_nop 3
	v_cvt_pk_bf16_f32 v90, v90, v91
	v_cvt_pk_bf16_f32 v91, v92, v93
	v_mfma_f32_16x16x32_bf16 v[86:89], v[172:175], v[236:239], v[86:89]
	ds_read_b64_tr_b16 v[236:237], v158 offset:56448
	ds_read_b64_tr_b16 v[238:239], v158 offset:57536
	ds_read_b64_tr_b16 v[180:181], v158 offset:56480
	v_lshl_add_u64 v[92:93], s[44:45], 0, v[116:117]
	s_add_u32 s44, s44, 0x20000
	s_addc_u32 s45, s45, 0
	v_mfma_f32_16x16x32_bf16 v[164:167], v[172:175], v[244:247], v[164:167]
	s_nop 0
	s_nop 0
	s_nop 0
	s_nop 0
	s_nop 0
	s_nop 0
	s_nop 0
	s_nop 0
	v_cvt_pk_bf16_f32 v86, v86, v87
	s_waitcnt lgkmcnt(13)
	v_mfma_f32_16x16x32_bf16 v[30:33], v[248:251], v[74:77], v[30:33]
	v_cvt_pk_bf16_f32 v87, v88, v89
	v_add_co_u32_e32 v88, vcc, s62, v92
	v_mfma_f32_16x16x32_bf16 v[58:61], v[248:251], v[78:81], v[58:61]
	s_nop 0
	v_addc_co_u32_e32 v89, vcc, 0, v93, vcc
	s_add_i32 s78, s78, 1
	v_mfma_f32_16x16x32_bf16 v[34:37], v[252:255], v[74:77], v[34:37]
	s_cmp_lg_u32 s46, 0x180000
	v_mfma_f32_16x16x32_bf16 v[14:17], v[252:255], v[78:81], v[14:17]
	s_nop 0
	s_nop 0
	s_nop 0
	s_nop 0
	s_nop 0
	s_nop 0
	s_nop 0
	s_nop 0
	s_waitcnt lgkmcnt(5)
	v_mfma_f32_16x16x32_bf16 v[30:33], v[232:235], v[82:85], v[30:33]
	v_mfma_f32_16x16x32_bf16 v[58:61], v[232:235], v[70:73], v[58:61]
	v_mfma_f32_16x16x32_bf16 v[54:57], v[184:187], v[74:77], v[54:57]
	v_mfma_f32_16x16x32_bf16 v[46:49], v[184:187], v[78:81], v[46:49]
	ds_read_b64_tr_b16 v[184:185], v158 offset:56512
	v_mfma_f32_16x16x32_bf16 v[62:65], v[188:191], v[74:77], v[62:65]
	v_mfma_f32_16x16x32_bf16 v[66:69], v[188:191], v[78:81], v[66:69]
	ds_read_b64_tr_b16 v[188:189], v158 offset:56544
	ds_read_b64_tr_b16 v[182:183], v158 offset:57568
	ds_read_b64_tr_b16 v[186:187], v158 offset:57600
	ds_read_b64_tr_b16 v[190:191], v158 offset:57632
	s_nop 0
	s_nop 0
	s_nop 0
	s_nop 0
	s_nop 0
	s_nop 0
	v_mfma_f32_16x16x32_bf16 v[34:37], v[192:195], v[82:85], v[34:37]
	v_mfma_f32_16x16x32_bf16 v[14:17], v[192:195], v[70:73], v[14:17]
	ds_read_b64_tr_b16 v[192:193], v158 offset:65152
	ds_read_b64_tr_b16 v[194:195], v159 offset:57536
	ds_read_b64_tr_b16 v[172:173], v158 offset:65184
	s_waitcnt lgkmcnt(12)
	v_mfma_f32_16x16x32_bf16 v[54:57], v[196:199], v[82:85], v[54:57]
	v_mfma_f32_16x16x32_bf16 v[46:49], v[196:199], v[70:73], v[46:49]
	ds_read_b64_tr_b16 v[196:197], v158 offset:65216
	s_waitcnt lgkmcnt(12)
	v_mfma_f32_16x16x32_bf16 v[62:65], v[200:203], v[82:85], v[62:65]
	v_mfma_f32_16x16x32_bf16 v[66:69], v[200:203], v[70:73], v[66:69]
	ds_read_b64_tr_b16 v[200:201], v158 offset:65248
	ds_read_b64_tr_b16 v[174:175], v159 offset:57568
	ds_read_b64_tr_b16 v[198:199], v159 offset:57600
	ds_read_b64_tr_b16 v[202:203], v159 offset:57632
	ds_read_b128 v[244:247], v1 offset:4096
	ds_read_b128 v[248:251], v1 offset:4160
	ds_read_b128 v[252:255], v1 offset:4224
	ds_read_b128 v[232:235], v1 offset:4288
	s_waitcnt lgkmcnt(15)
	v_mfma_f32_16x16x32_bf16 v[22:25], v[236:239], v[74:77], v[22:25]
	v_mfma_f32_16x16x32_bf16 v[10:13], v[236:239], v[78:81], v[10:13]
	ds_read_b128 v[236:239], v1 offset:4352
	s_nop 0
	s_nop 0
	s_nop 0
	s_nop 0
	s_nop 0
	s_nop 0
	global_store_dwordx2 v[92:93], v[86:87], off offset:32
	v_cvt_pk_bf16_f32 v86, v160, v161
	s_waitcnt lgkmcnt(15)
	v_mfma_f32_16x16x32_bf16 v[18:21], v[180:183], v[74:77], v[18:21]
	v_cvt_pk_bf16_f32 v87, v162, v163
	global_store_dwordx2 v[88:89], v[86:87], off
	v_cvt_pk_bf16_f32 v86, v94, v95
	v_mfma_f32_16x16x32_bf16 v[50:53], v[180:183], v[78:81], v[50:53]
	v_cvt_pk_bf16_f32 v87, v96, v97
	global_store_dwordx2 v[88:89], v[86:87], off offset:32
	v_add_co_u32_e32 v88, vcc, s72, v92
	s_waitcnt lgkmcnt(14)
	v_mfma_f32_16x16x32_bf16 v[38:41], v[184:187], v[74:77], v[38:41]
	v_cvt_pk_bf16_f32 v86, v168, v169
	v_cvt_pk_bf16_f32 v87, v170, v171
	v_addc_co_u32_e32 v89, vcc, 0, v93, vcc
	v_mfma_f32_16x16x32_bf16 v[42:45], v[184:187], v[78:81], v[42:45]
	global_store_dwordx2 v[88:89], v[86:87], off
	v_cvt_pk_bf16_f32 v86, v98, v99
	v_cvt_pk_bf16_f32 v87, v100, v101
	s_waitcnt lgkmcnt(13)
	v_mfma_f32_16x16x32_bf16 v[26:29], v[188:191], v[74:77], v[26:29]
	s_nop 0
	global_store_dwordx2 v[88:89], v[86:87], off offset:32
	v_add_co_u32_e32 v88, vcc, s64, v92
	v_mfma_f32_16x16x32_bf16 v[6:9], v[188:191], v[78:81], v[6:9]
	s_nop 0
	s_waitcnt lgkmcnt(4)
	v_mul_f32_e32 v74, 0x3fb8aa3b, v244
	v_mul_f32_e32 v75, 0x3fb8aa3b, v245
	v_mfma_f32_16x16x32_bf16 v[10:13], v[192:195], v[70:73], v[10:13]
	v_mul_f32_e32 v76, 0x3fb8aa3b, v246
	v_mul_f32_e32 v77, 0x3fb8aa3b, v247
	ds_read_b128 v[244:247], v1 offset:4416
	v_exp_f32_e32 v74, v74
	v_mfma_f32_16x16x32_bf16 v[50:53], v[172:175], v[70:73], v[50:53]
	v_exp_f32_e32 v76, v76
	v_exp_f32_e32 v77, v77
	v_exp_f32_e32 v75, v75
	v_mfma_f32_16x16x32_bf16 v[42:45], v[196:199], v[70:73], v[42:45]
	v_cvt_pk_bf16_f32 v86, v176, v177
	v_pk_mul_f32 v[36:37], v[36:37], v[76:77]
	v_pk_mul_f32 v[34:35], v[34:35], v[74:75]
	v_mfma_f32_16x16x32_bf16 v[6:9], v[200:203], v[70:73], v[6:9]
	s_waitcnt lgkmcnt(4)
	v_mul_f32_e32 v70, 0x3fb8aa3b, v248
	v_mul_f32_e32 v71, 0x3fb8aa3b, v250
	v_exp_f32_e32 v78, v70
	v_mul_f32_e32 v70, 0x3fb8aa3b, v249
	v_exp_f32_e32 v80, v71
	v_mul_f32_e32 v71, 0x3fb8aa3b, v251
	ds_read_b128 v[248:251], v1 offset:4480
	v_exp_f32_e32 v81, v71
	v_exp_f32_e32 v79, v70
	s_nop 0
	v_pk_mul_f32 v[16:17], v[16:17], v[76:77]
	v_pk_mul_f32 v[14:15], v[14:15], v[74:75]
	s_nop 0
	v_mfma_f32_16x16x32_bf16 v[22:25], v[192:195], v[82:85], v[22:25]
	s_waitcnt lgkmcnt(4)
	v_mul_f32_e32 v70, 0x3fb8aa3b, v252
	v_pk_mul_f32 v[32:33], v[32:33], v[80:81]
	v_pk_mul_f32 v[30:31], v[30:31], v[78:79]
	v_mfma_f32_16x16x32_bf16 v[18:21], v[172:175], v[82:85], v[18:21]
	v_mul_f32_e64 v60, v60, v80
	v_mul_f32_e64 v61, v61, v81
	v_pk_mul_f32 v[58:59], v[58:59], v[78:79]
	v_cvt_pk_bf16_f32 v87, v178, v179
	v_mfma_f32_16x16x32_bf16 v[38:41], v[196:199], v[82:85], v[38:41]
	v_addc_co_u32_e32 v89, vcc, 0, v93, vcc
	global_store_dwordx2 v[88:89], v[86:87], off
	v_mfma_f32_16x16x32_bf16 v[26:29], v[200:203], v[82:85], v[26:29]
	v_exp_f32_e32 v82, v70
	v_mul_f32_e32 v83, 0x3fb8aa3b, v253
	v_mul_f32_e32 v70, 0x3fb8aa3b, v254
	v_mul_f32_e32 v71, 0x3fb8aa3b, v255
	ds_read_b128 v[252:255], v1 offset:4544
	v_exp_f32_e32 v70, v70
	v_exp_f32_e32 v71, v71
	v_exp_f32_e32 v83, v83
	v_cvt_pk_bf16_f32 v86, v164, v165
	v_cvt_pk_bf16_f32 v87, v166, v167
	v_pk_mul_f32 v[56:57], v[56:57], v[70:71]
	v_pk_mul_f32 v[48:49], v[48:49], v[70:71]
	s_waitcnt lgkmcnt(4)
	v_mul_f32_e32 v70, 0x3fb8aa3b, v232
	v_mul_f32_e32 v71, 0x3fb8aa3b, v234
	v_exp_f32_e32 v78, v70
	v_mul_f32_e32 v70, 0x3fb8aa3b, v233
	v_exp_f32_e32 v80, v71
	v_mul_f32_e32 v71, 0x3fb8aa3b, v235
	v_exp_f32_e32 v81, v71
	v_exp_f32_e32 v79, v70
	s_nop 0
	s_nop 0
	v_pk_mul_f32 v[54:55], v[54:55], v[82:83]
	v_pk_mul_f32 v[46:47], v[46:47], v[82:83]
	v_pk_mul_f32 v[64:65], v[64:65], v[80:81]
	s_waitcnt lgkmcnt(3)
	v_mul_f32_e32 v70, 0x3fb8aa3b, v236
	v_exp_f32_e32 v82, v70
	v_mul_f32_e32 v83, 0x3fb8aa3b, v237
	v_mul_f32_e32 v70, 0x3fb8aa3b, v238
	v_mul_f32_e32 v71, 0x3fb8aa3b, v239
	v_exp_f32_e32 v70, v70
	v_exp_f32_e32 v71, v71
	v_pk_mul_f32 v[62:63], v[62:63], v[78:79]
	v_pk_mul_f32 v[68:69], v[68:69], v[80:81]
	v_pk_mul_f32 v[66:67], v[66:67], v[78:79]
	v_pk_mul_f32 v[24:25], v[24:25], v[70:71]
	v_pk_mul_f32 v[12:13], v[12:13], v[70:71]
	s_waitcnt lgkmcnt(2)
	v_mul_f32_e32 v70, 0x3fb8aa3b, v244
	v_mul_f32_e32 v71, 0x3fb8aa3b, v246
	v_exp_f32_e32 v78, v70
	v_mul_f32_e32 v70, 0x3fb8aa3b, v245
	v_exp_f32_e32 v80, v71
	v_mul_f32_e32 v71, 0x3fb8aa3b, v247
	v_exp_f32_e32 v81, v71
	v_exp_f32_e32 v79, v70
	s_nop 0
	s_nop 0
	v_exp_f32_e32 v83, v83
	v_pk_mul_f32 v[20:21], v[20:21], v[80:81]
	v_pk_mul_f32 v[18:19], v[18:19], v[78:79]
	s_waitcnt lgkmcnt(1)
	v_mul_f32_e32 v1, 0x3fb8aa3b, v248
	v_exp_f32_e32 v70, v1
	v_mul_f32_e32 v1, 0x3fb8aa3b, v249
	v_mul_f32_e32 v71, 0x3fb8aa3b, v250
	v_exp_f32_e32 v72, v71
	v_mul_f32_e32 v71, 0x3fb8aa3b, v251
	v_exp_f32_e32 v73, v71
	v_exp_f32_e32 v71, v1
	s_waitcnt lgkmcnt(0)
	v_mul_f32_e32 v1, 0x3fb8aa3b, v252
	v_exp_f32_e32 v74, v1
	v_mul_f32_e32 v1, 0x3fb8aa3b, v253
	v_mul_f32_e32 v75, 0x3fb8aa3b, v254
	v_exp_f32_e32 v76, v75
	v_mul_f32_e32 v75, 0x3fb8aa3b, v255
	v_exp_f32_e32 v77, v75
	v_exp_f32_e32 v75, v1
	v_pk_mul_f32 v[22:23], v[22:23], v[82:83]
	v_pk_mul_f32 v[10:11], v[10:11], v[82:83]
	v_pk_mul_f32 v[52:53], v[52:53], v[80:81]
	v_pk_mul_f32 v[50:51], v[50:51], v[78:79]
	v_pk_mul_f32 v[40:41], v[40:41], v[72:73]
	v_pk_mul_f32 v[38:39], v[38:39], v[70:71]
	v_pk_mul_f32 v[44:45], v[44:45], v[72:73]
	v_pk_mul_f32 v[42:43], v[42:43], v[70:71]
	v_pk_mul_f32 v[28:29], v[28:29], v[76:77]
	v_pk_mul_f32 v[26:27], v[26:27], v[74:75]
	v_pk_mul_f32 v[8:9], v[8:9], v[76:77]
	v_pk_mul_f32 v[6:7], v[6:7], v[74:75]
	global_store_dwordx2 v[92:93], v[90:91], off
	global_store_dwordx2 v[88:89], v[86:87], off offset:32
	s_waitcnt lgkmcnt(0)
	s_cbranch_scc0 .LBB0_451
.LBB0_502:
	s_add_u32 s50, s53, s46
	s_addc_u32 s51, s77, s47
	s_add_u32 s31, s43, s46
	s_addc_u32 s48, s52, s47
	s_add_u32 s80, s31, s76
	s_addc_u32 s81, s48, 0
	s_and_b32 s79, s78, 1
	s_cmp_eq_u32 s79, 0
	s_cselect_b64 s[48:49], -1, 0
	s_and_b64 s[82:83], s[48:49], exec
	s_cselect_b32 s31, 0xf0, s67
	v_add3_u32 v1, s31, v126, v133
	s_waitcnt lgkmcnt(0)
	ds_read2_b32 v[74:75], v1 offset1:4
	ds_read2_b32 v[232:233], v1 offset0:64 offset1:68
	ds_read2_b32 v[236:237], v1 offset0:8 offset1:12
	ds_read2_b32 v[244:245], v1 offset0:72 offset1:76
	ds_read2_b32 v[248:249], v1 offset0:128 offset1:132
	ds_read2_b32 v[252:253], v1 offset0:136 offset1:140
	v_lshl_add_u64 v[76:77], s[50:51], 0, v[112:113]
	s_nop 0
	global_load_dwordx4 v[94:97], v[76:77], off
	global_load_dwordx4 v[98:101], v[76:77], off offset:1024
	s_nop 0
	v_lshl_add_u64 v[84:85], s[80:81], 0, v[114:115]
	s_mov_b32 s31, 0x3d800000
	s_waitcnt vmcnt(6)
	s_waitcnt lgkmcnt(5)
	v_mfma_f32_16x16x4_f32 v[70:73], v74, v102, 0
	v_add_co_u32_e32 v74, vcc, s63, v76
	s_waitcnt vmcnt(5)
	v_mfma_f32_16x16x4_f32 v[70:73], v75, v103, v[70:73]
	v_addc_co_u32_e32 v75, vcc, 0, v77, vcc
	global_load_dwordx4 v[86:89], v[74:75], off
	global_load_dwordx4 v[90:93], v[74:75], off offset:1024
	v_add_co_u32_e32 v74, vcc, s64, v84
	s_nop 1
	v_addc_co_u32_e32 v75, vcc, 0, v85, vcc
	s_waitcnt vmcnt(6)
	s_waitcnt lgkmcnt(3)
	v_mfma_f32_16x16x4_f32 v[160:163], v236, v104, v[70:73]
	v_add_co_u32_e32 v168, vcc, s63, v84
	global_load_dwordx4 v[70:73], v[84:85], off
	s_nop 0
	global_load_dwordx4 v[74:77], v[74:75], off
	v_addc_co_u32_e32 v169, vcc, 0, v85, vcc
	v_mfma_f32_16x16x4_f32 v[78:81], v232, v102, 0
	v_add_co_u32_e32 v82, vcc, s65, v84
	s_waitcnt vmcnt(7)
	v_mfma_f32_16x16x4_f32 v[160:163], v237, v105, v[160:163]
	ds_read2_b32 v[236:237], v1 offset0:192 offset1:196
	v_mfma_f32_16x16x4_f32 v[164:167], v233, v103, v[78:81]
	ds_read2_b32 v[232:233], v1 offset0:200 offset1:204
	v_addc_co_u32_e32 v83, vcc, 0, v85, vcc
	s_nop 4
	global_load_dwordx4 v[78:81], v[168:169], off
	s_nop 0
	global_load_dwordx4 v[82:85], v[82:83], off
	s_nop 0
	s_waitcnt vmcnt(8)
	v_add_f32_e32 v107, v106, v160
	v_min_f32_e32 v170, 0, v107
	v_mul_f32_e64 v107, |v107|, s68
	v_exp_f32_e32 v107, v107
	v_add_f32_e32 v108, v106, v161
	v_add_f32_e32 v109, v106, v162
	v_mul_f32_e64 v160, |v108|, s68
	v_mul_f32_e64 v161, |v109|, s68
	v_exp_f32_e32 v160, v160
	v_exp_f32_e32 v161, v161
	v_add_f32_e32 v107, 1.0, v107
	v_log_f32_e32 v107, v107
	s_waitcnt lgkmcnt(4)
	v_mfma_f32_16x16x4_f32 v[164:167], v244, v104, v[164:167]
	v_add_f32_e32 v160, 1.0, v160
	v_add_f32_e32 v161, 1.0, v161
	v_log_f32_e32 v160, v160
	v_fmac_f32_e32 v170, 0xbf317218, v107
	v_log_f32_e32 v107, v161
	v_min_f32_e32 v171, 0, v108
	v_min_f32_e32 v172, 0, v109
	v_fmac_f32_e32 v171, 0xbf317218, v160
	v_fmac_f32_e32 v172, 0xbf317218, v107
	v_add_f32_e32 v107, v106, v163
	v_mfma_f32_16x16x4_f32 v[160:163], v245, v105, v[164:167]
	v_mul_f32_e64 v108, |v107|, s68
	v_exp_f32_e32 v168, v108
	v_min_f32_e32 v107, 0, v107
	v_add_f32_e32 v165, 1.0, v168
	v_log_f32_e32 v165, v165
	s_nop 4
	v_add_f32_e32 v160, v106, v160
	v_mul_f32_e64 v108, |v160|, s68
	v_exp_f32_e32 v164, v108
	s_nop 0
	v_min_f32_e32 v173, 0, v160
	v_fmac_f32_e32 v107, 0xbf317218, v165
	v_add_f32_e32 v164, 1.0, v164
	v_log_f32_e32 v164, v164
	s_nop 0
	v_add_f32_e32 v174, v106, v162
	v_add_f32_e32 v176, v106, v163
	v_fmac_f32_e32 v173, 0xbf317218, v164
	s_waitcnt lgkmcnt(3)
	v_mfma_f32_16x16x4_f32 v[164:167], v248, v102, 0
	v_add_f32_e32 v108, v106, v161
	v_mul_f32_e64 v160, |v108|, s68
	v_mul_f32_e64 v161, |v174|, s68
	v_exp_f32_e32 v160, v160
	v_exp_f32_e32 v161, v161
	v_min_f32_e32 v175, 0, v108
	v_mul_f32_e64 v177, |v176|, s68
	v_mfma_f32_16x16x4_f32 v[164:167], v249, v103, v[164:167]
	v_add_f32_e32 v108, 1.0, v160
	v_add_f32_e32 v109, 1.0, v161
	v_log_f32_e32 v108, v108
	v_log_f32_e32 v109, v109
	v_min_f32_e32 v174, 0, v174
	v_min_f32_e32 v176, 0, v176
	v_fmac_f32_e32 v175, 0xbf317218, v108
	s_waitcnt lgkmcnt(2)
	v_mfma_f32_16x16x4_f32 v[160:163], v252, v104, v[164:167]
	s_nop 0
	v_exp_f32_e32 v164, v177
	v_fmac_f32_e32 v174, 0xbf317218, v109
	v_add_f32_e32 v108, 1.0, v164
	v_log_f32_e32 v164, v108
	s_nop 0
	v_mfma_f32_16x16x4_f32 v[160:163], v253, v105, v[160:163]
	v_fmac_f32_e32 v176, 0xbf317218, v164
	s_nop 8
	v_add_f32_e32 v160, v106, v160
	v_mul_f32_e64 v164, |v160|, s68
	v_exp_f32_e32 v168, v164
	s_waitcnt lgkmcnt(1)
	v_mfma_f32_16x16x4_f32 v[164:167], v236, v102, 0
	v_add_f32_e32 v161, v106, v161
	v_mul_f32_e64 v169, |v161|, s68
	v_exp_f32_e32 v108, v169
	v_min_f32_e32 v177, 0, v160
	v_add_f32_e32 v160, 1.0, v168
	s_nop 0
	v_add_f32_e32 v108, 1.0, v108
	v_mfma_f32_16x16x4_f32 v[164:167], v237, v103, v[164:167]
	v_log_f32_e32 v160, v160
	v_log_f32_e32 v108, v108
	v_min_f32_e32 v1, 0, v161
	v_add_f32_e32 v178, v106, v163
	v_fmac_f32_e32 v177, 0xbf317218, v160
	v_fmac_f32_e32 v1, 0xbf317218, v108
	v_add_f32_e32 v108, v106, v162
	s_waitcnt lgkmcnt(0)
	v_mfma_f32_16x16x4_f32 v[160:163], v232, v104, v[164:167]
	v_mul_f32_e64 v109, |v108|, s68
	v_exp_f32_e32 v109, v109
	v_mul_f32_e64 v164, |v178|, s68
	v_exp_f32_e32 v164, v164
	v_min_f32_e32 v108, 0, v108
	v_add_f32_e32 v109, 1.0, v109
	v_log_f32_e32 v109, v109
	v_mfma_f32_16x16x4_f32 v[160:163], v233, v105, v[160:163]
	v_add_f32_e32 v164, 1.0, v164
	v_log_f32_e32 v164, v164
	v_fmac_f32_e32 v108, 0xbf317218, v109
	v_min_f32_e32 v109, 0, v178
	v_fmac_f32_e32 v109, 0xbf317218, v164
	s_nop 4
	v_add_f32_e32 v160, v106, v160
	v_mul_f32_e64 v165, |v160|, s68
	v_exp_f32_e32 v165, v165
	v_add_f32_e32 v161, v106, v161
	v_min_f32_e32 v160, 0, v160
	v_add_f32_e32 v162, v106, v162
	v_add_f32_e32 v164, 1.0, v165
	v_mul_f32_e64 v165, |v161|, s68
	v_log_f32_e32 v164, v164
	v_exp_f32_e32 v165, v165
	v_add_f32_e32 v163, v106, v163
	v_mul_f32_e64 v166, |v163|, s68
	v_fmac_f32_e32 v160, 0xbf317218, v164
	v_add_f32_e32 v164, 1.0, v165
	v_mul_f32_e64 v165, |v162|, s68
	v_log_f32_e32 v164, v164
	v_exp_f32_e32 v165, v165
	v_exp_f32_e32 v166, v166
	v_min_f32_e32 v161, 0, v161
	v_fmac_f32_e32 v161, 0xbf317218, v164
	v_add_f32_e32 v164, 1.0, v165
	v_log_f32_e32 v164, v164
	v_add_f32_e32 v165, 1.0, v166
	v_log_f32_e32 v165, v165
	v_min_f32_e32 v162, 0, v162
	v_fmac_f32_e32 v162, 0xbf317218, v164
	v_min_f32_e32 v163, 0, v163
	v_fma_f32 v164, v170, s31, 0
	v_fmac_f32_e32 v163, 0xbf317218, v165
	v_fmamk_f32 v165, v171, 0x3d800000, v164
	v_fmamk_f32 v166, v172, 0x3d800000, v165
	v_fmamk_f32 v107, v107, 0x3d800000, v166
	v_fmamk_f32 v167, v173, 0x3d800000, v107
	v_fmamk_f32 v168, v175, 0x3d800000, v167
	v_fmamk_f32 v169, v174, 0x3d800000, v168
	v_fmamk_f32 v170, v176, 0x3d800000, v169
	v_fmamk_f32 v171, v177, 0x3d800000, v170
	v_fmamk_f32 v1, v1, 0x3d800000, v171
	v_fmamk_f32 v108, v108, 0x3d800000, v1
	v_fmamk_f32 v109, v109, 0x3d800000, v108
	v_fmamk_f32 v160, v160, 0x3d800000, v109
	v_fmamk_f32 v161, v161, 0x3d800000, v160
	v_fmamk_f32 v162, v162, 0x3d800000, v161
	v_fmamk_f32 v163, v163, 0x3d800000, v162
	ds_bpermute_b32 v172, v137, v163
	ds_bpermute_b32 v173, v138, v163
	ds_bpermute_b32 v174, v139, v163
	s_waitcnt lgkmcnt(2)
	v_cndmask_b32_e64 v172, v172, 0, s[10:11]
	s_waitcnt lgkmcnt(1)
	v_cndmask_b32_e64 v173, 0, v173, s[12:13]
	v_add_f32_e32 v172, v172, v173
	s_waitcnt lgkmcnt(0)
	v_cndmask_b32_e64 v173, 0, v174, s[6:7]
	v_add_f32_e32 v172, v172, v173
	v_add_f32_e32 v164, v164, v172
	v_add_f32_e32 v165, v165, v172
	ds_write2st64_b32 v141, v164, v165 offset0:24 offset1:26
	v_add_f32_e32 v164, v166, v172
	v_add_f32_e32 v107, v107, v172
	ds_write2st64_b32 v141, v164, v107 offset0:28 offset1:30
	v_add_f32_e32 v107, v167, v172
	v_add_f32_e32 v164, v168, v172
	ds_write2st64_b32 v141, v107, v164 offset0:32 offset1:34
	v_add_f32_e32 v107, v169, v172
	v_add_f32_e32 v164, v170, v172
	ds_write2st64_b32 v141, v107, v164 offset0:36 offset1:38
	v_add_f32_e32 v107, v171, v172
	v_add_f32_e32 v1, v1, v172
	ds_write2st64_b32 v141, v107, v1 offset0:40 offset1:42
	v_add_f32_e32 v1, v172, v108
	v_add_f32_e32 v107, v172, v109
	ds_write2st64_b32 v141, v1, v107 offset0:44 offset1:46
	v_add_f32_e32 v1, v172, v160
	v_add_f32_e32 v107, v172, v161
	ds_write2st64_b32 v141, v1, v107 offset0:48 offset1:50
	v_add_f32_e32 v1, v172, v162
	v_add_f32_e32 v107, v172, v163
	ds_write2st64_b32 v141, v1, v107 offset0:52 offset1:54
	s_waitcnt lgkmcnt(0)
	s_barrier
	s_and_saveexec_b64 s[50:51], s[4:5]
	s_cbranch_execz .LBB0_504
	ds_read_b32 v1, v127 offset:38400
	v_lshl_add_u32 v107, s79, 9, v127
	s_waitcnt lgkmcnt(0)
	ds_write_b32 v107, v1 offset:4096

.LBB0_579:
	s_or_b64 exec, exec, s[0:1]
	s_waitcnt lgkmcnt(0)
	s_barrier
	s_waitcnt lgkmcnt(0)
	ds_read_b128 v[132:135], v180
	ds_read_b128 v[138:141], v180 offset:16
	s_add_i32 s58, s58, 1
	s_add_u32 s38, s38, 0xfffa0000
	s_addc_u32 s39, s39, -1
	s_waitcnt lgkmcnt(1)
	v_mov_b32_e32 v78, v133
	v_mov_b32_e32 v79, v134
	v_mov_b32_e32 v133, v135
	s_waitcnt vmcnt(9)
	v_lshlrev_b32_e32 v134, 16, v162
	v_and_b32_e32 v135, 0xffff0000, v162
	v_pk_add_f32 v[78:79], v[78:79], v[132:133]
	s_waitcnt lgkmcnt(0)
	v_mov_b32_e32 v132, v140
	v_mov_b32_e32 v133, v138
	v_mov_b32_e32 v138, v141
	v_mul_f32_e32 v140, 0xbfb8aa3b, v134
	v_mul_f32_e32 v141, 0xbfb8aa3b, v135
	v_exp_f32_e32 v140, v140
	v_exp_f32_e32 v141, v141
	v_pk_add_f32 v[144:145], v[132:133], v[138:139]
	v_lshlrev_b32_e32 v138, 16, v163
	v_and_b32_e32 v139, 0xffff0000, v163
	v_add_f32_e32 v132, 1.0, v140
	v_add_f32_e32 v133, 1.0, v141
	v_mul_f32_e32 v140, 0xbfb8aa3b, v138
	v_mul_f32_e32 v141, 0xbfb8aa3b, v139
	v_rcp_f32_e32 v132, v132
	v_rcp_f32_e32 v133, v133
	v_exp_f32_e32 v140, v140
	v_exp_f32_e32 v141, v141
	s_waitcnt vmcnt(8)
	v_lshlrev_b32_e32 v162, 16, v152
	v_pk_mul_f32 v[146:147], v[132:133], v[134:135]
	v_add_f32_e32 v132, 1.0, v140
	v_add_f32_e32 v133, 1.0, v141
	v_and_b32_e32 v163, 0xffff0000, v152
	v_mul_f32_e32 v134, 0xbfb8aa3b, v162
	v_rcp_f32_e32 v132, v132
	v_rcp_f32_e32 v133, v133
	v_exp_f32_e32 v134, v134
	v_mul_f32_e32 v135, 0xbfb8aa3b, v163
	v_exp_f32_e32 v135, v135
	v_pk_mul_f32 v[200:201], v[132:133], v[138:139]
	v_add_f32_e32 v132, 1.0, v134
	v_rcp_f32_e32 v202, v132
	v_add_f32_e32 v132, 1.0, v135
	v_lshlrev_b32_e32 v152, 16, v153
	v_and_b32_e32 v153, 0xffff0000, v153
	v_rcp_f32_e32 v203, v132
	v_mul_f32_e32 v132, 0xbfb8aa3b, v152
	v_mul_f32_e32 v133, 0xbfb8aa3b, v153
	v_exp_f32_e32 v132, v132
	v_exp_f32_e32 v138, v133
	s_sub_i32 s30, s30, 64
	v_add_f32_e32 v139, 1.0, v132
	ds_read_b128 v[132:135], v180 offset:512
	v_add_f32_e32 v138, 1.0, v138
	v_rcp_f32_e32 v204, v139
	v_rcp_f32_e32 v205, v138
	ds_read_b128 v[138:141], v180 offset:528
	s_waitcnt lgkmcnt(1)
	v_mov_b32_e32 v206, v133
	v_mov_b32_e32 v207, v134
	v_mov_b32_e32 v133, v135
	v_pk_add_f32 v[132:133], v[206:207], v[132:133]
	s_waitcnt lgkmcnt(0)
	v_mov_b32_e32 v134, v140
	v_mov_b32_e32 v135, v138
	v_mov_b32_e32 v138, v141
	v_pk_add_f32 v[134:135], v[134:135], v[138:139]
	v_mov_b32_e32 v138, v132
	v_mov_b32_e32 v139, v78
	v_mov_b32_e32 v78, v133
	v_pk_add_f32 v[78:79], v[138:139], v[78:79]
	v_mov_b32_e32 v132, v135
	v_mov_b32_e32 v133, v145
	v_pk_add_f32 v[78:79], v[78:79], v[132:133]
	v_mov_b32_e32 v135, v144
	v_pk_add_f32 v[132:133], v[134:135], v[78:79]
	v_mov_b64_e32 v[78:79], s[42:43]
	v_pk_fma_f32 v[132:133], v[132:133], s[40:41], v[78:79] op_sel_hi:[1,0,0]
	v_pk_mul_f32 v[138:139], v[202:203], v[162:163]
	v_mul_f32_e32 v134, 0x4b800000, v133
	v_cmp_gt_f32_e64 s[0:1], s57, v133
	v_pk_mul_f32 v[140:141], v[204:205], v[152:153]
	v_lshl_add_u64 v[152:153], s[34:35], 0, v[116:117]
	v_cndmask_b32_e64 v133, v133, v134, s[0:1]
	v_rsq_f32_e32 v133, v133
	v_lshl_add_u64 v[134:135], s[34:35], 0, v[106:107]
	v_mul_f32_e32 v144, 0x45800000, v133
	v_cndmask_b32_e64 v144, v133, v144, s[0:1]
	v_pk_mul_f32 v[148:149], v[148:149], v[144:145] op_sel_hi:[1,0]
	v_mul_f32_e32 v133, 0x4b800000, v132
	s_waitcnt vmcnt(1)
	v_pk_mul_f32 v[148:149], v[72:73], v[148:149]
	v_cmp_gt_f32_e64 s[0:1], s57, v132
	v_pk_mul_f32 v[146:147], v[146:147], v[148:149]
	v_pk_mul_f32 v[148:149], v[150:151], v[144:145] op_sel_hi:[1,0]
	v_cvt_pk_bf16_f32 v146, v146, v147
	v_pk_mul_f32 v[148:149], v[74:75], v[148:149]
	v_cndmask_b32_e64 v132, v132, v133, s[0:1]
	v_pk_mul_f32 v[148:149], v[200:201], v[148:149]
	v_rsq_f32_e32 v133, v132
	v_cvt_pk_bf16_f32 v147, v148, v149
	global_store_dwordx2 v[134:135], v[146:147], off
	v_pk_mul_f32 v[146:147], v[156:157], v[144:145] op_sel_hi:[1,0]
	v_pk_mul_f32 v[144:145], v[158:159], v[144:145] op_sel_hi:[1,0]
	s_waitcnt vmcnt(1)
	v_pk_mul_f32 v[146:147], v[68:69], v[146:147]
	v_pk_mul_f32 v[144:145], v[70:71], v[144:145]
	v_pk_mul_f32 v[138:139], v[138:139], v[146:147]
	v_pk_mul_f32 v[140:141], v[140:141], v[144:145]
	v_cvt_pk_bf16_f32 v138, v138, v139
	v_cvt_pk_bf16_f32 v139, v140, v141
	v_lshlrev_b32_e32 v132, 16, v142
	global_store_dwordx2 v[134:135], v[138:139], off offset:32
	v_mul_f32_e32 v134, 0xbfb8aa3b, v132
	v_exp_f32_e32 v135, v134
	v_mul_f32_e32 v134, 0x45800000, v133
	v_cndmask_b32_e64 v134, v133, v134, s[0:1]
	v_and_b32_e32 v133, 0xffff0000, v142
	v_mul_f32_e32 v138, 0xbfb8aa3b, v133
	v_exp_f32_e32 v139, v138
	v_add_f32_e32 v135, 1.0, v135
	v_rcp_f32_e32 v138, v135
	v_pk_mul_f32 v[140:141], v[160:161], v[134:135] op_sel_hi:[1,0]
	v_add_f32_e32 v135, 1.0, v139
	v_lshlrev_b32_e32 v142, 16, v143
	v_rcp_f32_e32 v139, v135
	v_and_b32_e32 v143, 0xffff0000, v143
	v_mul_f32_e32 v135, 0xbfb8aa3b, v142
	v_exp_f32_e32 v135, v135
	v_mul_f32_e32 v144, 0xbfb8aa3b, v143
	v_exp_f32_e32 v144, v144
	v_pk_mul_f32 v[132:133], v[138:139], v[132:133]
	v_add_f32_e32 v135, 1.0, v135
	v_rcp_f32_e32 v138, v135
	v_add_f32_e32 v135, 1.0, v144
	v_rcp_f32_e32 v139, v135
	v_pk_mul_f32 v[98:99], v[98:99], v[134:135] op_sel_hi:[1,0]
	v_pk_mul_f32 v[140:141], v[72:73], v[140:141]
	v_pk_mul_f32 v[98:99], v[74:75], v[98:99]
	v_pk_mul_f32 v[138:139], v[138:139], v[142:143]
	v_pk_mul_f32 v[132:133], v[132:133], v[140:141]
	v_pk_mul_f32 v[98:99], v[138:139], v[98:99]
	v_cvt_pk_bf16_f32 v132, v132, v133
	v_cvt_pk_bf16_f32 v133, v98, v99
	v_lshlrev_b32_e32 v98, 16, v136
	v_mul_f32_e32 v99, 0xbfb8aa3b, v98
	v_exp_f32_e32 v135, v99
	v_lshl_add_u64 v[138:139], s[34:35], 0, v[110:111]
	v_and_b32_e32 v99, 0xffff0000, v136
	global_store_dwordx2 v[138:139], v[132:133], off
	v_mul_f32_e32 v133, 0xbfb8aa3b, v99
	v_exp_f32_e32 v133, v133
	v_lshlrev_b32_e32 v136, 16, v137
	v_and_b32_e32 v137, 0xffff0000, v137
	v_add_f32_e32 v132, 1.0, v135
	v_pk_mul_f32 v[96:97], v[96:97], v[134:135] op_sel_hi:[1,0]
	v_add_f32_e32 v133, 1.0, v133
	v_mul_f32_e32 v135, 0xbfb8aa3b, v136
	v_mul_f32_e32 v138, 0xbfb8aa3b, v137
	v_rcp_f32_e32 v132, v132
	v_rcp_f32_e32 v133, v133
	v_exp_f32_e32 v135, v135
	v_exp_f32_e32 v138, v138
	v_pk_mul_f32 v[96:97], v[68:69], v[96:97]
	v_pk_mul_f32 v[98:99], v[132:133], v[98:99]
	v_add_f32_e32 v132, 1.0, v135
	v_add_f32_e32 v133, 1.0, v138
	v_rcp_f32_e32 v132, v132
	v_rcp_f32_e32 v133, v133
	v_pk_mul_f32 v[94:95], v[94:95], v[134:135] op_sel_hi:[1,0]
	v_pk_mul_f32 v[96:97], v[98:99], v[96:97]
	v_pk_mul_f32 v[94:95], v[70:71], v[94:95]
	v_pk_mul_f32 v[98:99], v[132:133], v[136:137]
	v_cvt_pk_bf16_f32 v132, v96, v97
	v_pk_mul_f32 v[98:99], v[98:99], v[94:95]
	ds_read_b128 v[94:97], v180 offset:1024
	v_cvt_pk_bf16_f32 v133, v98, v99
	v_lshl_add_u64 v[98:99], s[34:35], 0, v[112:113]
	global_store_dwordx2 v[98:99], v[132:133], off
	ds_read_b128 v[132:135], v180 offset:1040
	s_waitcnt lgkmcnt(1)
	v_mov_b32_e32 v98, v95
	v_mov_b32_e32 v99, v96
	v_mov_b32_e32 v95, v97
	v_lshlrev_b32_e32 v96, 16, v130
	v_pk_add_f32 v[98:99], v[98:99], v[94:95]
	v_and_b32_e32 v97, 0xffff0000, v130
	v_mul_f32_e32 v95, 0xbfb8aa3b, v96
	v_exp_f32_e32 v130, v95
	v_mul_f32_e32 v95, 0xbfb8aa3b, v97
	s_waitcnt lgkmcnt(0)
	v_mov_b32_e32 v94, v134
	v_exp_f32_e32 v134, v95
	v_lshlrev_b32_e32 v136, 16, v131
	v_and_b32_e32 v137, 0xffff0000, v131
	v_mul_f32_e32 v131, 0xbfb8aa3b, v136
	v_mov_b32_e32 v95, v132
	v_add_f32_e32 v132, 1.0, v134
	v_exp_f32_e32 v134, v131
	v_mul_f32_e32 v131, 0xbfb8aa3b, v137
	v_exp_f32_e32 v139, v131
	v_rcp_f32_e32 v131, v132
	v_add_f32_e32 v132, 1.0, v134
	v_rcp_f32_e32 v138, v132
	v_add_f32_e32 v132, 1.0, v139
	v_rcp_f32_e32 v139, v132
	v_mov_b32_e32 v132, v135
	v_pk_add_f32 v[132:133], v[94:95], v[132:133]
	v_lshlrev_b32_e32 v144, 16, v129
	v_pk_mul_f32 v[136:137], v[138:139], v[136:137]
	v_lshlrev_b32_e32 v138, 16, v128
	v_and_b32_e32 v139, 0xffff0000, v128
	v_mul_f32_e32 v94, 0xbfb8aa3b, v138
	v_exp_f32_e32 v94, v94
	v_mul_f32_e32 v95, 0xbfb8aa3b, v139
	v_exp_f32_e32 v95, v95
	v_and_b32_e32 v145, 0xffff0000, v129
	v_add_f32_e32 v94, 1.0, v94
	v_rcp_f32_e32 v142, v94
	v_add_f32_e32 v94, 1.0, v95
	v_add_f32_e32 v130, 1.0, v130
	v_rcp_f32_e32 v143, v94
	v_mul_f32_e32 v94, 0xbfb8aa3b, v144
	v_mul_f32_e32 v95, 0xbfb8aa3b, v145
	v_rcp_f32_e32 v130, v130
	v_exp_f32_e32 v94, v94
	v_exp_f32_e32 v128, v95
	v_lshl_add_u64 v[140:141], s[34:35], 0, v[114:115]
	v_pk_mul_f32 v[134:135], v[130:131], v[96:97]
	v_add_f32_e32 v129, 1.0, v94
	ds_read_b128 v[94:97], v180 offset:1536
	v_add_f32_e32 v128, 1.0, v128
	v_rcp_f32_e32 v146, v129
	v_rcp_f32_e32 v147, v128
	ds_read_b128 v[128:131], v180 offset:1552
	ds_read_b64_tr_b16 v[246:247], v196 offset:57408
	ds_read_b64_tr_b16 v[244:245], v196 offset:56320
	s_waitcnt lgkmcnt(3)
	v_mov_b32_e32 v148, v95
	v_mov_b32_e32 v149, v96
	v_mov_b32_e32 v95, v97
	v_pk_add_f32 v[94:95], v[148:149], v[94:95]
	s_waitcnt lgkmcnt(2)
	v_mov_b32_e32 v96, v130
	v_mov_b32_e32 v97, v128
	v_mov_b32_e32 v128, v131
	v_pk_add_f32 v[96:97], v[96:97], v[128:129]
	v_mov_b32_e32 v128, v94
	v_mov_b32_e32 v129, v98
	v_mov_b32_e32 v98, v95
	v_pk_add_f32 v[94:95], v[128:129], v[98:99]
	v_mov_b32_e32 v98, v97
	v_mov_b32_e32 v99, v133
	v_pk_add_f32 v[94:95], v[94:95], v[98:99]
	v_mov_b32_e32 v97, v132
	v_pk_add_f32 v[94:95], v[96:97], v[94:95]
	v_pk_mul_f32 v[98:99], v[146:147], v[144:145]
	v_pk_fma_f32 v[78:79], v[94:95], s[40:41], v[78:79] op_sel_hi:[1,0,0]
	s_nop 0
	v_mul_f32_e32 v94, 0x4b800000, v79
	v_cmp_gt_f32_e64 s[0:1], s57, v79
	s_nop 1
	v_cndmask_b32_e64 v79, v79, v94, s[0:1]
	v_rsq_f32_e32 v79, v79
	v_pk_mul_f32 v[94:95], v[142:143], v[138:139]
	v_mul_f32_e32 v96, 0x45800000, v79
	v_cndmask_b32_e64 v96, v79, v96, s[0:1]
	v_pk_mul_f32 v[88:89], v[88:89], v[96:97] op_sel_hi:[1,0]
	v_pk_mul_f32 v[92:93], v[92:93], v[96:97] op_sel_hi:[1,0]
	v_pk_mul_f32 v[88:89], v[72:73], v[88:89]
	v_pk_mul_f32 v[92:93], v[74:75], v[92:93]
	v_pk_mul_f32 v[88:89], v[134:135], v[88:89]
	v_pk_mul_f32 v[92:93], v[136:137], v[92:93]
	v_cvt_pk_bf16_f32 v88, v88, v89
	v_cvt_pk_bf16_f32 v89, v92, v93
	ds_read_b64_tr_b16 v[92:93], v198 offset:2112
	global_store_dwordx2 v[140:141], v[88:89], off
	v_pk_mul_f32 v[88:89], v[90:91], v[96:97] op_sel_hi:[1,0]
	ds_read_b64_tr_b16 v[90:91], v198
	v_mul_f32_e32 v79, 0x4b800000, v78
	v_cmp_gt_f32_e64 s[0:1], s57, v78
	v_pk_mul_f32 v[88:89], v[68:69], v[88:89]
	v_pk_mul_f32 v[86:87], v[86:87], v[96:97] op_sel_hi:[1,0]
	ds_read_b64_tr_b16 v[96:97], v198 offset:2144
	v_cndmask_b32_e64 v78, v78, v79, s[0:1]
	v_pk_mul_f32 v[200:201], v[94:95], v[88:89]
	ds_read_b64_tr_b16 v[94:95], v198 offset:32
	ds_read_b64_tr_b16 v[128:129], v196 offset:56352
	ds_read_b64_tr_b16 v[132:133], v196 offset:56384
	ds_read_b64_tr_b16 v[136:137], v196 offset:56416
	ds_read_b64_tr_b16 v[130:131], v196 offset:57440
	ds_read_b64_tr_b16 v[134:135], v196 offset:57472
	ds_read_b64_tr_b16 v[138:139], v196 offset:57504
	ds_read_b64_tr_b16 v[140:141], v196 offset:65024
	ds_read_b64_tr_b16 v[142:143], v197 offset:57408
	ds_read_b64_tr_b16 v[144:145], v198 offset:16896
	ds_read_b64_tr_b16 v[146:147], v198 offset:19008
	ds_read_b64_tr_b16 v[150:151], v198 offset:19040
	ds_read_b64_tr_b16 v[148:149], v198 offset:16928
	ds_read_b64_tr_b16 v[248:249], v196 offset:65056
	ds_read_b64_tr_b16 v[156:157], v196 offset:65088
	ds_read_b64_tr_b16 v[160:161], v196 offset:65120
	ds_read_b64_tr_b16 v[250:251], v197 offset:57440
	ds_read_b64_tr_b16 v[158:159], v197 offset:57472
	ds_read_b64_tr_b16 v[162:163], v197 offset:57504
	ds_read_b64_tr_b16 v[252:253], v196 offset:56448
	ds_read_b64_tr_b16 v[254:255], v196 offset:57536
	v_pk_mul_f32 v[202:203], v[70:71], v[86:87]
	s_nop 0
	s_nop 0
	s_nop 0
	s_nop 0
	s_nop 0
	s_nop 0
	s_nop 0
	s_nop 0
	s_nop 0
	s_nop 0
	s_nop 0
	s_nop 0
	v_rsq_f32_e32 v78, v78
	s_nop 0
	s_nop 0
	s_nop 0
	s_nop 0
	s_nop 0
	s_nop 0
	v_pk_mul_f32 v[98:99], v[98:99], v[202:203]
	s_waitcnt lgkmcnt(15)
	v_mfma_f32_16x16x32_bf16 v[12:15], v[128:131], v[90:93], v[12:15]
	v_cvt_pk_bf16_f32 v200, v200, v201
	v_cvt_pk_bf16_f32 v201, v98, v99
	v_mul_f32_e32 v79, 0x45800000, v78
	v_mfma_f32_16x16x32_bf16 v[36:39], v[128:131], v[94:97], v[36:39]
	v_lshlrev_b32_e32 v98, 16, v126
	v_cndmask_b32_e64 v78, v78, v79, s[0:1]
	v_and_b32_e32 v99, 0xffff0000, v126
	v_mfma_f32_16x16x32_bf16 v[8:11], v[244:247], v[90:93], v[8:11]
	v_mul_f32_e32 v79, 0xbfb8aa3b, v98
	v_exp_f32_e32 v79, v79
	v_mul_f32_e32 v126, 0xbfb8aa3b, v99
	v_mfma_f32_16x16x32_bf16 v[4:7], v[244:247], v[94:97], v[4:7]
	s_nop 0
	s_nop 0
	s_nop 0
	s_nop 0
	s_nop 0
	s_nop 0
	v_add_f32_e32 v79, 1.0, v79
	global_store_dwordx2 v[152:153], v[200:201], off
	s_waitcnt lgkmcnt(4)
	v_mfma_f32_16x16x32_bf16 v[12:15], v[248:251], v[144:147], v[12:15]
	v_mfma_f32_16x16x32_bf16 v[36:39], v[248:251], v[148:151], v[36:39]
	v_exp_f32_e32 v87, v126
	v_rcp_f32_e32 v86, v79
	v_add_f32_e32 v79, 1.0, v87
	v_rcp_f32_e32 v87, v79
	v_pk_mul_f32 v[84:85], v[84:85], v[78:79] op_sel_hi:[1,0]
	v_mfma_f32_16x16x32_bf16 v[24:27], v[132:135], v[90:93], v[24:27]
	v_mul_f32_e64 v72, v72, v84
	v_mul_f32_e64 v73, v73, v85
	v_pk_mul_f32 v[84:85], v[86:87], v[98:99]
	v_lshlrev_b32_e32 v86, 16, v127
	v_mul_f32_e32 v79, 0xbfb8aa3b, v86
	v_exp_f32_e32 v79, v79
	v_pk_mul_f32 v[98:99], v[84:85], v[72:73]
	v_and_b32_e32 v87, 0xffff0000, v127
	v_mfma_f32_16x16x32_bf16 v[32:35], v[132:135], v[94:97], v[32:35]
	v_add_f32_e32 v72, 1.0, v79
	v_rcp_f32_e32 v84, v72
	v_mul_f32_e32 v72, 0xbfb8aa3b, v87
	v_exp_f32_e32 v79, v72
	v_mfma_f32_16x16x32_bf16 v[40:43], v[136:139], v[90:93], v[40:43]
	v_cvt_pk_bf16_f32 v98, v98, v99
	v_pk_mul_f32 v[72:73], v[82:83], v[78:79] op_sel_hi:[1,0]
	ds_read_b64_tr_b16 v[82:83], v196 offset:56480
	s_nop 0
	v_pk_mul_f32 v[134:135], v[74:75], v[72:73]
	v_add_f32_e32 v72, 1.0, v79
	v_rcp_f32_e32 v85, v72
	s_nop 0
	s_nop 0
	v_mfma_f32_16x16x32_bf16 v[64:67], v[136:139], v[94:97], v[64:67]
	v_mul_f32_e64 v136, v84, v86
	v_mul_f32_e64 v137, v85, v87
	ds_read_b64_tr_b16 v[86:87], v196 offset:56512
	ds_read_b64_tr_b16 v[126:127], v196 offset:56544
	ds_read_b64_tr_b16 v[84:85], v196 offset:57568
	ds_read_b64_tr_b16 v[88:89], v196 offset:57600
	ds_read_b64_tr_b16 v[128:129], v196 offset:57632
	ds_read_b64_tr_b16 v[130:131], v196 offset:65152
	ds_read_b64_tr_b16 v[132:133], v197 offset:57536
	ds_read_b64_tr_b16 v[244:245], v196 offset:65184
	s_nop 0
	s_nop 0
	s_nop 0
	s_nop 0
	s_nop 0
	s_nop 0
	v_mfma_f32_16x16x32_bf16 v[8:11], v[140:143], v[144:147], v[8:11]
	s_nop 0
	s_nop 0
	v_mfma_f32_16x16x32_bf16 v[4:7], v[140:143], v[148:151], v[4:7]
	v_mul_f32_e64 v142, v136, v134
	v_mul_f32_e64 v143, v137, v135
	ds_read_b64_tr_b16 v[134:135], v196 offset:65216
	ds_read_b64_tr_b16 v[138:139], v196 offset:65248
	ds_read_b64_tr_b16 v[246:247], v197 offset:57568
	ds_read_b64_tr_b16 v[136:137], v197 offset:57600
	ds_read_b64_tr_b16 v[140:141], v197 offset:57632
	v_cvt_pk_bf16_f32 v99, v142, v143
	v_lshl_add_u64 v[142:143], s[34:35], 0, v[118:119]
	s_waitcnt lgkmcnt(14)
	v_mfma_f32_16x16x32_bf16 v[16:19], v[252:255], v[90:93], v[16:19]
	v_mfma_f32_16x16x32_bf16 v[20:23], v[252:255], v[94:97], v[20:23]
	s_nop 0
	s_nop 0
	s_nop 0
	s_nop 0
	s_nop 0
	s_nop 0
	global_store_dwordx2 v[142:143], v[98:99], off
	v_lshlrev_b32_e32 v98, 16, v124
	v_and_b32_e32 v99, 0xffff0000, v124
	v_mul_f32_e32 v79, 0xbfb8aa3b, v98
	v_exp_f32_e32 v79, v79
	v_mul_f32_e32 v124, 0xbfb8aa3b, v99
	s_waitcnt lgkmcnt(10)
	v_mfma_f32_16x16x32_bf16 v[28:31], v[82:85], v[90:93], v[28:31]
	v_add_f32_e32 v79, 1.0, v79
	v_mfma_f32_16x16x32_bf16 v[48:51], v[82:85], v[94:97], v[48:51]
	v_exp_f32_e32 v83, v124
	v_rcp_f32_e32 v82, v79
	v_add_f32_e32 v79, 1.0, v83
	v_rcp_f32_e32 v83, v79
	v_pk_mul_f32 v[80:81], v[80:81], v[78:79] op_sel_hi:[1,0]
	s_waitcnt lgkmcnt(2)
	v_mfma_f32_16x16x32_bf16 v[28:31], v[244:247], v[144:147], v[28:31]
	v_mul_f32_e64 v68, v68, v80
	v_mul_f32_e64 v69, v69, v81
	v_pk_mul_f32 v[76:77], v[76:77], v[78:79] op_sel_hi:[1,0]
	v_lshl_add_u64 v[78:79], s[34:35], 0, v[120:121]
	v_mfma_f32_16x16x32_bf16 v[48:51], v[244:247], v[148:151], v[48:51]
	v_mul_f32_e64 v72, v82, v98
	v_mul_f32_e64 v73, v83, v99
	v_pk_mul_f32 v[70:71], v[70:71], v[76:77]
	v_pk_mul_f32 v[68:69], v[72:73], v[68:69]
	v_lshlrev_b32_e32 v72, 16, v125
	v_and_b32_e32 v73, 0xffff0000, v125
	v_mul_f32_e32 v74, 0xbfb8aa3b, v72
	v_mul_f32_e32 v75, 0xbfb8aa3b, v73
	v_exp_f32_e32 v74, v74
	v_exp_f32_e32 v75, v75
	v_lshl_add_u32 v82, s59, 9, v176
	ds_read_b128 v[248:251], v82 offset:4096
	ds_read_b128 v[252:255], v82 offset:4160
	ds_read_b128 v[244:247], v82 offset:4224
	v_cvt_pk_bf16_f32 v76, v68, v69
	v_add_f32_e32 v74, 1.0, v74
	v_add_f32_e32 v75, 1.0, v75
	v_rcp_f32_e32 v74, v74
	v_rcp_f32_e32 v75, v75
	v_mfma_f32_16x16x32_bf16 v[24:27], v[156:159], v[144:147], v[24:27]
	s_add_u32 s34, s34, 0xfffe0000
	s_addc_u32 s35, s35, -1
	v_pk_mul_f32 v[72:73], v[74:75], v[72:73]
	v_mfma_f32_16x16x32_bf16 v[32:35], v[156:159], v[148:151], v[32:35]
	v_mul_f32_e64 v72, v72, v70
	v_mul_f32_e64 v73, v73, v71
	s_nop 0
	v_cvt_pk_bf16_f32 v77, v72, v73
	s_nop 0
	global_store_dwordx2 v[78:79], v[76:77], off
	v_mfma_f32_16x16x32_bf16 v[16:19], v[130:133], v[144:147], v[16:19]
	s_waitcnt lgkmcnt(2)
	v_mul_f32_e32 v68, 0x3fb8aa3b, v248
	v_exp_f32_e32 v80, v68
	v_mul_f32_e32 v81, 0x3fb8aa3b, v249
	v_mul_f32_e32 v68, 0x3fb8aa3b, v250
	v_mul_f32_e32 v69, 0x3fb8aa3b, v251
	ds_read_b128 v[248:251], v82 offset:4288
	v_exp_f32_e32 v68, v68
	v_exp_f32_e32 v69, v69
	v_exp_f32_e32 v81, v81
	v_mfma_f32_16x16x32_bf16 v[20:23], v[130:133], v[148:151], v[20:23]
	s_add_u32 s36, s36, 0xfffe0000
	v_pk_mul_f32 v[10:11], v[10:11], v[68:69]
	v_pk_mul_f32 v[6:7], v[6:7], v[68:69]
	s_waitcnt lgkmcnt(2)
	v_mul_f32_e32 v68, 0x3fb8aa3b, v252
	v_mul_f32_e32 v69, 0x3fb8aa3b, v254
	v_exp_f32_e32 v76, v68
	v_mul_f32_e32 v68, 0x3fb8aa3b, v253
	v_exp_f32_e32 v78, v69
	v_mul_f32_e32 v69, 0x3fb8aa3b, v255
	ds_read_b128 v[252:255], v82 offset:4352
	v_exp_f32_e32 v79, v69
	v_exp_f32_e32 v77, v68
	s_nop 0
	s_nop 0
	v_pk_mul_f32 v[8:9], v[8:9], v[80:81]
	v_pk_mul_f32 v[4:5], v[4:5], v[80:81]
	v_pk_mul_f32 v[14:15], v[14:15], v[78:79]
	s_waitcnt lgkmcnt(2)
	v_mul_f32_e32 v68, 0x3fb8aa3b, v244
	v_exp_f32_e32 v80, v68
	v_mul_f32_e32 v81, 0x3fb8aa3b, v245
	v_mul_f32_e32 v68, 0x3fb8aa3b, v246
	v_mul_f32_e32 v69, 0x3fb8aa3b, v247
	ds_read_b128 v[244:247], v82 offset:4416
	v_exp_f32_e32 v68, v68
	v_exp_f32_e32 v69, v69
	v_pk_mul_f32 v[12:13], v[12:13], v[76:77]
	v_pk_mul_f32 v[38:39], v[38:39], v[78:79]
	v_pk_mul_f32 v[36:37], v[36:37], v[76:77]
	v_pk_mul_f32 v[26:27], v[26:27], v[68:69]
	v_pk_mul_f32 v[34:35], v[34:35], v[68:69]
	s_waitcnt lgkmcnt(2)
	v_mul_f32_e32 v68, 0x3fb8aa3b, v248
	v_mul_f32_e32 v69, 0x3fb8aa3b, v250
	v_exp_f32_e32 v76, v68
	v_mul_f32_e32 v68, 0x3fb8aa3b, v249
	v_exp_f32_e32 v78, v69
	v_mul_f32_e32 v69, 0x3fb8aa3b, v251
	ds_read_b128 v[248:251], v82 offset:4480
	v_exp_f32_e32 v79, v69
	v_exp_f32_e32 v77, v68
	s_nop 0
	s_nop 0
	v_exp_f32_e32 v81, v81
	v_mfma_f32_16x16x32_bf16 v[40:43], v[160:163], v[144:147], v[40:43]
	s_addc_u32 s37, s37, -1
	s_waitcnt lgkmcnt(2)
	v_mul_f32_e32 v68, 0x3fb8aa3b, v252
	v_pk_mul_f32 v[24:25], v[24:25], v[80:81]
	v_pk_mul_f32 v[32:33], v[32:33], v[80:81]
	v_exp_f32_e32 v80, v68
	v_mul_f32_e32 v81, 0x3fb8aa3b, v253
	v_mul_f32_e32 v68, 0x3fb8aa3b, v254
	v_mul_f32_e32 v69, 0x3fb8aa3b, v255
	ds_read_b128 v[252:255], v82 offset:4544
	v_exp_f32_e32 v68, v68
	v_exp_f32_e32 v69, v69
	v_mfma_f32_16x16x32_bf16 v[64:67], v[160:163], v[148:151], v[64:67]
	v_mul_f32_e64 v42, v42, v78
	v_mul_f32_e64 v43, v43, v79
	v_pk_mul_f32 v[40:41], v[40:41], v[76:77]
	v_pk_mul_f32 v[18:19], v[18:19], v[68:69]
	v_pk_mul_f32 v[22:23], v[22:23], v[68:69]
	s_waitcnt lgkmcnt(2)
	v_mul_f32_e32 v68, 0x3fb8aa3b, v244
	v_mul_f32_e32 v69, 0x3fb8aa3b, v246
	v_pk_mul_f32 v[66:67], v[66:67], v[78:79]
	v_pk_mul_f32 v[64:65], v[64:65], v[76:77]
	v_exp_f32_e32 v76, v68
	v_mul_f32_e32 v68, 0x3fb8aa3b, v245
	v_exp_f32_e32 v78, v69
	v_mul_f32_e32 v69, 0x3fb8aa3b, v247
	v_exp_f32_e32 v79, v69
	v_exp_f32_e32 v77, v68
	s_nop 0
	s_nop 0
	v_mfma_f32_16x16x32_bf16 v[44:47], v[86:89], v[90:93], v[44:47]
	v_exp_f32_e32 v81, v81
	v_pk_mul_f32 v[30:31], v[30:31], v[78:79]
	s_waitcnt lgkmcnt(1)
	v_mul_f32_e32 v68, 0x3fb8aa3b, v248
	v_mfma_f32_16x16x32_bf16 v[56:59], v[86:89], v[94:97], v[56:59]
	v_mul_f32_e32 v69, 0x3fb8aa3b, v249
	v_mul_f32_e32 v70, 0x3fb8aa3b, v250
	v_mul_f32_e32 v71, 0x3fb8aa3b, v251
	v_mfma_f32_16x16x32_bf16 v[52:55], v[126:129], v[90:93], v[52:55]
	s_waitcnt lgkmcnt(0)
	v_mul_f32_e32 v72, 0x3fb8aa3b, v252
	v_mul_f32_e32 v73, 0x3fb8aa3b, v253
	v_mul_f32_e32 v74, 0x3fb8aa3b, v254
	v_mfma_f32_16x16x32_bf16 v[60:63], v[126:129], v[94:97], v[60:63]
	v_mul_f32_e32 v75, 0x3fb8aa3b, v255
	v_exp_f32_e32 v68, v68
	v_exp_f32_e32 v70, v70
	v_mfma_f32_16x16x32_bf16 v[44:47], v[134:137], v[144:147], v[44:47]
	v_exp_f32_e32 v71, v71
	v_exp_f32_e32 v69, v69
	v_exp_f32_e32 v72, v72
	v_mfma_f32_16x16x32_bf16 v[56:59], v[134:137], v[148:151], v[56:59]
	v_exp_f32_e32 v74, v74
	v_exp_f32_e32 v75, v75
	v_exp_f32_e32 v73, v73
	v_mfma_f32_16x16x32_bf16 v[52:55], v[138:141], v[144:147], v[52:55]
	v_mul_f32_e64 v16, v16, v80
	v_mul_f32_e64 v17, v17, v81
	v_pk_mul_f32 v[20:21], v[20:21], v[80:81]
	v_pk_mul_f32 v[28:29], v[28:29], v[76:77]
	v_mfma_f32_16x16x32_bf16 v[60:63], v[138:141], v[148:151], v[60:63]
	v_mul_f32_e64 v50, v50, v78
	v_mul_f32_e64 v51, v51, v79
	v_pk_mul_f32 v[48:49], v[48:49], v[76:77]
	v_pk_mul_f32 v[46:47], v[46:47], v[70:71]
	v_pk_mul_f32 v[44:45], v[44:45], v[68:69]
	v_pk_mul_f32 v[58:59], v[58:59], v[70:71]
	v_pk_mul_f32 v[56:57], v[56:57], v[68:69]
	v_pk_mul_f32 v[54:55], v[54:55], v[74:75]
	v_pk_mul_f32 v[52:53], v[52:53], v[72:73]
	v_pk_mul_f32 v[62:63], v[62:63], v[74:75]
	s_cmp_eq_u32 s58, 4
	v_pk_mul_f32 v[60:61], v[60:61], v[72:73]
	s_waitcnt lgkmcnt(0)
	s_cbranch_scc1 .LBB0_597
.LBB0_580:
	s_add_u32 s0, s50, s38
	s_addc_u32 s1, s51, s39
	s_add_u32 s60, s48, s38
	s_addc_u32 s61, s49, s39
	s_add_u32 s31, s60, s46
	s_addc_u32 s44, s61, 0
	s_add_u32 s62, s31, 0x16e40800
	s_addc_u32 s63, s44, 0
	s_and_b32 s59, s58, 1
	s_cmp_eq_u32 s59, 0
	s_cselect_b64 s[44:45], -1, 0
	s_and_b64 s[64:65], s[44:45], exec
	s_cselect_b32 s31, 0xf0, s54
	v_add3_u32 v136, s31, v171, v170
	s_waitcnt lgkmcnt(0)
	ds_read2_b32 v[72:73], v136 offset1:4
	ds_read2_b32 v[244:245], v136 offset0:64 offset1:68
	ds_read2_b32 v[248:249], v136 offset0:8 offset1:12
	ds_read2_b32 v[252:253], v136 offset0:72 offset1:76
	v_lshl_add_u64 v[74:75], s[0:1], 0, v[102:103]
	s_nop 0
	global_load_dwordx4 v[92:95], v[74:75], off
	global_load_dwordx4 v[96:99], v[74:75], off offset:1024
	s_nop 0
	v_lshl_add_u64 v[82:83], s[62:63], 0, v[104:105]
	s_waitcnt lgkmcnt(3)
	v_mfma_f32_16x16x4_f32 v[68:71], v72, v155, 0
	v_add_co_u32_e64 v72, s[0:1], s52, v74
	v_mfma_f32_16x16x4_f32 v[68:71], v73, v164, v[68:71]
	s_nop 0
	v_addc_co_u32_e64 v73, s[0:1], 0, v75, s[0:1]
	global_load_dwordx4 v[84:87], v[72:73], off
	global_load_dwordx4 v[88:91], v[72:73], off offset:1024
	v_add_co_u32_e64 v72, s[0:1], s47, v82
	s_nop 1
	v_addc_co_u32_e64 v73, s[0:1], 0, v83, s[0:1]
	s_waitcnt lgkmcnt(1)
	v_mfma_f32_16x16x4_f32 v[124:127], v248, v165, v[68:71]
	v_add_co_u32_e64 v134, s[0:1], s52, v82
	global_load_dwordx4 v[68:71], v[82:83], off
	s_nop 0
	global_load_dwordx4 v[72:75], v[72:73], off
	v_addc_co_u32_e64 v135, s[0:1], 0, v83, s[0:1]
	v_mfma_f32_16x16x4_f32 v[76:79], v244, v155, 0
	v_add_co_u32_e64 v80, s[0:1], s53, v82
	v_mfma_f32_16x16x4_f32 v[124:127], v249, v166, v[124:127]
	ds_read2_b32 v[248:249], v136 offset0:128 offset1:132
	ds_read2_b32 v[250:251], v136 offset0:136 offset1:140
	v_mfma_f32_16x16x4_f32 v[128:131], v245, v164, v[76:79]
	ds_read2_b32 v[244:245], v136 offset0:192 offset1:196
	v_addc_co_u32_e64 v81, s[0:1], 0, v83, s[0:1]
	s_nop 5
	global_load_dwordx4 v[76:79], v[134:135], off
	s_nop 0
	global_load_dwordx4 v[80:83], v[80:81], off
	s_nop 0
	v_add_f32_e32 v124, v167, v124
	v_min_f32_e32 v137, 0, v124
	v_mul_f32_e64 v124, |v124|, s55
	v_exp_f32_e32 v124, v124
	v_add_f32_e32 v126, v167, v126
	v_mul_f32_e64 v133, |v126|, s55
	v_exp_f32_e32 v133, v133
	v_add_f32_e32 v124, 1.0, v124
	v_log_f32_e32 v124, v124
	s_waitcnt lgkmcnt(3)
	v_mfma_f32_16x16x4_f32 v[128:131], v252, v165, v[128:131]
	v_add_f32_e32 v133, 1.0, v133
	v_min_f32_e32 v139, 0, v126
	v_fmac_f32_e32 v137, 0xbf317218, v124
	v_log_f32_e32 v124, v133
	v_add_f32_e32 v134, v167, v127
	v_add_f32_e32 v125, v167, v125
	v_mul_f32_e64 v132, |v125|, s55
	v_fmac_f32_e32 v139, 0xbf317218, v124
	v_mul_f32_e64 v124, |v134|, s55
	v_min_f32_e32 v138, 0, v125
	v_exp_f32_e32 v140, v124
	v_mfma_f32_16x16x4_f32 v[124:127], v253, v166, v[128:131]
	ds_read2_b32 v[252:253], v136 offset0:200 offset1:204
	v_exp_f32_e32 v132, v132
	v_add_f32_e32 v129, 1.0, v140
	v_log_f32_e32 v129, v129
	v_add_f32_e32 v132, 1.0, v132
	v_log_f32_e32 v132, v132
	v_min_f32_e32 v140, 0, v134
	s_nop 3
	v_add_f32_e32 v124, v167, v124
	v_mul_f32_e64 v128, |v124|, s55
	v_fmac_f32_e32 v138, 0xbf317218, v132
	v_exp_f32_e32 v128, v128
	s_nop 0
	v_min_f32_e32 v141, 0, v124
	v_fmac_f32_e32 v140, 0xbf317218, v129
	v_add_f32_e32 v128, 1.0, v128
	v_log_f32_e32 v128, v128
	s_nop 0
	v_add_f32_e32 v124, v167, v125
	v_mul_f32_e64 v125, |v124|, s55
	v_fmac_f32_e32 v141, 0xbf317218, v128
	s_waitcnt lgkmcnt(3)
	v_mfma_f32_16x16x4_f32 v[128:131], v248, v155, 0
	v_add_f32_e32 v132, v167, v126
	v_exp_f32_e32 v125, v125
	v_mul_f32_e64 v126, |v132|, s55
	v_exp_f32_e32 v126, v126
	v_min_f32_e32 v142, 0, v124
	v_add_f32_e32 v124, 1.0, v125
	v_add_f32_e32 v144, v167, v127
	v_mfma_f32_16x16x4_f32 v[128:131], v249, v164, v[128:131]
	v_log_f32_e32 v133, v124
	v_add_f32_e32 v124, 1.0, v126
	v_log_f32_e32 v143, v124
	v_mul_f32_e64 v145, |v144|, s55
	v_fmac_f32_e32 v142, 0xbf317218, v133
	s_waitcnt lgkmcnt(2)
	v_mfma_f32_16x16x4_f32 v[124:127], v250, v165, v[128:131]
	s_nop 2
	v_exp_f32_e32 v128, v145
	v_min_f32_e32 v145, 0, v132
	s_nop 0
	v_fmac_f32_e32 v145, 0xbf317218, v143
	v_add_f32_e32 v128, 1.0, v128
	v_log_f32_e32 v128, v128
	v_min_f32_e32 v143, 0, v144
	v_mfma_f32_16x16x4_f32 v[124:127], v251, v166, v[124:127]
	v_fmac_f32_e32 v143, 0xbf317218, v128
	s_nop 8
	v_add_f32_e32 v124, v167, v124
	v_mul_f32_e64 v128, |v124|, s55
	v_exp_f32_e32 v134, v128
	s_waitcnt lgkmcnt(1)
	v_mfma_f32_16x16x4_f32 v[128:131], v244, v155, 0
	v_add_f32_e32 v125, v167, v125
	v_mul_f32_e64 v135, |v125|, s55
	v_exp_f32_e32 v132, v135
	v_min_f32_e32 v144, 0, v124
	v_add_f32_e32 v124, 1.0, v134
	s_nop 0
	v_add_f32_e32 v132, 1.0, v132
	v_mfma_f32_16x16x4_f32 v[128:131], v245, v164, v[128:131]
	v_log_f32_e32 v132, v132
	v_log_f32_e32 v124, v124
	v_min_f32_e32 v133, 0, v125
	v_add_f32_e32 v146, v167, v127
	v_fmac_f32_e32 v133, 0xbf317218, v132
	v_add_f32_e32 v132, v167, v126
	v_fmac_f32_e32 v144, 0xbf317218, v124
	v_mul_f32_e64 v124, |v132|, s55
	v_exp_f32_e32 v136, v124
	s_waitcnt lgkmcnt(0)
	v_mfma_f32_16x16x4_f32 v[124:127], v252, v165, v[128:131]
	v_mul_f32_e64 v128, |v146|, s55
	v_exp_f32_e32 v128, v128
	v_add_f32_e32 v130, 1.0, v136
	v_log_f32_e32 v130, v130
	v_min_f32_e32 v129, 0, v132
	v_add_f32_e32 v128, 1.0, v128
	v_log_f32_e32 v128, v128
	v_mfma_f32_16x16x4_f32 v[124:127], v253, v166, v[124:127]
	v_fmac_f32_e32 v129, 0xbf317218, v130
	v_min_f32_e32 v130, 0, v146
	v_fmac_f32_e32 v130, 0xbf317218, v128
	s_nop 6
	v_add_f32_e32 v124, v167, v124
	v_mul_f32_e64 v131, |v124|, s55
	v_exp_f32_e32 v131, v131
	v_add_f32_e32 v125, v167, v125
	v_min_f32_e32 v124, 0, v124
	v_add_f32_e32 v126, v167, v126
	v_add_f32_e32 v128, 1.0, v131
	v_mul_f32_e64 v131, |v125|, s55
	v_log_f32_e32 v128, v128
	v_exp_f32_e32 v131, v131
	v_add_f32_e32 v127, v167, v127
	v_mul_f32_e64 v132, |v127|, s55
	v_fmac_f32_e32 v124, 0xbf317218, v128
	v_add_f32_e32 v128, 1.0, v131
	v_mul_f32_e64 v131, |v126|, s55
	v_log_f32_e32 v128, v128
	v_exp_f32_e32 v131, v131
	v_exp_f32_e32 v132, v132
	v_min_f32_e32 v125, 0, v125
	v_fmac_f32_e32 v125, 0xbf317218, v128
	v_add_f32_e32 v128, 1.0, v131
	v_add_f32_e32 v131, 1.0, v132
	v_log_f32_e32 v131, v131
	v_log_f32_e32 v128, v128
	v_min_f32_e32 v127, 0, v127
	v_min_f32_e32 v126, 0, v126
	v_fmac_f32_e32 v127, 0xbf317218, v131
	v_fmac_f32_e32 v126, 0xbf317218, v128
	v_fma_f32 v127, v127, s56, 0
	v_fmamk_f32 v126, v126, 0x3d800000, v127
	v_fmamk_f32 v125, v125, 0x3d800000, v126
	v_fmamk_f32 v124, v124, 0x3d800000, v125
	v_fmamk_f32 v128, v130, 0x3d800000, v124
	v_fmamk_f32 v129, v129, 0x3d800000, v128
	v_fmamk_f32 v130, v133, 0x3d800000, v129
	v_fmamk_f32 v131, v144, 0x3d800000, v130
	v_fmamk_f32 v132, v143, 0x3d800000, v131
	v_fmamk_f32 v133, v145, 0x3d800000, v132
	v_fmamk_f32 v134, v142, 0x3d800000, v133
	v_fmamk_f32 v135, v141, 0x3d800000, v134
	v_fmamk_f32 v136, v140, 0x3d800000, v135
	v_fmamk_f32 v139, v139, 0x3d800000, v136
	v_fmamk_f32 v138, v138, 0x3d800000, v139
	v_fmamk_f32 v137, v137, 0x3d800000, v138
	ds_bpermute_b32 v140, v174, v137
	ds_bpermute_b32 v141, v173, v137
	ds_bpermute_b32 v142, v172, v137
	s_waitcnt lgkmcnt(2)
	v_cndmask_b32_e64 v140, v140, 0, s[2:3]
	s_waitcnt lgkmcnt(1)
	v_cndmask_b32_e64 v141, 0, v141, s[4:5]
	v_add_f32_e32 v140, v141, v140
	s_waitcnt lgkmcnt(0)
	v_cndmask_b32_e64 v141, 0, v142, s[6:7]
	v_add_f32_e32 v140, v141, v140
	v_add_f32_e32 v137, v140, v137
	v_add_f32_e32 v138, v140, v138
	v_add_f32_e32 v124, v140, v124
	v_add_f32_e32 v125, v140, v125
	ds_write2st64_b32 v184, v137, v138 offset0:24 offset1:26
	v_add_f32_e32 v137, v140, v139
	v_add_f32_e32 v136, v140, v136
	v_add_f32_e32 v135, v140, v135
	v_add_f32_e32 v134, v140, v134
	v_add_f32_e32 v133, v140, v133
	v_add_f32_e32 v132, v140, v132
	v_add_f32_e32 v131, v140, v131
	v_add_f32_e32 v130, v140, v130
	v_add_f32_e32 v129, v140, v129
	v_add_f32_e32 v128, v140, v128
	ds_write2st64_b32 v184, v124, v125 offset0:48 offset1:50
	v_add_f32_e32 v124, v140, v126
	v_add_f32_e32 v125, v140, v127
	ds_write2st64_b32 v184, v137, v136 offset0:28 offset1:30
	ds_write2st64_b32 v184, v135, v134 offset0:32 offset1:34
	ds_write2st64_b32 v184, v133, v132 offset0:36 offset1:38
	ds_write2st64_b32 v184, v131, v130 offset0:40 offset1:42
	ds_write2st64_b32 v184, v129, v128 offset0:44 offset1:46
	ds_write2st64_b32 v184, v124, v125 offset0:52 offset1:54
	s_waitcnt lgkmcnt(0)
	s_barrier
	s_and_saveexec_b64 s[0:1], s[8:9]
	s_cbranch_execz .LBB0_582
	ds_read_b32 v124, v175 offset:6144
	v_lshl_add_u32 v125, s59, 9, v175
	s_waitcnt lgkmcnt(0)
	ds_write_b32 v125, v124 offset:4096

.LBB0_589:
	ds_read_b128 v[124:127], v185 offset:6144
	ds_read_b128 v[128:131], v185 offset:6160
	s_waitcnt vmcnt(6)
	v_lshlrev_b32_e32 v132, 16, v96
	s_waitcnt lgkmcnt(1)
	v_mul_f32_e32 v133, 0xbfb8aa3b, v124
	v_mul_f32_e32 v135, 0xbfb8aa3b, v125
	v_exp_f32_e32 v134, v133
	v_exp_f32_e32 v135, v135
	v_and_b32_e32 v133, 0xffff0000, v96
	v_mul_f32_e32 v96, 0xbfb8aa3b, v126
	v_exp_f32_e32 v136, v96
	v_pk_mul_f32 v[132:133], v[134:135], v[132:133]
	v_mul_f32_e32 v96, 0xbfb8aa3b, v127
	v_exp_f32_e32 v137, v96
	v_cvt_pk_bf16_f32 v96, v132, v133
	v_lshlrev_b32_e32 v132, 16, v97
	v_and_b32_e32 v133, 0xffff0000, v97
	s_waitcnt lgkmcnt(0)
	v_mul_f32_e32 v97, 0xbfb8aa3b, v128
	v_exp_f32_e32 v134, v97
	v_mul_f32_e32 v97, 0xbfb8aa3b, v129
	v_exp_f32_e32 v135, v97
	v_pk_mul_f32 v[132:133], v[136:137], v[132:133]
	v_mul_f32_e32 v124, 0x3fb8aa3b, v124
	v_cvt_pk_bf16_f32 v97, v132, v133
	v_lshlrev_b32_e32 v132, 16, v98
	v_and_b32_e32 v133, 0xffff0000, v98
	v_mul_f32_e32 v98, 0xbfb8aa3b, v130
	v_pk_mul_f32 v[132:133], v[134:135], v[132:133]
	v_exp_f32_e32 v134, v98
	v_mul_f32_e32 v98, 0xbfb8aa3b, v131
	v_exp_f32_e32 v135, v98
	v_mul_f32_e32 v125, 0x3fb8aa3b, v125
	v_exp_f32_e32 v124, v124
	v_exp_f32_e32 v125, v125
	v_cvt_pk_bf16_f32 v98, v132, v133
	v_lshlrev_b32_e32 v132, 16, v99
	v_and_b32_e32 v133, 0xffff0000, v99
	v_pk_mul_f32 v[132:133], v[134:135], v[132:133]
	s_nop 0
	v_cvt_pk_bf16_f32 v99, v132, v133
	ds_write_b128 v182, v[96:99] offset:56320
	v_lshlrev_b32_e32 v96, 16, v92
	v_and_b32_e32 v97, 0xffff0000, v92
	v_pk_mul_f32 v[98:99], v[124:125], s[28:29] op_sel_hi:[1,0]
	v_mul_f32_e32 v92, 0x3fb8aa3b, v126
	v_pk_mul_f32 v[96:97], v[98:99], v[96:97]
	v_exp_f32_e32 v98, v92
	v_mul_f32_e32 v92, 0x3fb8aa3b, v127
	v_exp_f32_e32 v99, v92
	v_cvt_pk_bf16_f32 v92, v96, v97
	v_lshlrev_b32_e32 v96, 16, v93
	v_and_b32_e32 v97, 0xffff0000, v93
	v_pk_mul_f32 v[98:99], v[98:99], s[28:29] op_sel_hi:[1,0]
	v_mul_f32_e32 v93, 0x3fb8aa3b, v128
	v_pk_mul_f32 v[96:97], v[98:99], v[96:97]
	v_exp_f32_e32 v98, v93
	v_mul_f32_e32 v93, 0x3fb8aa3b, v129
	v_exp_f32_e32 v99, v93
	v_cvt_pk_bf16_f32 v93, v96, v97
	v_lshlrev_b32_e32 v96, 16, v94
	v_and_b32_e32 v97, 0xffff0000, v94
	v_pk_mul_f32 v[98:99], v[98:99], s[28:29] op_sel_hi:[1,0]
	v_mul_f32_e32 v94, 0x3fb8aa3b, v130
	v_pk_mul_f32 v[96:97], v[98:99], v[96:97]
	v_exp_f32_e32 v98, v94
	v_mul_f32_e32 v94, 0x3fb8aa3b, v131
	v_exp_f32_e32 v99, v94
	v_cvt_pk_bf16_f32 v94, v96, v97
	v_lshlrev_b32_e32 v96, 16, v95
	v_and_b32_e32 v97, 0xffff0000, v95
	v_pk_mul_f32 v[98:99], v[98:99], s[28:29] op_sel_hi:[1,0]
	s_waitcnt vmcnt(4)
	v_lshlrev_b32_e32 v126, 16, v88
	v_pk_mul_f32 v[96:97], v[98:99], v[96:97]
	v_and_b32_e32 v127, 0xffff0000, v88
	v_cvt_pk_bf16_f32 v95, v96, v97
	ds_write_b128 v182, v[92:95] offset:38912
	ds_read_b128 v[92:95], v186 offset:6144
	ds_read_b128 v[96:99], v186 offset:6160
	s_waitcnt lgkmcnt(1)
	v_mul_f32_e32 v124, 0xbfb8aa3b, v92
	v_mul_f32_e32 v125, 0xbfb8aa3b, v93
	v_exp_f32_e32 v124, v124
	v_exp_f32_e32 v125, v125
	v_mul_f32_e32 v88, 0xbfb8aa3b, v94
	v_mul_f32_e32 v92, 0x3fb8aa3b, v92
	v_mul_f32_e32 v93, 0x3fb8aa3b, v93
	v_pk_mul_f32 v[124:125], v[124:125], v[126:127]
	v_exp_f32_e32 v126, v88
	v_mul_f32_e32 v88, 0xbfb8aa3b, v95
	v_exp_f32_e32 v127, v88
	v_cvt_pk_bf16_f32 v88, v124, v125
	v_lshlrev_b32_e32 v124, 16, v89
	v_and_b32_e32 v125, 0xffff0000, v89
	s_waitcnt lgkmcnt(0)
	v_mul_f32_e32 v89, 0xbfb8aa3b, v96
	v_pk_mul_f32 v[124:125], v[126:127], v[124:125]
	v_exp_f32_e32 v126, v89
	v_mul_f32_e32 v89, 0xbfb8aa3b, v97
	v_exp_f32_e32 v127, v89
	v_cvt_pk_bf16_f32 v89, v124, v125
	v_lshlrev_b32_e32 v124, 16, v90
	v_and_b32_e32 v125, 0xffff0000, v90
	v_mul_f32_e32 v90, 0xbfb8aa3b, v98
	v_pk_mul_f32 v[124:125], v[126:127], v[124:125]
	v_exp_f32_e32 v126, v90
	v_mul_f32_e32 v90, 0xbfb8aa3b, v99
	v_exp_f32_e32 v127, v90
	v_exp_f32_e32 v92, v92
	v_exp_f32_e32 v93, v93
	v_cvt_pk_bf16_f32 v90, v124, v125
	v_lshlrev_b32_e32 v124, 16, v91
	v_and_b32_e32 v125, 0xffff0000, v91
	v_pk_mul_f32 v[124:125], v[126:127], v[124:125]
	s_nop 0
	v_cvt_pk_bf16_f32 v91, v124, v125
	ds_write_b128 v183, v[88:91] offset:56320
	v_lshlrev_b32_e32 v88, 16, v84
	v_and_b32_e32 v89, 0xffff0000, v84
	v_pk_mul_f32 v[90:91], v[92:93], s[28:29] op_sel_hi:[1,0]
	v_mul_f32_e32 v84, 0x3fb8aa3b, v94
	v_pk_mul_f32 v[88:89], v[90:91], v[88:89]
	v_exp_f32_e32 v90, v84
	v_mul_f32_e32 v84, 0x3fb8aa3b, v95
	v_exp_f32_e32 v91, v84
	v_cvt_pk_bf16_f32 v84, v88, v89
	v_lshlrev_b32_e32 v88, 16, v85
	v_and_b32_e32 v89, 0xffff0000, v85
	v_pk_mul_f32 v[90:91], v[90:91], s[28:29] op_sel_hi:[1,0]
	v_mul_f32_e32 v85, 0x3fb8aa3b, v96
	v_pk_mul_f32 v[88:89], v[90:91], v[88:89]
	v_exp_f32_e32 v90, v85
	v_mul_f32_e32 v85, 0x3fb8aa3b, v97
	v_exp_f32_e32 v91, v85
	v_cvt_pk_bf16_f32 v85, v88, v89
	v_lshlrev_b32_e32 v88, 16, v86
	v_and_b32_e32 v89, 0xffff0000, v86
	v_pk_mul_f32 v[90:91], v[90:91], s[28:29] op_sel_hi:[1,0]
	v_mul_f32_e32 v86, 0x3fb8aa3b, v98
	v_pk_mul_f32 v[88:89], v[90:91], v[88:89]
	v_exp_f32_e32 v90, v86
	v_mul_f32_e32 v86, 0x3fb8aa3b, v99
	v_exp_f32_e32 v91, v86
	v_cvt_pk_bf16_f32 v86, v88, v89
	v_lshlrev_b32_e32 v88, 16, v87
	v_and_b32_e32 v89, 0xffff0000, v87
	v_pk_mul_f32 v[90:91], v[90:91], s[28:29] op_sel_hi:[1,0]
	s_nop 0
	v_pk_mul_f32 v[88:89], v[90:91], v[88:89]
	s_nop 0
	v_cvt_pk_bf16_f32 v87, v88, v89
	ds_write_b128 v183, v[84:87] offset:38912
	s_waitcnt vmcnt(3)
	ds_write_b128 v187, v[68:71]
	s_waitcnt vmcnt(2)
	ds_write_b128 v188, v[72:75]
	s_waitcnt vmcnt(1)
	ds_write_b128 v187, v[76:79] offset:16896
	s_waitcnt vmcnt(0)
	ds_write_b128 v189, v[80:83]
	v_lshl_add_u64 v[68:69], s[36:37], 0, v[106:107]
	v_lshl_add_u64 v[70:71], s[36:37], 0, v[110:111]
	v_lshl_add_u64 v[72:73], s[36:37], 0, v[112:113]
	global_load_dwordx2 v[78:79], v[68:69], off
	global_load_dwordx2 v[76:77], v[68:69], off offset:32
	global_load_dwordx2 v[146:147], v[70:71], off
	global_load_dwordx2 v[144:145], v[72:73], off
	v_lshl_add_u64 v[68:69], s[36:37], 0, v[114:115]
	v_lshl_add_u64 v[70:71], s[36:37], 0, v[116:117]
	v_lshl_add_u64 v[72:73], s[36:37], 0, v[118:119]
	v_lshl_add_u64 v[74:75], s[36:37], 0, v[120:121]
	global_load_dwordx2 v[140:141], v[68:69], off
	global_load_dwordx2 v[138:139], v[70:71], off
	global_load_dwordx2 v[134:135], v[72:73], off
	global_load_dwordx2 v[132:133], v[74:75], off
	s_waitcnt lgkmcnt(0)
	s_barrier
	s_waitcnt lgkmcnt(0)
	ds_read_b128 v[68:71], v190 offset:56320
	ds_read_b128 v[244:247], v190 offset:56384
	ds_read_b128 v[248:251], v177 offset:38912
	ds_read_b128 v[252:255], v177 offset:38976
	ds_read_b128 v[88:91], v190 offset:56448
	ds_read_b128 v[92:95], v190 offset:56512
	ds_read_b128 v[72:75], v177 offset:39040
	ds_read_b128 v[96:99], v177 offset:39104
	s_waitcnt lgkmcnt(5)
	v_mfma_f32_16x16x32_bf16 v[68:71], v[68:71], v[248:251], 0
	s_nop 0
	s_nop 0
	v_add_u32_e32 v199, 0x9800, v195
	v_add_u32_e32 v232, 0xa800, v195
	s_waitcnt lgkmcnt(4)
	v_mfma_f32_16x16x32_bf16 v[68:71], v[244:247], v[252:255], v[68:71]
	s_nop 0
	s_nop 0
	v_add_u32_e32 v236, 0xb800, v195
	v_add_u32_e32 v237, 0xc800, v195
	s_waitcnt lgkmcnt(1)
	v_mfma_f32_16x16x32_bf16 v[68:71], v[88:91], v[72:75], v[68:71]
	v_mov_b32_e32 v88, s29
	v_cvt_pk_bf16_f32 v204, v32, v33
	v_cvt_pk_bf16_f32 v205, v34, v35
	s_waitcnt lgkmcnt(0)
	v_mfma_f32_16x16x32_bf16 v[68:71], v[92:95], v[96:99], v[68:71]
	v_cvt_pk_bf16_f32 v206, v64, v65
	v_cvt_pk_bf16_f32 v207, v66, v67
	s_add_u32 s0, s60, s46
	s_addc_u32 s1, s61, 0
	s_add_u32 s0, s0, 0x16e41000
	s_nop 2
	v_cndmask_b32_e64 v68, v68, v88, s[10:11]
	v_cndmask_b32_e64 v69, v69, 0, s[12:13]
	v_cndmask_b32_e64 v70, v70, 0, s[14:15]
	v_cndmask_b32_e64 v71, v71, 0, s[16:17]
	v_cvt_pk_bf16_f32 v68, v68, v69
	v_cvt_pk_bf16_f32 v69, v70, v71
	ds_write_b64 v191, v[68:69]
	ds_read_b128 v[244:247], v192 offset:56320
	ds_read_b128 v[88:91], v192 offset:56384
	ds_read_b128 v[80:83], v192 offset:56448
	ds_read_b128 v[84:87], v192 offset:56512
	s_waitcnt lgkmcnt(3)
	v_mfma_f32_16x16x32_bf16 v[68:71], v[244:247], v[248:251], 0
	s_nop 0
	s_addc_u32 s1, s1, 0
	v_cvt_pk_bf16_f32 v208, v16, v17
	s_waitcnt lgkmcnt(2)
	v_mfma_f32_16x16x32_bf16 v[68:71], v[88:91], v[252:255], v[68:71]
	s_nop 0
	v_cvt_pk_bf16_f32 v209, v18, v19
	v_cvt_pk_bf16_f32 v210, v28, v29
	s_waitcnt lgkmcnt(1)
	v_mfma_f32_16x16x32_bf16 v[68:71], v[80:83], v[72:75], v[68:71]
	v_mov_b32_e32 v72, s29
	v_cvt_pk_bf16_f32 v211, v30, v31
	v_cvt_pk_bf16_f32 v224, v44, v45
	s_waitcnt lgkmcnt(0)
	v_mfma_f32_16x16x32_bf16 v[68:71], v[84:87], v[96:99], v[68:71]
	v_cvt_pk_bf16_f32 v225, v46, v47
	v_cvt_pk_bf16_f32 v226, v52, v53
	v_cvt_pk_bf16_f32 v227, v54, v55
	v_cvt_pk_bf16_f32 v228, v56, v57
	v_cvt_pk_bf16_f32 v229, v58, v59
	s_nop 2
	v_cndmask_b32_e64 v68, v68, v72, s[18:19]
	v_cndmask_b32_e64 v69, v69, 0, s[20:21]
	v_cndmask_b32_e64 v70, v70, 0, s[22:23]
	v_cndmask_b32_e64 v71, v71, 0, s[24:25]
	v_cvt_pk_bf16_f32 v68, v68, v69
	v_cvt_pk_bf16_f32 v69, v70, v71
	ds_write_b64 v193, v[68:69]
	s_waitcnt lgkmcnt(0)
	s_barrier
	s_waitcnt lgkmcnt(0)
	ds_read_b64_tr_b16 v[70:71], v198 offset:2112
	ds_read_b64_tr_b16 v[68:69], v198
	ds_read_b64_tr_b16 v[246:247], v198 offset:2144
	ds_read_b64_tr_b16 v[244:245], v198 offset:32
	ds_read_b128 v[248:251], v194
	ds_read_b128 v[252:255], v194 offset:64
	ds_read_b128 v[92:95], v194 offset:2304
	ds_read_b128 v[96:99], v194 offset:2368
	ds_read_b128 v[128:131], v194 offset:4608
	ds_read_b64_tr_b16 v[148:149], v198 offset:16896
	ds_read_b64_tr_b16 v[150:151], v198 offset:19008
	ds_read_b128 v[156:159], v194 offset:4672
	ds_read_b64_tr_b16 v[202:203], v198 offset:19040
	ds_read_b64_tr_b16 v[200:201], v198 offset:16928
	s_waitcnt lgkmcnt(9)
	v_mfma_f32_16x16x32_bf16 v[88:91], v[68:71], v[248:251], 0
	v_cvt_pk_bf16_f32 v230, v60, v61
	v_cvt_pk_bf16_f32 v231, v62, v63
	v_mfma_f32_16x16x32_bf16 v[80:83], v[244:247], v[248:251], 0
	ds_read_b128 v[248:251], v194 offset:6912
	s_waitcnt lgkmcnt(8)
	v_mfma_f32_16x16x32_bf16 v[124:127], v[68:71], v[92:95], 0
	v_mfma_f32_16x16x32_bf16 v[92:95], v[244:247], v[92:95], 0
	s_waitcnt lgkmcnt(6)
	v_mfma_f32_16x16x32_bf16 v[160:163], v[68:71], v[128:131], 0
	s_waitcnt lgkmcnt(4)
	v_mfma_f32_16x16x32_bf16 v[88:91], v[148:151], v[252:255], v[88:91]
	s_waitcnt lgkmcnt(1)
	v_mfma_f32_16x16x32_bf16 v[80:83], v[200:203], v[252:255], v[80:83]
	ds_read_b128 v[252:255], v194 offset:6976
	v_mfma_f32_16x16x32_bf16 v[84:87], v[148:151], v[96:99], v[124:127]
	v_mfma_f32_16x16x32_bf16 v[92:95], v[200:203], v[96:99], v[92:95]
	v_mfma_f32_16x16x32_bf16 v[96:99], v[244:247], v[128:131], 0
	v_mfma_f32_16x16x32_bf16 v[124:127], v[148:151], v[156:159], v[160:163]
	ds_read2_b64 v[160:163], v236 offset0:64 offset1:68
	v_mfma_f32_16x16x32_bf16 v[96:99], v[200:203], v[156:159], v[96:99]
	s_nop 0
	s_nop 0
	s_nop 0
	s_waitcnt lgkmcnt(2)
	v_mfma_f32_16x16x32_bf16 v[68:71], v[68:71], v[248:251], 0
	v_mfma_f32_16x16x32_bf16 v[72:75], v[244:247], v[248:251], 0
	ds_read2_b64 v[244:247], v199 offset1:4
	ds_read2_b64 v[248:251], v232 offset0:32 offset1:36
	v_cvt_pk_bf16_f32 v128, v8, v9
	v_cvt_pk_bf16_f32 v129, v10, v11
	v_cvt_pk_bf16_f32 v130, v12, v13
	s_waitcnt lgkmcnt(3)
	v_mfma_f32_16x16x32_bf16 v[68:71], v[148:151], v[252:255], v[68:71]
	v_cvt_pk_bf16_f32 v131, v14, v15
	s_nop 0
	v_mfma_f32_16x16x32_bf16 v[72:75], v[200:203], v[252:255], v[72:75]
	ds_read2_b64 v[252:255], v237 offset0:96 offset1:100
	v_cvt_pk_bf16_f32 v156, v4, v5
	v_cvt_pk_bf16_f32 v157, v6, v7
	v_cvt_pk_bf16_f32 v158, v36, v37
	v_cvt_pk_bf16_f32 v159, v38, v39
	s_waitcnt lgkmcnt(2)
	v_mfma_f32_16x16x32_bf16 v[88:91], v[128:131], v[244:247], v[88:91]
	v_cvt_pk_bf16_f32 v200, v24, v25
	v_cvt_pk_bf16_f32 v201, v26, v27
	v_cvt_pk_bf16_f32 v202, v40, v41
	v_mfma_f32_16x16x32_bf16 v[80:83], v[156:159], v[244:247], v[80:83]
	ds_read2_b64 v[244:247], v199 offset0:8 offset1:12
	s_nop 0
	v_cvt_pk_bf16_f32 v203, v42, v43
	s_waitcnt lgkmcnt(2)
	v_mfma_f32_16x16x32_bf16 v[84:87], v[128:131], v[248:251], v[84:87]
	v_mfma_f32_16x16x32_bf16 v[92:95], v[156:159], v[248:251], v[92:95]
	ds_read2_b64 v[248:251], v232 offset0:40 offset1:44
	s_nop 0
	v_mfma_f32_16x16x32_bf16 v[124:127], v[128:131], v[160:163], v[124:127]
	v_mfma_f32_16x16x32_bf16 v[96:99], v[156:159], v[160:163], v[96:99]
	s_waitcnt lgkmcnt(2)
	v_mfma_f32_16x16x32_bf16 v[68:71], v[128:131], v[252:255], v[68:71]
	s_nop 0
	s_nop 0
	v_mfma_f32_16x16x32_bf16 v[148:151], v[156:159], v[252:255], v[72:75]
	ds_read2_b64 v[252:255], v236 offset0:72 offset1:76
	ds_read2_b64 v[156:159], v237 offset0:104 offset1:108
	ds_read2_b64 v[212:215], v199 offset0:16 offset1:20
	s_nop 2
	s_nop 0
	s_nop 0
	s_nop 0
	s_waitcnt lgkmcnt(4)
	v_mfma_f32_16x16x32_bf16 v[88:91], v[200:203], v[244:247], v[88:91]
	v_mfma_f32_16x16x32_bf16 v[80:83], v[204:207], v[244:247], v[80:83]
	ds_read2_b64 v[244:247], v232 offset0:48 offset1:52
	v_lshl_add_u64 v[128:129], s[0:1], 0, v[108:109]
	v_add_co_u32_e64 v130, s[0:1], s47, v128
	s_waitcnt lgkmcnt(3)
	v_mfma_f32_16x16x32_bf16 v[216:219], v[200:203], v[252:255], v[124:127]
	v_addc_co_u32_e64 v131, s[0:1], 0, v129, s[0:1]
	v_mfma_f32_16x16x32_bf16 v[96:99], v[204:207], v[252:255], v[96:99]
	ds_read2_b64 v[252:255], v236 offset0:80 offset1:84
	ds_read2_b64 v[220:223], v237 offset0:112 offset1:116
	v_add_co_u32_e64 v72, s[0:1], s52, v128
	s_nop 1
	v_addc_co_u32_e64 v73, s[0:1], 0, v129, s[0:1]
	v_mfma_f32_16x16x32_bf16 v[84:87], v[200:203], v[248:251], v[84:87]
	s_waitcnt lgkmcnt(4)
	v_mfma_f32_16x16x32_bf16 v[200:203], v[200:203], v[156:159], v[68:71]
	s_nop 2
	v_add_co_u32_e64 v68, s[0:1], s53, v128
	v_mfma_f32_16x16x32_bf16 v[92:95], v[204:207], v[248:251], v[92:95]
	ds_read2_b64 v[248:251], v199 offset0:24 offset1:28
	s_nop 0
	v_addc_co_u32_e64 v69, s[0:1], 0, v129, s[0:1]
	global_load_dwordx2 v[162:163], v[128:129], off
	global_load_dwordx2 v[152:153], v[128:129], off offset:32
	global_load_dwordx2 v[142:143], v[130:131], off
	global_load_dwordx2 v[136:137], v[130:131], off offset:32
	s_nop 0
	global_load_dwordx2 v[130:131], v[72:73], off
	global_load_dwordx2 v[128:129], v[72:73], off offset:32
	global_load_dwordx2 v[126:127], v[68:69], off
	global_load_dwordx2 v[124:125], v[68:69], off offset:32
	s_nop 0
	global_load_dwordx4 v[72:75], v[122:123], off
	global_load_dwordx4 v[68:71], v[122:123], off offset:64
	v_mfma_f32_16x16x32_bf16 v[156:159], v[204:207], v[156:159], v[148:151]
	v_cvt_pk_bf16_f32 v204, v20, v21
	v_cvt_pk_bf16_f32 v205, v22, v23
	v_cvt_pk_bf16_f32 v206, v48, v49
	v_cvt_pk_bf16_f32 v207, v50, v51
	s_waitcnt lgkmcnt(4)
	v_mfma_f32_16x16x32_bf16 v[88:91], v[208:211], v[212:215], v[88:91]
	s_nop 0
	v_mfma_f32_16x16x32_bf16 v[80:83], v[204:207], v[212:215], v[80:83]
	s_nop 0
	s_nop 0
	s_waitcnt lgkmcnt(2)
	v_mfma_f32_16x16x32_bf16 v[216:219], v[208:211], v[252:255], v[216:219]
	v_mfma_f32_16x16x32_bf16 v[212:215], v[204:207], v[252:255], v[96:99]
	s_nop 2
	s_nop 0
	ds_read2_b64 v[232:235], v232 offset0:56 offset1:60
	s_waitcnt lgkmcnt(1)
	v_mfma_f32_16x16x32_bf16 v[88:91], v[224:227], v[248:251], v[88:91]
	v_mfma_f32_16x16x32_bf16 v[84:87], v[208:211], v[244:247], v[84:87]
	v_mfma_f32_16x16x32_bf16 v[92:95], v[204:207], v[244:247], v[92:95]
	s_waitcnt vmcnt(17)
	v_lshlrev_b32_e32 v148, 16, v78
	v_and_b32_e32 v149, 0xffff0000, v78
	v_lshlrev_b32_e32 v78, 16, v79
	v_and_b32_e32 v79, 0xffff0000, v79
	s_nop 0
	v_pk_add_f32 v[150:151], v[90:91], v[78:79]
	v_mfma_f32_16x16x32_bf16 v[78:81], v[228:231], v[248:251], v[80:83]
	v_add_f32_e64 v148, v88, v148
	v_add_f32_e64 v149, v89, v149
	s_waitcnt vmcnt(16)
	v_lshlrev_b32_e32 v88, 16, v76
	v_pk_mul_f32 v[160:161], v[148:149], v[148:149]
	v_and_b32_e32 v89, 0xffff0000, v76
	v_lshlrev_b32_e32 v76, 16, v77
	v_and_b32_e32 v77, 0xffff0000, v77
	v_mfma_f32_16x16x32_bf16 v[204:207], v[204:207], v[220:223], v[156:159]
	v_mul_f32_e64 v82, v150, v150
	v_mul_f32_e64 v83, v151, v151
	s_nop 0
	v_pk_add_f32 v[158:159], v[80:81], v[76:77]
	v_add_f32_e32 v80, v160, v161
	v_pk_add_f32 v[156:157], v[78:79], v[88:89]
	v_add_f32_e32 v80, v82, v80
	v_pk_mul_f32 v[76:77], v[156:157], v[156:157]
	v_add_f32_e32 v80, v83, v80
	v_add_f32_e32 v76, v76, v80
	v_pk_mul_f32 v[78:79], v[158:159], v[158:159]
	v_add_f32_e32 v76, v77, v76
	v_add_f32_e32 v76, v78, v76
	v_add_f32_e32 v76, v79, v76
	ds_bpermute_b32 v77, v178, v76
	v_mfma_f32_16x16x32_bf16 v[200:203], v[208:211], v[220:223], v[200:203]
	ds_read2_b64 v[208:211], v236 offset0:88 offset1:92
	ds_read2_b64 v[236:239], v237 offset0:120 offset1:124
	s_waitcnt lgkmcnt(2)
	v_add_f32_e32 v160, v76, v77
	ds_bpermute_b32 v161, v179, v160
	v_mfma_f32_16x16x32_bf16 v[96:99], v[224:227], v[232:235], v[84:87]
	v_mfma_f32_16x16x32_bf16 v[92:95], v[228:231], v[232:235], v[92:95]
	s_waitcnt lgkmcnt(2)
	v_mfma_f32_16x16x32_bf16 v[88:91], v[224:227], v[208:211], v[216:219]
	v_mfma_f32_16x16x32_bf16 v[84:87], v[228:231], v[208:211], v[212:215]
	s_waitcnt lgkmcnt(1)
	v_mfma_f32_16x16x32_bf16 v[80:83], v[224:227], v[236:239], v[200:203]
	v_mfma_f32_16x16x32_bf16 v[76:79], v[228:231], v[236:239], v[204:207]
	s_and_saveexec_b64 s[0:1], s[6:7]
	s_waitcnt lgkmcnt(0)
	s_cbranch_execz .LBB0_591
	s_waitcnt lgkmcnt(0)
	v_add_f32_e32 v160, v160, v161
	ds_write_b32 v181, v160

.LBB0_663:
	ds_read_b128 v[134:137], v201 offset:6144
	ds_read_b128 v[138:141], v201 offset:6160
	s_waitcnt vmcnt(6)
	v_lshlrev_b32_e32 v144, 16, v98
	v_and_b32_e32 v145, 0xffff0000, v98
	v_add_u32_e32 v215, 0x9800, v212
	s_waitcnt lgkmcnt(1)
	v_mul_f32_e32 v109, 0xbfb8aa3b, v134
	v_exp_f32_e32 v142, v109
	v_mul_f32_e32 v109, 0xbfb8aa3b, v135
	v_exp_f32_e32 v143, v109
	v_mul_f32_e32 v109, 0xbfb8aa3b, v136
	v_cvt_pk_bf16_f32 v156, v10, v11
	v_cvt_pk_bf16_f32 v157, v12, v13
	v_pk_mul_f32 v[142:143], v[142:143], v[144:145]
	v_lshlrev_b32_e32 v144, 16, v99
	v_cvt_pk_bf16_f32 v98, v142, v143
	v_exp_f32_e32 v142, v109
	v_mul_f32_e32 v109, 0xbfb8aa3b, v137
	v_exp_f32_e32 v143, v109
	v_and_b32_e32 v145, 0xffff0000, v99
	s_waitcnt lgkmcnt(0)
	v_mul_f32_e32 v109, 0xbfb8aa3b, v138
	v_cvt_pk_bf16_f32 v158, v26, v27
	v_pk_mul_f32 v[142:143], v[142:143], v[144:145]
	v_lshlrev_b32_e32 v144, 16, v100
	v_cvt_pk_bf16_f32 v99, v142, v143
	v_exp_f32_e32 v142, v109
	v_mul_f32_e32 v109, 0xbfb8aa3b, v139
	v_exp_f32_e32 v143, v109
	v_and_b32_e32 v145, 0xffff0000, v100
	v_mul_f32_e32 v109, 0xbfb8aa3b, v140
	v_cvt_pk_bf16_f32 v159, v28, v29
	v_pk_mul_f32 v[142:143], v[142:143], v[144:145]
	v_lshlrev_b32_e32 v144, 16, v101
	v_cvt_pk_bf16_f32 v100, v142, v143
	v_exp_f32_e32 v142, v109
	v_mul_f32_e32 v109, 0xbfb8aa3b, v141
	v_exp_f32_e32 v143, v109
	v_and_b32_e32 v145, 0xffff0000, v101
	v_add_u32_e32 v216, 0xa800, v212
	v_add_u32_e32 v217, 0xb800, v212
	v_pk_mul_f32 v[142:143], v[142:143], v[144:145]
	v_add_u32_e32 v218, 0xc800, v212
	v_cvt_pk_bf16_f32 v101, v142, v143
	ds_write_b128 v181, v[98:101] offset:56320
	v_mul_f32_e32 v98, 0x3fb8aa3b, v134
	v_mul_f32_e32 v99, 0x3fb8aa3b, v135
	v_exp_f32_e32 v98, v98
	v_exp_f32_e32 v99, v99
	v_lshlrev_b32_e32 v100, 16, v94
	v_and_b32_e32 v101, 0xffff0000, v94
	s_mov_b32 s62, 0x8000
	v_pk_mul_f32 v[98:99], v[98:99], s[50:51] op_sel_hi:[1,0]
	s_add_u32 s76, s76, 0x60000
	v_pk_mul_f32 v[98:99], v[98:99], v[100:101]
	v_lshlrev_b32_e32 v100, 16, v95
	v_cvt_pk_bf16_f32 v94, v98, v99
	v_mul_f32_e32 v98, 0x3fb8aa3b, v136
	v_mul_f32_e32 v99, 0x3fb8aa3b, v137
	v_exp_f32_e32 v98, v98
	v_exp_f32_e32 v99, v99
	v_and_b32_e32 v101, 0xffff0000, v95
	s_waitcnt vmcnt(4)
	v_lshlrev_b32_e32 v136, 16, v90
	v_and_b32_e32 v137, 0xffff0000, v90
	v_pk_mul_f32 v[98:99], v[98:99], s[50:51] op_sel_hi:[1,0]
	s_addc_u32 s77, s77, 0
	v_pk_mul_f32 v[98:99], v[98:99], v[100:101]
	v_lshlrev_b32_e32 v100, 16, v96
	v_cvt_pk_bf16_f32 v95, v98, v99
	v_mul_f32_e32 v98, 0x3fb8aa3b, v138
	v_mul_f32_e32 v99, 0x3fb8aa3b, v139
	v_exp_f32_e32 v98, v98
	v_exp_f32_e32 v99, v99
	v_and_b32_e32 v101, 0xffff0000, v96
	s_add_i32 s64, s64, 64
	v_pk_mul_f32 v[98:99], v[98:99], s[50:51] op_sel_hi:[1,0]
	s_nop 0
	v_pk_mul_f32 v[98:99], v[98:99], v[100:101]
	v_lshlrev_b32_e32 v100, 16, v97
	v_cvt_pk_bf16_f32 v96, v98, v99
	v_mul_f32_e32 v98, 0x3fb8aa3b, v140
	v_mul_f32_e32 v99, 0x3fb8aa3b, v141
	v_exp_f32_e32 v98, v98
	v_exp_f32_e32 v99, v99
	v_and_b32_e32 v101, 0xffff0000, v97
	v_pk_mul_f32 v[98:99], v[98:99], s[50:51] op_sel_hi:[1,0]
	s_nop 0
	v_pk_mul_f32 v[98:99], v[98:99], v[100:101]
	s_nop 0
	v_cvt_pk_bf16_f32 v97, v98, v99
	ds_write_b128 v181, v[94:97] offset:38912
	ds_read_b128 v[94:97], v202 offset:6144
	ds_read_b128 v[98:101], v202 offset:6160
	s_waitcnt lgkmcnt(1)
	v_mul_f32_e32 v109, 0xbfb8aa3b, v94
	v_exp_f32_e32 v134, v109
	v_mul_f32_e32 v109, 0xbfb8aa3b, v95
	v_exp_f32_e32 v135, v109
	v_mul_f32_e32 v109, 0xbfb8aa3b, v96
	v_pk_mul_f32 v[134:135], v[134:135], v[136:137]
	s_nop 0
	v_cvt_pk_bf16_f32 v90, v134, v135
	v_exp_f32_e32 v134, v109
	v_mul_f32_e32 v109, 0xbfb8aa3b, v97
	v_exp_f32_e32 v135, v109
	v_lshlrev_b32_e32 v136, 16, v91
	v_and_b32_e32 v137, 0xffff0000, v91
	s_waitcnt lgkmcnt(0)
	v_mul_f32_e32 v109, 0xbfb8aa3b, v98
	v_pk_mul_f32 v[134:135], v[134:135], v[136:137]
	v_lshlrev_b32_e32 v136, 16, v92
	v_cvt_pk_bf16_f32 v91, v134, v135
	v_exp_f32_e32 v134, v109
	v_mul_f32_e32 v109, 0xbfb8aa3b, v99
	v_exp_f32_e32 v135, v109
	v_and_b32_e32 v137, 0xffff0000, v92
	v_mul_f32_e32 v109, 0xbfb8aa3b, v100
	v_pk_mul_f32 v[134:135], v[134:135], v[136:137]
	s_nop 0
	v_cvt_pk_bf16_f32 v92, v134, v135
	v_exp_f32_e32 v134, v109
	v_mul_f32_e32 v109, 0xbfb8aa3b, v101
	v_exp_f32_e32 v135, v109
	v_lshlrev_b32_e32 v136, 16, v93
	v_and_b32_e32 v137, 0xffff0000, v93
	v_pk_mul_f32 v[134:135], v[134:135], v[136:137]
	s_nop 0
	v_cvt_pk_bf16_f32 v93, v134, v135
	ds_write_b128 v182, v[90:93] offset:56320
	v_mul_f32_e32 v90, 0x3fb8aa3b, v94
	v_mul_f32_e32 v91, 0x3fb8aa3b, v95
	v_exp_f32_e32 v90, v90
	v_exp_f32_e32 v91, v91
	v_lshlrev_b32_e32 v92, 16, v70
	v_and_b32_e32 v93, 0xffff0000, v70
	v_pk_mul_f32 v[90:91], v[90:91], s[50:51] op_sel_hi:[1,0]
	s_nop 0
	v_pk_mul_f32 v[90:91], v[90:91], v[92:93]
	v_lshlrev_b32_e32 v92, 16, v71
	v_cvt_pk_bf16_f32 v70, v90, v91
	v_mul_f32_e32 v90, 0x3fb8aa3b, v96
	v_mul_f32_e32 v91, 0x3fb8aa3b, v97
	v_exp_f32_e32 v90, v90
	v_exp_f32_e32 v91, v91
	v_and_b32_e32 v93, 0xffff0000, v71
	v_pk_mul_f32 v[90:91], v[90:91], s[50:51] op_sel_hi:[1,0]
	s_nop 0
	v_pk_mul_f32 v[90:91], v[90:91], v[92:93]
	v_lshlrev_b32_e32 v92, 16, v72
	v_cvt_pk_bf16_f32 v71, v90, v91
	v_mul_f32_e32 v90, 0x3fb8aa3b, v98
	v_mul_f32_e32 v91, 0x3fb8aa3b, v99
	v_exp_f32_e32 v90, v90
	v_exp_f32_e32 v91, v91
	v_and_b32_e32 v93, 0xffff0000, v72
	v_pk_mul_f32 v[90:91], v[90:91], s[50:51] op_sel_hi:[1,0]
	s_nop 0
	v_pk_mul_f32 v[90:91], v[90:91], v[92:93]
	v_lshlrev_b32_e32 v92, 16, v73
	v_cvt_pk_bf16_f32 v72, v90, v91
	v_mul_f32_e32 v90, 0x3fb8aa3b, v100
	v_mul_f32_e32 v91, 0x3fb8aa3b, v101
	v_exp_f32_e32 v90, v90
	v_exp_f32_e32 v91, v91
	v_and_b32_e32 v93, 0xffff0000, v73
	v_pk_mul_f32 v[90:91], v[90:91], s[50:51] op_sel_hi:[1,0]
	s_nop 0
	v_pk_mul_f32 v[90:91], v[90:91], v[92:93]
	s_nop 0
	v_cvt_pk_bf16_f32 v73, v90, v91
	ds_write_b128 v182, v[70:73] offset:38912
	s_waitcnt vmcnt(3)
	ds_write_b128 v203, v[74:77]
	s_waitcnt vmcnt(2)
	ds_write_b128 v204, v[78:81]
	s_waitcnt vmcnt(1)
	ds_write_b128 v203, v[82:85] offset:16896
	s_waitcnt vmcnt(0)
	ds_write_b128 v205, v[86:89]
	s_waitcnt lgkmcnt(0)
	s_barrier
	s_waitcnt lgkmcnt(0)
	ds_read_b128 v[70:73], v206 offset:56320
	ds_read_b128 v[232:235], v180 offset:38912
	ds_read_b128 v[236:239], v206 offset:56384
	ds_read_b128 v[82:85], v180 offset:38976
	ds_read_b128 v[244:247], v206 offset:56448
	ds_read_b128 v[86:89], v180 offset:39040
	ds_read_b128 v[78:81], v206 offset:56512
	ds_read_b128 v[90:93], v180 offset:39104
	s_waitcnt lgkmcnt(6)
	v_mfma_f32_16x16x32_bf16 v[70:73], v[70:73], v[232:235], 0
	s_waitcnt lgkmcnt(4)
	v_mfma_f32_16x16x32_bf16 v[70:73], v[236:239], v[82:85], v[70:73]
	s_nop 0
	s_nop 0
	s_waitcnt lgkmcnt(2)
	v_mfma_f32_16x16x32_bf16 v[70:73], v[244:247], v[86:89], v[70:73]
	s_nop 0
	s_nop 0
	s_waitcnt lgkmcnt(0)
	v_mfma_f32_16x16x32_bf16 v[70:73], v[78:81], v[90:93], v[70:73]
	v_mov_b32_e32 v78, s49
	s_nop 6
	v_cndmask_b32_e64 v78, v70, v78, s[12:13]
	v_cndmask_b32_e64 v70, v78, v70, s[14:15]
	v_cndmask_b32_e64 v71, 0, v71, s[14:15]
	v_cndmask_b32_e64 v72, v72, 0, s[16:17]
	v_cndmask_b32_e64 v73, v73, 0, s[18:19]
	v_cvt_pk_bf16_f32 v70, v70, v71
	v_cvt_pk_bf16_f32 v71, v72, v73
	ds_write_b64 v207, v[70:71]
	ds_read_b128 v[248:251], v208 offset:56320
	ds_read_b128 v[252:255], v208 offset:56384
	ds_read_b128 v[236:239], v208 offset:56448
	ds_read_b128 v[74:77], v208 offset:56512
	s_waitcnt lgkmcnt(3)
	v_mfma_f32_16x16x32_bf16 v[70:73], v[248:251], v[232:235], 0
	s_nop 0
	s_waitcnt lgkmcnt(2)
	v_mfma_f32_16x16x32_bf16 v[70:73], v[252:255], v[82:85], v[70:73]
	s_nop 0
	s_waitcnt lgkmcnt(1)
	v_mfma_f32_16x16x32_bf16 v[70:73], v[236:239], v[86:89], v[70:73]
	s_nop 0
	s_waitcnt lgkmcnt(0)
	v_mfma_f32_16x16x32_bf16 v[70:73], v[74:77], v[90:93], v[70:73]
	v_mov_b32_e32 v74, s49
	s_nop 6
	v_cndmask_b32_e64 v74, v70, v74, s[20:21]
	v_cndmask_b32_e64 v70, v74, v70, s[22:23]
	v_cndmask_b32_e64 v71, 0, v71, s[22:23]
	v_cndmask_b32_e64 v72, v72, 0, s[24:25]
	v_cndmask_b32_e64 v73, v73, 0, s[26:27]
	v_cvt_pk_bf16_f32 v70, v70, v71
	v_cvt_pk_bf16_f32 v71, v72, v73
	ds_write_b64 v209, v[70:71]
	s_waitcnt lgkmcnt(0)
	s_barrier
	s_waitcnt lgkmcnt(0)
	ds_read_b64_tr_b16 v[80:81], v210 offset:2112
	ds_read_b64_tr_b16 v[78:79], v210
	ds_read_b64_tr_b16 v[82:83], v210 offset:32
	ds_read_b64_tr_b16 v[70:71], v210 offset:16896
	ds_read_b64_tr_b16 v[72:73], v210 offset:19008
	ds_read_b64_tr_b16 v[84:85], v210 offset:2144
	ds_read_b64_tr_b16 v[74:75], v210 offset:16928
	ds_read_b64_tr_b16 v[76:77], v210 offset:19040
	ds_read_b128 v[232:235], v211
	ds_read_b128 v[236:239], v211 offset:64
	ds_read_b128 v[244:247], v211 offset:2368
	ds_read_b128 v[248:251], v211 offset:4672
	ds_read_b128 v[252:255], v211 offset:6976
	ds_read2_b64 v[160:163], v215 offset1:4
	s_waitcnt lgkmcnt(5)
	v_mfma_f32_16x16x32_bf16 v[90:93], v[78:81], v[232:235], 0
	s_nop 0
	s_nop 0
	s_nop 0
	v_mfma_f32_16x16x32_bf16 v[86:89], v[82:85], v[232:235], 0
	ds_read_b128 v[232:235], v211 offset:2304
	s_waitcnt lgkmcnt(5)
	v_mfma_f32_16x16x32_bf16 v[90:93], v[70:73], v[236:239], v[90:93]
	v_mfma_f32_16x16x32_bf16 v[86:89], v[74:77], v[236:239], v[86:89]
	ds_read_b128 v[236:239], v211 offset:4608
	s_nop 0
	s_waitcnt lgkmcnt(1)
	v_mfma_f32_16x16x32_bf16 v[98:101], v[78:81], v[232:235], 0
	v_mfma_f32_16x16x32_bf16 v[94:97], v[82:85], v[232:235], 0
	ds_read_b128 v[232:235], v211 offset:6912
	v_mfma_f32_16x16x32_bf16 v[98:101], v[70:73], v[244:247], v[98:101]
	v_mfma_f32_16x16x32_bf16 v[94:97], v[74:77], v[244:247], v[94:97]
	ds_read2_b64 v[244:247], v216 offset0:32 offset1:36
	s_nop 0
	s_waitcnt lgkmcnt(2)
	v_mfma_f32_16x16x32_bf16 v[138:141], v[78:81], v[236:239], 0
	v_mfma_f32_16x16x32_bf16 v[134:137], v[82:85], v[236:239], 0
	ds_read2_b64 v[236:239], v217 offset0:64 offset1:68
	v_mfma_f32_16x16x32_bf16 v[138:141], v[70:73], v[248:251], v[138:141]
	v_mfma_f32_16x16x32_bf16 v[134:137], v[74:77], v[248:251], v[134:137]
	ds_read2_b64 v[248:251], v218 offset0:96 offset1:100
	s_nop 0
	s_waitcnt lgkmcnt(3)
	v_mfma_f32_16x16x32_bf16 v[146:149], v[78:81], v[232:235], 0
	v_mfma_f32_16x16x32_bf16 v[142:145], v[82:85], v[232:235], 0
	ds_read2_b64 v[232:235], v215 offset0:8 offset1:12
	v_mfma_f32_16x16x32_bf16 v[146:149], v[70:73], v[252:255], v[146:149]
	v_mfma_f32_16x16x32_bf16 v[142:145], v[74:77], v[252:255], v[142:145]
	ds_read2_b64 v[252:255], v216 offset0:40 offset1:44
	v_cvt_pk_bf16_f32 v150, v6, v7
	v_cvt_pk_bf16_f32 v151, v8, v9
	v_cvt_pk_bf16_f32 v152, v22, v23
	v_cvt_pk_bf16_f32 v153, v24, v25
	v_mfma_f32_16x16x32_bf16 v[86:89], v[156:159], v[160:163], v[86:89]
	s_nop 0
	v_mfma_f32_16x16x32_bf16 v[90:93], v[150:153], v[160:163], v[90:93]
	s_nop 0
	s_waitcnt lgkmcnt(4)
	v_mfma_f32_16x16x32_bf16 v[98:101], v[150:153], v[244:247], v[98:101]
	v_mfma_f32_16x16x32_bf16 v[94:97], v[156:159], v[244:247], v[94:97]
	ds_read2_b64 v[244:247], v217 offset0:72 offset1:76
	s_nop 0
	s_waitcnt lgkmcnt(4)
	v_mfma_f32_16x16x32_bf16 v[138:141], v[150:153], v[236:239], v[138:141]
	v_mfma_f32_16x16x32_bf16 v[134:137], v[156:159], v[236:239], v[134:137]
	ds_read2_b64 v[236:239], v218 offset0:104 offset1:108
	s_nop 0
	s_waitcnt lgkmcnt(4)
	v_mfma_f32_16x16x32_bf16 v[146:149], v[150:153], v[248:251], v[146:149]
	v_cvt_pk_bf16_f32 v150, v14, v15
	v_cvt_pk_bf16_f32 v151, v16, v17
	v_cvt_pk_bf16_f32 v152, v38, v39
	v_mfma_f32_16x16x32_bf16 v[142:145], v[156:159], v[248:251], v[142:145]
	ds_read2_b64 v[248:251], v215 offset0:16 offset1:20
	v_cvt_pk_bf16_f32 v153, v40, v41
	v_cvt_pk_bf16_f32 v156, v18, v19
	v_cvt_pk_bf16_f32 v157, v20, v21
	v_cvt_pk_bf16_f32 v158, v42, v43
	v_cvt_pk_bf16_f32 v159, v44, v45
	s_nop 0
	s_waitcnt lgkmcnt(4)
	v_mfma_f32_16x16x32_bf16 v[90:93], v[150:153], v[232:235], v[90:93]
	v_mfma_f32_16x16x32_bf16 v[86:89], v[156:159], v[232:235], v[86:89]
	ds_read2_b64 v[232:235], v216 offset0:48 offset1:52
	s_nop 0
	s_waitcnt lgkmcnt(4)
	v_mfma_f32_16x16x32_bf16 v[98:101], v[150:153], v[252:255], v[98:101]
	v_mfma_f32_16x16x32_bf16 v[94:97], v[156:159], v[252:255], v[94:97]
	ds_read2_b64 v[252:255], v217 offset0:80 offset1:84
	s_nop 0
	s_waitcnt lgkmcnt(4)
	v_mfma_f32_16x16x32_bf16 v[138:141], v[150:153], v[244:247], v[138:141]
	v_mfma_f32_16x16x32_bf16 v[134:137], v[156:159], v[244:247], v[134:137]
	ds_read2_b64 v[244:247], v218 offset0:112 offset1:116
	s_nop 0
	s_waitcnt lgkmcnt(4)
	v_mfma_f32_16x16x32_bf16 v[146:149], v[150:153], v[236:239], v[146:149]
	v_cvt_pk_bf16_f32 v150, v30, v31
	v_cvt_pk_bf16_f32 v151, v32, v33
	v_cvt_pk_bf16_f32 v152, v46, v47
	v_mfma_f32_16x16x32_bf16 v[142:145], v[156:159], v[236:239], v[142:145]
	ds_read2_b64 v[236:239], v215 offset0:24 offset1:28
	v_cvt_pk_bf16_f32 v153, v48, v49
	v_cvt_pk_bf16_f32 v156, v34, v35
	v_cvt_pk_bf16_f32 v157, v36, v37
	v_cvt_pk_bf16_f32 v158, v54, v55
	v_cvt_pk_bf16_f32 v159, v56, v57
	s_nop 0
	s_waitcnt lgkmcnt(4)
	v_mfma_f32_16x16x32_bf16 v[90:93], v[150:153], v[248:251], v[90:93]
	v_mfma_f32_16x16x32_bf16 v[86:89], v[156:159], v[248:251], v[86:89]
	ds_read2_b64 v[248:251], v216 offset0:56 offset1:60
	s_nop 0
	s_waitcnt lgkmcnt(4)
	v_mfma_f32_16x16x32_bf16 v[98:101], v[150:153], v[232:235], v[98:101]
	v_mfma_f32_16x16x32_bf16 v[94:97], v[156:159], v[232:235], v[94:97]
	ds_read2_b64 v[232:235], v217 offset0:88 offset1:92
	ds_read2_b64 v[160:163], v218 offset0:120 offset1:124
	s_nop 0
	s_waitcnt lgkmcnt(5)
	v_mfma_f32_16x16x32_bf16 v[138:141], v[150:153], v[252:255], v[138:141]
	v_mfma_f32_16x16x32_bf16 v[134:137], v[156:159], v[252:255], v[134:137]
	ds_read_b64_tr_b16 v[254:255], v213 offset:57408
	ds_read_b64_tr_b16 v[252:253], v213 offset:56320
	s_nop 0
	s_waitcnt lgkmcnt(6)
	v_mfma_f32_16x16x32_bf16 v[146:149], v[150:153], v[244:247], v[146:149]
	v_cvt_pk_bf16_f32 v150, v50, v51
	v_cvt_pk_bf16_f32 v151, v52, v53
	v_cvt_pk_bf16_f32 v152, v62, v63
	v_mfma_f32_16x16x32_bf16 v[142:145], v[156:159], v[244:247], v[142:145]
	v_cvt_pk_bf16_f32 v153, v64, v65
	v_cvt_pk_bf16_f32 v156, v58, v59
	v_cvt_pk_bf16_f32 v157, v60, v61
	v_cvt_pk_bf16_f32 v158, v66, v67
	v_cvt_pk_bf16_f32 v159, v68, v69
	s_nop 0
	s_waitcnt lgkmcnt(5)
	v_mfma_f32_16x16x32_bf16 v[90:93], v[150:153], v[236:239], v[90:93]
	v_mfma_f32_16x16x32_bf16 v[86:89], v[156:159], v[236:239], v[86:89]
	s_nop 0
	s_nop 5
	v_cvt_pk_bf16_f32 v90, v90, v91
	v_cvt_pk_bf16_f32 v91, v92, v93
	s_waitcnt lgkmcnt(4)
	v_mfma_f32_16x16x32_bf16 v[98:101], v[150:153], v[248:251], v[98:101]
	v_lshl_add_u64 v[92:93], s[74:75], 0, v[116:117]
	v_cvt_pk_bf16_f32 v86, v86, v87
	v_cvt_pk_bf16_f32 v87, v88, v89
	v_mfma_f32_16x16x32_bf16 v[94:97], v[156:159], v[248:251], v[94:97]
	s_nop 0
	v_add_co_u32_e32 v88, vcc, s62, v92
	s_waitcnt lgkmcnt(3)
	v_mfma_f32_16x16x32_bf16 v[138:141], v[150:153], v[232:235], v[138:141]
	global_store_dwordx2 v[92:93], v[86:87], off offset:32
	v_cvt_pk_bf16_f32 v86, v98, v99
	v_cvt_pk_bf16_f32 v87, v100, v101
	v_mfma_f32_16x16x32_bf16 v[134:137], v[156:159], v[232:235], v[134:137]
	s_nop 0
	v_addc_co_u32_e32 v89, vcc, 0, v93, vcc
	global_store_dwordx2 v[88:89], v[86:87], off
	v_cvt_pk_bf16_f32 v86, v94, v95
	v_cvt_pk_bf16_f32 v87, v96, v97
	s_mov_b32 s62, 0x10000
	s_waitcnt lgkmcnt(2)
	v_mfma_f32_16x16x32_bf16 v[146:149], v[150:153], v[160:163], v[146:149]
	global_store_dwordx2 v[88:89], v[86:87], off offset:32
	v_add_co_u32_e32 v88, vcc, s62, v92
	v_mfma_f32_16x16x32_bf16 v[142:145], v[156:159], v[160:163], v[142:145]
	v_cvt_pk_bf16_f32 v86, v138, v139
	v_cvt_pk_bf16_f32 v87, v140, v141
	v_addc_co_u32_e32 v89, vcc, 0, v93, vcc
	global_store_dwordx2 v[88:89], v[86:87], off
	v_cvt_pk_bf16_f32 v86, v134, v135
	v_cvt_pk_bf16_f32 v87, v136, v137
	global_store_dwordx2 v[88:89], v[86:87], off offset:32
	v_add_co_u32_e32 v88, vcc, s81, v92
	v_cvt_pk_bf16_f32 v86, v146, v147
	v_cvt_pk_bf16_f32 v87, v148, v149
	v_addc_co_u32_e32 v89, vcc, 0, v93, vcc
	global_store_dwordx2 v[88:89], v[86:87], off
	v_cvt_pk_bf16_f32 v86, v142, v143
	v_cvt_pk_bf16_f32 v87, v144, v145
	global_store_dwordx2 v[92:93], v[90:91], off
	ds_read_b64_tr_b16 v[90:91], v213 offset:56352
	ds_read_b64_tr_b16 v[244:245], v213 offset:65024
	ds_read_b64_tr_b16 v[246:247], v214 offset:57408
	ds_read_b64_tr_b16 v[94:95], v214 offset:57440
	ds_read_b64_tr_b16 v[92:93], v213 offset:57440
	global_store_dwordx2 v[88:89], v[86:87], off offset:32
	s_nop 0
	s_nop 0
	s_nop 0
	s_waitcnt lgkmcnt(5)
	v_mfma_f32_16x16x32_bf16 v[6:9], v[252:255], v[78:81], v[6:9]
	s_add_u32 s74, s74, 0x20000
	s_addc_u32 s75, s75, 0
	s_add_i32 s92, s92, 1
	v_mfma_f32_16x16x32_bf16 v[10:13], v[252:255], v[82:85], v[10:13]
	s_nop 0
	s_nop 0
	s_nop 0
	s_nop 0
	s_cmp_lg_u32 s76, 0x300000
	s_waitcnt lgkmcnt(2)
	v_mfma_f32_16x16x32_bf16 v[6:9], v[244:247], v[70:73], v[6:9]
	v_mfma_f32_16x16x32_bf16 v[10:13], v[244:247], v[74:77], v[10:13]
	s_waitcnt lgkmcnt(0)
	v_mfma_f32_16x16x32_bf16 v[22:25], v[90:93], v[78:81], v[22:25]
	v_mfma_f32_16x16x32_bf16 v[26:29], v[90:93], v[82:85], v[26:29]
	ds_read_b64_tr_b16 v[92:93], v213 offset:65056
	ds_read_b64_tr_b16 v[236:237], v213 offset:56384
	ds_read_b64_tr_b16 v[238:239], v213 offset:57472
	ds_read_b64_tr_b16 v[248:249], v213 offset:65088
	ds_read_b64_tr_b16 v[250:251], v214 offset:57472
	ds_read_b64_tr_b16 v[232:233], v213 offset:56416
	ds_read_b64_tr_b16 v[234:235], v213 offset:57504
	ds_read_b64_tr_b16 v[252:253], v213 offset:65120
	ds_read_b64_tr_b16 v[254:255], v214 offset:57504
	ds_read_b64_tr_b16 v[244:245], v213 offset:56448
	ds_read_b64_tr_b16 v[246:247], v213 offset:57536
	s_waitcnt lgkmcnt(8)
	v_mfma_f32_16x16x32_bf16 v[14:17], v[236:239], v[78:81], v[14:17]
	v_mfma_f32_16x16x32_bf16 v[18:21], v[236:239], v[82:85], v[18:21]
	ds_read_b64_tr_b16 v[236:237], v213 offset:65152
	ds_read_b64_tr_b16 v[238:239], v214 offset:57536
	s_nop 0
	s_nop 0
	s_waitcnt lgkmcnt(8)
	v_mfma_f32_16x16x32_bf16 v[14:17], v[248:251], v[70:73], v[14:17]
	v_mfma_f32_16x16x32_bf16 v[18:21], v[248:251], v[74:77], v[18:21]
	ds_read_b64_tr_b16 v[248:249], v213 offset:56480
	ds_read_b64_tr_b16 v[250:251], v213 offset:57568
	s_nop 0
	s_nop 0
	s_waitcnt lgkmcnt(8)
	v_mfma_f32_16x16x32_bf16 v[38:41], v[232:235], v[78:81], v[38:41]
	v_mfma_f32_16x16x32_bf16 v[42:45], v[232:235], v[82:85], v[42:45]
	ds_read_b64_tr_b16 v[232:233], v213 offset:65184
	ds_read_b64_tr_b16 v[234:235], v214 offset:57568
	s_nop 0
	s_nop 0
	s_waitcnt lgkmcnt(8)
	v_mfma_f32_16x16x32_bf16 v[38:41], v[252:255], v[70:73], v[38:41]
	v_mfma_f32_16x16x32_bf16 v[42:45], v[252:255], v[74:77], v[42:45]
	ds_read_b64_tr_b16 v[252:253], v213 offset:56512
	ds_read_b64_tr_b16 v[254:255], v213 offset:57600
	s_nop 0
	s_nop 0
	s_waitcnt lgkmcnt(8)
	v_mfma_f32_16x16x32_bf16 v[30:33], v[244:247], v[78:81], v[30:33]
	v_mfma_f32_16x16x32_bf16 v[34:37], v[244:247], v[82:85], v[34:37]
	ds_read_b64_tr_b16 v[244:245], v213 offset:65216
	ds_read_b64_tr_b16 v[246:247], v214 offset:57600
	ds_read_b64_tr_b16 v[86:87], v213 offset:56544
	ds_read_b64_tr_b16 v[88:89], v213 offset:57632
	s_nop 0
	s_nop 0
	s_waitcnt lgkmcnt(10)
	v_mfma_f32_16x16x32_bf16 v[30:33], v[236:239], v[70:73], v[30:33]
	v_mfma_f32_16x16x32_bf16 v[34:37], v[236:239], v[74:77], v[34:37]
	s_nop 0
	s_nop 0
	s_waitcnt lgkmcnt(8)
	v_mfma_f32_16x16x32_bf16 v[46:49], v[248:251], v[78:81], v[46:49]
	v_mfma_f32_16x16x32_bf16 v[54:57], v[248:251], v[82:85], v[54:57]
	s_nop 0
	s_nop 0
	s_waitcnt lgkmcnt(6)
	v_mfma_f32_16x16x32_bf16 v[46:49], v[232:235], v[70:73], v[46:49]
	v_mfma_f32_16x16x32_bf16 v[54:57], v[232:235], v[74:77], v[54:57]
	s_nop 0
	s_nop 0
	s_waitcnt lgkmcnt(4)
	v_mfma_f32_16x16x32_bf16 v[50:53], v[252:255], v[78:81], v[50:53]
	v_mfma_f32_16x16x32_bf16 v[58:61], v[252:255], v[82:85], v[58:61]
	s_nop 0
	s_nop 0
	s_waitcnt lgkmcnt(2)
	v_mfma_f32_16x16x32_bf16 v[50:53], v[244:247], v[70:73], v[50:53]
	v_mfma_f32_16x16x32_bf16 v[58:61], v[244:247], v[74:77], v[58:61]
	s_nop 0
	s_nop 0
	s_waitcnt lgkmcnt(0)
	v_mfma_f32_16x16x32_bf16 v[62:65], v[86:89], v[78:81], v[62:65]
	ds_read_b64_tr_b16 v[78:79], v213 offset:65248
	ds_read_b64_tr_b16 v[80:81], v214 offset:57632
	v_mfma_f32_16x16x32_bf16 v[66:69], v[86:89], v[82:85], v[66:69]
	v_mfma_f32_16x16x32_bf16 v[22:25], v[92:95], v[70:73], v[22:25]
	s_waitcnt lgkmcnt(0)
	v_mfma_f32_16x16x32_bf16 v[62:65], v[78:81], v[70:73], v[62:65]
	v_lshl_add_u32 v70, s93, 9, v179
	ds_read_b128 v[236:239], v70 offset:4096
	ds_read_b128 v[248:251], v70 offset:4160
	ds_read_b128 v[232:235], v70 offset:4224
	ds_read_b128 v[252:255], v70 offset:4288
	ds_read_b128 v[244:247], v70 offset:4352
	v_mfma_f32_16x16x32_bf16 v[26:29], v[92:95], v[74:77], v[26:29]
	v_mfma_f32_16x16x32_bf16 v[66:69], v[78:81], v[74:77], v[66:69]
	s_nop 0
	s_waitcnt lgkmcnt(4)
	v_mul_f32_e32 v71, 0x3fb8aa3b, v236
	v_exp_f32_e32 v72, v71
	v_mul_f32_e32 v71, 0x3fb8aa3b, v237
	v_exp_f32_e32 v73, v71
	v_mul_f32_e32 v71, 0x3fb8aa3b, v238
	v_exp_f32_e32 v74, v71
	v_mul_f32_e32 v71, 0x3fb8aa3b, v239
	ds_read_b128 v[236:239], v70 offset:4416
	v_exp_f32_e32 v75, v71
	v_pk_mul_f32 v[6:7], v[6:7], v[72:73]
	v_pk_mul_f32 v[10:11], v[10:11], v[72:73]
	v_pk_mul_f32 v[8:9], v[8:9], v[74:75]
	v_pk_mul_f32 v[12:13], v[12:13], v[74:75]
	s_nop 0
	s_waitcnt lgkmcnt(4)
	v_mul_f32_e32 v71, 0x3fb8aa3b, v248
	v_exp_f32_e32 v72, v71
	v_mul_f32_e32 v71, 0x3fb8aa3b, v249
	v_exp_f32_e32 v73, v71
	v_mul_f32_e32 v71, 0x3fb8aa3b, v250
	v_exp_f32_e32 v74, v71
	v_mul_f32_e32 v71, 0x3fb8aa3b, v251
	ds_read_b128 v[248:251], v70 offset:4480
	v_exp_f32_e32 v75, v71
	v_pk_mul_f32 v[22:23], v[22:23], v[72:73]
	v_pk_mul_f32 v[26:27], v[26:27], v[72:73]
	v_pk_mul_f32 v[24:25], v[24:25], v[74:75]
	v_pk_mul_f32 v[28:29], v[28:29], v[74:75]
	s_nop 0
	s_waitcnt lgkmcnt(4)
	v_mul_f32_e32 v71, 0x3fb8aa3b, v232
	v_exp_f32_e32 v72, v71
	v_mul_f32_e32 v71, 0x3fb8aa3b, v233
	v_exp_f32_e32 v73, v71
	v_mul_f32_e32 v71, 0x3fb8aa3b, v234
	v_exp_f32_e32 v74, v71
	v_mul_f32_e32 v71, 0x3fb8aa3b, v235
	v_exp_f32_e32 v75, v71
	v_pk_mul_f32 v[14:15], v[14:15], v[72:73]
	v_pk_mul_f32 v[18:19], v[18:19], v[72:73]
	v_pk_mul_f32 v[16:17], v[16:17], v[74:75]
	v_pk_mul_f32 v[20:21], v[20:21], v[74:75]
	s_nop 0
	s_waitcnt lgkmcnt(3)
	v_mul_f32_e32 v71, 0x3fb8aa3b, v252
	v_exp_f32_e32 v72, v71
	v_mul_f32_e32 v71, 0x3fb8aa3b, v253
	v_exp_f32_e32 v73, v71
	v_mul_f32_e32 v71, 0x3fb8aa3b, v254
	v_exp_f32_e32 v74, v71
	v_mul_f32_e32 v71, 0x3fb8aa3b, v255
	v_exp_f32_e32 v75, v71
	v_pk_mul_f32 v[38:39], v[38:39], v[72:73]
	v_pk_mul_f32 v[42:43], v[42:43], v[72:73]
	v_pk_mul_f32 v[40:41], v[40:41], v[74:75]
	v_pk_mul_f32 v[44:45], v[44:45], v[74:75]
	s_nop 0
	s_waitcnt lgkmcnt(2)
	v_mul_f32_e32 v71, 0x3fb8aa3b, v244
	v_exp_f32_e32 v72, v71
	v_mul_f32_e32 v71, 0x3fb8aa3b, v245
	v_exp_f32_e32 v73, v71
	v_mul_f32_e32 v71, 0x3fb8aa3b, v246
	v_exp_f32_e32 v74, v71
	v_mul_f32_e32 v71, 0x3fb8aa3b, v247
	v_exp_f32_e32 v75, v71
	v_pk_mul_f32 v[30:31], v[30:31], v[72:73]
	v_pk_mul_f32 v[34:35], v[34:35], v[72:73]
	v_pk_mul_f32 v[32:33], v[32:33], v[74:75]
	v_pk_mul_f32 v[36:37], v[36:37], v[74:75]
	s_nop 0
	s_waitcnt lgkmcnt(1)
	v_mul_f32_e32 v71, 0x3fb8aa3b, v236
	v_exp_f32_e32 v72, v71
	v_mul_f32_e32 v71, 0x3fb8aa3b, v237
	v_exp_f32_e32 v73, v71
	v_mul_f32_e32 v71, 0x3fb8aa3b, v238
	v_exp_f32_e32 v74, v71
	v_mul_f32_e32 v71, 0x3fb8aa3b, v239
	v_exp_f32_e32 v75, v71
	v_pk_mul_f32 v[46:47], v[46:47], v[72:73]
	v_pk_mul_f32 v[54:55], v[54:55], v[72:73]
	v_pk_mul_f32 v[48:49], v[48:49], v[74:75]
	v_pk_mul_f32 v[56:57], v[56:57], v[74:75]
	s_nop 0
	s_waitcnt lgkmcnt(0)
	v_mul_f32_e32 v71, 0x3fb8aa3b, v248
	v_exp_f32_e32 v72, v71
	v_mul_f32_e32 v71, 0x3fb8aa3b, v249
	v_exp_f32_e32 v73, v71
	v_mul_f32_e32 v71, 0x3fb8aa3b, v250
	v_exp_f32_e32 v74, v71
	v_mul_f32_e32 v71, 0x3fb8aa3b, v251
	v_exp_f32_e32 v75, v71
	v_pk_mul_f32 v[50:51], v[50:51], v[72:73]
	v_pk_mul_f32 v[58:59], v[58:59], v[72:73]
	ds_read_b128 v[70:73], v70 offset:4544
	v_pk_mul_f32 v[52:53], v[52:53], v[74:75]
	v_pk_mul_f32 v[60:61], v[60:61], v[74:75]
	s_waitcnt lgkmcnt(0)
	v_mul_f32_e32 v70, 0x3fb8aa3b, v70
	v_mul_f32_e32 v71, 0x3fb8aa3b, v71
	v_mul_f32_e32 v72, 0x3fb8aa3b, v72
	v_mul_f32_e32 v73, 0x3fb8aa3b, v73
	v_exp_f32_e32 v70, v70
	v_exp_f32_e32 v71, v71
	v_exp_f32_e32 v72, v72
	v_exp_f32_e32 v73, v73
	v_pk_mul_f32 v[62:63], v[62:63], v[70:71]
	v_pk_mul_f32 v[66:67], v[66:67], v[70:71]
	v_pk_mul_f32 v[64:65], v[64:65], v[72:73]
	v_pk_mul_f32 v[68:69], v[68:69], v[72:73]
	s_waitcnt lgkmcnt(0)
	s_cbranch_scc0 .LBB0_672
.LBB0_664:
	s_add_u32 s62, s61, s76
	s_addc_u32 s63, s91, s77
	v_lshl_add_u64 v[70:71], s[62:63], 0, v[112:113]
	s_add_u32 s62, s55, s76
	s_addc_u32 s63, s57, s77
	s_add_u32 s62, s62, s68
	v_add_co_u32_e32 v74, vcc, s95, v70
	s_addc_u32 s63, s63, 0
	s_nop 0
	v_addc_co_u32_e32 v75, vcc, 0, v71, vcc
	v_lshl_add_u64 v[86:87], s[62:63], 0, v[114:115]
	v_add_co_u32_e32 v78, vcc, s81, v86
	s_and_b32 s93, s92, 1
	s_add_i32 s69, s66, 0xf0
	v_addc_co_u32_e32 v79, vcc, 0, v87, vcc
	s_cmp_eq_u32 s93, 0
	v_add_co_u32_e32 v82, vcc, s95, v86
	s_cselect_b64 s[78:79], -1, 0
	s_nop 0
	v_addc_co_u32_e32 v83, vcc, 0, v87, vcc
	s_and_b64 s[62:63], s[78:79], exec
	global_load_dwordx4 v[94:97], v[70:71], off
	global_load_dwordx4 v[98:101], v[70:71], off offset:1024
	s_nop 0
	global_load_dwordx4 v[70:73], v[74:75], off
	global_load_dwordx4 v[90:93], v[74:75], off offset:1024
	s_cselect_b32 s62, 0xf0, s69
	global_load_dwordx4 v[74:77], v[86:87], off
	v_add_co_u32_e32 v86, vcc, s96, v86
	v_add3_u32 v137, s62, v177, v175
	s_nop 0
	v_addc_co_u32_e32 v87, vcc, 0, v87, vcc
	global_load_dwordx4 v[78:81], v[78:79], off
	s_nop 0
	global_load_dwordx4 v[82:85], v[82:83], off
	s_nop 0
	global_load_dwordx4 v[86:89], v[86:87], off
	s_waitcnt lgkmcnt(0)
	ds_read2_b32 v[134:135], v137 offset1:4
	ds_read2_b32 v[232:233], v137 offset0:8 offset1:12
	ds_read2_b32 v[146:147], v137 offset0:128 offset1:132
	ds_read2_b32 v[236:237], v137 offset0:64 offset1:68
	ds_read2_b32 v[244:245], v137 offset0:72 offset1:76
	ds_read2_b32 v[248:249], v137 offset0:136 offset1:140
	ds_read2_b32 v[252:253], v137 offset0:192 offset1:196
	s_waitcnt lgkmcnt(6)
	v_mfma_f32_16x16x4_f32 v[138:141], v134, v104, 0
	s_nop 0
	v_mfma_f32_16x16x4_f32 v[138:141], v135, v105, v[138:141]
	s_waitcnt lgkmcnt(5)
	v_mfma_f32_16x16x4_f32 v[138:141], v232, v106, v[138:141]
	v_mfma_f32_16x16x4_f32 v[138:141], v233, v107, v[138:141]
	ds_read2_b32 v[232:233], v137 offset0:200 offset1:204
	s_nop 0
	s_nop 8
	v_add_f32_e32 v134, v108, v138
	v_min_f32_e32 v109, 0, v134
	v_mul_f32_e64 v134, |v134|, s97
	v_exp_f32_e32 v134, v134
	v_add_f32_e32 v135, v108, v139
	v_add_f32_e32 v136, v108, v140
	v_add_f32_e32 v138, v108, v141
	v_add_f32_e32 v134, 1.0, v134
	v_log_f32_e32 v134, v134
	s_nop 0
	v_fmac_f32_e32 v109, 0xbf317218, v134
	v_min_f32_e32 v134, 0, v135
	v_mul_f32_e64 v135, |v135|, s97
	v_exp_f32_e32 v135, v135
	v_fma_f32 v109, v109, s0, 0
	v_add_f32_e32 v135, 1.0, v135
	v_log_f32_e32 v135, v135
	s_nop 0
	v_fmac_f32_e32 v134, 0xbf317218, v135
	v_min_f32_e32 v135, 0, v136
	v_mul_f32_e64 v136, |v136|, s97
	v_exp_f32_e32 v136, v136
	v_fmamk_f32 v134, v134, 0x3d800000, v109
	v_add_f32_e32 v136, 1.0, v136
	v_log_f32_e32 v136, v136
	s_nop 0
	v_fmac_f32_e32 v135, 0xbf317218, v136
	v_min_f32_e32 v136, 0, v138
	v_mul_f32_e64 v138, |v138|, s97
	v_exp_f32_e32 v138, v138
	v_fmamk_f32 v135, v135, 0x3d800000, v134
	v_add_f32_e32 v138, 1.0, v138
	v_log_f32_e32 v138, v138
	s_nop 0
	v_fmac_f32_e32 v136, 0xbf317218, v138
	s_waitcnt lgkmcnt(4)
	v_mfma_f32_16x16x4_f32 v[138:141], v236, v104, 0
	v_fmamk_f32 v136, v136, 0x3d800000, v135
	v_mfma_f32_16x16x4_f32 v[138:141], v237, v105, v[138:141]
	s_nop 0
	s_waitcnt lgkmcnt(3)
	v_mfma_f32_16x16x4_f32 v[138:141], v244, v106, v[138:141]
	v_mfma_f32_16x16x4_f32 v[138:141], v245, v107, v[138:141]
	s_nop 9
	v_add_f32_e32 v142, v108, v138
	v_min_f32_e32 v138, 0, v142
	v_mul_f32_e64 v142, |v142|, s97
	v_exp_f32_e32 v142, v142
	s_nop 0
	v_add_f32_e32 v142, 1.0, v142
	v_log_f32_e32 v142, v142
	s_nop 0
	v_fmac_f32_e32 v138, 0xbf317218, v142
	v_add_f32_e32 v142, v108, v139
	v_min_f32_e32 v139, 0, v142
	v_mul_f32_e64 v142, |v142|, s97
	v_exp_f32_e32 v142, v142
	s_nop 0
	v_add_f32_e32 v142, 1.0, v142
	v_log_f32_e32 v142, v142
	s_nop 0
	v_fmac_f32_e32 v139, 0xbf317218, v142
	v_add_f32_e32 v142, v108, v140
	v_min_f32_e32 v140, 0, v142
	v_mul_f32_e64 v142, |v142|, s97
	v_exp_f32_e32 v142, v142
	s_nop 0
	v_add_f32_e32 v142, 1.0, v142
	v_log_f32_e32 v142, v142
	s_nop 0
	v_fmac_f32_e32 v140, 0xbf317218, v142
	v_add_f32_e32 v142, v108, v141
	v_min_f32_e32 v141, 0, v142
	v_mul_f32_e64 v142, |v142|, s97
	v_exp_f32_e32 v142, v142
	s_nop 0
	v_add_f32_e32 v142, 1.0, v142
	v_log_f32_e32 v142, v142
	s_nop 0
	v_fmac_f32_e32 v141, 0xbf317218, v142
	v_mfma_f32_16x16x4_f32 v[142:145], v146, v104, 0
	v_mfma_f32_16x16x4_f32 v[142:145], v147, v105, v[142:145]
	s_nop 0
	s_waitcnt lgkmcnt(2)
	v_mfma_f32_16x16x4_f32 v[142:145], v248, v106, v[142:145]
	v_mfma_f32_16x16x4_f32 v[142:145], v249, v107, v[142:145]
	s_nop 0
	s_nop 8
	v_add_f32_e32 v142, v108, v142
	v_min_f32_e32 v148, 0, v142
	v_mul_f32_e64 v142, |v142|, s97
	v_exp_f32_e32 v142, v142
	s_nop 0
	v_add_f32_e32 v142, 1.0, v142
	v_log_f32_e32 v142, v142
	s_nop 0
	v_fmac_f32_e32 v148, 0xbf317218, v142
	v_add_f32_e32 v142, v108, v143
	v_min_f32_e32 v149, 0, v142
	v_mul_f32_e64 v142, |v142|, s97
	v_exp_f32_e32 v142, v142
	s_nop 0
	v_add_f32_e32 v142, 1.0, v142
	v_log_f32_e32 v142, v142
	s_nop 0
	v_fmac_f32_e32 v149, 0xbf317218, v142
	v_add_f32_e32 v142, v108, v144
	v_min_f32_e32 v150, 0, v142
	v_mul_f32_e64 v142, |v142|, s97
	v_exp_f32_e32 v142, v142
	s_nop 0
	v_add_f32_e32 v142, 1.0, v142
	v_log_f32_e32 v142, v142
	s_nop 0
	v_fmac_f32_e32 v150, 0xbf317218, v142
	v_add_f32_e32 v142, v108, v145
	v_min_f32_e32 v151, 0, v142
	v_mul_f32_e64 v142, |v142|, s97
	v_exp_f32_e32 v142, v142
	s_nop 0
	v_add_f32_e32 v142, 1.0, v142
	v_log_f32_e32 v142, v142
	s_nop 0
	v_fmac_f32_e32 v151, 0xbf317218, v142
	s_waitcnt lgkmcnt(1)
	v_mfma_f32_16x16x4_f32 v[142:145], v252, v104, 0
	v_mfma_f32_16x16x4_f32 v[142:145], v253, v105, v[142:145]
	s_nop 0
	s_waitcnt lgkmcnt(0)
	v_mfma_f32_16x16x4_f32 v[142:145], v232, v106, v[142:145]
	v_mfma_f32_16x16x4_f32 v[142:145], v233, v107, v[142:145]
	s_nop 9
	v_add_f32_e32 v137, v108, v142
	v_min_f32_e32 v142, 0, v137
	v_mul_f32_e64 v137, |v137|, s97
	v_exp_f32_e32 v137, v137
	s_nop 0
	v_add_f32_e32 v137, 1.0, v137
	v_log_f32_e32 v137, v137
	s_nop 0
	v_fmac_f32_e32 v142, 0xbf317218, v137
	v_add_f32_e32 v137, v108, v143
	v_min_f32_e32 v143, 0, v137
	v_mul_f32_e64 v137, |v137|, s97
	v_exp_f32_e32 v137, v137
	s_nop 0
	v_add_f32_e32 v137, 1.0, v137
	v_log_f32_e32 v137, v137
	s_nop 0
	v_fmac_f32_e32 v143, 0xbf317218, v137
	v_add_f32_e32 v137, v108, v144
	v_min_f32_e32 v144, 0, v137
	v_mul_f32_e64 v137, |v137|, s97
	v_exp_f32_e32 v137, v137
	s_nop 0
	v_add_f32_e32 v137, 1.0, v137
	v_log_f32_e32 v137, v137
	s_nop 0
	v_fmac_f32_e32 v144, 0xbf317218, v137
	v_add_f32_e32 v137, v108, v145
	v_min_f32_e32 v145, 0, v137
	v_mul_f32_e64 v137, |v137|, s97
	v_exp_f32_e32 v137, v137
	s_nop 0
	v_add_f32_e32 v137, 1.0, v137
	v_log_f32_e32 v137, v137
	s_nop 0
	v_fmac_f32_e32 v145, 0xbf317218, v137
	v_fmamk_f32 v137, v138, 0x3d800000, v136
	v_fmamk_f32 v138, v139, 0x3d800000, v137
	v_fmamk_f32 v139, v140, 0x3d800000, v138
	v_fmamk_f32 v140, v141, 0x3d800000, v139
	v_fmamk_f32 v141, v148, 0x3d800000, v140
	v_fmamk_f32 v146, v149, 0x3d800000, v141
	v_fmamk_f32 v147, v150, 0x3d800000, v146
	v_fmamk_f32 v148, v151, 0x3d800000, v147
	v_fmamk_f32 v142, v142, 0x3d800000, v148
	v_fmamk_f32 v143, v143, 0x3d800000, v142
	v_fmamk_f32 v144, v144, 0x3d800000, v143
	v_fmamk_f32 v145, v145, 0x3d800000, v144
	ds_bpermute_b32 v149, v186, v145
	ds_bpermute_b32 v150, v187, v145
	ds_bpermute_b32 v151, v188, v145
	s_waitcnt lgkmcnt(2)
	v_cndmask_b32_e64 v149, v149, 0, s[4:5]
	s_waitcnt lgkmcnt(1)
	v_cndmask_b32_e64 v150, 0, v150, s[6:7]
	v_add_f32_e32 v149, v149, v150
	s_waitcnt lgkmcnt(0)
	v_cndmask_b32_e64 v150, 0, v151, s[8:9]
	v_add_f32_e32 v149, v149, v150
	v_add_f32_e32 v109, v109, v149
	v_add_f32_e32 v134, v134, v149
	ds_write2st64_b32 v200, v109, v134 offset0:24 offset1:26
	v_add_f32_e32 v109, v135, v149
	v_add_f32_e32 v134, v136, v149
	ds_write2st64_b32 v200, v109, v134 offset0:28 offset1:30
	v_add_f32_e32 v109, v137, v149
	v_add_f32_e32 v134, v138, v149
	ds_write2st64_b32 v200, v109, v134 offset0:32 offset1:34
	v_add_f32_e32 v109, v139, v149
	v_add_f32_e32 v134, v140, v149
	ds_write2st64_b32 v200, v109, v134 offset0:36 offset1:38
	v_add_f32_e32 v109, v141, v149
	v_add_f32_e32 v134, v146, v149
	ds_write2st64_b32 v200, v109, v134 offset0:40 offset1:42
	v_add_f32_e32 v109, v149, v147
	v_add_f32_e32 v134, v149, v148
	ds_write2st64_b32 v200, v109, v134 offset0:44 offset1:46
	v_add_f32_e32 v109, v149, v142
	v_add_f32_e32 v134, v149, v143
	ds_write2st64_b32 v200, v109, v134 offset0:48 offset1:50
	v_add_f32_e32 v109, v149, v144
	v_add_f32_e32 v134, v149, v145
	ds_write2st64_b32 v200, v109, v134 offset0:52 offset1:54
	s_waitcnt lgkmcnt(0)
	s_barrier
	s_and_saveexec_b64 s[62:63], s[10:11]
	s_cbranch_execz .LBB0_666
	ds_read_b32 v109, v178 offset:38400
	v_lshl_add_u32 v134, s93, 9, v178
	s_waitcnt lgkmcnt(0)
	ds_write_b32 v134, v109 offset:4096

.LBB0_679:
	s_or_b64 exec, exec, s[62:63]
	s_waitcnt lgkmcnt(0)
	s_barrier
	s_waitcnt lgkmcnt(0)
	ds_read_b128 v[136:139], v184
	ds_read_b128 v[142:145], v184 offset:16
	s_waitcnt vmcnt(8)
	v_lshlrev_b32_e32 v156, 16, v166
	v_and_b32_e32 v157, 0xffff0000, v166
	v_lshlrev_b32_e32 v166, 16, v167
	s_waitcnt lgkmcnt(1)
	v_mov_b32_e32 v81, v138
	v_lshlrev_b32_e32 v138, 16, v168
	v_mov_b32_e32 v80, v137
	v_mov_b32_e32 v137, v139
	v_and_b32_e32 v139, 0xffff0000, v168
	v_mul_f32_e32 v0, 0xbfb8aa3b, v138
	v_pk_add_f32 v[80:81], v[80:81], v[136:137]
	s_waitcnt lgkmcnt(0)
	v_mov_b32_e32 v136, v144
	v_exp_f32_e32 v0, v0
	v_mul_f32_e32 v144, 0xbfb8aa3b, v139
	v_exp_f32_e32 v144, v144
	v_mov_b32_e32 v137, v142
	v_mov_b32_e32 v142, v145
	v_add_f32_e32 v0, 1.0, v0
	v_pk_add_f32 v[146:147], v[136:137], v[142:143]
	v_rcp_f32_e32 v136, v0
	v_add_f32_e32 v0, 1.0, v144
	v_lshlrev_b32_e32 v142, 16, v169
	v_rcp_f32_e32 v137, v0
	v_and_b32_e32 v143, 0xffff0000, v169
	v_mul_f32_e32 v0, 0xbfb8aa3b, v142
	v_exp_f32_e32 v0, v0
	v_mul_f32_e32 v144, 0xbfb8aa3b, v143
	v_exp_f32_e32 v144, v144
	v_pk_mul_f32 v[148:149], v[136:137], v[138:139]
	v_add_f32_e32 v0, 1.0, v0
	v_rcp_f32_e32 v136, v0
	v_add_f32_e32 v0, 1.0, v144
	v_rcp_f32_e32 v137, v0
	v_mul_f32_e32 v0, 0xbfb8aa3b, v156
	v_exp_f32_e32 v0, v0
	v_mul_f32_e32 v138, 0xbfb8aa3b, v157
	v_exp_f32_e32 v138, v138
	v_and_b32_e32 v167, 0xffff0000, v167
	v_add_f32_e32 v0, 1.0, v0
	v_rcp_f32_e32 v224, v0
	v_add_f32_e32 v0, 1.0, v138
	v_rcp_f32_e32 v225, v0
	v_mul_f32_e32 v0, 0xbfb8aa3b, v166
	v_pk_mul_f32 v[168:169], v[136:137], v[142:143]
	v_exp_f32_e32 v0, v0
	v_mul_f32_e32 v136, 0xbfb8aa3b, v167
	v_exp_f32_e32 v142, v136
	ds_read_b128 v[136:139], v184 offset:512
	v_add_f32_e32 v0, 1.0, v0
	v_rcp_f32_e32 v226, v0
	v_add_f32_e32 v0, 1.0, v142
	ds_read_b128 v[142:145], v184 offset:528
	s_waitcnt lgkmcnt(1)
	v_mov_b32_e32 v228, v137
	v_mov_b32_e32 v229, v138
	v_mov_b32_e32 v137, v139
	v_pk_add_f32 v[136:137], v[228:229], v[136:137]
	s_waitcnt lgkmcnt(0)
	v_mov_b32_e32 v138, v144
	v_mov_b32_e32 v139, v142
	v_mov_b32_e32 v142, v145
	v_pk_add_f32 v[138:139], v[138:139], v[142:143]
	v_mov_b32_e32 v142, v136
	v_mov_b32_e32 v143, v80
	v_mov_b32_e32 v80, v137
	v_pk_add_f32 v[80:81], v[142:143], v[80:81]
	v_mov_b32_e32 v136, v139
	v_mov_b32_e32 v137, v147
	v_pk_add_f32 v[80:81], v[80:81], v[136:137]
	v_mov_b32_e32 v139, v146
	s_mov_b32 s62, 0x358637bd
	v_pk_add_f32 v[136:137], v[138:139], v[80:81]
	v_mov_b64_e32 v[80:81], s[62:63]
	v_pk_fma_f32 v[136:137], v[136:137], s[52:53], v[80:81] op_sel_hi:[1,0,0]
	v_rcp_f32_e32 v227, v0
	v_mul_f32_e32 v0, 0x4b800000, v137
	v_cmp_gt_f32_e32 vcc, s1, v137
	v_pk_mul_f32 v[142:143], v[224:225], v[156:157]
	v_pk_mul_f32 v[144:145], v[226:227], v[166:167]
	v_cndmask_b32_e32 v0, v137, v0, vcc
	v_rsq_f32_e32 v0, v0
	v_lshl_add_u64 v[138:139], s[56:57], 0, v[116:117]
	s_waitcnt vmcnt(4)
	v_lshlrev_b32_e32 v146, 16, v159
	v_and_b32_e32 v147, 0xffff0000, v159
	v_mul_f32_e32 v137, 0x45800000, v0
	v_cndmask_b32_e32 v0, v0, v137, vcc
	v_pk_mul_f32 v[106:107], v[106:107], v[0:1] op_sel_hi:[1,0]
	v_pk_mul_f32 v[108:109], v[108:109], v[0:1] op_sel_hi:[1,0]
	v_pk_mul_f32 v[102:103], v[102:103], v[0:1] op_sel_hi:[1,0]
	v_pk_mul_f32 v[104:105], v[104:105], v[0:1] op_sel_hi:[1,0]
	v_mul_f32_e32 v0, 0x4b800000, v136
	v_cmp_gt_f32_e32 vcc, s1, v136
	s_waitcnt vmcnt(0)
	v_pk_mul_f32 v[102:103], v[70:71], v[102:103]
	v_pk_mul_f32 v[104:105], v[72:73], v[104:105]
	v_cndmask_b32_e32 v0, v136, v0, vcc
	v_pk_mul_f32 v[102:103], v[142:143], v[102:103]
	v_pk_mul_f32 v[104:105], v[144:145], v[104:105]
	v_rsq_f32_e32 v0, v0
	v_cvt_pk_bf16_f32 v102, v102, v103
	v_cvt_pk_bf16_f32 v103, v104, v105
	global_store_dwordx2 v[138:139], v[102:103], off offset:32
	v_lshlrev_b32_e32 v102, 16, v164
	v_mul_f32_e32 v103, 0xbfb8aa3b, v102
	v_exp_f32_e32 v104, v103
	v_mul_f32_e32 v103, 0x45800000, v0
	v_cndmask_b32_e32 v0, v0, v103, vcc
	v_and_b32_e32 v103, 0xffff0000, v164
	v_mul_f32_e32 v105, 0xbfb8aa3b, v103
	v_exp_f32_e32 v105, v105
	v_pk_mul_f32 v[106:107], v[74:75], v[106:107]
	v_pk_mul_f32 v[108:109], v[76:77], v[108:109]
	v_pk_mul_f32 v[106:107], v[148:149], v[106:107]
	v_pk_mul_f32 v[108:109], v[168:169], v[108:109]
	v_cvt_pk_bf16_f32 v106, v106, v107
	v_cvt_pk_bf16_f32 v107, v108, v109
	v_lshlrev_b32_e32 v108, 16, v165
	v_and_b32_e32 v109, 0xffff0000, v165
	v_add_f32_e32 v104, 1.0, v104
	v_add_f32_e32 v105, 1.0, v105
	v_mul_f32_e32 v136, 0xbfb8aa3b, v108
	v_mul_f32_e32 v137, 0xbfb8aa3b, v109
	v_rcp_f32_e32 v104, v104
	v_rcp_f32_e32 v105, v105
	v_exp_f32_e32 v136, v136
	v_exp_f32_e32 v137, v137
	global_store_dwordx2 v[138:139], v[106:107], off
	v_pk_mul_f32 v[102:103], v[104:105], v[102:103]
	v_add_f32_e32 v104, 1.0, v136
	v_add_f32_e32 v105, 1.0, v137
	v_rcp_f32_e32 v104, v104
	v_rcp_f32_e32 v105, v105
	v_pk_mul_f32 v[106:107], v[152:153], v[0:1] op_sel_hi:[1,0]
	v_pk_mul_f32 v[100:101], v[100:101], v[0:1] op_sel_hi:[1,0]
	v_pk_mul_f32 v[106:107], v[74:75], v[106:107]
	v_pk_mul_f32 v[100:101], v[76:77], v[100:101]
	v_pk_mul_f32 v[104:105], v[104:105], v[108:109]
	v_pk_mul_f32 v[102:103], v[102:103], v[106:107]
	v_pk_mul_f32 v[100:101], v[104:105], v[100:101]
	v_cvt_pk_bf16_f32 v102, v102, v103
	v_cvt_pk_bf16_f32 v103, v100, v101
	v_lshlrev_b32_e32 v100, 16, v162
	v_mul_f32_e32 v101, 0xbfb8aa3b, v100
	v_exp_f32_e32 v106, v101
	v_lshl_add_u64 v[104:105], s[56:57], 0, v[120:121]
	v_and_b32_e32 v101, 0xffff0000, v162
	global_store_dwordx2 v[104:105], v[102:103], off
	v_mul_f32_e32 v103, 0xbfb8aa3b, v101
	v_exp_f32_e32 v103, v103
	v_lshlrev_b32_e32 v104, 16, v163
	v_and_b32_e32 v105, 0xffff0000, v163
	v_add_f32_e32 v102, 1.0, v106
	v_add_f32_e32 v103, 1.0, v103
	v_mul_f32_e32 v106, 0xbfb8aa3b, v104
	v_mul_f32_e32 v107, 0xbfb8aa3b, v105
	v_rcp_f32_e32 v102, v102
	v_rcp_f32_e32 v103, v103
	v_exp_f32_e32 v106, v106
	v_exp_f32_e32 v107, v107
	v_pk_mul_f32 v[98:99], v[98:99], v[0:1] op_sel_hi:[1,0]
	v_pk_mul_f32 v[100:101], v[102:103], v[100:101]
	v_add_f32_e32 v102, 1.0, v106
	v_add_f32_e32 v103, 1.0, v107
	v_rcp_f32_e32 v102, v102
	v_rcp_f32_e32 v103, v103
	v_pk_mul_f32 v[98:99], v[70:71], v[98:99]
	v_pk_mul_f32 v[96:97], v[96:97], v[0:1] op_sel_hi:[1,0]
	v_pk_mul_f32 v[98:99], v[100:101], v[98:99]
	v_pk_mul_f32 v[96:97], v[72:73], v[96:97]
	v_pk_mul_f32 v[100:101], v[102:103], v[104:105]
	v_cvt_pk_bf16_f32 v102, v98, v99
	v_pk_mul_f32 v[100:101], v[100:101], v[96:97]
	ds_read_b128 v[96:99], v184 offset:1024
	v_cvt_pk_bf16_f32 v103, v100, v101
	v_lshl_add_u64 v[100:101], s[56:57], 0, v[122:123]
	global_store_dwordx2 v[100:101], v[102:103], off
	ds_read_b128 v[100:103], v184 offset:1040
	s_waitcnt lgkmcnt(1)
	v_mov_b32_e32 v105, v98
	v_lshlrev_b32_e32 v98, 16, v160
	v_mov_b32_e32 v104, v97
	v_mov_b32_e32 v97, v99
	v_and_b32_e32 v99, 0xffff0000, v160
	v_mul_f32_e32 v0, 0xbfb8aa3b, v98
	v_pk_add_f32 v[104:105], v[104:105], v[96:97]
	v_exp_f32_e32 v0, v0
	v_mul_f32_e32 v97, 0xbfb8aa3b, v99
	s_waitcnt lgkmcnt(0)
	v_mov_b32_e32 v96, v102
	v_exp_f32_e32 v102, v97
	v_lshlrev_b32_e32 v108, 16, v161
	v_mov_b32_e32 v97, v100
	v_add_f32_e32 v0, 1.0, v0
	v_and_b32_e32 v109, 0xffff0000, v161
	v_mul_f32_e32 v100, 0xbfb8aa3b, v108
	v_rcp_f32_e32 v106, v0
	v_add_f32_e32 v0, 1.0, v102
	v_exp_f32_e32 v100, v100
	v_mul_f32_e32 v102, 0xbfb8aa3b, v109
	v_exp_f32_e32 v102, v102
	v_rcp_f32_e32 v107, v0
	v_add_f32_e32 v0, 1.0, v100
	v_rcp_f32_e32 v136, v0
	v_add_f32_e32 v0, 1.0, v102
	v_rcp_f32_e32 v137, v0
	v_mov_b32_e32 v100, v103
	v_pk_add_f32 v[138:139], v[96:97], v[100:101]
	v_pk_mul_f32 v[106:107], v[106:107], v[98:99]
	v_pk_mul_f32 v[108:109], v[136:137], v[108:109]
	v_lshlrev_b32_e32 v136, 16, v158
	v_and_b32_e32 v137, 0xffff0000, v158
	v_mul_f32_e32 v0, 0xbfb8aa3b, v136
	v_exp_f32_e32 v0, v0
	v_mul_f32_e32 v96, 0xbfb8aa3b, v137
	v_exp_f32_e32 v96, v96
	v_lshl_add_u64 v[142:143], s[56:57], 0, v[124:125]
	v_add_f32_e32 v0, 1.0, v0
	v_rcp_f32_e32 v144, v0
	v_add_f32_e32 v0, 1.0, v96
	v_rcp_f32_e32 v145, v0
	v_mul_f32_e32 v0, 0xbfb8aa3b, v146
	v_exp_f32_e32 v0, v0
	v_mul_f32_e32 v96, 0xbfb8aa3b, v147
	v_exp_f32_e32 v100, v96
	ds_read_b128 v[96:99], v184 offset:1536
	v_add_f32_e32 v0, 1.0, v0
	v_rcp_f32_e32 v148, v0
	v_add_f32_e32 v0, 1.0, v100
	ds_read_b128 v[100:103], v184 offset:1552
	ds_read_b64_tr_b16 v[234:235], v213 offset:57408
	ds_read_b64_tr_b16 v[232:233], v213 offset:56320
	s_waitcnt lgkmcnt(3)
	v_mov_b32_e32 v152, v97
	v_mov_b32_e32 v153, v98
	v_mov_b32_e32 v97, v99
	v_pk_add_f32 v[96:97], v[152:153], v[96:97]
	s_waitcnt lgkmcnt(2)
	v_mov_b32_e32 v98, v102
	v_mov_b32_e32 v99, v100
	v_mov_b32_e32 v100, v103
	v_pk_add_f32 v[98:99], v[98:99], v[100:101]
	v_mov_b32_e32 v100, v96
	v_mov_b32_e32 v101, v104
	v_mov_b32_e32 v104, v97
	v_pk_add_f32 v[96:97], v[100:101], v[104:105]
	v_mov_b32_e32 v100, v99
	v_mov_b32_e32 v101, v139
	v_pk_add_f32 v[96:97], v[96:97], v[100:101]
	v_mov_b32_e32 v99, v138
	v_pk_add_f32 v[96:97], v[98:99], v[96:97]
	v_rcp_f32_e32 v149, v0
	v_pk_fma_f32 v[80:81], v[96:97], s[52:53], v[80:81] op_sel_hi:[1,0,0]
	v_pk_mul_f32 v[96:97], v[144:145], v[136:137]
	v_mul_f32_e32 v0, 0x4b800000, v81
	v_cmp_gt_f32_e32 vcc, s1, v81
	v_pk_mul_f32 v[152:153], v[148:149], v[146:147]
	v_lshl_add_u64 v[168:169], s[56:57], 0, v[126:127]
	v_cndmask_b32_e32 v0, v81, v0, vcc
	v_rsq_f32_e32 v0, v0
	s_add_i32 s75, s75, 1
	s_add_u32 s60, s60, 0xfffa0000
	s_addc_u32 s61, s61, -1
	v_mul_f32_e32 v81, 0x45800000, v0
	v_cndmask_b32_e32 v0, v0, v81, vcc
	v_pk_mul_f32 v[90:91], v[90:91], v[0:1] op_sel_hi:[1,0]
	v_pk_mul_f32 v[94:95], v[94:95], v[0:1] op_sel_hi:[1,0]
	v_pk_mul_f32 v[90:91], v[74:75], v[90:91]
	v_pk_mul_f32 v[94:95], v[76:77], v[94:95]
	v_pk_mul_f32 v[90:91], v[106:107], v[90:91]
	v_pk_mul_f32 v[94:95], v[108:109], v[94:95]
	v_cvt_pk_bf16_f32 v90, v90, v91
	v_cvt_pk_bf16_f32 v91, v94, v95
	ds_read_b64_tr_b16 v[94:95], v210 offset:2112
	global_store_dwordx2 v[142:143], v[90:91], off
	v_pk_mul_f32 v[90:91], v[92:93], v[0:1] op_sel_hi:[1,0]
	ds_read_b64_tr_b16 v[92:93], v210
	ds_read_b64_tr_b16 v[98:99], v210 offset:2144
	v_pk_mul_f32 v[88:89], v[88:89], v[0:1] op_sel_hi:[1,0]
	v_mul_f32_e32 v0, 0x4b800000, v80
	v_cmp_gt_f32_e32 vcc, s1, v80
	v_pk_mul_f32 v[90:91], v[70:71], v[90:91]
	v_pk_mul_f32 v[224:225], v[72:73], v[88:89]
	v_cndmask_b32_e32 v0, v80, v0, vcc
	v_pk_mul_f32 v[108:109], v[96:97], v[90:91]
	ds_read_b64_tr_b16 v[96:97], v210 offset:32
	ds_read_b64_tr_b16 v[100:101], v213 offset:56352
	ds_read_b64_tr_b16 v[104:105], v213 offset:56384
	ds_read_b64_tr_b16 v[136:137], v213 offset:56416
	ds_read_b64_tr_b16 v[102:103], v213 offset:57440
	ds_read_b64_tr_b16 v[106:107], v213 offset:57472
	ds_read_b64_tr_b16 v[138:139], v213 offset:57504
	ds_read_b64_tr_b16 v[142:143], v213 offset:65024
	ds_read_b64_tr_b16 v[144:145], v214 offset:57408
	ds_read_b64_tr_b16 v[146:147], v210 offset:16896
	ds_read_b64_tr_b16 v[148:149], v210 offset:19008
	ds_read_b64_tr_b16 v[158:159], v210 offset:19040
	ds_read_b64_tr_b16 v[156:157], v210 offset:16928
	ds_read_b64_tr_b16 v[236:237], v213 offset:65056
	ds_read_b64_tr_b16 v[160:161], v213 offset:65088
	ds_read_b64_tr_b16 v[164:165], v213 offset:65120
	ds_read_b64_tr_b16 v[238:239], v214 offset:57440
	ds_read_b64_tr_b16 v[162:163], v214 offset:57472
	ds_read_b64_tr_b16 v[166:167], v214 offset:57504
	ds_read_b64_tr_b16 v[244:245], v213 offset:56448
	ds_read_b64_tr_b16 v[246:247], v213 offset:57536
	s_nop 0
	s_nop 0
	s_nop 0
	s_nop 0
	s_nop 0
	s_nop 0
	s_nop 0
	s_nop 0
	s_nop 0
	s_nop 0
	s_nop 0
	s_nop 0
	v_rsq_f32_e32 v0, v0
	s_nop 0
	s_nop 0
	s_nop 0
	s_nop 0
	s_nop 0
	s_nop 0
	s_waitcnt lgkmcnt(15)
	v_mfma_f32_16x16x32_bf16 v[10:13], v[100:103], v[92:95], v[10:13]
	v_and_b32_e32 v81, 0xffff0000, v150
	v_mul_f32_e32 v80, 0x45800000, v0
	v_cndmask_b32_e32 v0, v0, v80, vcc
	v_mfma_f32_16x16x32_bf16 v[18:21], v[100:103], v[96:99], v[18:21]
	v_lshlrev_b32_e32 v80, 16, v150
	v_mul_f32_e32 v100, 0xbfb8aa3b, v80
	v_mul_f32_e32 v101, 0xbfb8aa3b, v81
	v_mfma_f32_16x16x32_bf16 v[30:33], v[232:235], v[92:95], v[30:33]
	v_exp_f32_e32 v100, v100
	v_pk_mul_f32 v[86:87], v[86:87], v[0:1] op_sel_hi:[1,0]
	v_pk_mul_f32 v[152:153], v[152:153], v[224:225]
	v_mfma_f32_16x16x32_bf16 v[6:9], v[232:235], v[96:99], v[6:9]
	s_nop 0
	s_nop 0
	s_nop 0
	s_nop 0
	s_nop 0
	s_nop 0
	v_pk_mul_f32 v[74:75], v[74:75], v[86:87]
	v_lshlrev_b32_e32 v86, 16, v151
	s_waitcnt lgkmcnt(4)
	v_mfma_f32_16x16x32_bf16 v[10:13], v[236:239], v[146:149], v[10:13]
	v_mul_f32_e32 v87, 0xbfb8aa3b, v86
	v_cvt_pk_bf16_f32 v108, v108, v109
	v_cvt_pk_bf16_f32 v109, v152, v153
	v_mfma_f32_16x16x32_bf16 v[18:21], v[236:239], v[156:159], v[18:21]
	v_exp_f32_e32 v89, v101
	v_add_f32_e32 v88, 1.0, v100
	v_rcp_f32_e32 v88, v88
	global_store_dwordx2 v[168:169], v[108:109], off
	v_add_f32_e32 v89, 1.0, v89
	v_rcp_f32_e32 v89, v89
	v_mfma_f32_16x16x32_bf16 v[14:17], v[104:107], v[92:95], v[14:17]
	v_mul_f32_e64 v82, v82, v0
	v_mul_f32_e64 v83, v83, v0
	v_pk_mul_f32 v[78:79], v[78:79], v[0:1] op_sel_hi:[1,0]
	v_pk_mul_f32 v[80:81], v[88:89], v[80:81]
	v_exp_f32_e32 v88, v87
	v_pk_mul_f32 v[80:81], v[80:81], v[74:75]
	v_and_b32_e32 v87, 0xffff0000, v151
	v_mfma_f32_16x16x32_bf16 v[26:29], v[104:107], v[96:99], v[26:29]
	v_add_f32_e32 v74, 1.0, v88
	v_rcp_f32_e32 v88, v74
	v_mul_f32_e32 v74, 0xbfb8aa3b, v87
	v_exp_f32_e32 v89, v74
	v_pk_mul_f32 v[74:75], v[84:85], v[0:1] op_sel_hi:[1,0]
	ds_read_b64_tr_b16 v[84:85], v213 offset:56480
	v_mfma_f32_16x16x32_bf16 v[38:41], v[136:139], v[92:95], v[38:41]
	v_mul_f32_e64 v108, v76, v74
	v_mul_f32_e64 v109, v77, v75
	v_add_f32_e32 v74, 1.0, v89
	v_rcp_f32_e32 v89, v74
	s_nop 0
	s_nop 0
	v_mfma_f32_16x16x32_bf16 v[50:53], v[136:139], v[96:99], v[50:53]
	v_cvt_pk_bf16_f32 v80, v80, v81
	v_pk_mul_f32 v[136:137], v[88:89], v[86:87]
	ds_read_b64_tr_b16 v[88:89], v213 offset:56512
	ds_read_b64_tr_b16 v[100:101], v213 offset:56544
	ds_read_b64_tr_b16 v[86:87], v213 offset:57568
	ds_read_b64_tr_b16 v[90:91], v213 offset:57600
	ds_read_b64_tr_b16 v[102:103], v213 offset:57632
	ds_read_b64_tr_b16 v[104:105], v213 offset:65152
	ds_read_b64_tr_b16 v[106:107], v214 offset:57536
	ds_read_b64_tr_b16 v[248:249], v213 offset:65184
	s_nop 0
	s_nop 0
	s_nop 0
	s_nop 0
	s_nop 0
	s_nop 0
	s_nop 0
	s_nop 0
	s_waitcnt lgkmcnt(9)
	v_mfma_f32_16x16x32_bf16 v[22:25], v[244:247], v[92:95], v[22:25]
	v_mul_f32_e64 v108, v136, v108
	v_mul_f32_e64 v109, v137, v109
	ds_read_b64_tr_b16 v[136:137], v213 offset:65216
	v_pk_mul_f32 v[70:71], v[70:71], v[82:83]
	v_cvt_pk_bf16_f32 v81, v108, v109
	v_mfma_f32_16x16x32_bf16 v[34:37], v[244:247], v[96:99], v[34:37]
	v_lshl_add_u64 v[108:109], s[56:57], 0, v[128:129]
	v_pk_mul_f32 v[72:73], v[72:73], v[78:79]
	v_lshl_add_u32 v0, s67, 9, v179
	v_mfma_f32_16x16x32_bf16 v[30:33], v[142:145], v[146:149], v[30:33]
	s_sub_i32 s54, s54, 64
	v_mfma_f32_16x16x32_bf16 v[6:9], v[142:145], v[156:159], v[6:9]
	ds_read_b64_tr_b16 v[142:143], v213 offset:65248
	ds_read_b64_tr_b16 v[250:251], v214 offset:57568
	ds_read_b64_tr_b16 v[138:139], v214 offset:57600
	ds_read_b64_tr_b16 v[144:145], v214 offset:57632
	ds_read_b128 v[252:255], v0 offset:4096
	ds_read_b128 v[232:235], v0 offset:4160
	ds_read_b128 v[236:239], v0 offset:4224
	ds_read_b128 v[244:247], v0 offset:4288
	s_nop 0
	s_nop 0
	s_nop 0
	s_nop 0
	s_nop 0
	s_nop 0
	global_store_dwordx2 v[108:109], v[80:81], off
	v_lshlrev_b32_e32 v80, 16, v140
	v_and_b32_e32 v81, 0xffff0000, v140
	s_waitcnt lgkmcnt(10)
	v_mfma_f32_16x16x32_bf16 v[22:25], v[104:107], v[146:149], v[22:25]
	v_mfma_f32_16x16x32_bf16 v[34:37], v[104:107], v[156:159], v[34:37]
	v_mul_f32_e32 v104, 0xbfb8aa3b, v80
	v_mul_f32_e32 v105, 0xbfb8aa3b, v81
	v_exp_f32_e32 v104, v104
	v_mfma_f32_16x16x32_bf16 v[42:45], v[84:87], v[92:95], v[42:45]
	v_mfma_f32_16x16x32_bf16 v[54:57], v[84:87], v[96:99], v[54:57]
	v_exp_f32_e32 v85, v105
	v_add_f32_e32 v84, 1.0, v104
	v_rcp_f32_e32 v84, v84
	s_waitcnt lgkmcnt(6)
	v_mfma_f32_16x16x32_bf16 v[42:45], v[248:251], v[146:149], v[42:45]
	v_add_f32_e32 v85, 1.0, v85
	v_rcp_f32_e32 v85, v85
	v_mfma_f32_16x16x32_bf16 v[54:57], v[248:251], v[156:159], v[54:57]
	ds_read_b128 v[248:251], v0 offset:4352
	v_mul_f32_e64 v74, v84, v80
	v_mul_f32_e64 v75, v85, v81
	v_pk_mul_f32 v[70:71], v[74:75], v[70:71]
	v_lshlrev_b32_e32 v74, 16, v141
	v_and_b32_e32 v75, 0xffff0000, v141
	v_mul_f32_e32 v76, 0xbfb8aa3b, v74
	v_mul_f32_e32 v77, 0xbfb8aa3b, v75
	v_exp_f32_e32 v76, v76
	v_exp_f32_e32 v77, v77
	v_cvt_pk_bf16_f32 v78, v70, v71
	v_lshl_add_u64 v[80:81], s[56:57], 0, v[130:131]
	v_add_f32_e32 v76, 1.0, v76
	v_add_f32_e32 v77, 1.0, v77
	v_rcp_f32_e32 v76, v76
	v_rcp_f32_e32 v77, v77
	v_mfma_f32_16x16x32_bf16 v[14:17], v[160:163], v[146:149], v[14:17]
	s_add_u32 s56, s56, 0xfffe0000
	s_addc_u32 s57, s57, -1
	v_pk_mul_f32 v[74:75], v[76:77], v[74:75]
	v_mfma_f32_16x16x32_bf16 v[26:29], v[160:163], v[156:159], v[26:29]
	v_mul_f32_e64 v74, v74, v72
	v_mul_f32_e64 v75, v75, v73
	s_nop 0
	v_cvt_pk_bf16_f32 v79, v74, v75
	s_nop 0
	global_store_dwordx2 v[80:81], v[78:79], off
	v_mfma_f32_16x16x32_bf16 v[38:41], v[164:167], v[146:149], v[38:41]
	s_waitcnt lgkmcnt(4)
	v_mul_f32_e32 v70, 0x3fb8aa3b, v252
	v_exp_f32_e32 v82, v70
	v_mul_f32_e32 v83, 0x3fb8aa3b, v253
	v_mul_f32_e32 v70, 0x3fb8aa3b, v254
	v_mul_f32_e32 v71, 0x3fb8aa3b, v255
	ds_read_b128 v[252:255], v0 offset:4416
	v_exp_f32_e32 v70, v70
	v_exp_f32_e32 v71, v71
	v_exp_f32_e32 v83, v83
	v_mfma_f32_16x16x32_bf16 v[50:53], v[164:167], v[156:159], v[50:53]
	s_add_u32 s58, s58, 0xfffe0000
	v_pk_mul_f32 v[32:33], v[32:33], v[70:71]
	v_pk_mul_f32 v[8:9], v[8:9], v[70:71]
	s_waitcnt lgkmcnt(4)
	v_mul_f32_e32 v70, 0x3fb8aa3b, v232
	v_mul_f32_e32 v71, 0x3fb8aa3b, v234
	v_exp_f32_e32 v78, v70
	v_mul_f32_e32 v70, 0x3fb8aa3b, v233
	v_exp_f32_e32 v80, v71
	v_mul_f32_e32 v71, 0x3fb8aa3b, v235
	ds_read_b128 v[232:235], v0 offset:4480
	v_exp_f32_e32 v81, v71
	v_exp_f32_e32 v79, v70
	s_nop 0
	s_nop 0
	v_pk_mul_f32 v[30:31], v[30:31], v[82:83]
	v_pk_mul_f32 v[6:7], v[6:7], v[82:83]
	v_pk_mul_f32 v[12:13], v[12:13], v[80:81]
	s_waitcnt lgkmcnt(4)
	v_mul_f32_e32 v70, 0x3fb8aa3b, v236
	v_exp_f32_e32 v82, v70
	v_mul_f32_e32 v83, 0x3fb8aa3b, v237
	v_mul_f32_e32 v70, 0x3fb8aa3b, v238
	v_mul_f32_e32 v71, 0x3fb8aa3b, v239
	ds_read_b128 v[236:239], v0 offset:4544
	v_exp_f32_e32 v70, v70
	v_exp_f32_e32 v71, v71
	v_pk_mul_f32 v[10:11], v[10:11], v[78:79]
	v_pk_mul_f32 v[20:21], v[20:21], v[80:81]
	v_pk_mul_f32 v[18:19], v[18:19], v[78:79]
	v_pk_mul_f32 v[16:17], v[16:17], v[70:71]
	v_pk_mul_f32 v[28:29], v[28:29], v[70:71]
	s_waitcnt lgkmcnt(4)
	v_mul_f32_e32 v70, 0x3fb8aa3b, v244
	v_mul_f32_e32 v71, 0x3fb8aa3b, v246
	v_exp_f32_e32 v78, v70
	v_mul_f32_e32 v70, 0x3fb8aa3b, v245
	v_exp_f32_e32 v80, v71
	v_mul_f32_e32 v71, 0x3fb8aa3b, v247
	v_exp_f32_e32 v81, v71
	v_exp_f32_e32 v79, v70
	s_nop 0
	s_nop 0
	v_exp_f32_e32 v83, v83
	v_pk_mul_f32 v[40:41], v[40:41], v[80:81]
	v_pk_mul_f32 v[38:39], v[38:39], v[78:79]
	s_waitcnt lgkmcnt(3)
	v_mul_f32_e32 v70, 0x3fb8aa3b, v248
	v_pk_mul_f32 v[14:15], v[14:15], v[82:83]
	v_pk_mul_f32 v[26:27], v[26:27], v[82:83]
	v_exp_f32_e32 v82, v70
	v_mul_f32_e32 v83, 0x3fb8aa3b, v249
	v_mul_f32_e32 v70, 0x3fb8aa3b, v250
	v_mul_f32_e32 v71, 0x3fb8aa3b, v251
	v_exp_f32_e32 v70, v70
	v_exp_f32_e32 v71, v71
	v_pk_mul_f32 v[52:53], v[52:53], v[80:81]
	v_pk_mul_f32 v[50:51], v[50:51], v[78:79]
	v_mfma_f32_16x16x32_bf16 v[46:49], v[88:91], v[92:95], v[46:49]
	v_mul_f32_e64 v24, v24, v70
	v_mul_f32_e64 v25, v25, v71
	v_pk_mul_f32 v[36:37], v[36:37], v[70:71]
	s_waitcnt lgkmcnt(2)
	v_mul_f32_e32 v70, 0x3fb8aa3b, v252
	v_mul_f32_e32 v71, 0x3fb8aa3b, v254
	v_exp_f32_e32 v78, v70
	v_mul_f32_e32 v70, 0x3fb8aa3b, v253
	v_exp_f32_e32 v80, v71
	v_mul_f32_e32 v71, 0x3fb8aa3b, v255
	v_exp_f32_e32 v81, v71
	v_exp_f32_e32 v79, v70
	s_nop 0
	s_nop 0
	v_mfma_f32_16x16x32_bf16 v[62:65], v[88:91], v[96:99], v[62:65]
	v_exp_f32_e32 v83, v83
	s_addc_u32 s59, s59, -1
	s_waitcnt lgkmcnt(1)
	v_mul_f32_e32 v0, 0x3fb8aa3b, v232
	v_exp_f32_e32 v70, v0
	v_mul_f32_e32 v0, 0x3fb8aa3b, v233
	v_mul_f32_e32 v71, 0x3fb8aa3b, v234
	v_mfma_f32_16x16x32_bf16 v[58:61], v[100:103], v[92:95], v[58:61]
	v_exp_f32_e32 v72, v71
	v_mul_f32_e32 v71, 0x3fb8aa3b, v235
	v_exp_f32_e32 v73, v71
	v_mfma_f32_16x16x32_bf16 v[66:69], v[100:103], v[96:99], v[66:69]
	v_exp_f32_e32 v71, v0
	s_waitcnt lgkmcnt(0)
	v_mul_f32_e32 v0, 0x3fb8aa3b, v236
	v_exp_f32_e32 v74, v0
	v_mul_f32_e32 v0, 0x3fb8aa3b, v237
	v_mul_f32_e32 v75, 0x3fb8aa3b, v238
	v_exp_f32_e32 v76, v75
	v_mul_f32_e32 v75, 0x3fb8aa3b, v239
	v_mfma_f32_16x16x32_bf16 v[46:49], v[136:139], v[146:149], v[46:49]
	v_exp_f32_e32 v77, v75
	v_exp_f32_e32 v75, v0
	v_pk_mul_f32 v[22:23], v[22:23], v[82:83]
	v_mfma_f32_16x16x32_bf16 v[62:65], v[136:139], v[156:159], v[62:65]
	v_mul_f32_e64 v34, v34, v82
	v_mul_f32_e64 v35, v35, v83
	v_pk_mul_f32 v[44:45], v[44:45], v[80:81]
	v_pk_mul_f32 v[42:43], v[42:43], v[78:79]
	v_mfma_f32_16x16x32_bf16 v[58:61], v[142:145], v[146:149], v[58:61]
	v_mul_f32_e64 v56, v56, v80
	v_mul_f32_e64 v57, v57, v81
	v_pk_mul_f32 v[54:55], v[54:55], v[78:79]
	v_pk_mul_f32 v[48:49], v[48:49], v[72:73]
	v_mfma_f32_16x16x32_bf16 v[66:69], v[142:145], v[156:159], v[66:69]
	v_mul_f32_e64 v46, v46, v70
	v_mul_f32_e64 v47, v47, v71
	v_pk_mul_f32 v[64:65], v[64:65], v[72:73]
	v_pk_mul_f32 v[62:63], v[62:63], v[70:71]
	v_pk_mul_f32 v[60:61], v[60:61], v[76:77]
	v_pk_mul_f32 v[58:59], v[58:59], v[74:75]
	s_nop 1
	v_pk_mul_f32 v[68:69], v[68:69], v[76:77]
	s_cmp_lg_u32 s75, 8
	v_pk_mul_f32 v[66:67], v[66:67], v[74:75]
	s_waitcnt lgkmcnt(0)
	s_cbranch_scc0 .LBB0_654
.LBB0_680:
	s_add_u32 s62, s71, s60
	s_addc_u32 s63, s74, s61
	s_add_u32 s72, s48, s60
	s_addc_u32 s73, s70, s61
	s_add_u32 s55, s72, s68
	v_lshl_add_u64 v[70:71], s[62:63], 0, v[112:113]
	s_addc_u32 s63, s73, 0
	s_add_u32 s62, s55, 0xafc0800
	v_add_co_u32_e32 v74, vcc, s95, v70
	s_addc_u32 s63, s63, 0
	s_nop 0
	v_addc_co_u32_e32 v75, vcc, 0, v71, vcc
	v_lshl_add_u64 v[86:87], s[62:63], 0, v[114:115]
	v_add_co_u32_e32 v78, vcc, s81, v86
	s_and_b32 s67, s75, 1
	s_nop 0
	v_addc_co_u32_e32 v79, vcc, 0, v87, vcc
	s_cmp_eq_u32 s67, 0
	v_add_co_u32_e32 v82, vcc, s95, v86
	s_cselect_b64 s[64:65], -1, 0
	s_nop 0
	v_addc_co_u32_e32 v83, vcc, 0, v87, vcc
	s_and_b64 s[62:63], s[64:65], exec
	global_load_dwordx4 v[94:97], v[70:71], off
	global_load_dwordx4 v[98:101], v[70:71], off offset:1024
	s_nop 0
	global_load_dwordx4 v[70:73], v[74:75], off
	global_load_dwordx4 v[90:93], v[74:75], off offset:1024
	s_cselect_b32 s55, 0xf0, s69
	global_load_dwordx4 v[74:77], v[86:87], off
	v_add_co_u32_e32 v86, vcc, s96, v86
	v_add3_u32 v105, s55, v177, v175
	s_nop 0
	v_addc_co_u32_e32 v87, vcc, 0, v87, vcc
	global_load_dwordx4 v[78:81], v[78:79], off
	s_nop 0
	global_load_dwordx4 v[82:85], v[82:83], off
	s_nop 0
	global_load_dwordx4 v[86:89], v[86:87], off
	s_waitcnt lgkmcnt(0)
	ds_read2_b32 v[102:103], v105 offset1:4
	ds_read2_b32 v[232:233], v105 offset0:8 offset1:12
	ds_read2_b32 v[140:141], v105 offset0:128 offset1:132
	ds_read2_b32 v[236:237], v105 offset0:64 offset1:68
	ds_read2_b32 v[244:245], v105 offset0:72 offset1:76
	ds_read2_b32 v[248:249], v105 offset0:136 offset1:140
	ds_read2_b32 v[252:253], v105 offset0:192 offset1:196
	s_waitcnt vmcnt(12)
	s_waitcnt lgkmcnt(6)
	v_mfma_f32_16x16x4_f32 v[106:109], v102, v219, 0
	s_nop 0
	s_waitcnt vmcnt(11)
	v_mfma_f32_16x16x4_f32 v[106:109], v103, v220, v[106:109]
	s_waitcnt vmcnt(10)
	s_waitcnt lgkmcnt(5)
	v_mfma_f32_16x16x4_f32 v[106:109], v232, v221, v[106:109]
	s_waitcnt vmcnt(9)
	v_mfma_f32_16x16x4_f32 v[106:109], v233, v222, v[106:109]
	ds_read2_b32 v[232:233], v105 offset0:200 offset1:204
	s_nop 0
	s_waitcnt vmcnt(8)
	s_nop 7
	v_add_f32_e32 v102, v223, v106
	v_min_f32_e32 v0, 0, v102
	v_mul_f32_e64 v102, |v102|, s97
	v_exp_f32_e32 v102, v102
	v_add_f32_e32 v103, v223, v107
	v_add_f32_e32 v104, v223, v108
	v_add_f32_e32 v106, v223, v109
	v_add_f32_e32 v102, 1.0, v102
	v_log_f32_e32 v102, v102
	s_nop 0
	v_fmac_f32_e32 v0, 0xbf317218, v102
	v_min_f32_e32 v102, 0, v103
	v_mul_f32_e64 v103, |v103|, s97
	v_exp_f32_e32 v103, v103
	s_nop 0
	v_add_f32_e32 v103, 1.0, v103
	v_log_f32_e32 v103, v103
	s_nop 0
	v_fmac_f32_e32 v102, 0xbf317218, v103
	v_min_f32_e32 v103, 0, v104
	v_mul_f32_e64 v104, |v104|, s97
	v_exp_f32_e32 v104, v104
	s_nop 0
	v_add_f32_e32 v104, 1.0, v104
	v_log_f32_e32 v104, v104
	s_nop 0
	v_fmac_f32_e32 v103, 0xbf317218, v104
	v_min_f32_e32 v104, 0, v106
	v_mul_f32_e64 v106, |v106|, s97
	v_exp_f32_e32 v106, v106
	s_nop 0
	v_add_f32_e32 v106, 1.0, v106
	v_log_f32_e32 v106, v106
	s_nop 0
	v_fmac_f32_e32 v104, 0xbf317218, v106
	s_waitcnt lgkmcnt(4)
	v_mfma_f32_16x16x4_f32 v[106:109], v236, v219, 0
	v_mfma_f32_16x16x4_f32 v[106:109], v237, v220, v[106:109]
	s_nop 0
	s_waitcnt lgkmcnt(3)
	v_mfma_f32_16x16x4_f32 v[106:109], v244, v221, v[106:109]
	v_mfma_f32_16x16x4_f32 v[106:109], v245, v222, v[106:109]
	s_nop 9
	v_add_f32_e32 v136, v223, v106
	v_min_f32_e32 v106, 0, v136
	v_mul_f32_e64 v136, |v136|, s97
	v_exp_f32_e32 v136, v136
	s_nop 0
	v_add_f32_e32 v136, 1.0, v136
	v_log_f32_e32 v136, v136
	s_nop 0
	v_fmac_f32_e32 v106, 0xbf317218, v136
	v_add_f32_e32 v136, v223, v107
	v_min_f32_e32 v107, 0, v136
	v_mul_f32_e64 v136, |v136|, s97
	v_exp_f32_e32 v136, v136
	s_nop 0
	v_add_f32_e32 v136, 1.0, v136
	v_log_f32_e32 v136, v136
	s_nop 0
	v_fmac_f32_e32 v107, 0xbf317218, v136
	v_add_f32_e32 v136, v223, v108
	v_min_f32_e32 v108, 0, v136
	v_mul_f32_e64 v136, |v136|, s97
	v_exp_f32_e32 v136, v136
	s_nop 0
	v_add_f32_e32 v136, 1.0, v136
	v_log_f32_e32 v136, v136
	s_nop 0
	v_fmac_f32_e32 v108, 0xbf317218, v136
	v_add_f32_e32 v136, v223, v109
	v_min_f32_e32 v109, 0, v136
	v_mul_f32_e64 v136, |v136|, s97
	v_exp_f32_e32 v136, v136
	s_nop 0
	v_add_f32_e32 v136, 1.0, v136
	v_log_f32_e32 v136, v136
	s_nop 0
	v_fmac_f32_e32 v109, 0xbf317218, v136
	v_mfma_f32_16x16x4_f32 v[136:139], v140, v219, 0
	v_mfma_f32_16x16x4_f32 v[136:139], v141, v220, v[136:139]
	s_nop 0
	s_waitcnt lgkmcnt(2)
	v_mfma_f32_16x16x4_f32 v[136:139], v248, v221, v[136:139]
	v_mfma_f32_16x16x4_f32 v[136:139], v249, v222, v[136:139]
	s_nop 0
	s_nop 8
	v_add_f32_e32 v136, v223, v136
	v_min_f32_e32 v142, 0, v136
	v_mul_f32_e64 v136, |v136|, s97
	v_exp_f32_e32 v136, v136
	s_nop 0
	v_add_f32_e32 v136, 1.0, v136
	v_log_f32_e32 v136, v136
	s_nop 0
	v_fmac_f32_e32 v142, 0xbf317218, v136
	v_add_f32_e32 v136, v223, v137
	v_min_f32_e32 v143, 0, v136
	v_mul_f32_e64 v136, |v136|, s97
	v_exp_f32_e32 v136, v136
	s_nop 0
	v_add_f32_e32 v136, 1.0, v136
	v_log_f32_e32 v136, v136
	s_nop 0
	v_fmac_f32_e32 v143, 0xbf317218, v136
	v_add_f32_e32 v136, v223, v138
	v_min_f32_e32 v144, 0, v136
	v_mul_f32_e64 v136, |v136|, s97
	v_exp_f32_e32 v136, v136
	s_nop 0
	v_add_f32_e32 v136, 1.0, v136
	v_log_f32_e32 v136, v136
	s_nop 0
	v_fmac_f32_e32 v144, 0xbf317218, v136
	v_add_f32_e32 v136, v223, v139
	v_min_f32_e32 v145, 0, v136
	v_mul_f32_e64 v136, |v136|, s97
	v_exp_f32_e32 v136, v136
	s_nop 0
	v_add_f32_e32 v136, 1.0, v136
	v_log_f32_e32 v136, v136
	s_nop 0
	v_fmac_f32_e32 v145, 0xbf317218, v136
	s_waitcnt lgkmcnt(1)
	v_mfma_f32_16x16x4_f32 v[136:139], v252, v219, 0
	v_mfma_f32_16x16x4_f32 v[136:139], v253, v220, v[136:139]
	s_nop 0
	s_waitcnt lgkmcnt(0)
	v_mfma_f32_16x16x4_f32 v[136:139], v232, v221, v[136:139]
	v_mfma_f32_16x16x4_f32 v[136:139], v233, v222, v[136:139]
	s_nop 9
	v_add_f32_e32 v105, v223, v136
	v_min_f32_e32 v136, 0, v105
	v_mul_f32_e64 v105, |v105|, s97
	v_exp_f32_e32 v105, v105
	s_nop 0
	v_add_f32_e32 v105, 1.0, v105
	v_log_f32_e32 v105, v105
	s_nop 0
	v_fmac_f32_e32 v136, 0xbf317218, v105
	v_add_f32_e32 v105, v223, v137
	v_min_f32_e32 v137, 0, v105
	v_mul_f32_e64 v105, |v105|, s97
	v_exp_f32_e32 v105, v105
	s_nop 0
	v_add_f32_e32 v105, 1.0, v105
	v_log_f32_e32 v105, v105
	s_nop 0
	v_fmac_f32_e32 v137, 0xbf317218, v105
	v_add_f32_e32 v105, v223, v138
	v_min_f32_e32 v138, 0, v105
	v_mul_f32_e64 v105, |v105|, s97
	v_exp_f32_e32 v105, v105
	s_nop 0
	v_add_f32_e32 v105, 1.0, v105
	v_log_f32_e32 v105, v105
	s_nop 0
	v_fmac_f32_e32 v138, 0xbf317218, v105
	v_add_f32_e32 v105, v223, v139
	v_min_f32_e32 v139, 0, v105
	v_mul_f32_e64 v105, |v105|, s97
	v_exp_f32_e32 v105, v105
	s_nop 0
	v_add_f32_e32 v105, 1.0, v105
	v_log_f32_e32 v105, v105
	s_nop 0
	v_fmac_f32_e32 v139, 0xbf317218, v105
	v_fma_f32 v105, v139, s0, 0
	v_fmamk_f32 v138, v138, 0x3d800000, v105
	v_fmamk_f32 v137, v137, 0x3d800000, v138
	v_fmamk_f32 v136, v136, 0x3d800000, v137
	v_fmamk_f32 v139, v145, 0x3d800000, v136
	v_fmamk_f32 v140, v144, 0x3d800000, v139
	v_fmamk_f32 v141, v143, 0x3d800000, v140
	v_fmamk_f32 v142, v142, 0x3d800000, v141
	v_fmamk_f32 v109, v109, 0x3d800000, v142
	v_fmamk_f32 v108, v108, 0x3d800000, v109
	v_fmamk_f32 v107, v107, 0x3d800000, v108
	v_fmamk_f32 v106, v106, 0x3d800000, v107
	v_fmamk_f32 v104, v104, 0x3d800000, v106
	v_fmamk_f32 v103, v103, 0x3d800000, v104
	v_fmamk_f32 v102, v102, 0x3d800000, v103
	v_fmamk_f32 v0, v0, 0x3d800000, v102
	ds_bpermute_b32 v144, v188, v0
	ds_bpermute_b32 v145, v189, v0
	ds_bpermute_b32 v143, v187, v0
	s_waitcnt lgkmcnt(2)
	v_cndmask_b32_e64 v144, 0, v144, s[28:29]
	s_waitcnt lgkmcnt(1)
	v_cndmask_b32_e64 v145, v145, 0, s[8:9]
	v_add_f32_e32 v144, v144, v145
	s_waitcnt lgkmcnt(0)
	v_cndmask_b32_e64 v143, 0, v143, s[4:5]
	v_add_f32_e32 v143, v143, v144
	v_add_f32_e32 v0, v143, v0
	v_add_f32_e32 v102, v143, v102
	ds_write2st64_b32 v200, v0, v102 offset0:24 offset1:26
	v_add_f32_e32 v0, v143, v103
	v_add_f32_e32 v102, v143, v104
	ds_write2st64_b32 v200, v0, v102 offset0:28 offset1:30
	v_add_f32_e32 v0, v143, v106
	v_add_f32_e32 v102, v143, v107
	ds_write2st64_b32 v200, v0, v102 offset0:32 offset1:34
	v_add_f32_e32 v0, v143, v108
	v_add_f32_e32 v102, v143, v109
	ds_write2st64_b32 v200, v0, v102 offset0:36 offset1:38
	v_add_f32_e32 v0, v143, v142
	v_add_f32_e32 v102, v143, v141
	ds_write2st64_b32 v200, v0, v102 offset0:40 offset1:42
	v_add_f32_e32 v0, v143, v140
	v_add_f32_e32 v102, v143, v139
	ds_write2st64_b32 v200, v0, v102 offset0:44 offset1:46
	v_add_f32_e32 v0, v143, v136
	v_add_f32_e32 v102, v143, v137
	ds_write2st64_b32 v200, v0, v102 offset0:48 offset1:50
	v_add_f32_e32 v0, v143, v138
	v_add_f32_e32 v102, v143, v105
	ds_write2st64_b32 v200, v0, v102 offset0:52 offset1:54
	s_waitcnt lgkmcnt(0)
	s_barrier
	s_and_saveexec_b64 s[62:63], s[10:11]
	s_cbranch_execz .LBB0_682
	ds_read_b32 v0, v178 offset:6144
	v_lshl_add_u32 v102, s67, 9, v178
	s_waitcnt lgkmcnt(0)
	ds_write_b32 v102, v0 offset:4096

.LBB0_689:
	ds_read_b128 v[102:105], v201 offset:6144
	ds_read_b128 v[106:109], v201 offset:6160
	s_waitcnt vmcnt(6)
	v_lshlrev_b32_e32 v138, 16, v98
	v_and_b32_e32 v139, 0xffff0000, v98
	s_waitcnt lgkmcnt(1)
	v_mul_f32_e32 v0, 0xbfb8aa3b, v102
	v_exp_f32_e32 v136, v0
	v_mul_f32_e32 v0, 0xbfb8aa3b, v103
	v_exp_f32_e32 v137, v0
	v_mul_f32_e32 v0, 0xbfb8aa3b, v104
	v_pk_mul_f32 v[136:137], v[136:137], v[138:139]
	s_nop 0
	v_cvt_pk_bf16_f32 v98, v136, v137
	v_exp_f32_e32 v136, v0
	v_mul_f32_e32 v0, 0xbfb8aa3b, v105
	v_exp_f32_e32 v137, v0
	v_lshlrev_b32_e32 v138, 16, v99
	v_and_b32_e32 v139, 0xffff0000, v99
	s_waitcnt lgkmcnt(0)
	v_mul_f32_e32 v0, 0xbfb8aa3b, v106
	v_pk_mul_f32 v[136:137], v[136:137], v[138:139]
	v_lshlrev_b32_e32 v138, 16, v100
	v_cvt_pk_bf16_f32 v99, v136, v137
	v_exp_f32_e32 v136, v0
	v_mul_f32_e32 v0, 0xbfb8aa3b, v107
	v_exp_f32_e32 v137, v0
	v_and_b32_e32 v139, 0xffff0000, v100
	v_mul_f32_e32 v0, 0xbfb8aa3b, v108
	v_pk_mul_f32 v[136:137], v[136:137], v[138:139]
	s_nop 0
	v_cvt_pk_bf16_f32 v100, v136, v137
	v_exp_f32_e32 v136, v0
	v_mul_f32_e32 v0, 0xbfb8aa3b, v109
	v_exp_f32_e32 v137, v0
	v_lshlrev_b32_e32 v138, 16, v101
	v_and_b32_e32 v139, 0xffff0000, v101
	v_mul_f32_e32 v0, 0x3fb8aa3b, v102
	v_pk_mul_f32 v[136:137], v[136:137], v[138:139]
	s_nop 0
	v_cvt_pk_bf16_f32 v101, v136, v137
	ds_write_b128 v181, v[98:101] offset:56320
	v_exp_f32_e32 v98, v0
	v_mul_f32_e32 v0, 0x3fb8aa3b, v103
	v_exp_f32_e32 v99, v0
	v_lshlrev_b32_e32 v100, 16, v94
	v_and_b32_e32 v101, 0xffff0000, v94
	v_mul_f32_e32 v0, 0x3fb8aa3b, v104
	v_pk_mul_f32 v[98:99], v[98:99], s[50:51] op_sel_hi:[1,0]
	s_waitcnt vmcnt(4)
	v_lshlrev_b32_e32 v104, 16, v90
	v_pk_mul_f32 v[98:99], v[98:99], v[100:101]
	v_lshlrev_b32_e32 v100, 16, v95
	v_cvt_pk_bf16_f32 v94, v98, v99
	v_exp_f32_e32 v98, v0
	v_mul_f32_e32 v0, 0x3fb8aa3b, v105
	v_exp_f32_e32 v99, v0
	v_and_b32_e32 v101, 0xffff0000, v95
	v_mul_f32_e32 v0, 0x3fb8aa3b, v106
	v_and_b32_e32 v105, 0xffff0000, v90
	v_pk_mul_f32 v[98:99], v[98:99], s[50:51] op_sel_hi:[1,0]
	s_nop 0
	v_pk_mul_f32 v[98:99], v[98:99], v[100:101]
	v_lshlrev_b32_e32 v100, 16, v96
	v_cvt_pk_bf16_f32 v95, v98, v99
	v_exp_f32_e32 v98, v0
	v_mul_f32_e32 v0, 0x3fb8aa3b, v107
	v_exp_f32_e32 v99, v0
	v_and_b32_e32 v101, 0xffff0000, v96
	v_mul_f32_e32 v0, 0x3fb8aa3b, v108
	v_pk_mul_f32 v[98:99], v[98:99], s[50:51] op_sel_hi:[1,0]
	s_nop 0
	v_pk_mul_f32 v[98:99], v[98:99], v[100:101]
	v_lshlrev_b32_e32 v100, 16, v97
	v_cvt_pk_bf16_f32 v96, v98, v99
	v_exp_f32_e32 v98, v0
	v_mul_f32_e32 v0, 0x3fb8aa3b, v109
	v_exp_f32_e32 v99, v0
	v_and_b32_e32 v101, 0xffff0000, v97
	v_pk_mul_f32 v[98:99], v[98:99], s[50:51] op_sel_hi:[1,0]
	s_nop 0
	v_pk_mul_f32 v[98:99], v[98:99], v[100:101]
	s_nop 0
	v_cvt_pk_bf16_f32 v97, v98, v99
	ds_write_b128 v181, v[94:97] offset:38912
	ds_read_b128 v[94:97], v202 offset:6144
	ds_read_b128 v[98:101], v202 offset:6160
	s_waitcnt lgkmcnt(1)
	v_mul_f32_e32 v0, 0xbfb8aa3b, v94
	v_exp_f32_e32 v102, v0
	v_mul_f32_e32 v0, 0xbfb8aa3b, v95
	v_exp_f32_e32 v103, v0
	v_mul_f32_e32 v0, 0xbfb8aa3b, v96
	v_pk_mul_f32 v[102:103], v[102:103], v[104:105]
	s_nop 0
	v_cvt_pk_bf16_f32 v90, v102, v103
	v_exp_f32_e32 v102, v0
	v_mul_f32_e32 v0, 0xbfb8aa3b, v97
	v_exp_f32_e32 v103, v0
	v_lshlrev_b32_e32 v104, 16, v91
	v_and_b32_e32 v105, 0xffff0000, v91
	s_waitcnt lgkmcnt(0)
	v_mul_f32_e32 v0, 0xbfb8aa3b, v98
	v_pk_mul_f32 v[102:103], v[102:103], v[104:105]
	v_lshlrev_b32_e32 v104, 16, v92
	v_cvt_pk_bf16_f32 v91, v102, v103
	v_exp_f32_e32 v102, v0
	v_mul_f32_e32 v0, 0xbfb8aa3b, v99
	v_exp_f32_e32 v103, v0
	v_and_b32_e32 v105, 0xffff0000, v92
	v_mul_f32_e32 v0, 0xbfb8aa3b, v100
	v_pk_mul_f32 v[102:103], v[102:103], v[104:105]
	s_nop 0
	v_cvt_pk_bf16_f32 v92, v102, v103
	v_exp_f32_e32 v102, v0
	v_mul_f32_e32 v0, 0xbfb8aa3b, v101
	v_exp_f32_e32 v103, v0
	v_lshlrev_b32_e32 v104, 16, v93
	v_and_b32_e32 v105, 0xffff0000, v93
	v_mul_f32_e32 v0, 0x3fb8aa3b, v94
	v_pk_mul_f32 v[102:103], v[102:103], v[104:105]
	s_nop 0
	v_cvt_pk_bf16_f32 v93, v102, v103
	ds_write_b128 v182, v[90:93] offset:56320
	v_exp_f32_e32 v90, v0
	v_mul_f32_e32 v0, 0x3fb8aa3b, v95
	v_exp_f32_e32 v91, v0
	v_lshlrev_b32_e32 v92, 16, v70
	v_and_b32_e32 v93, 0xffff0000, v70
	v_mul_f32_e32 v0, 0x3fb8aa3b, v96
	v_pk_mul_f32 v[90:91], v[90:91], s[50:51] op_sel_hi:[1,0]
	s_nop 0
	v_pk_mul_f32 v[90:91], v[90:91], v[92:93]
	v_lshlrev_b32_e32 v92, 16, v71
	v_cvt_pk_bf16_f32 v70, v90, v91
	v_exp_f32_e32 v90, v0
	v_mul_f32_e32 v0, 0x3fb8aa3b, v97
	v_exp_f32_e32 v91, v0
	v_and_b32_e32 v93, 0xffff0000, v71
	v_mul_f32_e32 v0, 0x3fb8aa3b, v98
	v_pk_mul_f32 v[90:91], v[90:91], s[50:51] op_sel_hi:[1,0]
	s_nop 0
	v_pk_mul_f32 v[90:91], v[90:91], v[92:93]
	v_lshlrev_b32_e32 v92, 16, v72
	v_cvt_pk_bf16_f32 v71, v90, v91
	v_exp_f32_e32 v90, v0
	v_mul_f32_e32 v0, 0x3fb8aa3b, v99
	v_exp_f32_e32 v91, v0
	v_and_b32_e32 v93, 0xffff0000, v72
	v_mul_f32_e32 v0, 0x3fb8aa3b, v100
	v_pk_mul_f32 v[90:91], v[90:91], s[50:51] op_sel_hi:[1,0]
	s_nop 0
	v_pk_mul_f32 v[90:91], v[90:91], v[92:93]
	v_lshlrev_b32_e32 v92, 16, v73
	v_cvt_pk_bf16_f32 v72, v90, v91
	v_exp_f32_e32 v90, v0
	v_mul_f32_e32 v0, 0x3fb8aa3b, v101
	v_exp_f32_e32 v91, v0
	v_and_b32_e32 v93, 0xffff0000, v73
	v_pk_mul_f32 v[90:91], v[90:91], s[50:51] op_sel_hi:[1,0]
	s_nop 0
	v_pk_mul_f32 v[90:91], v[90:91], v[92:93]
	s_nop 0
	v_cvt_pk_bf16_f32 v73, v90, v91
	ds_write_b128 v182, v[70:73] offset:38912
	s_waitcnt vmcnt(3)
	ds_write_b128 v203, v[74:77]
	s_waitcnt vmcnt(2)
	ds_write_b128 v204, v[78:81]
	s_waitcnt vmcnt(1)
	ds_write_b128 v203, v[82:85] offset:16896
	s_waitcnt vmcnt(0)
	ds_write_b128 v205, v[86:89]
	v_lshl_add_u64 v[70:71], s[58:59], 0, v[116:117]
	v_lshl_add_u64 v[72:73], s[58:59], 0, v[120:121]
	v_lshl_add_u64 v[74:75], s[58:59], 0, v[122:123]
	global_load_dwordx2 v[156:157], v[70:71], off
	global_load_dwordx2 v[152:153], v[70:71], off offset:32
	global_load_dwordx2 v[148:149], v[72:73], off
	global_load_dwordx2 v[146:147], v[74:75], off
	v_lshl_add_u64 v[70:71], s[58:59], 0, v[124:125]
	v_lshl_add_u64 v[72:73], s[58:59], 0, v[126:127]
	v_lshl_add_u64 v[74:75], s[58:59], 0, v[128:129]
	v_lshl_add_u64 v[76:77], s[58:59], 0, v[130:131]
	global_load_dwordx2 v[144:145], v[70:71], off
	global_load_dwordx2 v[142:143], v[72:73], off
	global_load_dwordx2 v[138:139], v[74:75], off
	global_load_dwordx2 v[136:137], v[76:77], off
	s_waitcnt lgkmcnt(0)
	s_barrier
	s_waitcnt lgkmcnt(0)
	ds_read_b128 v[70:73], v206 offset:56320
	ds_read_b128 v[232:235], v180 offset:38912
	ds_read_b128 v[236:239], v206 offset:56384
	ds_read_b128 v[82:85], v180 offset:38976
	ds_read_b128 v[244:247], v206 offset:56448
	ds_read_b128 v[86:89], v180 offset:39040
	ds_read_b128 v[78:81], v206 offset:56512
	ds_read_b128 v[90:93], v180 offset:39104
	s_waitcnt lgkmcnt(6)
	v_mfma_f32_16x16x32_bf16 v[70:73], v[70:73], v[232:235], 0
	v_mov_b32_e32 v0, s49
	v_cvt_pk_bf16_f32 v166, v62, v63
	v_cvt_pk_bf16_f32 v167, v64, v65
	s_waitcnt lgkmcnt(4)
	v_mfma_f32_16x16x32_bf16 v[70:73], v[236:239], v[82:85], v[70:73]
	s_nop 0
	s_nop 0
	v_cvt_pk_bf16_f32 v168, v66, v67
	v_cvt_pk_bf16_f32 v169, v68, v69
	s_waitcnt lgkmcnt(2)
	v_mfma_f32_16x16x32_bf16 v[70:73], v[244:247], v[86:89], v[70:73]
	s_nop 0
	s_nop 0
	s_add_u32 s55, s72, s68
	s_addc_u32 s63, s73, 0
	s_waitcnt lgkmcnt(0)
	v_mfma_f32_16x16x32_bf16 v[70:73], v[78:81], v[90:93], v[70:73]
	s_add_u32 s62, s55, 0xafc1000
	s_addc_u32 s63, s63, 0
	s_waitcnt vmcnt(7)
	v_lshlrev_b32_e32 v224, 16, v156
	s_nop 3
	v_cndmask_b32_e64 v0, v70, v0, s[14:15]
	v_cndmask_b32_e64 v70, v71, 0, s[30:31]
	v_cndmask_b32_e64 v71, v72, 0, s[34:35]
	v_cndmask_b32_e64 v72, v73, 0, s[36:37]
	v_cvt_pk_bf16_f32 v70, v0, v70
	v_cvt_pk_bf16_f32 v71, v71, v72
	ds_write_b64 v207, v[70:71]
	ds_read_b128 v[248:251], v208 offset:56320
	ds_read_b128 v[252:255], v208 offset:56384
	ds_read_b128 v[236:239], v208 offset:56448
	ds_read_b128 v[74:77], v208 offset:56512
	s_waitcnt lgkmcnt(3)
	v_mfma_f32_16x16x32_bf16 v[70:73], v[248:251], v[232:235], 0
	s_nop 0
	v_mov_b32_e32 v0, s49
	v_and_b32_e32 v225, 0xffff0000, v156
	s_waitcnt lgkmcnt(2)
	v_mfma_f32_16x16x32_bf16 v[70:73], v[252:255], v[82:85], v[70:73]
	s_nop 0
	v_lshlrev_b32_e32 v156, 16, v157
	v_and_b32_e32 v157, 0xffff0000, v157
	s_waitcnt lgkmcnt(1)
	v_mfma_f32_16x16x32_bf16 v[70:73], v[236:239], v[86:89], v[70:73]
	s_nop 0
	s_waitcnt vmcnt(6)
	v_lshlrev_b32_e32 v226, 16, v152
	v_and_b32_e32 v227, 0xffff0000, v152
	s_waitcnt lgkmcnt(0)
	v_mfma_f32_16x16x32_bf16 v[70:73], v[74:77], v[90:93], v[70:73]
	v_lshlrev_b32_e32 v152, 16, v153
	v_and_b32_e32 v153, 0xffff0000, v153
	s_nop 5
	v_cndmask_b32_e64 v0, v70, v0, s[22:23]
	v_cndmask_b32_e64 v70, v71, 0, s[38:39]
	v_cndmask_b32_e64 v71, v72, 0, s[40:41]
	v_cndmask_b32_e64 v72, v73, 0, s[42:43]
	v_cvt_pk_bf16_f32 v70, v0, v70
	v_cvt_pk_bf16_f32 v71, v71, v72
	ds_write_b64 v209, v[70:71]
	s_waitcnt lgkmcnt(0)
	s_barrier
	s_waitcnt lgkmcnt(0)
	ds_read_b64_tr_b16 v[72:73], v210 offset:2112
	ds_read_b64_tr_b16 v[70:71], v210
	ds_read_b64_tr_b16 v[232:233], v210 offset:32
	ds_read_b64_tr_b16 v[236:237], v210 offset:16896
	ds_read_b64_tr_b16 v[238:239], v210 offset:19008
	ds_read_b64_tr_b16 v[234:235], v210 offset:2144
	ds_read_b64_tr_b16 v[244:245], v210 offset:16928
	ds_read_b64_tr_b16 v[246:247], v210 offset:19040
	ds_read_b128 v[248:251], v211
	ds_read_b128 v[252:255], v211 offset:64
	ds_read_b128 v[102:105], v211 offset:2368
	ds_read_b128 v[158:161], v211 offset:4672
	s_waitcnt lgkmcnt(3)
	v_mfma_f32_16x16x32_bf16 v[90:93], v[70:73], v[248:251], 0
	s_nop 0
	v_mfma_f32_16x16x32_bf16 v[86:89], v[232:235], v[248:251], 0
	ds_read_b128 v[248:251], v211 offset:2304
	s_waitcnt lgkmcnt(3)
	v_mfma_f32_16x16x32_bf16 v[90:93], v[236:239], v[252:255], v[90:93]
	v_mfma_f32_16x16x32_bf16 v[86:89], v[244:247], v[252:255], v[86:89]
	ds_read_b128 v[252:255], v211 offset:4608
	s_nop 0
	s_waitcnt lgkmcnt(1)
	v_mfma_f32_16x16x32_bf16 v[98:101], v[70:73], v[248:251], 0
	v_mfma_f32_16x16x32_bf16 v[94:97], v[232:235], v[248:251], 0
	ds_read_b128 v[248:251], v211 offset:6912
	v_mfma_f32_16x16x32_bf16 v[98:101], v[236:239], v[102:105], v[98:101]
	v_mfma_f32_16x16x32_bf16 v[94:97], v[244:247], v[102:105], v[94:97]
	s_nop 0
	s_waitcnt lgkmcnt(1)
	v_mfma_f32_16x16x32_bf16 v[106:109], v[70:73], v[252:255], 0
	v_mfma_f32_16x16x32_bf16 v[102:105], v[232:235], v[252:255], 0
	ds_read_b128 v[252:255], v211 offset:6976
	v_mfma_f32_16x16x32_bf16 v[106:109], v[236:239], v[158:161], v[106:109]
	v_mfma_f32_16x16x32_bf16 v[102:105], v[244:247], v[158:161], v[102:105]
	s_nop 0
	s_waitcnt lgkmcnt(1)
	v_mfma_f32_16x16x32_bf16 v[70:73], v[70:73], v[248:251], 0
	v_mfma_f32_16x16x32_bf16 v[74:77], v[232:235], v[248:251], 0
	ds_read2_b64 v[232:235], v215 offset1:4
	ds_read2_b64 v[248:251], v216 offset0:32 offset1:36
	s_nop 0
	s_waitcnt lgkmcnt(2)
	v_mfma_f32_16x16x32_bf16 v[70:73], v[236:239], v[252:255], v[70:73]
	ds_read2_b64 v[236:239], v217 offset0:64 offset1:68
	v_cvt_pk_bf16_f32 v78, v30, v31
	v_cvt_pk_bf16_f32 v79, v32, v33
	v_cvt_pk_bf16_f32 v80, v10, v11
	v_mfma_f32_16x16x32_bf16 v[74:77], v[244:247], v[252:255], v[74:77]
	ds_read2_b64 v[244:247], v218 offset0:96 offset1:100
	ds_read2_b64 v[252:255], v215 offset0:8 offset1:12
	v_cvt_pk_bf16_f32 v81, v12, v13
	v_cvt_pk_bf16_f32 v82, v6, v7
	v_cvt_pk_bf16_f32 v83, v8, v9
	v_cvt_pk_bf16_f32 v84, v18, v19
	v_cvt_pk_bf16_f32 v85, v20, v21
	s_nop 0
	s_waitcnt lgkmcnt(4)
	v_mfma_f32_16x16x32_bf16 v[90:93], v[78:81], v[232:235], v[90:93]
	v_mfma_f32_16x16x32_bf16 v[86:89], v[82:85], v[232:235], v[86:89]
	ds_read2_b64 v[232:235], v216 offset0:40 offset1:44
	s_nop 0
	s_waitcnt lgkmcnt(4)
	v_mfma_f32_16x16x32_bf16 v[98:101], v[78:81], v[248:251], v[98:101]
	v_mfma_f32_16x16x32_bf16 v[94:97], v[82:85], v[248:251], v[94:97]
	ds_read2_b64 v[248:251], v217 offset0:72 offset1:76
	s_nop 0
	s_waitcnt lgkmcnt(4)
	v_mfma_f32_16x16x32_bf16 v[106:109], v[78:81], v[236:239], v[106:109]
	v_mfma_f32_16x16x32_bf16 v[102:105], v[82:85], v[236:239], v[102:105]
	ds_read2_b64 v[236:239], v218 offset0:104 offset1:108
	s_nop 0
	s_waitcnt lgkmcnt(4)
	v_mfma_f32_16x16x32_bf16 v[70:73], v[78:81], v[244:247], v[70:73]
	v_cvt_pk_bf16_f32 v78, v14, v15
	v_cvt_pk_bf16_f32 v79, v16, v17
	v_cvt_pk_bf16_f32 v80, v38, v39
	v_mfma_f32_16x16x32_bf16 v[74:77], v[82:85], v[244:247], v[74:77]
	ds_read2_b64 v[244:247], v215 offset0:16 offset1:20
	v_cvt_pk_bf16_f32 v81, v40, v41
	v_cvt_pk_bf16_f32 v82, v26, v27
	v_cvt_pk_bf16_f32 v83, v28, v29
	v_cvt_pk_bf16_f32 v84, v50, v51
	v_cvt_pk_bf16_f32 v85, v52, v53
	s_nop 0
	s_waitcnt lgkmcnt(4)
	v_mfma_f32_16x16x32_bf16 v[90:93], v[78:81], v[252:255], v[90:93]
	v_mfma_f32_16x16x32_bf16 v[86:89], v[82:85], v[252:255], v[86:89]
	ds_read2_b64 v[252:255], v216 offset0:48 offset1:52
	s_nop 0
	s_waitcnt lgkmcnt(4)
	v_mfma_f32_16x16x32_bf16 v[98:101], v[78:81], v[232:235], v[98:101]
	v_mfma_f32_16x16x32_bf16 v[94:97], v[82:85], v[232:235], v[94:97]
	ds_read2_b64 v[232:235], v217 offset0:80 offset1:84
	s_nop 0
	s_waitcnt lgkmcnt(4)
	v_mfma_f32_16x16x32_bf16 v[106:109], v[78:81], v[248:251], v[106:109]
	v_mfma_f32_16x16x32_bf16 v[102:105], v[82:85], v[248:251], v[102:105]
	ds_read2_b64 v[248:251], v218 offset0:112 offset1:116
	s_nop 0
	s_waitcnt lgkmcnt(4)
	v_mfma_f32_16x16x32_bf16 v[70:73], v[78:81], v[236:239], v[70:73]
	v_cvt_pk_bf16_f32 v78, v22, v23
	v_cvt_pk_bf16_f32 v79, v24, v25
	v_cvt_pk_bf16_f32 v80, v42, v43
	v_mfma_f32_16x16x32_bf16 v[74:77], v[82:85], v[236:239], v[74:77]
	ds_read2_b64 v[236:239], v215 offset0:24 offset1:28
	v_cvt_pk_bf16_f32 v81, v44, v45
	v_cvt_pk_bf16_f32 v82, v34, v35
	v_cvt_pk_bf16_f32 v83, v36, v37
	v_cvt_pk_bf16_f32 v84, v54, v55
	v_cvt_pk_bf16_f32 v85, v56, v57
	s_nop 0
	s_waitcnt lgkmcnt(4)
	v_mfma_f32_16x16x32_bf16 v[90:93], v[78:81], v[244:247], v[90:93]
	v_mfma_f32_16x16x32_bf16 v[86:89], v[82:85], v[244:247], v[86:89]
	ds_read2_b64 v[244:247], v216 offset0:56 offset1:60
	s_nop 0
	s_waitcnt lgkmcnt(4)
	v_mfma_f32_16x16x32_bf16 v[98:101], v[78:81], v[252:255], v[98:101]
	v_mfma_f32_16x16x32_bf16 v[94:97], v[82:85], v[252:255], v[94:97]
	ds_read2_b64 v[252:255], v217 offset0:88 offset1:92
	s_nop 0
	s_waitcnt lgkmcnt(4)
	v_mfma_f32_16x16x32_bf16 v[162:165], v[78:81], v[232:235], v[106:109]
	v_mfma_f32_16x16x32_bf16 v[158:161], v[82:85], v[232:235], v[102:105]
	ds_read2_b64 v[232:235], v218 offset0:120 offset1:124
	s_nop 2
	s_nop 0
	s_waitcnt lgkmcnt(4)
	v_mfma_f32_16x16x32_bf16 v[70:73], v[78:81], v[248:251], v[70:73]
	v_cvt_pk_bf16_f32 v78, v46, v47
	v_cvt_pk_bf16_f32 v79, v48, v49
	v_cvt_pk_bf16_f32 v80, v58, v59
	v_mfma_f32_16x16x32_bf16 v[74:77], v[82:85], v[248:251], v[74:77]
	v_cvt_pk_bf16_f32 v81, v60, v61
	s_nop 0
	s_waitcnt lgkmcnt(3)
	v_mfma_f32_16x16x32_bf16 v[106:109], v[78:81], v[236:239], v[90:93]
	v_mfma_f32_16x16x32_bf16 v[102:105], v[166:169], v[236:239], v[86:89]
	s_nop 0
	s_nop 5
	v_pk_add_f32 v[106:107], v[106:107], v[224:225]
	v_pk_add_f32 v[108:109], v[108:109], v[156:157]
	s_waitcnt lgkmcnt(2)
	v_mfma_f32_16x16x32_bf16 v[98:101], v[78:81], v[244:247], v[98:101]
	v_mul_f32_e64 v156, v106, v106
	v_mul_f32_e64 v157, v107, v107
	v_pk_mul_f32 v[224:225], v[108:109], v[108:109]
	v_add_f32_e32 v0, v156, v157
	v_mfma_f32_16x16x32_bf16 v[94:97], v[166:169], v[244:247], v[94:97]
	s_nop 0
	v_pk_add_f32 v[102:103], v[102:103], v[226:227]
	v_add_f32_e32 v0, v224, v0
	s_waitcnt lgkmcnt(1)
	v_mfma_f32_16x16x32_bf16 v[86:89], v[166:169], v[252:255], v[158:161]
	v_add_f32_e64 v104, v104, v152
	v_add_f32_e64 v105, v105, v153
	s_nop 0
	s_nop 0
	v_pk_mul_f32 v[152:153], v[102:103], v[102:103]
	v_mfma_f32_16x16x32_bf16 v[90:93], v[78:81], v[252:255], v[162:165]
	v_add_f32_e32 v0, v225, v0
	v_add_f32_e32 v0, v152, v0
	v_pk_mul_f32 v[226:227], v[104:105], v[104:105]
	s_waitcnt lgkmcnt(0)
	v_mfma_f32_16x16x32_bf16 v[82:85], v[78:81], v[232:235], v[70:73]
	v_add_f32_e32 v0, v153, v0
	v_add_f32_e32 v0, v226, v0
	v_add_f32_e32 v0, v227, v0
	v_lshl_add_u64 v[70:71], s[62:63], 0, v[118:119]
	v_add_co_u32_e32 v72, vcc, s81, v70
	v_mfma_f32_16x16x32_bf16 v[78:81], v[166:169], v[232:235], v[74:77]
	s_nop 0
	v_addc_co_u32_e32 v73, vcc, 0, v71, vcc
	global_load_dwordx2 v[168:169], v[70:71], off
	global_load_dwordx2 v[166:167], v[70:71], off offset:32
	global_load_dwordx2 v[164:165], v[72:73], off
	global_load_dwordx2 v[162:163], v[72:73], off offset:32
	v_add_co_u32_e32 v72, vcc, s95, v70
	ds_bpermute_b32 v152, v190, v0
	s_nop 0
	v_addc_co_u32_e32 v73, vcc, 0, v71, vcc
	v_add_co_u32_e32 v70, vcc, s96, v70
	global_load_dwordx2 v[160:161], v[72:73], off
	global_load_dwordx2 v[158:159], v[72:73], off offset:32
	v_addc_co_u32_e32 v71, vcc, 0, v71, vcc
	global_load_dwordx2 v[150:151], v[70:71], off
	global_load_dwordx2 v[140:141], v[70:71], off offset:32
	global_load_dwordx4 v[74:77], v[134:135], off
	s_nop 0
	global_load_dwordx4 v[70:73], v[134:135], off offset:64
	s_waitcnt lgkmcnt(0)
	v_add_f32_e32 v0, v0, v152
	ds_bpermute_b32 v152, v191, v0
	s_and_saveexec_b64 s[62:63], s[4:5]
	s_waitcnt lgkmcnt(0)
	s_cbranch_execz .LBB0_691
	s_waitcnt lgkmcnt(0)
	v_add_f32_e32 v0, v0, v152
	ds_write_b32 v185, v0

.LBB0_2085:
	s_waitcnt lgkmcnt(0)
	ds_read_b128 v[136:139], v119 offset:6144
	ds_read_b128 v[140:143], v119 offset:6160
	s_waitcnt vmcnt(5)
	v_lshlrev_b32_e32 v144, 16, v54
	v_and_b32_e32 v145, 0xffff0000, v54
	s_add_i32 s24, s25, s24
	s_waitcnt lgkmcnt(1)
	v_mul_f32_e32 v136, 0xbfb8aa3b, v136
	v_mul_f32_e32 v137, 0xbfb8aa3b, v137
	v_exp_f32_e32 v136, v136
	v_exp_f32_e32 v137, v137
	v_mul_f32_e32 v54, 0xbfb8aa3b, v138
	v_exp_f32_e32 v138, v54
	v_mul_f32_e32 v54, 0xbfb8aa3b, v139
	v_exp_f32_e32 v139, v54
	v_pk_mul_f32 v[136:137], v[136:137], v[144:145]
	s_add_i32 s57, s57, 1
	v_cvt_pk_bf16_f32 v54, v136, v137
	v_lshlrev_b32_e32 v136, 16, v55
	v_and_b32_e32 v137, 0xffff0000, v55
	s_waitcnt lgkmcnt(0)
	v_mul_f32_e32 v55, 0xbfb8aa3b, v140
	v_pk_mul_f32 v[136:137], v[138:139], v[136:137]
	v_exp_f32_e32 v138, v55
	v_mul_f32_e32 v55, 0xbfb8aa3b, v141
	v_exp_f32_e32 v139, v55
	v_cvt_pk_bf16_f32 v55, v136, v137
	v_lshlrev_b32_e32 v136, 16, v56
	v_and_b32_e32 v137, 0xffff0000, v56
	v_mul_f32_e32 v56, 0xbfb8aa3b, v142
	v_pk_mul_f32 v[136:137], v[138:139], v[136:137]
	v_exp_f32_e32 v138, v56
	v_mul_f32_e32 v56, 0xbfb8aa3b, v143
	v_exp_f32_e32 v139, v56
	v_cvt_pk_bf16_f32 v56, v136, v137
	v_lshlrev_b32_e32 v136, 16, v57
	v_and_b32_e32 v137, 0xffff0000, v57
	v_pk_mul_f32 v[136:137], v[138:139], v[136:137]
	s_waitcnt vmcnt(4)
	v_lshlrev_b32_e32 v140, 16, v6
	v_cvt_pk_bf16_f32 v57, v136, v137
	ds_write_b128 v120, v[54:57] offset:56320
	ds_read_b128 v[232:235], v121 offset:6144
	ds_read_b128 v[136:139], v121 offset:6160
	v_and_b32_e32 v141, 0xffff0000, v6
	s_mul_i32 s31, s24, 0x1800
	s_mul_hi_i32 s30, s24, 0x1800
	s_waitcnt lgkmcnt(1)
	v_mul_f32_e32 v54, 0xbfb8aa3b, v232
	v_mul_f32_e32 v55, 0xbfb8aa3b, v233
	v_exp_f32_e32 v54, v54
	v_exp_f32_e32 v55, v55
	v_mul_f32_e32 v6, 0xbfb8aa3b, v234
	v_exp_f32_e32 v56, v6
	v_mul_f32_e32 v6, 0xbfb8aa3b, v235
	v_exp_f32_e32 v57, v6
	v_pk_mul_f32 v[54:55], v[54:55], v[140:141]
	s_add_u32 s28, s61, s31
	v_cvt_pk_bf16_f32 v6, v54, v55
	v_lshlrev_b32_e32 v54, 16, v7
	v_and_b32_e32 v55, 0xffff0000, v7
	s_waitcnt lgkmcnt(0)
	v_mul_f32_e32 v7, 0xbfb8aa3b, v136
	v_pk_mul_f32 v[54:55], v[56:57], v[54:55]
	v_exp_f32_e32 v56, v7
	v_mul_f32_e32 v7, 0xbfb8aa3b, v137
	v_exp_f32_e32 v57, v7
	v_cvt_pk_bf16_f32 v7, v54, v55
	v_lshlrev_b32_e32 v54, 16, v8
	v_and_b32_e32 v55, 0xffff0000, v8
	v_mul_f32_e32 v8, 0xbfb8aa3b, v138
	v_pk_mul_f32 v[54:55], v[56:57], v[54:55]
	v_exp_f32_e32 v56, v8
	v_mul_f32_e32 v8, 0xbfb8aa3b, v139
	v_exp_f32_e32 v57, v8
	v_cvt_pk_bf16_f32 v8, v54, v55
	v_lshlrev_b32_e32 v54, 16, v9
	v_and_b32_e32 v55, 0xffff0000, v9
	v_pk_mul_f32 v[54:55], v[56:57], v[54:55]
	s_addc_u32 s29, s62, s30
	v_cvt_pk_bf16_f32 v9, v54, v55
	ds_write_b128 v122, v[6:9] offset:56320
	s_waitcnt vmcnt(3)
	ds_write_b128 v123, v[2:5]
	s_waitcnt vmcnt(2)
	ds_write_b128 v124, v[10:13]
	s_waitcnt vmcnt(1)
	ds_write_b128 v123, v[14:17] offset:16896
	s_waitcnt vmcnt(0)
	ds_write_b128 v125, v[18:21]
	v_lshl_add_u64 v[2:3], s[28:29], 0, v[96:97]
	s_add_u32 s28, s20, s31
	s_addc_u32 s29, s21, s30
	s_add_u32 s28, s28, s56
	s_addc_u32 s29, s29, 0
	s_add_u32 s28, s28, 0xad20800
	v_add_co_u32_e32 v4, vcc, s42, v2
	s_addc_u32 s29, s29, 0
	s_nop 0
	v_addc_co_u32_e32 v5, vcc, 0, v3, vcc
	v_lshl_add_u64 v[14:15], s[28:29], 0, v[98:99]
	v_add_co_u32_e32 v10, vcc, s43, v14
	global_load_dwordx4 v[54:57], v[2:3], off offset:1024
	global_load_dwordx4 v[6:9], v[4:5], off offset:1024
	v_addc_co_u32_e32 v11, vcc, 0, v15, vcc
	v_add_co_u32_e32 v16, vcc, s42, v14
	global_load_dwordx4 v[2:5], v[14:15], off
	s_nop 0
	global_load_dwordx4 v[10:13], v[10:11], off
	v_addc_co_u32_e32 v17, vcc, 0, v15, vcc
	v_add_co_u32_e32 v18, vcc, s44, v14
	s_cmp_eq_u32 s23, s57
	s_nop 0
	v_addc_co_u32_e32 v19, vcc, 0, v15, vcc
	global_load_dwordx4 v[14:17], v[16:17], off
	s_nop 0
	global_load_dwordx4 v[18:21], v[18:19], off
	s_waitcnt lgkmcnt(0)
	s_barrier
	s_waitcnt lgkmcnt(0)
	ds_read_b64_tr_b16 v[138:139], v127 offset:57408
	ds_read_b64_tr_b16 v[136:137], v127 offset:56320
	ds_read_b64_tr_b16 v[142:143], v126 offset:2112
	ds_read_b64_tr_b16 v[140:141], v126
	ds_read_b64_tr_b16 v[146:147], v126 offset:2144
	ds_read_b64_tr_b16 v[144:145], v126 offset:32
	ds_read_b64_tr_b16 v[232:233], v127 offset:56352
	ds_read_b64_tr_b16 v[156:157], v127 offset:56384
	ds_read_b64_tr_b16 v[160:161], v127 offset:56416
	ds_read_b64_tr_b16 v[234:235], v127 offset:57440
	ds_read_b64_tr_b16 v[158:159], v127 offset:57472
	ds_read_b64_tr_b16 v[162:163], v127 offset:57504
	ds_read_b64_tr_b16 v[164:165], v127 offset:65024
	ds_read_b64_tr_b16 v[166:167], v128 offset:57408
	ds_read_b64_tr_b16 v[168:169], v126 offset:16896
	ds_read_b64_tr_b16 v[170:171], v126 offset:19008
	ds_read_b64_tr_b16 v[174:175], v126 offset:19040
	ds_read_b64_tr_b16 v[172:173], v126 offset:16928
	ds_read_b64_tr_b16 v[236:237], v127 offset:65056
	ds_read_b64_tr_b16 v[176:177], v127 offset:65088
	ds_read_b64_tr_b16 v[180:181], v127 offset:65120
	ds_read_b64_tr_b16 v[238:239], v128 offset:57440
	ds_read_b64_tr_b16 v[178:179], v128 offset:57472
	ds_read_b64_tr_b16 v[182:183], v128 offset:57504
	ds_read_b64_tr_b16 v[244:245], v127 offset:56448
	ds_read_b64_tr_b16 v[246:247], v127 offset:57536
	ds_read_b64_tr_b16 v[148:149], v127 offset:56480
	s_waitcnt lgkmcnt(15)
	v_mfma_f32_16x16x32_bf16 v[58:61], v[232:235], v[140:143], v[58:61]
	v_mfma_f32_16x16x32_bf16 v[78:81], v[232:235], v[144:147], v[78:81]
	v_mfma_f32_16x16x32_bf16 v[66:69], v[136:139], v[140:143], v[66:69]
	v_mfma_f32_16x16x32_bf16 v[62:65], v[136:139], v[144:147], v[62:65]
	s_nop 0
	s_nop 0
	s_nop 0
	s_nop 0
	s_nop 0
	s_nop 0
	s_waitcnt lgkmcnt(5)
	v_mfma_f32_16x16x32_bf16 v[58:61], v[236:239], v[168:171], v[58:61]
	v_mfma_f32_16x16x32_bf16 v[78:81], v[236:239], v[172:175], v[78:81]
	s_nop 0
	s_nop 0
	v_mfma_f32_16x16x32_bf16 v[74:77], v[156:159], v[140:143], v[74:77]
	v_mfma_f32_16x16x32_bf16 v[70:73], v[156:159], v[144:147], v[70:73]
	ds_read_b64_tr_b16 v[156:157], v127 offset:56512
	v_mfma_f32_16x16x32_bf16 v[82:85], v[160:163], v[140:143], v[82:85]
	v_mfma_f32_16x16x32_bf16 v[86:89], v[160:163], v[144:147], v[86:89]
	ds_read_b64_tr_b16 v[160:161], v127 offset:56544
	ds_read_b64_tr_b16 v[150:151], v127 offset:57568
	ds_read_b64_tr_b16 v[158:159], v127 offset:57600
	ds_read_b64_tr_b16 v[162:163], v127 offset:57632
	s_nop 0
	s_nop 0
	s_nop 0
	s_nop 0
	s_nop 0
	s_nop 0
	s_waitcnt lgkmcnt(2)
	v_mfma_f32_16x16x32_bf16 v[22:25], v[148:151], v[140:143], v[22:25]
	v_mfma_f32_16x16x32_bf16 v[50:53], v[148:151], v[144:147], v[50:53]
	v_lshl_add_u32 v150, s63, 9, v111
	v_mfma_f32_16x16x32_bf16 v[66:69], v[164:167], v[168:171], v[66:69]
	v_mfma_f32_16x16x32_bf16 v[62:65], v[164:167], v[172:175], v[62:65]
	ds_read_b64_tr_b16 v[164:165], v127 offset:65152
	ds_read_b64_tr_b16 v[166:167], v128 offset:57536
	ds_read_b64_tr_b16 v[248:249], v127 offset:65184
	v_mfma_f32_16x16x32_bf16 v[74:77], v[176:179], v[168:171], v[74:77]
	v_mfma_f32_16x16x32_bf16 v[70:73], v[176:179], v[172:175], v[70:73]
	ds_read_b64_tr_b16 v[176:177], v127 offset:65216
	v_mfma_f32_16x16x32_bf16 v[82:85], v[180:183], v[168:171], v[82:85]
	v_mfma_f32_16x16x32_bf16 v[86:89], v[180:183], v[172:175], v[86:89]
	ds_read_b64_tr_b16 v[180:181], v127 offset:65248
	ds_read_b64_tr_b16 v[250:251], v128 offset:57568
	ds_read_b64_tr_b16 v[178:179], v128 offset:57600
	ds_read_b64_tr_b16 v[182:183], v128 offset:57632
	ds_read_b128 v[252:255], v150 offset:4096
	ds_read_b128 v[232:235], v150 offset:4160
	ds_read_b128 v[236:239], v150 offset:4224
	v_mfma_f32_16x16x32_bf16 v[30:33], v[244:247], v[140:143], v[30:33]
	v_mfma_f32_16x16x32_bf16 v[26:29], v[244:247], v[144:147], v[26:29]
	ds_read_b128 v[244:247], v150 offset:4288
	s_nop 0
	s_nop 0
	s_nop 0
	s_nop 0
	s_nop 0
	s_nop 0
	s_waitcnt lgkmcnt(6)
	v_mfma_f32_16x16x32_bf16 v[22:25], v[248:251], v[168:171], v[22:25]
	v_mfma_f32_16x16x32_bf16 v[50:53], v[248:251], v[172:175], v[50:53]
	ds_read_b128 v[248:251], v150 offset:4352
	s_nop 0
	v_mfma_f32_16x16x32_bf16 v[34:37], v[156:159], v[140:143], v[34:37]
	v_mfma_f32_16x16x32_bf16 v[38:41], v[160:163], v[140:143], v[38:41]
	s_nop 0
	s_waitcnt lgkmcnt(4)
	v_mul_f32_e32 v136, 0x3fb8aa3b, v252
	v_mfma_f32_16x16x32_bf16 v[46:49], v[156:159], v[144:147], v[46:49]
	v_mfma_f32_16x16x32_bf16 v[42:45], v[160:163], v[144:147], v[42:45]
	v_exp_f32_e32 v144, v136
	v_mul_f32_e32 v145, 0x3fb8aa3b, v253
	v_mul_f32_e32 v136, 0x3fb8aa3b, v254
	v_mul_f32_e32 v137, 0x3fb8aa3b, v255
	ds_read_b128 v[252:255], v150 offset:4416
	v_exp_f32_e32 v136, v136
	v_exp_f32_e32 v137, v137
	v_exp_f32_e32 v145, v145
	v_mfma_f32_16x16x32_bf16 v[30:33], v[164:167], v[168:171], v[30:33]
	v_mul_f32_e64 v68, v68, v136
	v_mul_f32_e64 v69, v69, v137
	v_pk_mul_f32 v[64:65], v[64:65], v[136:137]
	s_waitcnt lgkmcnt(4)
	v_mul_f32_e32 v136, 0x3fb8aa3b, v232
	v_mul_f32_e32 v137, 0x3fb8aa3b, v234
	v_exp_f32_e32 v146, v136
	v_mul_f32_e32 v136, 0x3fb8aa3b, v233
	v_exp_f32_e32 v148, v137
	v_mul_f32_e32 v137, 0x3fb8aa3b, v235
	ds_read_b128 v[232:235], v150 offset:4480
	v_exp_f32_e32 v149, v137
	v_exp_f32_e32 v147, v136
	s_nop 0
	s_nop 0
	v_pk_mul_f32 v[66:67], v[66:67], v[144:145]
	v_pk_mul_f32 v[62:63], v[62:63], v[144:145]
	v_pk_mul_f32 v[60:61], v[60:61], v[148:149]
	s_waitcnt lgkmcnt(4)
	v_mul_f32_e32 v136, 0x3fb8aa3b, v236
	v_exp_f32_e32 v144, v136
	v_mul_f32_e32 v145, 0x3fb8aa3b, v237
	v_mul_f32_e32 v136, 0x3fb8aa3b, v238
	v_mul_f32_e32 v137, 0x3fb8aa3b, v239
	ds_read_b128 v[236:239], v150 offset:4544
	v_exp_f32_e32 v136, v136
	v_exp_f32_e32 v137, v137
	v_pk_mul_f32 v[58:59], v[58:59], v[146:147]
	v_pk_mul_f32 v[80:81], v[80:81], v[148:149]
	v_pk_mul_f32 v[78:79], v[78:79], v[146:147]
	v_pk_mul_f32 v[76:77], v[76:77], v[136:137]
	v_pk_mul_f32 v[72:73], v[72:73], v[136:137]
	s_waitcnt lgkmcnt(4)
	v_mul_f32_e32 v136, 0x3fb8aa3b, v244
	v_mul_f32_e32 v137, 0x3fb8aa3b, v246
	v_exp_f32_e32 v146, v136
	v_mul_f32_e32 v136, 0x3fb8aa3b, v245
	v_exp_f32_e32 v148, v137
	v_mul_f32_e32 v137, 0x3fb8aa3b, v247
	v_exp_f32_e32 v149, v137
	v_exp_f32_e32 v147, v136
	s_nop 0
	s_nop 0
	v_exp_f32_e32 v145, v145
	v_mfma_f32_16x16x32_bf16 v[26:29], v[164:167], v[172:175], v[26:29]
	v_mul_f32_e64 v84, v84, v148
	v_mul_f32_e64 v85, v85, v149
	s_waitcnt lgkmcnt(3)
	v_mul_f32_e32 v136, 0x3fb8aa3b, v248
	v_pk_mul_f32 v[74:75], v[74:75], v[144:145]
	v_pk_mul_f32 v[70:71], v[70:71], v[144:145]
	v_exp_f32_e32 v144, v136
	v_mul_f32_e32 v145, 0x3fb8aa3b, v249
	v_mul_f32_e32 v136, 0x3fb8aa3b, v250
	v_mul_f32_e32 v137, 0x3fb8aa3b, v251
	v_exp_f32_e32 v136, v136
	v_exp_f32_e32 v137, v137
	v_pk_mul_f32 v[82:83], v[82:83], v[146:147]
	v_pk_mul_f32 v[88:89], v[88:89], v[148:149]
	v_pk_mul_f32 v[86:87], v[86:87], v[146:147]
	v_pk_mul_f32 v[32:33], v[32:33], v[136:137]
	v_pk_mul_f32 v[28:29], v[28:29], v[136:137]
	s_waitcnt lgkmcnt(2)
	v_mul_f32_e32 v136, 0x3fb8aa3b, v252
	v_mul_f32_e32 v137, 0x3fb8aa3b, v254
	v_exp_f32_e32 v146, v136
	v_mul_f32_e32 v136, 0x3fb8aa3b, v253
	v_exp_f32_e32 v148, v137
	v_mul_f32_e32 v137, 0x3fb8aa3b, v255
	v_exp_f32_e32 v149, v137
	v_exp_f32_e32 v147, v136
	s_nop 0
	s_nop 0
	v_mfma_f32_16x16x32_bf16 v[34:37], v[176:179], v[168:171], v[34:37]
	v_exp_f32_e32 v145, v145
	v_pk_mul_f32 v[24:25], v[24:25], v[148:149]
	s_waitcnt lgkmcnt(1)
	v_mul_f32_e32 v136, 0x3fb8aa3b, v232
	v_mul_f32_e32 v137, 0x3fb8aa3b, v233
	v_mul_f32_e32 v138, 0x3fb8aa3b, v234
	v_mul_f32_e32 v139, 0x3fb8aa3b, v235
	s_waitcnt lgkmcnt(0)
	v_mul_f32_e32 v140, 0x3fb8aa3b, v236
	v_mul_f32_e32 v141, 0x3fb8aa3b, v237
	v_mul_f32_e32 v142, 0x3fb8aa3b, v238
	v_mul_f32_e32 v143, 0x3fb8aa3b, v239
	v_mfma_f32_16x16x32_bf16 v[46:49], v[176:179], v[172:175], v[46:49]
	v_exp_f32_e32 v136, v136
	v_exp_f32_e32 v138, v138
	v_exp_f32_e32 v139, v139
	v_mfma_f32_16x16x32_bf16 v[38:41], v[180:183], v[168:171], v[38:41]
	v_exp_f32_e32 v137, v137
	v_exp_f32_e32 v140, v140
	v_exp_f32_e32 v142, v142
	v_mfma_f32_16x16x32_bf16 v[42:45], v[180:183], v[172:175], v[42:45]
	v_exp_f32_e32 v143, v143
	v_exp_f32_e32 v141, v141
	v_pk_mul_f32 v[30:31], v[30:31], v[144:145]
	v_pk_mul_f32 v[26:27], v[26:27], v[144:145]
	v_pk_mul_f32 v[22:23], v[22:23], v[146:147]
	v_pk_mul_f32 v[52:53], v[52:53], v[148:149]
	v_pk_mul_f32 v[50:51], v[50:51], v[146:147]
	v_pk_mul_f32 v[36:37], v[36:37], v[138:139]
	v_pk_mul_f32 v[34:35], v[34:35], v[136:137]
	v_pk_mul_f32 v[48:49], v[48:49], v[138:139]
	v_pk_mul_f32 v[46:47], v[46:47], v[136:137]
	v_pk_mul_f32 v[40:41], v[40:41], v[142:143]
	v_pk_mul_f32 v[38:39], v[38:39], v[140:141]
	v_pk_mul_f32 v[44:45], v[44:45], v[142:143]
	v_pk_mul_f32 v[42:43], v[42:43], v[140:141]
	s_waitcnt lgkmcnt(0)
	s_cbranch_scc1 .LBB0_2101
.LBB0_2086:
	s_and_b32 s63, s57, 1
	s_cmp_eq_u32 s63, 0
	s_cselect_b64 s[28:29], -1, 0
	s_and_b64 s[14:15], s[28:29], exec
	s_cselect_b32 s14, 0xf0, s46
	v_lshlrev_b32_e32 v135, 2, v104
	v_add3_u32 v155, s14, v109, v135
	s_waitcnt lgkmcnt(0)
	ds_read2_b32 v[144:145], v155 offset1:4
	ds_read2_b32 v[234:235], v155 offset0:64 offset1:68
	ds_read2_b32 v[232:233], v155 offset0:8 offset1:12
	ds_read2_b32 v[236:237], v155 offset0:72 offset1:76
	ds_read2_b32 v[244:245], v155 offset0:128 offset1:132
	ds_read2_b32 v[248:249], v155 offset0:136 offset1:140
	ds_read2_b32 v[252:253], v155 offset0:192 offset1:196
	s_andn2_b64 vcc, exec, s[26:27]
	s_mov_b64 s[30:31], -1
	s_waitcnt lgkmcnt(6)
	v_mfma_f32_16x16x4_f32 v[136:139], v144, v134, 0
	v_mfma_f32_16x16x4_f32 v[136:139], v145, v133, v[136:139]
	s_nop 0
	s_waitcnt lgkmcnt(4)
	v_mfma_f32_16x16x4_f32 v[136:139], v232, v132, v[136:139]
	v_mfma_f32_16x16x4_f32 v[140:143], v234, v134, 0
	v_mfma_f32_16x16x4_f32 v[136:139], v233, v131, v[136:139]
	s_nop 0
	v_mfma_f32_16x16x4_f32 v[140:143], v235, v133, v[140:143]
	s_nop 7
	v_add_f32_e32 v138, v130, v138
	v_min_f32_e32 v148, 0, v138
	v_mul_f32_e64 v138, |v138|, s47
	v_exp_f32_e32 v138, v138
	v_add_f32_e32 v139, v130, v139
	v_mul_f32_e64 v149, |v139|, s47
	v_exp_f32_e32 v149, v149
	s_waitcnt lgkmcnt(3)
	v_mfma_f32_16x16x4_f32 v[140:143], v236, v132, v[140:143]
	v_add_f32_e32 v138, 1.0, v138
	v_log_f32_e32 v138, v138
	v_add_f32_e32 v136, v130, v136
	v_add_f32_e32 v137, v130, v137
	v_min_f32_e32 v146, 0, v136
	v_mul_f32_e64 v136, |v136|, s47
	v_min_f32_e32 v147, 0, v137
	v_mfma_f32_16x16x4_f32 v[140:143], v237, v131, v[140:143]
	v_mul_f32_e64 v137, |v137|, s47
	v_exp_f32_e32 v136, v136
	v_exp_f32_e32 v137, v137
	v_add_f32_e32 v149, 1.0, v149
	v_fmac_f32_e32 v148, 0xbf317218, v138
	v_log_f32_e32 v144, v149
	v_mul_f32_e32 v138, 0x3d800000, v148
	s_nop 0
	s_nop 1
	v_add_f32_e32 v140, v130, v140
	v_mul_f32_e64 v145, |v140|, s47
	v_add_f32_e32 v136, 1.0, v136
	v_add_f32_e32 v137, 1.0, v137
	v_exp_f32_e32 v145, v145
	v_log_f32_e32 v136, v136
	v_log_f32_e32 v137, v137
	v_min_f32_e32 v139, 0, v139
	v_fmac_f32_e32 v139, 0xbf317218, v144
	v_add_f32_e32 v144, 1.0, v145
	v_add_f32_e32 v141, v130, v141
	v_fmac_f32_e32 v146, 0xbf317218, v136
	v_fmac_f32_e32 v147, 0xbf317218, v137
	v_log_f32_e32 v150, v144
	v_mul_f32_e64 v144, |v141|, s47
	v_mul_f32_e32 v136, 0x3d800000, v146
	v_mul_f32_e32 v137, 0x3d800000, v147
	v_exp_f32_e32 v151, v144
	s_waitcnt lgkmcnt(2)
	v_mfma_f32_16x16x4_f32 v[144:147], v244, v134, 0
	v_min_f32_e32 v140, 0, v140
	v_fmac_f32_e32 v140, 0xbf317218, v150
	v_add_f32_e32 v148, 1.0, v151
	s_nop 0
	v_add_f32_e32 v152, v130, v142
	v_mul_f32_e64 v142, |v152|, s47
	v_exp_f32_e32 v142, v142
	v_mfma_f32_16x16x4_f32 v[144:147], v245, v133, v[144:147]
	v_log_f32_e32 v148, v148
	v_min_f32_e32 v141, 0, v141
	v_add_f32_e32 v142, 1.0, v142
	v_add_f32_e32 v149, v130, v143
	v_fmac_f32_e32 v141, 0xbf317218, v148
	v_log_f32_e32 v148, v142
	v_mul_f32_e32 v139, 0x3d800000, v139
	s_waitcnt lgkmcnt(1)
	v_mfma_f32_16x16x4_f32 v[142:145], v248, v132, v[144:147]
	s_nop 0
	v_mul_f32_e64 v146, |v149|, s47
	v_exp_f32_e32 v146, v146
	v_min_f32_e32 v150, 0, v152
	v_fmac_f32_e32 v150, 0xbf317218, v148
	s_nop 0
	v_add_f32_e32 v146, 1.0, v146
	v_log_f32_e32 v148, v146
	v_mfma_f32_16x16x4_f32 v[144:147], v249, v131, v[142:145]
	v_min_f32_e32 v149, 0, v149
	v_mul_f32_e32 v140, 0x3d800000, v140
	v_fmac_f32_e32 v149, 0xbf317218, v148
	v_mul_f32_e32 v141, 0x3d800000, v141
	s_nop 5
	v_add_f32_e32 v144, v130, v144
	v_mul_f32_e64 v142, |v144|, s47
	v_exp_f32_e32 v143, v142
	v_add_f32_e32 v145, v130, v145
	v_mul_f32_e32 v142, 0x3d800000, v150
	v_min_f32_e32 v144, 0, v144
	v_add_f32_e32 v143, 1.0, v143
	v_log_f32_e32 v148, v143
	v_mul_f32_e64 v143, |v145|, s47
	v_exp_f32_e32 v150, v143
	v_mul_f32_e32 v143, 0x3d800000, v149
	v_fmac_f32_e32 v144, 0xbf317218, v148
	v_min_f32_e32 v145, 0, v145
	v_add_f32_e32 v148, 1.0, v150
	v_log_f32_e32 v156, v148
	s_waitcnt lgkmcnt(0)
	v_mfma_f32_16x16x4_f32 v[148:151], v252, v134, 0
	v_add_f32_e32 v146, v130, v146
	v_min_f32_e32 v152, 0, v146
	v_fmac_f32_e32 v145, 0xbf317218, v156
	ds_read2_b32 v[156:157], v155 offset0:200 offset1:204
	v_mul_f32_e64 v146, |v146|, s47
	v_exp_f32_e32 v146, v146
	v_mul_f32_e32 v144, 0x3d800000, v144
	v_mfma_f32_16x16x4_f32 v[148:151], v253, v133, v[148:151]
	v_add_f32_e32 v153, v130, v147
	v_mul_f32_e64 v147, |v153|, s47
	v_add_f32_e32 v146, 1.0, v146
	v_exp_f32_e32 v155, v147
	v_log_f32_e32 v158, v146
	v_mul_f32_e32 v145, 0x3d800000, v145
	v_fmac_f32_e32 v152, 0xbf317218, v158
	s_waitcnt lgkmcnt(0)
	v_mfma_f32_16x16x4_f32 v[146:149], v156, v132, v[148:151]
	s_nop 0
	v_add_f32_e32 v150, 1.0, v155
	v_log_f32_e32 v150, v150
	v_min_f32_e32 v151, 0, v153
	v_mul_f32_e32 v163, 0x3d800000, v152
	v_fmac_f32_e32 v151, 0xbf317218, v150
	v_mul_f32_e32 v164, 0x3d800000, v151
	v_mfma_f32_16x16x4_f32 v[146:149], v157, v131, v[146:149]
	s_nop 9
	v_add_f32_e32 v146, v130, v146
	v_mul_f32_e64 v150, |v146|, s47
	v_exp_f32_e32 v150, v150
	v_add_f32_e32 v147, v130, v147
	v_mul_f32_e64 v151, |v147|, s47
	v_exp_f32_e32 v151, v151
	v_add_f32_e32 v150, 1.0, v150
	v_log_f32_e32 v150, v150
	v_min_f32_e32 v146, 0, v146
	v_add_f32_e32 v151, 1.0, v151
	v_log_f32_e32 v151, v151
	v_fmac_f32_e32 v146, 0xbf317218, v150
	v_mul_f32_e32 v165, 0x3d800000, v146
	v_min_f32_e32 v146, 0, v147
	v_fmac_f32_e32 v146, 0xbf317218, v151
	v_mul_f32_e32 v166, 0x3d800000, v146
	v_add_f32_e32 v146, v130, v148
	v_mul_f32_e64 v147, |v146|, s47
	v_exp_f32_e32 v147, v147
	v_add_f32_e32 v148, v130, v149
	v_mul_f32_e64 v149, |v148|, s47
	v_exp_f32_e32 v149, v149
	v_add_f32_e32 v147, 1.0, v147
	v_log_f32_e32 v147, v147
	v_min_f32_e32 v146, 0, v146
	v_add_f32_e32 v149, 1.0, v149
	v_log_f32_e32 v149, v149
	v_fmac_f32_e32 v146, 0xbf317218, v147
	v_mul_f32_e32 v167, 0x3d800000, v146
	v_min_f32_e32 v146, 0, v148
	v_fmac_f32_e32 v146, 0xbf317218, v149
	v_mul_f32_e32 v168, 0x3d800000, v146
	v_cndmask_b32_e64 v146, 0, 1, s[26:27]
	v_cmp_ne_u32_e64 s[14:15], 1, v146
	s_waitcnt lgkmcnt(0)
	s_cbranch_vccnz .LBB0_2088
	v_add_f32_e32 v146, 0, v168
	v_add_f32_e32 v147, v167, v146
	v_add_f32_e32 v148, v166, v147
	v_add_f32_e32 v149, v165, v148
	v_add_f32_e32 v150, v164, v149
	v_add_f32_e32 v151, v163, v150
	v_add_f32_e32 v152, v145, v151
	v_add_f32_e32 v153, v144, v152
	v_add_f32_e32 v155, v143, v153
	v_add_f32_e32 v156, v142, v155
	v_add_f32_e32 v157, v141, v156
	v_add_f32_e32 v158, v140, v157
	v_add_f32_e32 v159, v139, v158
	v_add_f32_e32 v160, v138, v159
	v_add_f32_e32 v161, v137, v160
	v_add_f32_e32 v162, v136, v161
	s_mov_b64 s[30:31], 0

.LBB0_2101:
	v_add3_u32 v148, s46, v109, v135
	s_waitcnt lgkmcnt(0)
	ds_read2_b32 v[136:137], v148 offset1:4
	ds_read2_b32 v[232:233], v148 offset0:8 offset1:12
	ds_read2_b32 v[234:235], v148 offset0:64 offset1:68
	ds_read2_b32 v[236:237], v148 offset0:72 offset1:76
	ds_read2_b32 v[244:245], v148 offset0:128 offset1:132
	s_and_b64 vcc, exec, s[14:15]
	s_mov_b64 s[24:25], -1
	s_waitcnt lgkmcnt(4)
	v_mfma_f32_16x16x4_f32 v[90:93], v136, v134, 0
	v_mfma_f32_16x16x4_f32 v[90:93], v137, v133, v[90:93]
	s_waitcnt lgkmcnt(3)
	v_mfma_f32_16x16x4_f32 v[90:93], v232, v132, v[90:93]
	s_waitcnt lgkmcnt(2)
	v_mfma_f32_16x16x4_f32 v[136:139], v234, v134, 0
	v_mfma_f32_16x16x4_f32 v[90:93], v233, v131, v[90:93]
	v_mfma_f32_16x16x4_f32 v[136:139], v235, v133, v[136:139]
	s_nop 8
	v_add_f32_e32 v90, v130, v90
	v_min_f32_e32 v135, 0, v90
	v_mul_f32_e64 v90, |v90|, s47
	v_exp_f32_e32 v90, v90
	v_add_f32_e32 v91, v130, v91
	v_min_f32_e32 v140, 0, v91
	v_mul_f32_e64 v91, |v91|, s47
	s_waitcnt lgkmcnt(1)
	v_mfma_f32_16x16x4_f32 v[136:139], v236, v132, v[136:139]
	v_add_f32_e32 v90, 1.0, v90
	v_exp_f32_e32 v91, v91
	v_log_f32_e32 v90, v90
	v_add_f32_e32 v92, v130, v92
	v_add_f32_e32 v93, v130, v93
	v_add_f32_e32 v91, 1.0, v91
	v_fmac_f32_e32 v135, 0xbf317218, v90
	v_mfma_f32_16x16x4_f32 v[136:139], v237, v131, v[136:139]
	v_mul_f32_e64 v141, |v92|, s47
	v_log_f32_e32 v91, v91
	v_mul_f32_e32 v90, 0x3d800000, v135
	v_mul_f32_e64 v135, |v93|, s47
	v_exp_f32_e32 v141, v141
	v_exp_f32_e32 v135, v135
	s_nop 0
	v_fmac_f32_e32 v140, 0xbf317218, v91
	s_nop 1
	v_add_f32_e32 v136, v130, v136
	v_add_f32_e32 v141, 1.0, v141
	v_mul_f32_e32 v91, 0x3d800000, v140
	v_add_f32_e32 v135, 1.0, v135
	v_mul_f32_e64 v140, |v136|, s47
	v_log_f32_e32 v141, v141
	v_log_f32_e32 v135, v135
	v_exp_f32_e32 v140, v140
	v_min_f32_e32 v92, 0, v92
	v_min_f32_e32 v93, 0, v93
	v_fmac_f32_e32 v92, 0xbf317218, v141
	v_fmac_f32_e32 v93, 0xbf317218, v135
	v_add_f32_e32 v135, 1.0, v140
	s_waitcnt lgkmcnt(0)
	v_mfma_f32_16x16x4_f32 v[140:143], v244, v134, 0
	v_add_f32_e32 v146, v130, v137
	v_mul_f32_e64 v137, |v146|, s47
	v_log_f32_e32 v135, v135
	v_exp_f32_e32 v137, v137
	v_min_f32_e32 v144, 0, v136
	v_add_f32_e32 v149, v130, v138
	v_fmac_f32_e32 v144, 0xbf317218, v135
	v_add_f32_e32 v135, 1.0, v137
	ds_read2_b32 v[136:137], v148 offset0:136 offset1:140
	ds_read2_b32 v[248:249], v148 offset0:192 offset1:196
	v_mfma_f32_16x16x4_f32 v[140:143], v245, v133, v[140:143]
	v_log_f32_e32 v147, v135
	v_mul_f32_e64 v135, |v149|, s47
	v_exp_f32_e32 v138, v135
	v_mul_f32_e32 v135, 0x3d800000, v144
	v_min_f32_e32 v144, 0, v146
	v_add_f32_e32 v146, v130, v139
	v_add_f32_e32 v138, 1.0, v138
	v_log_f32_e32 v145, v138
	s_waitcnt lgkmcnt(1)
	v_mfma_f32_16x16x4_f32 v[138:141], v136, v132, v[140:143]
	v_mul_f32_e64 v136, |v146|, s47
	v_exp_f32_e32 v142, v136
	v_fmac_f32_e32 v144, 0xbf317218, v147
	v_mul_f32_e32 v136, 0x3d800000, v144
	v_min_f32_e32 v143, 0, v149
	v_add_f32_e32 v142, 1.0, v142
	v_fmac_f32_e32 v143, 0xbf317218, v145
	v_mfma_f32_16x16x4_f32 v[138:141], v137, v131, v[138:141]
	v_log_f32_e32 v142, v142
	v_mul_f32_e32 v92, 0x3d800000, v92
	v_mul_f32_e32 v93, 0x3d800000, v93
	s_nop 6
	v_add_f32_e32 v144, v130, v138
	v_mul_f32_e64 v137, |v144|, s47
	v_exp_f32_e32 v138, v137
	v_mul_f32_e32 v137, 0x3d800000, v143
	v_min_f32_e32 v143, 0, v146
	s_nop 0
	v_add_f32_e32 v138, 1.0, v138
	v_add_f32_e32 v139, v130, v139
	v_fmac_f32_e32 v143, 0xbf317218, v142
	v_log_f32_e32 v142, v138
	v_mul_f32_e64 v138, |v139|, s47
	v_exp_f32_e32 v145, v138
	v_min_f32_e32 v149, 0, v144
	v_fmac_f32_e32 v149, 0xbf317218, v142
	v_mul_f32_e32 v138, 0x3d800000, v143
	v_add_f32_e32 v142, 1.0, v145
	v_log_f32_e32 v150, v142
	s_waitcnt lgkmcnt(0)
	v_mfma_f32_16x16x4_f32 v[142:145], v248, v134, 0
	v_mul_f32_e32 v134, 0x3d800000, v149
	ds_read2_b32 v[148:149], v148 offset0:200 offset1:204
	v_add_f32_e32 v140, v130, v140
	v_min_f32_e32 v139, 0, v139
	v_min_f32_e32 v146, 0, v140
	v_fmac_f32_e32 v139, 0xbf317218, v150
	v_mul_f32_e32 v139, 0x3d800000, v139
	v_mfma_f32_16x16x4_f32 v[142:145], v249, v133, v[142:145]
	v_add_f32_e32 v147, v130, v141
	v_mul_f32_e64 v133, |v140|, s47
	v_mul_f32_e64 v140, |v147|, s47
	v_exp_f32_e32 v150, v140
	v_exp_f32_e32 v133, v133
	s_nop 0
	v_add_f32_e32 v133, 1.0, v133
	s_waitcnt lgkmcnt(0)
	v_mfma_f32_16x16x4_f32 v[140:143], v148, v132, v[142:145]
	v_log_f32_e32 v133, v133
	v_add_f32_e32 v132, 1.0, v150
	v_log_f32_e32 v132, v132
	v_fmac_f32_e32 v146, 0xbf317218, v133
	v_min_f32_e32 v133, 0, v147
	v_fmac_f32_e32 v133, 0xbf317218, v132
	v_mfma_f32_16x16x4_f32 v[140:143], v149, v131, v[140:143]
	v_mul_f32_e32 v153, 0x3d800000, v133
	v_mul_f32_e32 v152, 0x3d800000, v146
	s_nop 7
	v_add_f32_e32 v131, v130, v140
	v_mul_f32_e64 v132, |v131|, s47
	v_exp_f32_e32 v132, v132
	v_add_f32_e32 v133, v130, v141
	v_mul_f32_e64 v140, |v133|, s47
	v_exp_f32_e32 v140, v140
	v_add_f32_e32 v132, 1.0, v132
	v_log_f32_e32 v132, v132
	v_min_f32_e32 v131, 0, v131
	v_add_f32_e32 v140, 1.0, v140
	v_log_f32_e32 v140, v140
	v_fmac_f32_e32 v131, 0xbf317218, v132
	v_mul_f32_e32 v155, 0x3d800000, v131
	v_min_f32_e32 v131, 0, v133
	v_fmac_f32_e32 v131, 0xbf317218, v140
	v_mul_f32_e32 v156, 0x3d800000, v131
	v_add_f32_e32 v131, v130, v142
	v_add_f32_e32 v130, v130, v143
	v_mul_f32_e64 v132, |v131|, s47
	v_mul_f32_e64 v133, |v130|, s47
	v_exp_f32_e32 v132, v132
	v_exp_f32_e32 v133, v133
	v_min_f32_e32 v131, 0, v131
	v_min_f32_e32 v130, 0, v130
	v_add_f32_e32 v132, 1.0, v132
	v_add_f32_e32 v133, 1.0, v133
	v_log_f32_e32 v132, v132
	v_log_f32_e32 v133, v133
	v_fmac_f32_e32 v131, 0xbf317218, v132
	v_fmac_f32_e32 v130, 0xbf317218, v133
	v_mul_f32_e32 v157, 0x3d800000, v131
	v_mul_f32_e32 v158, 0x3d800000, v130
	s_waitcnt lgkmcnt(0)
	s_cbranch_vccnz .LBB0_2103
	v_add_f32_e32 v130, 0, v158
	v_add_f32_e32 v131, v157, v130
	v_add_f32_e32 v132, v156, v131
	v_add_f32_e32 v133, v155, v132
	v_add_f32_e32 v140, v153, v133
	v_add_f32_e32 v141, v152, v140
	v_add_f32_e32 v142, v139, v141
	v_add_f32_e32 v143, v134, v142
	v_add_f32_e32 v144, v138, v143
	v_add_f32_e32 v145, v137, v144
	v_add_f32_e32 v146, v136, v145
	v_add_f32_e32 v147, v135, v146
	v_add_f32_e32 v148, v93, v147
	v_add_f32_e32 v149, v92, v148
	v_add_f32_e32 v150, v91, v149
	v_add_f32_e32 v151, v90, v150
	s_mov_b64 s[24:25], 0

.LBB0_2111:
	s_or_b64 exec, exec, s[14:15]
	s_waitcnt lgkmcnt(0)
	ds_read_b128 v[90:93], v119 offset:6144
	ds_read_b128 v[130:133], v119 offset:6160
	s_waitcnt vmcnt(5)
	v_lshlrev_b32_e32 v134, 16, v54
	v_and_b32_e32 v135, 0xffff0000, v54
	s_waitcnt lgkmcnt(1)
	v_mul_f32_e32 v90, 0xbfb8aa3b, v90
	v_mul_f32_e32 v91, 0xbfb8aa3b, v91
	v_exp_f32_e32 v90, v90
	v_exp_f32_e32 v91, v91
	v_mul_f32_e32 v54, 0xbfb8aa3b, v92
	v_exp_f32_e32 v92, v54
	v_mul_f32_e32 v54, 0xbfb8aa3b, v93
	v_exp_f32_e32 v93, v54
	v_pk_mul_f32 v[90:91], v[90:91], v[134:135]
	s_nop 0
	v_cvt_pk_bf16_f32 v54, v90, v91
	v_lshlrev_b32_e32 v90, 16, v55
	v_and_b32_e32 v91, 0xffff0000, v55
	s_waitcnt lgkmcnt(0)
	v_mul_f32_e32 v55, 0xbfb8aa3b, v130
	v_pk_mul_f32 v[90:91], v[92:93], v[90:91]
	v_exp_f32_e32 v92, v55
	v_mul_f32_e32 v55, 0xbfb8aa3b, v131
	v_exp_f32_e32 v93, v55
	v_cvt_pk_bf16_f32 v55, v90, v91
	v_lshlrev_b32_e32 v90, 16, v56
	v_and_b32_e32 v91, 0xffff0000, v56
	v_mul_f32_e32 v56, 0xbfb8aa3b, v132
	v_pk_mul_f32 v[90:91], v[92:93], v[90:91]
	v_exp_f32_e32 v92, v56
	v_mul_f32_e32 v56, 0xbfb8aa3b, v133
	v_exp_f32_e32 v93, v56
	v_cvt_pk_bf16_f32 v56, v90, v91
	v_lshlrev_b32_e32 v90, 16, v57
	v_and_b32_e32 v91, 0xffff0000, v57
	v_pk_mul_f32 v[90:91], v[92:93], v[90:91]
	s_waitcnt vmcnt(4)
	v_lshlrev_b32_e32 v130, 16, v6
	v_cvt_pk_bf16_f32 v57, v90, v91
	ds_write_b128 v120, v[54:57] offset:56320
	ds_read_b128 v[232:235], v121 offset:6144
	ds_read_b128 v[90:93], v121 offset:6160
	v_and_b32_e32 v131, 0xffff0000, v6
	s_waitcnt lgkmcnt(1)
	v_mul_f32_e32 v54, 0xbfb8aa3b, v232
	v_mul_f32_e32 v55, 0xbfb8aa3b, v233
	v_exp_f32_e32 v54, v54
	v_exp_f32_e32 v55, v55
	v_mul_f32_e32 v6, 0xbfb8aa3b, v234
	v_exp_f32_e32 v56, v6
	v_mul_f32_e32 v6, 0xbfb8aa3b, v235
	v_exp_f32_e32 v57, v6
	v_pk_mul_f32 v[54:55], v[54:55], v[130:131]
	s_nop 0
	v_cvt_pk_bf16_f32 v6, v54, v55
	v_lshlrev_b32_e32 v54, 16, v7
	v_and_b32_e32 v55, 0xffff0000, v7
	s_waitcnt lgkmcnt(0)
	v_mul_f32_e32 v7, 0xbfb8aa3b, v90
	v_pk_mul_f32 v[54:55], v[56:57], v[54:55]
	v_exp_f32_e32 v56, v7
	v_mul_f32_e32 v7, 0xbfb8aa3b, v91
	v_exp_f32_e32 v57, v7
	v_cvt_pk_bf16_f32 v7, v54, v55
	v_lshlrev_b32_e32 v54, 16, v8
	v_and_b32_e32 v55, 0xffff0000, v8
	v_mul_f32_e32 v8, 0xbfb8aa3b, v92
	v_pk_mul_f32 v[54:55], v[56:57], v[54:55]
	v_exp_f32_e32 v56, v8
	v_mul_f32_e32 v8, 0xbfb8aa3b, v93
	v_exp_f32_e32 v57, v8
	v_cvt_pk_bf16_f32 v8, v54, v55
	v_lshlrev_b32_e32 v54, 16, v9
	v_and_b32_e32 v55, 0xffff0000, v9
	v_pk_mul_f32 v[54:55], v[56:57], v[54:55]
	s_nop 0
	v_cvt_pk_bf16_f32 v9, v54, v55
	ds_write_b128 v122, v[6:9] offset:56320
	s_waitcnt vmcnt(3)
	ds_write_b128 v123, v[2:5]
	s_waitcnt vmcnt(2)
	ds_write_b128 v124, v[10:13]
	s_waitcnt vmcnt(1)
	ds_write_b128 v123, v[14:17] offset:16896
	s_waitcnt vmcnt(0)
	ds_write_b128 v125, v[18:21]
	s_waitcnt lgkmcnt(0)
	s_barrier
	s_waitcnt lgkmcnt(0)
	ds_read_b64_tr_b16 v[4:5], v127 offset:57408
	ds_read_b64_tr_b16 v[2:3], v127 offset:56320
	ds_read_b64_tr_b16 v[8:9], v126 offset:2112
	ds_read_b64_tr_b16 v[6:7], v126
	ds_read_b64_tr_b16 v[12:13], v126 offset:2144
	ds_read_b64_tr_b16 v[10:11], v126 offset:32
	ds_read_b64_tr_b16 v[14:15], v127 offset:56352
	ds_read_b64_tr_b16 v[18:19], v127 offset:56384
	ds_read_b64_tr_b16 v[232:233], v127 offset:56416
	ds_read_b64_tr_b16 v[16:17], v127 offset:57440
	ds_read_b64_tr_b16 v[20:21], v127 offset:57472
	ds_read_b64_tr_b16 v[234:235], v127 offset:57504
	ds_read_b64_tr_b16 v[236:237], v127 offset:65024
	ds_read_b64_tr_b16 v[238:239], v128 offset:57408
	ds_read_b64_tr_b16 v[130:131], v126 offset:16896
	ds_read_b64_tr_b16 v[132:133], v126 offset:19008
	ds_read_b64_tr_b16 v[136:137], v126 offset:19040
	ds_read_b64_tr_b16 v[134:135], v126 offset:16928
	ds_read_b64_tr_b16 v[244:245], v127 offset:65056
	ds_read_b64_tr_b16 v[138:139], v127 offset:65088
	ds_read_b64_tr_b16 v[142:143], v127 offset:65120
	ds_read_b64_tr_b16 v[246:247], v128 offset:57440
	ds_read_b64_tr_b16 v[140:141], v128 offset:57472
	ds_read_b64_tr_b16 v[144:145], v128 offset:57504
	ds_read_b64_tr_b16 v[248:249], v127 offset:56448
	ds_read_b64_tr_b16 v[250:251], v127 offset:57536
	s_waitcnt lgkmcnt(15)
	v_mfma_f32_16x16x32_bf16 v[58:61], v[14:17], v[6:9], v[58:61]
	v_mfma_f32_16x16x32_bf16 v[14:17], v[14:17], v[10:13], v[78:81]
	ds_read_b64_tr_b16 v[78:79], v127 offset:56480
	v_mfma_f32_16x16x32_bf16 v[66:69], v[2:5], v[6:9], v[66:69]
	v_mfma_f32_16x16x32_bf16 v[2:5], v[2:5], v[10:13], v[62:65]
	s_nop 2
	s_nop 0
	s_nop 0
	s_nop 0
	s_nop 0
	s_nop 0
	s_nop 0
	s_waitcnt lgkmcnt(5)
	v_mfma_f32_16x16x32_bf16 v[58:61], v[244:247], v[130:133], v[58:61]
	v_mfma_f32_16x16x32_bf16 v[14:17], v[244:247], v[134:137], v[14:17]
	v_mfma_f32_16x16x32_bf16 v[62:65], v[18:21], v[6:9], v[74:77]
	s_nop 2
	s_nop 0
	s_nop 0
	v_mfma_f32_16x16x32_bf16 v[18:21], v[18:21], v[10:13], v[70:73]
	v_mfma_f32_16x16x32_bf16 v[70:73], v[232:235], v[6:9], v[82:85]
	ds_read_b64_tr_b16 v[82:83], v127 offset:56512
	v_mfma_f32_16x16x32_bf16 v[54:57], v[232:235], v[10:13], v[86:89]
	ds_read_b64_tr_b16 v[86:87], v127 offset:56544
	ds_read_b64_tr_b16 v[80:81], v127 offset:57568
	ds_read_b64_tr_b16 v[84:85], v127 offset:57600
	ds_read_b64_tr_b16 v[88:89], v127 offset:57632
	ds_read_b64_tr_b16 v[90:91], v127 offset:65152
	ds_read_b64_tr_b16 v[92:93], v128 offset:57536
	ds_read_b64_tr_b16 v[252:253], v127 offset:65184
	s_nop 0
	s_nop 0
	s_nop 0
	s_nop 0
	s_nop 0
	s_nop 0
	s_nop 0
	s_waitcnt lgkmcnt(4)
	v_mfma_f32_16x16x32_bf16 v[34:37], v[82:85], v[6:9], v[34:37]
	v_mfma_f32_16x16x32_bf16 v[46:49], v[82:85], v[10:13], v[46:49]
	v_add_u32_e32 v82, s23, v111
	s_ashr_i32 s23, s22, 31
	s_lshl_b64 s[14:15], s[22:23], 17
	v_mfma_f32_16x16x32_bf16 v[66:69], v[236:239], v[130:133], v[66:69]
	v_mfma_f32_16x16x32_bf16 v[2:5], v[236:239], v[134:137], v[2:5]
	s_nop 0
	s_nop 0
	v_mfma_f32_16x16x32_bf16 v[62:65], v[138:141], v[130:133], v[62:65]
	v_mfma_f32_16x16x32_bf16 v[18:21], v[138:141], v[134:137], v[18:21]
	ds_read_b64_tr_b16 v[138:139], v127 offset:65216
	v_mfma_f32_16x16x32_bf16 v[70:73], v[142:145], v[130:133], v[70:73]
	v_mfma_f32_16x16x32_bf16 v[54:57], v[142:145], v[134:137], v[54:57]
	ds_read_b64_tr_b16 v[142:143], v127 offset:65248
	ds_read_b64_tr_b16 v[254:255], v128 offset:57568
	ds_read_b64_tr_b16 v[140:141], v128 offset:57600
	ds_read_b64_tr_b16 v[144:145], v128 offset:57632
	ds_read_b128 v[244:247], v82 offset:4096
	ds_read_b128 v[232:235], v82 offset:4160
	ds_read_b128 v[236:239], v82 offset:4224
	v_mfma_f32_16x16x32_bf16 v[30:33], v[248:251], v[6:9], v[30:33]
	v_mfma_f32_16x16x32_bf16 v[26:29], v[248:251], v[10:13], v[26:29]
	ds_read_b128 v[248:251], v82 offset:4288
	s_nop 0
	s_nop 0
	s_nop 0
	s_nop 0
	s_nop 0
	s_nop 0
	v_mfma_f32_16x16x32_bf16 v[22:25], v[78:81], v[6:9], v[22:25]
	s_waitcnt lgkmcnt(12)
	v_mfma_f32_16x16x32_bf16 v[6:9], v[86:89], v[6:9], v[38:41]
	s_nop 2
	s_nop 0
	v_mfma_f32_16x16x32_bf16 v[50:53], v[78:81], v[10:13], v[50:53]
	v_mfma_f32_16x16x32_bf16 v[10:13], v[86:89], v[10:13], v[42:45]
	s_nop 2
	s_nop 0
	s_waitcnt lgkmcnt(3)
	v_mul_f32_e32 v38, 0x3fb8aa3b, v244
	v_mfma_f32_16x16x32_bf16 v[22:25], v[252:255], v[130:133], v[22:25]
	s_waitcnt lgkmcnt(2)
	v_mul_f32_e32 v42, 0x3fb8aa3b, v232
	v_mfma_f32_16x16x32_bf16 v[50:53], v[252:255], v[134:137], v[50:53]
	ds_read_b128 v[252:255], v82 offset:4352
	v_exp_f32_e32 v74, v38
	v_mul_f32_e32 v38, 0x3fb8aa3b, v245
	v_mul_f32_e32 v39, 0x3fb8aa3b, v246
	v_exp_f32_e32 v76, v39
	v_mul_f32_e32 v39, 0x3fb8aa3b, v247
	ds_read_b128 v[244:247], v82 offset:4416
	v_exp_f32_e32 v77, v39
	v_exp_f32_e32 v75, v38
	v_mfma_f32_16x16x32_bf16 v[30:33], v[90:93], v[130:133], v[30:33]
	v_mul_f32_e64 v40, v68, v76
	v_mul_f32_e64 v41, v69, v77
	v_pk_mul_f32 v[4:5], v[4:5], v[76:77]
	v_exp_f32_e32 v76, v42
	v_mul_f32_e32 v42, 0x3fb8aa3b, v233
	v_mul_f32_e32 v43, 0x3fb8aa3b, v234
	v_exp_f32_e32 v78, v43
	v_mul_f32_e32 v43, 0x3fb8aa3b, v235
	ds_read_b128 v[232:235], v82 offset:4480
	v_exp_f32_e32 v79, v43
	v_exp_f32_e32 v77, v42
	s_nop 0
	v_pk_mul_f32 v[38:39], v[66:67], v[74:75]
	s_nop 0
	v_pk_mul_f32 v[2:3], v[2:3], v[74:75]
	v_pk_mul_f32 v[60:61], v[60:61], v[78:79]
	s_waitcnt lgkmcnt(4)
	v_mul_f32_e32 v42, 0x3fb8aa3b, v236
	v_exp_f32_e32 v74, v42
	v_mul_f32_e32 v42, 0x3fb8aa3b, v237
	v_mul_f32_e32 v43, 0x3fb8aa3b, v238
	v_exp_f32_e32 v75, v42
	v_exp_f32_e32 v80, v43
	v_mul_f32_e32 v43, 0x3fb8aa3b, v239
	ds_read_b128 v[236:239], v82 offset:4544
	v_exp_f32_e32 v81, v43
	v_pk_mul_f32 v[42:43], v[62:63], v[74:75]
	s_waitcnt lgkmcnt(4)
	v_mul_f32_e32 v62, 0x3fb8aa3b, v248
	v_mul_f32_e32 v63, 0x3fb8aa3b, v250
	v_pk_mul_f32 v[58:59], v[58:59], v[76:77]
	v_pk_mul_f32 v[16:17], v[16:17], v[78:79]
	v_pk_mul_f32 v[14:15], v[14:15], v[76:77]
	v_exp_f32_e32 v76, v62
	v_mul_f32_e32 v62, 0x3fb8aa3b, v249
	v_exp_f32_e32 v78, v63
	v_mul_f32_e32 v63, 0x3fb8aa3b, v251
	v_pk_mul_f32 v[44:45], v[64:65], v[80:81]
	v_exp_f32_e32 v79, v63
	v_exp_f32_e32 v77, v62
	s_nop 0
	v_pk_mul_f32 v[18:19], v[18:19], v[74:75]
	v_pk_mul_f32 v[68:69], v[72:73], v[78:79]
	v_pk_mul_f32 v[66:67], v[70:71], v[76:77]
	s_nop 0
	s_waitcnt lgkmcnt(3)
	v_mul_f32_e32 v62, 0x3fb8aa3b, v252
	v_exp_f32_e32 v74, v62
	v_mul_f32_e32 v75, 0x3fb8aa3b, v253
	v_mul_f32_e32 v62, 0x3fb8aa3b, v254
	v_mul_f32_e32 v63, 0x3fb8aa3b, v255
	v_mfma_f32_16x16x32_bf16 v[26:29], v[90:93], v[134:137], v[26:29]
	v_exp_f32_e32 v62, v62
	v_exp_f32_e32 v63, v63
	v_pk_mul_f32 v[56:57], v[56:57], v[78:79]
	v_pk_mul_f32 v[54:55], v[54:55], v[76:77]
	v_mfma_f32_16x16x32_bf16 v[34:37], v[138:141], v[130:133], v[34:37]
	v_mul_f32_e64 v32, v32, v62
	v_mul_f32_e64 v33, v33, v63
	s_nop 0
	v_pk_mul_f32 v[28:29], v[28:29], v[62:63]
	s_waitcnt lgkmcnt(2)
	v_mul_f32_e32 v62, 0x3fb8aa3b, v244
	v_mul_f32_e32 v63, 0x3fb8aa3b, v246
	v_exp_f32_e32 v76, v62
	v_mul_f32_e32 v62, 0x3fb8aa3b, v245
	v_exp_f32_e32 v78, v63
	v_mul_f32_e32 v63, 0x3fb8aa3b, v247
	v_exp_f32_e32 v79, v63
	v_exp_f32_e32 v77, v62
	s_nop 0
	s_nop 0
	v_mfma_f32_16x16x32_bf16 v[46:49], v[138:141], v[134:137], v[46:49]
	v_mul_f32_e64 v20, v20, v80
	v_mul_f32_e64 v21, v21, v81
	v_exp_f32_e32 v75, v75
	s_waitcnt lgkmcnt(1)
	v_mul_f32_e32 v62, 0x3fb8aa3b, v232
	v_mul_f32_e32 v63, 0x3fb8aa3b, v233
	v_exp_f32_e32 v62, v62
	v_exp_f32_e32 v63, v63
	v_pk_mul_f32 v[30:31], v[30:31], v[74:75]
	v_pk_mul_f32 v[26:27], v[26:27], v[74:75]
	v_mul_f32_e32 v64, 0x3fb8aa3b, v234
	v_pk_mul_f32 v[34:35], v[34:35], v[62:63]
	v_pk_mul_f32 v[46:47], v[46:47], v[62:63]
	v_lshl_add_u64 v[62:63], v[102:103], 0, s[14:15]
	global_store_dwordx4 v[62:63], v[38:41], off
	v_mul_f32_e32 v65, 0x3fb8aa3b, v235
	v_pk_mul_f32 v[24:25], v[24:25], v[78:79]
	v_add_co_u32_e32 v38, vcc, s40, v62
	v_pk_mul_f32 v[22:23], v[22:23], v[76:77]
	s_nop 0
	v_addc_co_u32_e32 v39, vcc, 0, v63, vcc
	global_store_dwordx4 v[38:39], v[2:5], off
	v_exp_f32_e32 v64, v64
	v_exp_f32_e32 v65, v65
	v_add_co_u32_e32 v2, vcc, s34, v62
	v_pk_mul_f32 v[52:53], v[52:53], v[78:79]
	s_nop 0
	v_addc_co_u32_e32 v3, vcc, 0, v63, vcc
	global_store_dwordx4 v[2:3], v[58:61], off
	v_add_co_u32_e32 v2, vcc, s41, v62
	v_pk_mul_f32 v[50:51], v[50:51], v[76:77]
	s_nop 0
	v_addc_co_u32_e32 v3, vcc, 0, v63, vcc
	global_store_dwordx4 v[2:3], v[14:17], off
	v_add_co_u32_e32 v2, vcc, s39, v62
	s_waitcnt lgkmcnt(0)
	v_mul_f32_e32 v70, 0x3fb8aa3b, v236
	v_addc_co_u32_e32 v3, vcc, 0, v63, vcc
	global_store_dwordx4 v[2:3], v[42:45], off
	v_add_co_u32_e32 v2, vcc, s48, v62
	v_mul_f32_e32 v71, 0x3fb8aa3b, v237
	s_nop 0
	v_addc_co_u32_e32 v3, vcc, 0, v63, vcc
	global_store_dwordx4 v[2:3], v[18:21], off
	v_add_co_u32_e32 v2, vcc, s49, v62
	v_mul_f32_e32 v72, 0x3fb8aa3b, v238
	s_nop 0
	v_addc_co_u32_e32 v3, vcc, 0, v63, vcc
	global_store_dwordx4 v[2:3], v[66:69], off
	v_add_co_u32_e32 v2, vcc, s50, v62
	v_mul_f32_e32 v73, 0x3fb8aa3b, v239
	s_nop 0
	v_addc_co_u32_e32 v3, vcc, 0, v63, vcc
	global_store_dwordx4 v[2:3], v[54:57], off
	v_add_co_u32_e32 v2, vcc, s51, v62
	v_mfma_f32_16x16x32_bf16 v[6:9], v[142:145], v[130:133], v[6:9]
	s_nop 0
	v_addc_co_u32_e32 v3, vcc, 0, v63, vcc
	global_store_dwordx4 v[2:3], v[30:33], off
	v_add_co_u32_e32 v2, vcc, s45, v62
	v_pk_mul_f32 v[36:37], v[36:37], v[64:65]
	s_nop 0
	v_addc_co_u32_e32 v3, vcc, 0, v63, vcc
	global_store_dwordx4 v[2:3], v[26:29], off
	v_add_co_u32_e32 v2, vcc, s52, v62
	v_exp_f32_e32 v70, v70
	s_nop 0
	v_addc_co_u32_e32 v3, vcc, 0, v63, vcc
	global_store_dwordx4 v[2:3], v[22:25], off
	v_add_co_u32_e32 v2, vcc, s53, v62
	v_exp_f32_e32 v72, v72
	s_nop 0
	v_addc_co_u32_e32 v3, vcc, 0, v63, vcc
	global_store_dwordx4 v[2:3], v[50:53], off
	v_add_co_u32_e32 v2, vcc, s43, v62
	v_exp_f32_e32 v73, v73
	v_exp_f32_e32 v71, v71
	v_addc_co_u32_e32 v3, vcc, 0, v63, vcc
	global_store_dwordx4 v[2:3], v[34:37], off
	v_add_co_u32_e32 v2, vcc, s54, v62
	v_mfma_f32_16x16x32_bf16 v[10:13], v[142:145], v[134:137], v[10:13]
	v_mul_f32_e64 v48, v48, v64
	v_mul_f32_e64 v49, v49, v65
	v_addc_co_u32_e32 v3, vcc, 0, v63, vcc
	global_store_dwordx4 v[2:3], v[46:49], off
	v_add_co_u32_e32 v2, vcc, 0x1c000, v62
	v_pk_mul_f32 v[8:9], v[8:9], v[72:73]
	v_pk_mul_f32 v[6:7], v[6:7], v[70:71]
	v_addc_co_u32_e32 v3, vcc, 0, v63, vcc
	global_store_dwordx4 v[2:3], v[6:9], off
	v_add_co_u32_e32 v2, vcc, 0x1e000, v62
	v_pk_mul_f32 v[12:13], v[12:13], v[72:73]
	v_pk_mul_f32 v[10:11], v[10:11], v[70:71]
	v_addc_co_u32_e32 v3, vcc, 0, v63, vcc
	global_store_dwordx4 v[2:3], v[10:13], off
	s_and_saveexec_b64 s[14:15], s[4:5]
	s_waitcnt lgkmcnt(0)
	s_cbranch_execz .LBB0_2073
	v_mul_f32_e32 v1, 0x3fb8aa3b, v1
	v_exp_f32_e32 v1, v1
	s_lshl_b64 s[24:25], s[22:23], 9
	v_lshl_add_u64 v[2:3], v[100:101], 0, s[24:25]
	global_store_dword v[2:3], v1, off
	s_branch .LBB0_2073

.LBB0_2182:
	s_or_b64 exec, exec, s[0:1]
	s_waitcnt lgkmcnt(0)
	s_barrier
	s_waitcnt lgkmcnt(0)
	ds_read_b128 v[132:135], v180
	ds_read_b128 v[138:141], v180 offset:16
	s_add_i32 s56, s56, 1
	s_add_u32 s46, s46, 0xffffe000
	s_addc_u32 s47, s47, -1
	s_waitcnt lgkmcnt(1)
	v_mov_b32_e32 v78, v133
	v_mov_b32_e32 v79, v134
	v_mov_b32_e32 v133, v135
	s_waitcnt vmcnt(9)
	v_lshlrev_b32_e32 v134, 16, v162
	v_and_b32_e32 v135, 0xffff0000, v162
	v_pk_add_f32 v[78:79], v[78:79], v[132:133]
	s_waitcnt lgkmcnt(0)
	v_mov_b32_e32 v132, v140
	v_mov_b32_e32 v133, v138
	v_mov_b32_e32 v138, v141
	v_mul_f32_e32 v140, 0xbfb8aa3b, v134
	v_mul_f32_e32 v141, 0xbfb8aa3b, v135
	v_exp_f32_e32 v140, v140
	v_exp_f32_e32 v141, v141
	v_pk_add_f32 v[144:145], v[132:133], v[138:139]
	v_lshlrev_b32_e32 v138, 16, v163
	v_and_b32_e32 v139, 0xffff0000, v163
	v_add_f32_e32 v132, 1.0, v140
	v_add_f32_e32 v133, 1.0, v141
	v_mul_f32_e32 v140, 0xbfb8aa3b, v138
	v_mul_f32_e32 v141, 0xbfb8aa3b, v139
	v_rcp_f32_e32 v132, v132
	v_rcp_f32_e32 v133, v133
	v_exp_f32_e32 v140, v140
	v_exp_f32_e32 v141, v141
	s_waitcnt vmcnt(8)
	v_lshlrev_b32_e32 v162, 16, v152
	v_pk_mul_f32 v[146:147], v[132:133], v[134:135]
	v_add_f32_e32 v132, 1.0, v140
	v_add_f32_e32 v133, 1.0, v141
	v_and_b32_e32 v163, 0xffff0000, v152
	v_mul_f32_e32 v134, 0xbfb8aa3b, v162
	v_rcp_f32_e32 v132, v132
	v_rcp_f32_e32 v133, v133
	v_exp_f32_e32 v134, v134
	v_mul_f32_e32 v135, 0xbfb8aa3b, v163
	v_exp_f32_e32 v135, v135
	v_pk_mul_f32 v[200:201], v[132:133], v[138:139]
	v_add_f32_e32 v132, 1.0, v134
	v_rcp_f32_e32 v202, v132
	v_add_f32_e32 v132, 1.0, v135
	v_lshlrev_b32_e32 v152, 16, v153
	v_and_b32_e32 v153, 0xffff0000, v153
	v_rcp_f32_e32 v203, v132
	v_mul_f32_e32 v132, 0xbfb8aa3b, v152
	v_mul_f32_e32 v133, 0xbfb8aa3b, v153
	v_exp_f32_e32 v132, v132
	v_exp_f32_e32 v138, v133
	s_add_u32 s34, s34, 0xfffa0000
	s_addc_u32 s35, s35, -1
	v_add_f32_e32 v139, 1.0, v132
	ds_read_b128 v[132:135], v180 offset:512
	v_add_f32_e32 v138, 1.0, v138
	v_rcp_f32_e32 v204, v139
	v_rcp_f32_e32 v205, v138
	ds_read_b128 v[138:141], v180 offset:528
	s_waitcnt lgkmcnt(1)
	v_mov_b32_e32 v206, v133
	v_mov_b32_e32 v207, v134
	v_mov_b32_e32 v133, v135
	v_pk_add_f32 v[132:133], v[206:207], v[132:133]
	s_waitcnt lgkmcnt(0)
	v_mov_b32_e32 v134, v140
	v_mov_b32_e32 v135, v138
	v_mov_b32_e32 v138, v141
	v_pk_add_f32 v[134:135], v[134:135], v[138:139]
	v_mov_b32_e32 v138, v132
	v_mov_b32_e32 v139, v78
	v_mov_b32_e32 v78, v133
	v_pk_add_f32 v[78:79], v[138:139], v[78:79]
	v_mov_b32_e32 v132, v135
	v_mov_b32_e32 v133, v145
	v_pk_add_f32 v[78:79], v[78:79], v[132:133]
	v_mov_b32_e32 v135, v144
	v_pk_add_f32 v[132:133], v[134:135], v[78:79]
	v_mov_b64_e32 v[78:79], s[40:41]
	v_pk_fma_f32 v[132:133], v[132:133], s[38:39], v[78:79] op_sel_hi:[1,0,0]
	v_pk_mul_f32 v[138:139], v[202:203], v[162:163]
	v_mul_f32_e32 v134, 0x4b800000, v133
	v_cmp_gt_f32_e64 s[0:1], s55, v133
	v_pk_mul_f32 v[140:141], v[204:205], v[152:153]
	v_lshl_add_u64 v[152:153], s[28:29], 0, v[116:117]
	v_cndmask_b32_e64 v133, v133, v134, s[0:1]
	v_rsq_f32_e32 v133, v133
	v_lshl_add_u64 v[134:135], s[28:29], 0, v[106:107]
	v_mul_f32_e32 v144, 0x45800000, v133
	v_cndmask_b32_e64 v144, v133, v144, s[0:1]
	v_pk_mul_f32 v[148:149], v[148:149], v[144:145] op_sel_hi:[1,0]
	v_mul_f32_e32 v133, 0x4b800000, v132
	s_waitcnt vmcnt(1)
	v_pk_mul_f32 v[148:149], v[72:73], v[148:149]
	v_cmp_gt_f32_e64 s[0:1], s55, v132
	v_pk_mul_f32 v[146:147], v[146:147], v[148:149]
	v_pk_mul_f32 v[148:149], v[150:151], v[144:145] op_sel_hi:[1,0]
	v_cvt_pk_bf16_f32 v146, v146, v147
	v_pk_mul_f32 v[148:149], v[74:75], v[148:149]
	v_cndmask_b32_e64 v132, v132, v133, s[0:1]
	v_pk_mul_f32 v[148:149], v[200:201], v[148:149]
	v_rsq_f32_e32 v133, v132
	v_cvt_pk_bf16_f32 v147, v148, v149
	global_store_dwordx2 v[134:135], v[146:147], off
	v_pk_mul_f32 v[146:147], v[156:157], v[144:145] op_sel_hi:[1,0]
	v_pk_mul_f32 v[144:145], v[158:159], v[144:145] op_sel_hi:[1,0]
	s_waitcnt vmcnt(1)
	v_pk_mul_f32 v[146:147], v[68:69], v[146:147]
	v_pk_mul_f32 v[144:145], v[70:71], v[144:145]
	v_pk_mul_f32 v[138:139], v[138:139], v[146:147]
	v_pk_mul_f32 v[140:141], v[140:141], v[144:145]
	v_cvt_pk_bf16_f32 v138, v138, v139
	v_cvt_pk_bf16_f32 v139, v140, v141
	v_lshlrev_b32_e32 v132, 16, v142
	global_store_dwordx2 v[134:135], v[138:139], off offset:32
	v_mul_f32_e32 v134, 0xbfb8aa3b, v132
	v_exp_f32_e32 v135, v134
	v_mul_f32_e32 v134, 0x45800000, v133
	v_cndmask_b32_e64 v134, v133, v134, s[0:1]
	v_and_b32_e32 v133, 0xffff0000, v142
	v_mul_f32_e32 v138, 0xbfb8aa3b, v133
	v_exp_f32_e32 v139, v138
	v_add_f32_e32 v135, 1.0, v135
	v_rcp_f32_e32 v138, v135
	v_pk_mul_f32 v[140:141], v[160:161], v[134:135] op_sel_hi:[1,0]
	v_add_f32_e32 v135, 1.0, v139
	v_lshlrev_b32_e32 v142, 16, v143
	v_rcp_f32_e32 v139, v135
	v_and_b32_e32 v143, 0xffff0000, v143
	v_mul_f32_e32 v135, 0xbfb8aa3b, v142
	v_exp_f32_e32 v135, v135
	v_mul_f32_e32 v144, 0xbfb8aa3b, v143
	v_exp_f32_e32 v144, v144
	v_pk_mul_f32 v[132:133], v[138:139], v[132:133]
	v_add_f32_e32 v135, 1.0, v135
	v_rcp_f32_e32 v138, v135
	v_add_f32_e32 v135, 1.0, v144
	v_rcp_f32_e32 v139, v135
	v_pk_mul_f32 v[98:99], v[98:99], v[134:135] op_sel_hi:[1,0]
	v_pk_mul_f32 v[140:141], v[72:73], v[140:141]
	v_pk_mul_f32 v[98:99], v[74:75], v[98:99]
	v_pk_mul_f32 v[138:139], v[138:139], v[142:143]
	v_pk_mul_f32 v[132:133], v[132:133], v[140:141]
	v_pk_mul_f32 v[98:99], v[138:139], v[98:99]
	v_cvt_pk_bf16_f32 v132, v132, v133
	v_cvt_pk_bf16_f32 v133, v98, v99
	v_lshlrev_b32_e32 v98, 16, v136
	v_mul_f32_e32 v99, 0xbfb8aa3b, v98
	v_exp_f32_e32 v135, v99
	v_lshl_add_u64 v[138:139], s[28:29], 0, v[110:111]
	v_and_b32_e32 v99, 0xffff0000, v136
	global_store_dwordx2 v[138:139], v[132:133], off
	v_mul_f32_e32 v133, 0xbfb8aa3b, v99
	v_exp_f32_e32 v133, v133
	v_lshlrev_b32_e32 v136, 16, v137
	v_and_b32_e32 v137, 0xffff0000, v137
	v_add_f32_e32 v132, 1.0, v135
	v_pk_mul_f32 v[96:97], v[96:97], v[134:135] op_sel_hi:[1,0]
	v_add_f32_e32 v133, 1.0, v133
	v_mul_f32_e32 v135, 0xbfb8aa3b, v136
	v_mul_f32_e32 v138, 0xbfb8aa3b, v137
	v_rcp_f32_e32 v132, v132
	v_rcp_f32_e32 v133, v133
	v_exp_f32_e32 v135, v135
	v_exp_f32_e32 v138, v138
	v_pk_mul_f32 v[96:97], v[68:69], v[96:97]
	v_pk_mul_f32 v[98:99], v[132:133], v[98:99]
	v_add_f32_e32 v132, 1.0, v135
	v_add_f32_e32 v133, 1.0, v138
	v_rcp_f32_e32 v132, v132
	v_rcp_f32_e32 v133, v133
	v_pk_mul_f32 v[94:95], v[94:95], v[134:135] op_sel_hi:[1,0]
	v_pk_mul_f32 v[96:97], v[98:99], v[96:97]
	v_pk_mul_f32 v[94:95], v[70:71], v[94:95]
	v_pk_mul_f32 v[98:99], v[132:133], v[136:137]
	v_cvt_pk_bf16_f32 v132, v96, v97
	v_pk_mul_f32 v[98:99], v[98:99], v[94:95]
	ds_read_b128 v[94:97], v180 offset:1024
	v_cvt_pk_bf16_f32 v133, v98, v99
	v_lshl_add_u64 v[98:99], s[28:29], 0, v[112:113]
	global_store_dwordx2 v[98:99], v[132:133], off
	ds_read_b128 v[132:135], v180 offset:1040
	s_waitcnt lgkmcnt(1)
	v_mov_b32_e32 v98, v95
	v_mov_b32_e32 v99, v96
	v_mov_b32_e32 v95, v97
	v_lshlrev_b32_e32 v96, 16, v130
	v_pk_add_f32 v[98:99], v[98:99], v[94:95]
	v_and_b32_e32 v97, 0xffff0000, v130
	v_mul_f32_e32 v95, 0xbfb8aa3b, v96
	v_exp_f32_e32 v130, v95
	v_mul_f32_e32 v95, 0xbfb8aa3b, v97
	s_waitcnt lgkmcnt(0)
	v_mov_b32_e32 v94, v134
	v_exp_f32_e32 v134, v95
	v_lshlrev_b32_e32 v136, 16, v131
	v_and_b32_e32 v137, 0xffff0000, v131
	v_mul_f32_e32 v131, 0xbfb8aa3b, v136
	v_mov_b32_e32 v95, v132
	v_add_f32_e32 v132, 1.0, v134
	v_exp_f32_e32 v134, v131
	v_mul_f32_e32 v131, 0xbfb8aa3b, v137
	v_exp_f32_e32 v139, v131
	v_rcp_f32_e32 v131, v132
	v_add_f32_e32 v132, 1.0, v134
	v_rcp_f32_e32 v138, v132
	v_add_f32_e32 v132, 1.0, v139
	v_rcp_f32_e32 v139, v132
	v_mov_b32_e32 v132, v135
	v_pk_add_f32 v[132:133], v[94:95], v[132:133]
	v_lshlrev_b32_e32 v144, 16, v129
	v_pk_mul_f32 v[136:137], v[138:139], v[136:137]
	v_lshlrev_b32_e32 v138, 16, v128
	v_and_b32_e32 v139, 0xffff0000, v128
	v_mul_f32_e32 v94, 0xbfb8aa3b, v138
	v_exp_f32_e32 v94, v94
	v_mul_f32_e32 v95, 0xbfb8aa3b, v139
	v_exp_f32_e32 v95, v95
	v_and_b32_e32 v145, 0xffff0000, v129
	v_add_f32_e32 v94, 1.0, v94
	v_rcp_f32_e32 v142, v94
	v_add_f32_e32 v94, 1.0, v95
	v_add_f32_e32 v130, 1.0, v130
	v_rcp_f32_e32 v143, v94
	v_mul_f32_e32 v94, 0xbfb8aa3b, v144
	v_mul_f32_e32 v95, 0xbfb8aa3b, v145
	v_rcp_f32_e32 v130, v130
	v_exp_f32_e32 v94, v94
	v_exp_f32_e32 v128, v95
	v_lshl_add_u64 v[140:141], s[28:29], 0, v[114:115]
	v_pk_mul_f32 v[134:135], v[130:131], v[96:97]
	v_add_f32_e32 v129, 1.0, v94
	ds_read_b128 v[94:97], v180 offset:1536
	v_add_f32_e32 v128, 1.0, v128
	v_rcp_f32_e32 v146, v129
	v_rcp_f32_e32 v147, v128
	ds_read_b128 v[128:131], v180 offset:1552
	ds_read_b64_tr_b16 v[246:247], v196 offset:57408
	ds_read_b64_tr_b16 v[244:245], v196 offset:56320
	s_waitcnt lgkmcnt(3)
	v_mov_b32_e32 v148, v95
	v_mov_b32_e32 v149, v96
	v_mov_b32_e32 v95, v97
	v_pk_add_f32 v[94:95], v[148:149], v[94:95]
	s_waitcnt lgkmcnt(2)
	v_mov_b32_e32 v96, v130
	v_mov_b32_e32 v97, v128
	v_mov_b32_e32 v128, v131
	v_pk_add_f32 v[96:97], v[96:97], v[128:129]
	v_mov_b32_e32 v128, v94
	v_mov_b32_e32 v129, v98
	v_mov_b32_e32 v98, v95
	v_pk_add_f32 v[94:95], v[128:129], v[98:99]
	v_mov_b32_e32 v98, v97
	v_mov_b32_e32 v99, v133
	v_pk_add_f32 v[94:95], v[94:95], v[98:99]
	v_mov_b32_e32 v97, v132
	v_pk_add_f32 v[94:95], v[96:97], v[94:95]
	v_pk_mul_f32 v[98:99], v[146:147], v[144:145]
	v_pk_fma_f32 v[78:79], v[94:95], s[38:39], v[78:79] op_sel_hi:[1,0,0]
	s_nop 0
	v_mul_f32_e32 v94, 0x4b800000, v79
	v_cmp_gt_f32_e64 s[0:1], s55, v79
	s_nop 1
	v_cndmask_b32_e64 v79, v79, v94, s[0:1]
	v_rsq_f32_e32 v79, v79
	v_pk_mul_f32 v[94:95], v[142:143], v[138:139]
	v_mul_f32_e32 v96, 0x45800000, v79
	v_cndmask_b32_e64 v96, v79, v96, s[0:1]
	v_pk_mul_f32 v[88:89], v[88:89], v[96:97] op_sel_hi:[1,0]
	v_pk_mul_f32 v[92:93], v[92:93], v[96:97] op_sel_hi:[1,0]
	v_pk_mul_f32 v[88:89], v[72:73], v[88:89]
	v_pk_mul_f32 v[92:93], v[74:75], v[92:93]
	v_pk_mul_f32 v[88:89], v[134:135], v[88:89]
	v_pk_mul_f32 v[92:93], v[136:137], v[92:93]
	v_cvt_pk_bf16_f32 v88, v88, v89
	v_cvt_pk_bf16_f32 v89, v92, v93
	ds_read_b64_tr_b16 v[92:93], v198 offset:2112
	global_store_dwordx2 v[140:141], v[88:89], off
	v_pk_mul_f32 v[88:89], v[90:91], v[96:97] op_sel_hi:[1,0]
	ds_read_b64_tr_b16 v[90:91], v198
	v_mul_f32_e32 v79, 0x4b800000, v78
	v_cmp_gt_f32_e64 s[0:1], s55, v78
	v_pk_mul_f32 v[88:89], v[68:69], v[88:89]
	v_pk_mul_f32 v[86:87], v[86:87], v[96:97] op_sel_hi:[1,0]
	ds_read_b64_tr_b16 v[96:97], v198 offset:2144
	v_cndmask_b32_e64 v78, v78, v79, s[0:1]
	v_pk_mul_f32 v[200:201], v[94:95], v[88:89]
	ds_read_b64_tr_b16 v[94:95], v198 offset:32
	ds_read_b64_tr_b16 v[128:129], v196 offset:56352
	ds_read_b64_tr_b16 v[132:133], v196 offset:56384
	ds_read_b64_tr_b16 v[136:137], v196 offset:56416
	ds_read_b64_tr_b16 v[130:131], v196 offset:57440
	ds_read_b64_tr_b16 v[134:135], v196 offset:57472
	ds_read_b64_tr_b16 v[138:139], v196 offset:57504
	ds_read_b64_tr_b16 v[140:141], v196 offset:65024
	ds_read_b64_tr_b16 v[142:143], v197 offset:57408
	ds_read_b64_tr_b16 v[144:145], v198 offset:16896
	ds_read_b64_tr_b16 v[146:147], v198 offset:19008
	ds_read_b64_tr_b16 v[150:151], v198 offset:19040
	ds_read_b64_tr_b16 v[148:149], v198 offset:16928
	ds_read_b64_tr_b16 v[248:249], v196 offset:65056
	ds_read_b64_tr_b16 v[156:157], v196 offset:65088
	ds_read_b64_tr_b16 v[160:161], v196 offset:65120
	ds_read_b64_tr_b16 v[250:251], v197 offset:57440
	ds_read_b64_tr_b16 v[158:159], v197 offset:57472
	ds_read_b64_tr_b16 v[162:163], v197 offset:57504
	ds_read_b64_tr_b16 v[252:253], v196 offset:56448
	ds_read_b64_tr_b16 v[254:255], v196 offset:57536
	v_pk_mul_f32 v[202:203], v[70:71], v[86:87]
	s_nop 0
	s_nop 0
	s_nop 0
	s_nop 0
	s_nop 0
	s_nop 0
	s_nop 0
	s_nop 0
	s_nop 0
	s_nop 0
	s_nop 0
	s_nop 0
	v_rsq_f32_e32 v78, v78
	s_nop 0
	s_nop 0
	s_nop 0
	s_nop 0
	s_nop 0
	s_nop 0
	v_pk_mul_f32 v[98:99], v[98:99], v[202:203]
	s_waitcnt lgkmcnt(15)
	v_mfma_f32_16x16x32_bf16 v[12:15], v[128:131], v[90:93], v[12:15]
	v_cvt_pk_bf16_f32 v200, v200, v201
	v_cvt_pk_bf16_f32 v201, v98, v99
	v_mul_f32_e32 v79, 0x45800000, v78
	v_mfma_f32_16x16x32_bf16 v[36:39], v[128:131], v[94:97], v[36:39]
	v_lshlrev_b32_e32 v98, 16, v126
	v_cndmask_b32_e64 v78, v78, v79, s[0:1]
	v_and_b32_e32 v99, 0xffff0000, v126
	v_mfma_f32_16x16x32_bf16 v[8:11], v[244:247], v[90:93], v[8:11]
	v_mul_f32_e32 v79, 0xbfb8aa3b, v98
	v_exp_f32_e32 v79, v79
	v_mul_f32_e32 v126, 0xbfb8aa3b, v99
	v_mfma_f32_16x16x32_bf16 v[4:7], v[244:247], v[94:97], v[4:7]
	s_nop 0
	s_nop 0
	s_nop 0
	s_nop 0
	s_nop 0
	s_nop 0
	v_add_f32_e32 v79, 1.0, v79
	global_store_dwordx2 v[152:153], v[200:201], off
	s_waitcnt lgkmcnt(4)
	v_mfma_f32_16x16x32_bf16 v[12:15], v[248:251], v[144:147], v[12:15]
	v_mfma_f32_16x16x32_bf16 v[36:39], v[248:251], v[148:151], v[36:39]
	v_exp_f32_e32 v87, v126
	v_rcp_f32_e32 v86, v79
	v_add_f32_e32 v79, 1.0, v87
	v_rcp_f32_e32 v87, v79
	v_pk_mul_f32 v[84:85], v[84:85], v[78:79] op_sel_hi:[1,0]
	v_mfma_f32_16x16x32_bf16 v[24:27], v[132:135], v[90:93], v[24:27]
	v_mul_f32_e64 v72, v72, v84
	v_mul_f32_e64 v73, v73, v85
	v_pk_mul_f32 v[84:85], v[86:87], v[98:99]
	v_lshlrev_b32_e32 v86, 16, v127
	v_mul_f32_e32 v79, 0xbfb8aa3b, v86
	v_exp_f32_e32 v79, v79
	v_pk_mul_f32 v[98:99], v[84:85], v[72:73]
	v_and_b32_e32 v87, 0xffff0000, v127
	v_mfma_f32_16x16x32_bf16 v[32:35], v[132:135], v[94:97], v[32:35]
	v_add_f32_e32 v72, 1.0, v79
	v_rcp_f32_e32 v84, v72
	v_mul_f32_e32 v72, 0xbfb8aa3b, v87
	v_exp_f32_e32 v79, v72
	v_mfma_f32_16x16x32_bf16 v[40:43], v[136:139], v[90:93], v[40:43]
	v_cvt_pk_bf16_f32 v98, v98, v99
	v_pk_mul_f32 v[72:73], v[82:83], v[78:79] op_sel_hi:[1,0]
	ds_read_b64_tr_b16 v[82:83], v196 offset:56480
	s_nop 0
	v_pk_mul_f32 v[134:135], v[74:75], v[72:73]
	v_add_f32_e32 v72, 1.0, v79
	v_rcp_f32_e32 v85, v72
	s_nop 0
	s_nop 0
	v_mfma_f32_16x16x32_bf16 v[64:67], v[136:139], v[94:97], v[64:67]
	v_mul_f32_e64 v136, v84, v86
	v_mul_f32_e64 v137, v85, v87
	ds_read_b64_tr_b16 v[86:87], v196 offset:56512
	ds_read_b64_tr_b16 v[126:127], v196 offset:56544
	ds_read_b64_tr_b16 v[84:85], v196 offset:57568
	ds_read_b64_tr_b16 v[88:89], v196 offset:57600
	ds_read_b64_tr_b16 v[128:129], v196 offset:57632
	ds_read_b64_tr_b16 v[130:131], v196 offset:65152
	ds_read_b64_tr_b16 v[132:133], v197 offset:57536
	ds_read_b64_tr_b16 v[244:245], v196 offset:65184
	s_nop 0
	s_nop 0
	s_nop 0
	s_nop 0
	s_nop 0
	s_nop 0
	v_mfma_f32_16x16x32_bf16 v[8:11], v[140:143], v[144:147], v[8:11]
	s_nop 0
	s_nop 0
	v_mfma_f32_16x16x32_bf16 v[4:7], v[140:143], v[148:151], v[4:7]
	v_mul_f32_e64 v142, v136, v134
	v_mul_f32_e64 v143, v137, v135
	ds_read_b64_tr_b16 v[134:135], v196 offset:65216
	ds_read_b64_tr_b16 v[138:139], v196 offset:65248
	ds_read_b64_tr_b16 v[246:247], v197 offset:57568
	ds_read_b64_tr_b16 v[136:137], v197 offset:57600
	ds_read_b64_tr_b16 v[140:141], v197 offset:57632
	v_cvt_pk_bf16_f32 v99, v142, v143
	v_lshl_add_u64 v[142:143], s[28:29], 0, v[118:119]
	s_waitcnt lgkmcnt(14)
	v_mfma_f32_16x16x32_bf16 v[16:19], v[252:255], v[90:93], v[16:19]
	v_mfma_f32_16x16x32_bf16 v[20:23], v[252:255], v[94:97], v[20:23]
	s_nop 0
	s_nop 0
	s_nop 0
	s_nop 0
	s_nop 0
	s_nop 0
	global_store_dwordx2 v[142:143], v[98:99], off
	v_lshlrev_b32_e32 v98, 16, v124
	v_and_b32_e32 v99, 0xffff0000, v124
	v_mul_f32_e32 v79, 0xbfb8aa3b, v98
	v_exp_f32_e32 v79, v79
	v_mul_f32_e32 v124, 0xbfb8aa3b, v99
	s_waitcnt lgkmcnt(10)
	v_mfma_f32_16x16x32_bf16 v[28:31], v[82:85], v[90:93], v[28:31]
	v_add_f32_e32 v79, 1.0, v79
	v_mfma_f32_16x16x32_bf16 v[48:51], v[82:85], v[94:97], v[48:51]
	v_exp_f32_e32 v83, v124
	v_rcp_f32_e32 v82, v79
	v_add_f32_e32 v79, 1.0, v83
	v_rcp_f32_e32 v83, v79
	v_pk_mul_f32 v[80:81], v[80:81], v[78:79] op_sel_hi:[1,0]
	s_waitcnt lgkmcnt(2)
	v_mfma_f32_16x16x32_bf16 v[28:31], v[244:247], v[144:147], v[28:31]
	v_mul_f32_e64 v68, v68, v80
	v_mul_f32_e64 v69, v69, v81
	v_pk_mul_f32 v[76:77], v[76:77], v[78:79] op_sel_hi:[1,0]
	v_lshl_add_u64 v[78:79], s[28:29], 0, v[120:121]
	v_mfma_f32_16x16x32_bf16 v[48:51], v[244:247], v[148:151], v[48:51]
	v_mul_f32_e64 v72, v82, v98
	v_mul_f32_e64 v73, v83, v99
	v_pk_mul_f32 v[70:71], v[70:71], v[76:77]
	v_pk_mul_f32 v[68:69], v[72:73], v[68:69]
	v_lshlrev_b32_e32 v72, 16, v125
	v_and_b32_e32 v73, 0xffff0000, v125
	v_mul_f32_e32 v74, 0xbfb8aa3b, v72
	v_mul_f32_e32 v75, 0xbfb8aa3b, v73
	v_exp_f32_e32 v74, v74
	v_exp_f32_e32 v75, v75
	v_lshl_add_u32 v82, s57, 9, v176
	ds_read_b128 v[248:251], v82 offset:4096
	ds_read_b128 v[252:255], v82 offset:4160
	ds_read_b128 v[244:247], v82 offset:4224
	v_cvt_pk_bf16_f32 v76, v68, v69
	v_add_f32_e32 v74, 1.0, v74
	v_add_f32_e32 v75, 1.0, v75
	v_rcp_f32_e32 v74, v74
	v_rcp_f32_e32 v75, v75
	v_mfma_f32_16x16x32_bf16 v[24:27], v[156:159], v[144:147], v[24:27]
	s_add_u32 s28, s28, 0xfffe0000
	s_addc_u32 s29, s29, -1
	v_pk_mul_f32 v[72:73], v[74:75], v[72:73]
	v_mfma_f32_16x16x32_bf16 v[32:35], v[156:159], v[148:151], v[32:35]
	v_mul_f32_e64 v72, v72, v70
	v_mul_f32_e64 v73, v73, v71
	s_nop 0
	v_cvt_pk_bf16_f32 v77, v72, v73
	s_nop 0
	global_store_dwordx2 v[78:79], v[76:77], off
	v_mfma_f32_16x16x32_bf16 v[16:19], v[130:133], v[144:147], v[16:19]
	s_waitcnt lgkmcnt(2)
	v_mul_f32_e32 v68, 0x3fb8aa3b, v248
	v_exp_f32_e32 v80, v68
	v_mul_f32_e32 v81, 0x3fb8aa3b, v249
	v_mul_f32_e32 v68, 0x3fb8aa3b, v250
	v_mul_f32_e32 v69, 0x3fb8aa3b, v251
	ds_read_b128 v[248:251], v82 offset:4288
	v_exp_f32_e32 v68, v68
	v_exp_f32_e32 v69, v69
	v_exp_f32_e32 v81, v81
	v_mfma_f32_16x16x32_bf16 v[20:23], v[130:133], v[148:151], v[20:23]
	s_add_u32 s30, s30, 0xfffe0000
	v_pk_mul_f32 v[10:11], v[10:11], v[68:69]
	v_pk_mul_f32 v[6:7], v[6:7], v[68:69]
	s_waitcnt lgkmcnt(2)
	v_mul_f32_e32 v68, 0x3fb8aa3b, v252
	v_mul_f32_e32 v69, 0x3fb8aa3b, v254
	v_exp_f32_e32 v76, v68
	v_mul_f32_e32 v68, 0x3fb8aa3b, v253
	v_exp_f32_e32 v78, v69
	v_mul_f32_e32 v69, 0x3fb8aa3b, v255
	ds_read_b128 v[252:255], v82 offset:4352
	v_exp_f32_e32 v79, v69
	v_exp_f32_e32 v77, v68
	s_nop 0
	s_nop 0
	v_pk_mul_f32 v[8:9], v[8:9], v[80:81]
	v_pk_mul_f32 v[4:5], v[4:5], v[80:81]
	v_pk_mul_f32 v[14:15], v[14:15], v[78:79]
	s_waitcnt lgkmcnt(2)
	v_mul_f32_e32 v68, 0x3fb8aa3b, v244
	v_exp_f32_e32 v80, v68
	v_mul_f32_e32 v81, 0x3fb8aa3b, v245
	v_mul_f32_e32 v68, 0x3fb8aa3b, v246
	v_mul_f32_e32 v69, 0x3fb8aa3b, v247
	ds_read_b128 v[244:247], v82 offset:4416
	v_exp_f32_e32 v68, v68
	v_exp_f32_e32 v69, v69
	v_pk_mul_f32 v[12:13], v[12:13], v[76:77]
	v_pk_mul_f32 v[38:39], v[38:39], v[78:79]
	v_pk_mul_f32 v[36:37], v[36:37], v[76:77]
	v_pk_mul_f32 v[26:27], v[26:27], v[68:69]
	v_pk_mul_f32 v[34:35], v[34:35], v[68:69]
	s_waitcnt lgkmcnt(2)
	v_mul_f32_e32 v68, 0x3fb8aa3b, v248
	v_mul_f32_e32 v69, 0x3fb8aa3b, v250
	v_exp_f32_e32 v76, v68
	v_mul_f32_e32 v68, 0x3fb8aa3b, v249
	v_exp_f32_e32 v78, v69
	v_mul_f32_e32 v69, 0x3fb8aa3b, v251
	ds_read_b128 v[248:251], v82 offset:4480
	v_exp_f32_e32 v79, v69
	v_exp_f32_e32 v77, v68
	s_nop 0
	s_nop 0
	v_exp_f32_e32 v81, v81
	v_mfma_f32_16x16x32_bf16 v[40:43], v[160:163], v[144:147], v[40:43]
	s_addc_u32 s31, s31, -1
	s_waitcnt lgkmcnt(2)
	v_mul_f32_e32 v68, 0x3fb8aa3b, v252
	v_pk_mul_f32 v[24:25], v[24:25], v[80:81]
	v_pk_mul_f32 v[32:33], v[32:33], v[80:81]
	v_exp_f32_e32 v80, v68
	v_mul_f32_e32 v81, 0x3fb8aa3b, v253
	v_mul_f32_e32 v68, 0x3fb8aa3b, v254
	v_mul_f32_e32 v69, 0x3fb8aa3b, v255
	ds_read_b128 v[252:255], v82 offset:4544
	v_exp_f32_e32 v68, v68
	v_exp_f32_e32 v69, v69
	v_mfma_f32_16x16x32_bf16 v[64:67], v[160:163], v[148:151], v[64:67]
	v_mul_f32_e64 v42, v42, v78
	v_mul_f32_e64 v43, v43, v79
	v_pk_mul_f32 v[40:41], v[40:41], v[76:77]
	v_pk_mul_f32 v[18:19], v[18:19], v[68:69]
	v_pk_mul_f32 v[22:23], v[22:23], v[68:69]
	s_waitcnt lgkmcnt(2)
	v_mul_f32_e32 v68, 0x3fb8aa3b, v244
	v_mul_f32_e32 v69, 0x3fb8aa3b, v246
	v_pk_mul_f32 v[66:67], v[66:67], v[78:79]
	v_pk_mul_f32 v[64:65], v[64:65], v[76:77]
	v_exp_f32_e32 v76, v68
	v_mul_f32_e32 v68, 0x3fb8aa3b, v245
	v_exp_f32_e32 v78, v69
	v_mul_f32_e32 v69, 0x3fb8aa3b, v247
	v_exp_f32_e32 v79, v69
	v_exp_f32_e32 v77, v68
	s_nop 0
	s_nop 0
	v_mfma_f32_16x16x32_bf16 v[44:47], v[86:89], v[90:93], v[44:47]
	v_exp_f32_e32 v81, v81
	v_pk_mul_f32 v[30:31], v[30:31], v[78:79]
	s_waitcnt lgkmcnt(1)
	v_mul_f32_e32 v68, 0x3fb8aa3b, v248
	v_mfma_f32_16x16x32_bf16 v[56:59], v[86:89], v[94:97], v[56:59]
	v_mul_f32_e32 v69, 0x3fb8aa3b, v249
	v_mul_f32_e32 v70, 0x3fb8aa3b, v250
	v_mul_f32_e32 v71, 0x3fb8aa3b, v251
	v_mfma_f32_16x16x32_bf16 v[52:55], v[126:129], v[90:93], v[52:55]
	s_waitcnt lgkmcnt(0)
	v_mul_f32_e32 v72, 0x3fb8aa3b, v252
	v_mul_f32_e32 v73, 0x3fb8aa3b, v253
	v_mul_f32_e32 v74, 0x3fb8aa3b, v254
	v_mfma_f32_16x16x32_bf16 v[60:63], v[126:129], v[94:97], v[60:63]
	v_mul_f32_e32 v75, 0x3fb8aa3b, v255
	v_exp_f32_e32 v68, v68
	v_exp_f32_e32 v70, v70
	v_mfma_f32_16x16x32_bf16 v[44:47], v[134:137], v[144:147], v[44:47]
	v_exp_f32_e32 v71, v71
	v_exp_f32_e32 v69, v69
	v_exp_f32_e32 v72, v72
	v_mfma_f32_16x16x32_bf16 v[56:59], v[134:137], v[148:151], v[56:59]
	v_exp_f32_e32 v74, v74
	v_exp_f32_e32 v75, v75
	v_exp_f32_e32 v73, v73
	v_mfma_f32_16x16x32_bf16 v[52:55], v[138:141], v[144:147], v[52:55]
	v_mul_f32_e64 v16, v16, v80
	v_mul_f32_e64 v17, v17, v81
	v_pk_mul_f32 v[20:21], v[20:21], v[80:81]
	v_pk_mul_f32 v[28:29], v[28:29], v[76:77]
	v_mfma_f32_16x16x32_bf16 v[60:63], v[138:141], v[148:151], v[60:63]
	v_mul_f32_e64 v50, v50, v78
	v_mul_f32_e64 v51, v51, v79
	v_pk_mul_f32 v[48:49], v[48:49], v[76:77]
	v_pk_mul_f32 v[46:47], v[46:47], v[70:71]
	v_pk_mul_f32 v[44:45], v[44:45], v[68:69]
	v_pk_mul_f32 v[58:59], v[58:59], v[70:71]
	v_pk_mul_f32 v[56:57], v[56:57], v[68:69]
	v_pk_mul_f32 v[54:55], v[54:55], v[74:75]
	v_pk_mul_f32 v[52:53], v[52:53], v[72:73]
	v_pk_mul_f32 v[62:63], v[62:63], v[74:75]
	s_cmp_eq_u32 s56, 4
	v_pk_mul_f32 v[60:61], v[60:61], v[72:73]
	s_waitcnt lgkmcnt(0)
	s_cbranch_scc1 .LBB0_2200
.LBB0_2183:
	s_add_u32 s0, s48, s34
	s_addc_u32 s1, s49, s35
	s_add_u32 s58, s39, s34
	s_addc_u32 s59, s37, s35
	s_add_u32 s42, s58, s44
	s_addc_u32 s43, s59, 0
	s_add_u32 s60, s42, 0x16e40800
	s_addc_u32 s61, s43, 0
	s_and_b32 s57, s56, 1
	s_cmp_eq_u32 s57, 0
	s_cselect_b64 s[42:43], -1, 0
	s_and_b64 s[62:63], s[42:43], exec
	s_cselect_b32 s62, 0xf0, s52
	v_add3_u32 v136, s62, v171, v170
	s_waitcnt lgkmcnt(0)
	ds_read2_b32 v[72:73], v136 offset1:4
	ds_read2_b32 v[244:245], v136 offset0:64 offset1:68
	ds_read2_b32 v[248:249], v136 offset0:8 offset1:12
	ds_read2_b32 v[252:253], v136 offset0:72 offset1:76
	v_lshl_add_u64 v[74:75], s[0:1], 0, v[102:103]
	s_nop 0
	global_load_dwordx4 v[92:95], v[74:75], off
	global_load_dwordx4 v[96:99], v[74:75], off offset:1024
	s_nop 0
	v_lshl_add_u64 v[82:83], s[60:61], 0, v[104:105]
	s_waitcnt lgkmcnt(3)
	v_mfma_f32_16x16x4_f32 v[68:71], v72, v155, 0
	v_add_co_u32_e64 v72, s[0:1], s50, v74
	v_mfma_f32_16x16x4_f32 v[68:71], v73, v164, v[68:71]
	s_nop 0
	v_addc_co_u32_e64 v73, s[0:1], 0, v75, s[0:1]
	global_load_dwordx4 v[84:87], v[72:73], off
	global_load_dwordx4 v[88:91], v[72:73], off offset:1024
	v_add_co_u32_e64 v72, s[0:1], s45, v82
	s_nop 1
	v_addc_co_u32_e64 v73, s[0:1], 0, v83, s[0:1]
	s_waitcnt lgkmcnt(1)
	v_mfma_f32_16x16x4_f32 v[124:127], v248, v165, v[68:71]
	v_add_co_u32_e64 v134, s[0:1], s50, v82
	global_load_dwordx4 v[68:71], v[82:83], off
	s_nop 0
	global_load_dwordx4 v[72:75], v[72:73], off
	v_addc_co_u32_e64 v135, s[0:1], 0, v83, s[0:1]
	v_mfma_f32_16x16x4_f32 v[76:79], v244, v155, 0
	v_add_co_u32_e64 v80, s[0:1], s51, v82
	v_mfma_f32_16x16x4_f32 v[124:127], v249, v166, v[124:127]
	ds_read2_b32 v[248:249], v136 offset0:128 offset1:132
	ds_read2_b32 v[250:251], v136 offset0:136 offset1:140
	v_mfma_f32_16x16x4_f32 v[128:131], v245, v164, v[76:79]
	ds_read2_b32 v[244:245], v136 offset0:192 offset1:196
	v_addc_co_u32_e64 v81, s[0:1], 0, v83, s[0:1]
	s_nop 5
	global_load_dwordx4 v[76:79], v[134:135], off
	s_nop 0
	global_load_dwordx4 v[80:83], v[80:81], off
	s_nop 0
	v_add_f32_e32 v124, v167, v124
	v_min_f32_e32 v137, 0, v124
	v_mul_f32_e64 v124, |v124|, s53
	v_exp_f32_e32 v124, v124
	v_add_f32_e32 v126, v167, v126
	v_mul_f32_e64 v133, |v126|, s53
	v_exp_f32_e32 v133, v133
	v_add_f32_e32 v124, 1.0, v124
	v_log_f32_e32 v124, v124
	s_waitcnt lgkmcnt(3)
	v_mfma_f32_16x16x4_f32 v[128:131], v252, v165, v[128:131]
	v_add_f32_e32 v133, 1.0, v133
	v_min_f32_e32 v139, 0, v126
	v_fmac_f32_e32 v137, 0xbf317218, v124
	v_log_f32_e32 v124, v133
	v_add_f32_e32 v134, v167, v127
	v_add_f32_e32 v125, v167, v125
	v_mul_f32_e64 v132, |v125|, s53
	v_fmac_f32_e32 v139, 0xbf317218, v124
	v_mul_f32_e64 v124, |v134|, s53
	v_min_f32_e32 v138, 0, v125
	v_exp_f32_e32 v140, v124
	v_mfma_f32_16x16x4_f32 v[124:127], v253, v166, v[128:131]
	ds_read2_b32 v[252:253], v136 offset0:200 offset1:204
	v_exp_f32_e32 v132, v132
	v_add_f32_e32 v129, 1.0, v140
	v_log_f32_e32 v129, v129
	v_add_f32_e32 v132, 1.0, v132
	v_log_f32_e32 v132, v132
	v_min_f32_e32 v140, 0, v134
	s_nop 3
	v_add_f32_e32 v124, v167, v124
	v_mul_f32_e64 v128, |v124|, s53
	v_fmac_f32_e32 v138, 0xbf317218, v132
	v_exp_f32_e32 v128, v128
	s_nop 0
	v_min_f32_e32 v141, 0, v124
	v_fmac_f32_e32 v140, 0xbf317218, v129
	v_add_f32_e32 v128, 1.0, v128
	v_log_f32_e32 v128, v128
	s_nop 0
	v_add_f32_e32 v124, v167, v125
	v_mul_f32_e64 v125, |v124|, s53
	v_fmac_f32_e32 v141, 0xbf317218, v128
	s_waitcnt lgkmcnt(3)
	v_mfma_f32_16x16x4_f32 v[128:131], v248, v155, 0
	v_add_f32_e32 v132, v167, v126
	v_exp_f32_e32 v125, v125
	v_mul_f32_e64 v126, |v132|, s53
	v_exp_f32_e32 v126, v126
	v_min_f32_e32 v142, 0, v124
	v_add_f32_e32 v124, 1.0, v125
	v_add_f32_e32 v144, v167, v127
	v_mfma_f32_16x16x4_f32 v[128:131], v249, v164, v[128:131]
	v_log_f32_e32 v133, v124
	v_add_f32_e32 v124, 1.0, v126
	v_log_f32_e32 v143, v124
	v_mul_f32_e64 v145, |v144|, s53
	v_fmac_f32_e32 v142, 0xbf317218, v133
	s_waitcnt lgkmcnt(2)
	v_mfma_f32_16x16x4_f32 v[124:127], v250, v165, v[128:131]
	s_nop 2
	v_exp_f32_e32 v128, v145
	v_min_f32_e32 v145, 0, v132
	s_nop 0
	v_fmac_f32_e32 v145, 0xbf317218, v143
	v_add_f32_e32 v128, 1.0, v128
	v_log_f32_e32 v128, v128
	v_min_f32_e32 v143, 0, v144
	v_mfma_f32_16x16x4_f32 v[124:127], v251, v166, v[124:127]
	v_fmac_f32_e32 v143, 0xbf317218, v128
	s_nop 8
	v_add_f32_e32 v124, v167, v124
	v_mul_f32_e64 v128, |v124|, s53
	v_exp_f32_e32 v134, v128
	s_waitcnt lgkmcnt(1)
	v_mfma_f32_16x16x4_f32 v[128:131], v244, v155, 0
	v_add_f32_e32 v125, v167, v125
	v_mul_f32_e64 v135, |v125|, s53
	v_exp_f32_e32 v132, v135
	v_min_f32_e32 v144, 0, v124
	v_add_f32_e32 v124, 1.0, v134
	s_nop 0
	v_add_f32_e32 v132, 1.0, v132
	v_mfma_f32_16x16x4_f32 v[128:131], v245, v164, v[128:131]
	v_log_f32_e32 v132, v132
	v_log_f32_e32 v124, v124
	v_min_f32_e32 v133, 0, v125
	v_add_f32_e32 v146, v167, v127
	v_fmac_f32_e32 v133, 0xbf317218, v132
	v_add_f32_e32 v132, v167, v126
	v_fmac_f32_e32 v144, 0xbf317218, v124
	v_mul_f32_e64 v124, |v132|, s53
	v_exp_f32_e32 v136, v124
	s_waitcnt lgkmcnt(0)
	v_mfma_f32_16x16x4_f32 v[124:127], v252, v165, v[128:131]
	v_mul_f32_e64 v128, |v146|, s53
	v_exp_f32_e32 v128, v128
	v_add_f32_e32 v130, 1.0, v136
	v_log_f32_e32 v130, v130
	v_min_f32_e32 v129, 0, v132
	v_add_f32_e32 v128, 1.0, v128
	v_log_f32_e32 v128, v128
	v_mfma_f32_16x16x4_f32 v[124:127], v253, v166, v[124:127]
	v_fmac_f32_e32 v129, 0xbf317218, v130
	v_min_f32_e32 v130, 0, v146
	v_fmac_f32_e32 v130, 0xbf317218, v128
	s_nop 6
	v_add_f32_e32 v124, v167, v124
	v_mul_f32_e64 v131, |v124|, s53
	v_exp_f32_e32 v131, v131
	v_add_f32_e32 v125, v167, v125
	v_min_f32_e32 v124, 0, v124
	v_add_f32_e32 v126, v167, v126
	v_add_f32_e32 v128, 1.0, v131
	v_mul_f32_e64 v131, |v125|, s53
	v_log_f32_e32 v128, v128
	v_exp_f32_e32 v131, v131
	v_add_f32_e32 v127, v167, v127
	v_mul_f32_e64 v132, |v127|, s53
	v_fmac_f32_e32 v124, 0xbf317218, v128
	v_add_f32_e32 v128, 1.0, v131
	v_mul_f32_e64 v131, |v126|, s53
	v_log_f32_e32 v128, v128
	v_exp_f32_e32 v131, v131
	v_exp_f32_e32 v132, v132
	v_min_f32_e32 v125, 0, v125
	v_fmac_f32_e32 v125, 0xbf317218, v128
	v_add_f32_e32 v128, 1.0, v131
	v_add_f32_e32 v131, 1.0, v132
	v_log_f32_e32 v131, v131
	v_log_f32_e32 v128, v128
	v_min_f32_e32 v127, 0, v127
	v_min_f32_e32 v126, 0, v126
	v_fmac_f32_e32 v127, 0xbf317218, v131
	v_fmac_f32_e32 v126, 0xbf317218, v128
	v_fma_f32 v127, v127, s54, 0
	v_fmamk_f32 v126, v126, 0x3d800000, v127
	v_fmamk_f32 v125, v125, 0x3d800000, v126
	v_fmamk_f32 v124, v124, 0x3d800000, v125
	v_fmamk_f32 v128, v130, 0x3d800000, v124
	v_fmamk_f32 v129, v129, 0x3d800000, v128
	v_fmamk_f32 v130, v133, 0x3d800000, v129
	v_fmamk_f32 v131, v144, 0x3d800000, v130
	v_fmamk_f32 v132, v143, 0x3d800000, v131
	v_fmamk_f32 v133, v145, 0x3d800000, v132
	v_fmamk_f32 v134, v142, 0x3d800000, v133
	v_fmamk_f32 v135, v141, 0x3d800000, v134
	v_fmamk_f32 v136, v140, 0x3d800000, v135
	v_fmamk_f32 v139, v139, 0x3d800000, v136
	v_fmamk_f32 v138, v138, 0x3d800000, v139
	v_fmamk_f32 v137, v137, 0x3d800000, v138
	ds_bpermute_b32 v140, v174, v137
	ds_bpermute_b32 v141, v173, v137
	ds_bpermute_b32 v142, v172, v137
	s_waitcnt lgkmcnt(2)
	v_cndmask_b32_e64 v140, v140, 0, s[2:3]
	s_waitcnt lgkmcnt(1)
	v_cndmask_b32_e64 v141, 0, v141, s[4:5]
	v_add_f32_e32 v140, v141, v140
	s_waitcnt lgkmcnt(0)
	v_cndmask_b32_e64 v141, 0, v142, s[6:7]
	v_add_f32_e32 v140, v141, v140
	v_add_f32_e32 v137, v140, v137
	v_add_f32_e32 v138, v140, v138
	v_add_f32_e32 v124, v140, v124
	v_add_f32_e32 v125, v140, v125
	ds_write2st64_b32 v184, v137, v138 offset0:24 offset1:26
	v_add_f32_e32 v137, v140, v139
	v_add_f32_e32 v136, v140, v136
	v_add_f32_e32 v135, v140, v135
	v_add_f32_e32 v134, v140, v134
	v_add_f32_e32 v133, v140, v133
	v_add_f32_e32 v132, v140, v132
	v_add_f32_e32 v131, v140, v131
	v_add_f32_e32 v130, v140, v130
	v_add_f32_e32 v129, v140, v129
	v_add_f32_e32 v128, v140, v128
	ds_write2st64_b32 v184, v124, v125 offset0:48 offset1:50
	v_add_f32_e32 v124, v140, v126
	v_add_f32_e32 v125, v140, v127
	ds_write2st64_b32 v184, v137, v136 offset0:28 offset1:30
	ds_write2st64_b32 v184, v135, v134 offset0:32 offset1:34
	ds_write2st64_b32 v184, v133, v132 offset0:36 offset1:38
	ds_write2st64_b32 v184, v131, v130 offset0:40 offset1:42
	ds_write2st64_b32 v184, v129, v128 offset0:44 offset1:46
	ds_write2st64_b32 v184, v124, v125 offset0:52 offset1:54
	s_waitcnt lgkmcnt(0)
	s_barrier
	s_and_saveexec_b64 s[0:1], s[8:9]
	s_cbranch_execz .LBB0_2185
	ds_read_b32 v124, v175 offset:6144
	v_lshl_add_u32 v125, s57, 9, v175
	s_waitcnt lgkmcnt(0)
	ds_write_b32 v125, v124 offset:4096

.LBB0_2192:
	ds_read_b128 v[124:127], v185 offset:6144
	ds_read_b128 v[128:131], v185 offset:6160
	s_waitcnt vmcnt(6)
	v_lshlrev_b32_e32 v132, 16, v96
	s_waitcnt lgkmcnt(1)
	v_mul_f32_e32 v133, 0xbfb8aa3b, v124
	v_mul_f32_e32 v135, 0xbfb8aa3b, v125
	v_exp_f32_e32 v134, v133
	v_exp_f32_e32 v135, v135
	v_and_b32_e32 v133, 0xffff0000, v96
	v_mul_f32_e32 v96, 0xbfb8aa3b, v126
	v_exp_f32_e32 v136, v96
	v_pk_mul_f32 v[132:133], v[134:135], v[132:133]
	v_mul_f32_e32 v96, 0xbfb8aa3b, v127
	v_exp_f32_e32 v137, v96
	v_cvt_pk_bf16_f32 v96, v132, v133
	v_lshlrev_b32_e32 v132, 16, v97
	v_and_b32_e32 v133, 0xffff0000, v97
	s_waitcnt lgkmcnt(0)
	v_mul_f32_e32 v97, 0xbfb8aa3b, v128
	v_exp_f32_e32 v134, v97
	v_mul_f32_e32 v97, 0xbfb8aa3b, v129
	v_exp_f32_e32 v135, v97
	v_pk_mul_f32 v[132:133], v[136:137], v[132:133]
	v_mul_f32_e32 v124, 0x3fb8aa3b, v124
	v_cvt_pk_bf16_f32 v97, v132, v133
	v_lshlrev_b32_e32 v132, 16, v98
	v_and_b32_e32 v133, 0xffff0000, v98
	v_mul_f32_e32 v98, 0xbfb8aa3b, v130
	v_pk_mul_f32 v[132:133], v[134:135], v[132:133]
	v_exp_f32_e32 v134, v98
	v_mul_f32_e32 v98, 0xbfb8aa3b, v131
	v_exp_f32_e32 v135, v98
	v_mul_f32_e32 v125, 0x3fb8aa3b, v125
	v_exp_f32_e32 v124, v124
	v_exp_f32_e32 v125, v125
	v_cvt_pk_bf16_f32 v98, v132, v133
	v_lshlrev_b32_e32 v132, 16, v99
	v_and_b32_e32 v133, 0xffff0000, v99
	v_pk_mul_f32 v[132:133], v[134:135], v[132:133]
	s_nop 0
	v_cvt_pk_bf16_f32 v99, v132, v133
	ds_write_b128 v182, v[96:99] offset:56320
	v_lshlrev_b32_e32 v96, 16, v92
	v_and_b32_e32 v97, 0xffff0000, v92
	v_pk_mul_f32 v[98:99], v[124:125], s[36:37] op_sel_hi:[1,0]
	v_mul_f32_e32 v92, 0x3fb8aa3b, v126
	v_pk_mul_f32 v[96:97], v[98:99], v[96:97]
	v_exp_f32_e32 v98, v92
	v_mul_f32_e32 v92, 0x3fb8aa3b, v127
	v_exp_f32_e32 v99, v92
	v_cvt_pk_bf16_f32 v92, v96, v97
	v_lshlrev_b32_e32 v96, 16, v93
	v_and_b32_e32 v97, 0xffff0000, v93
	v_pk_mul_f32 v[98:99], v[98:99], s[36:37] op_sel_hi:[1,0]
	v_mul_f32_e32 v93, 0x3fb8aa3b, v128
	v_pk_mul_f32 v[96:97], v[98:99], v[96:97]
	v_exp_f32_e32 v98, v93
	v_mul_f32_e32 v93, 0x3fb8aa3b, v129
	v_exp_f32_e32 v99, v93
	v_cvt_pk_bf16_f32 v93, v96, v97
	v_lshlrev_b32_e32 v96, 16, v94
	v_and_b32_e32 v97, 0xffff0000, v94
	v_pk_mul_f32 v[98:99], v[98:99], s[36:37] op_sel_hi:[1,0]
	v_mul_f32_e32 v94, 0x3fb8aa3b, v130
	v_pk_mul_f32 v[96:97], v[98:99], v[96:97]
	v_exp_f32_e32 v98, v94
	v_mul_f32_e32 v94, 0x3fb8aa3b, v131
	v_exp_f32_e32 v99, v94
	v_cvt_pk_bf16_f32 v94, v96, v97
	v_lshlrev_b32_e32 v96, 16, v95
	v_and_b32_e32 v97, 0xffff0000, v95
	v_pk_mul_f32 v[98:99], v[98:99], s[36:37] op_sel_hi:[1,0]
	s_waitcnt vmcnt(4)
	v_lshlrev_b32_e32 v126, 16, v88
	v_pk_mul_f32 v[96:97], v[98:99], v[96:97]
	v_and_b32_e32 v127, 0xffff0000, v88
	v_cvt_pk_bf16_f32 v95, v96, v97
	ds_write_b128 v182, v[92:95] offset:38912
	ds_read_b128 v[92:95], v186 offset:6144
	ds_read_b128 v[96:99], v186 offset:6160
	s_waitcnt lgkmcnt(1)
	v_mul_f32_e32 v124, 0xbfb8aa3b, v92
	v_mul_f32_e32 v125, 0xbfb8aa3b, v93
	v_exp_f32_e32 v124, v124
	v_exp_f32_e32 v125, v125
	v_mul_f32_e32 v88, 0xbfb8aa3b, v94
	v_mul_f32_e32 v92, 0x3fb8aa3b, v92
	v_mul_f32_e32 v93, 0x3fb8aa3b, v93
	v_pk_mul_f32 v[124:125], v[124:125], v[126:127]
	v_exp_f32_e32 v126, v88
	v_mul_f32_e32 v88, 0xbfb8aa3b, v95
	v_exp_f32_e32 v127, v88
	v_cvt_pk_bf16_f32 v88, v124, v125
	v_lshlrev_b32_e32 v124, 16, v89
	v_and_b32_e32 v125, 0xffff0000, v89
	s_waitcnt lgkmcnt(0)
	v_mul_f32_e32 v89, 0xbfb8aa3b, v96
	v_pk_mul_f32 v[124:125], v[126:127], v[124:125]
	v_exp_f32_e32 v126, v89
	v_mul_f32_e32 v89, 0xbfb8aa3b, v97
	v_exp_f32_e32 v127, v89
	v_cvt_pk_bf16_f32 v89, v124, v125
	v_lshlrev_b32_e32 v124, 16, v90
	v_and_b32_e32 v125, 0xffff0000, v90
	v_mul_f32_e32 v90, 0xbfb8aa3b, v98
	v_pk_mul_f32 v[124:125], v[126:127], v[124:125]
	v_exp_f32_e32 v126, v90
	v_mul_f32_e32 v90, 0xbfb8aa3b, v99
	v_exp_f32_e32 v127, v90
	v_exp_f32_e32 v92, v92
	v_exp_f32_e32 v93, v93
	v_cvt_pk_bf16_f32 v90, v124, v125
	v_lshlrev_b32_e32 v124, 16, v91
	v_and_b32_e32 v125, 0xffff0000, v91
	v_pk_mul_f32 v[124:125], v[126:127], v[124:125]
	s_nop 0
	v_cvt_pk_bf16_f32 v91, v124, v125
	ds_write_b128 v183, v[88:91] offset:56320
	v_lshlrev_b32_e32 v88, 16, v84
	v_and_b32_e32 v89, 0xffff0000, v84
	v_pk_mul_f32 v[90:91], v[92:93], s[36:37] op_sel_hi:[1,0]
	v_mul_f32_e32 v84, 0x3fb8aa3b, v94
	v_pk_mul_f32 v[88:89], v[90:91], v[88:89]
	v_exp_f32_e32 v90, v84
	v_mul_f32_e32 v84, 0x3fb8aa3b, v95
	v_exp_f32_e32 v91, v84
	v_cvt_pk_bf16_f32 v84, v88, v89
	v_lshlrev_b32_e32 v88, 16, v85
	v_and_b32_e32 v89, 0xffff0000, v85
	v_pk_mul_f32 v[90:91], v[90:91], s[36:37] op_sel_hi:[1,0]
	v_mul_f32_e32 v85, 0x3fb8aa3b, v96
	v_pk_mul_f32 v[88:89], v[90:91], v[88:89]
	v_exp_f32_e32 v90, v85
	v_mul_f32_e32 v85, 0x3fb8aa3b, v97
	v_exp_f32_e32 v91, v85
	v_cvt_pk_bf16_f32 v85, v88, v89
	v_lshlrev_b32_e32 v88, 16, v86
	v_and_b32_e32 v89, 0xffff0000, v86
	v_pk_mul_f32 v[90:91], v[90:91], s[36:37] op_sel_hi:[1,0]
	v_mul_f32_e32 v86, 0x3fb8aa3b, v98
	v_pk_mul_f32 v[88:89], v[90:91], v[88:89]
	v_exp_f32_e32 v90, v86
	v_mul_f32_e32 v86, 0x3fb8aa3b, v99
	v_exp_f32_e32 v91, v86
	v_cvt_pk_bf16_f32 v86, v88, v89
	v_lshlrev_b32_e32 v88, 16, v87
	v_and_b32_e32 v89, 0xffff0000, v87
	v_pk_mul_f32 v[90:91], v[90:91], s[36:37] op_sel_hi:[1,0]
	s_nop 0
	v_pk_mul_f32 v[88:89], v[90:91], v[88:89]
	s_nop 0
	v_cvt_pk_bf16_f32 v87, v88, v89
	ds_write_b128 v183, v[84:87] offset:38912
	s_waitcnt vmcnt(3)
	ds_write_b128 v187, v[68:71]
	s_waitcnt vmcnt(2)
	ds_write_b128 v188, v[72:75]
	s_waitcnt vmcnt(1)
	ds_write_b128 v187, v[76:79] offset:16896
	s_waitcnt vmcnt(0)
	ds_write_b128 v189, v[80:83]
	v_lshl_add_u64 v[68:69], s[30:31], 0, v[106:107]
	v_lshl_add_u64 v[70:71], s[30:31], 0, v[110:111]
	v_lshl_add_u64 v[72:73], s[30:31], 0, v[112:113]
	global_load_dwordx2 v[78:79], v[68:69], off
	global_load_dwordx2 v[76:77], v[68:69], off offset:32
	global_load_dwordx2 v[146:147], v[70:71], off
	global_load_dwordx2 v[144:145], v[72:73], off
	v_lshl_add_u64 v[68:69], s[30:31], 0, v[114:115]
	v_lshl_add_u64 v[70:71], s[30:31], 0, v[116:117]
	v_lshl_add_u64 v[72:73], s[30:31], 0, v[118:119]
	v_lshl_add_u64 v[74:75], s[30:31], 0, v[120:121]
	global_load_dwordx2 v[140:141], v[68:69], off
	global_load_dwordx2 v[138:139], v[70:71], off
	global_load_dwordx2 v[134:135], v[72:73], off
	global_load_dwordx2 v[132:133], v[74:75], off
	s_waitcnt lgkmcnt(0)
	s_barrier
	s_waitcnt lgkmcnt(0)
	ds_read_b128 v[68:71], v190 offset:56320
	ds_read_b128 v[244:247], v190 offset:56384
	ds_read_b128 v[248:251], v177 offset:38912
	ds_read_b128 v[252:255], v177 offset:38976
	ds_read_b128 v[88:91], v190 offset:56448
	ds_read_b128 v[92:95], v190 offset:56512
	ds_read_b128 v[72:75], v177 offset:39040
	ds_read_b128 v[96:99], v177 offset:39104
	s_waitcnt lgkmcnt(5)
	v_mfma_f32_16x16x32_bf16 v[68:71], v[68:71], v[248:251], 0
	s_nop 0
	s_nop 0
	v_add_u32_e32 v199, 0x9800, v195
	v_add_u32_e32 v232, 0xa800, v195
	s_waitcnt lgkmcnt(4)
	v_mfma_f32_16x16x32_bf16 v[68:71], v[244:247], v[252:255], v[68:71]
	s_nop 0
	s_nop 0
	v_add_u32_e32 v236, 0xb800, v195
	v_add_u32_e32 v237, 0xc800, v195
	s_waitcnt lgkmcnt(1)
	v_mfma_f32_16x16x32_bf16 v[68:71], v[88:91], v[72:75], v[68:71]
	v_mov_b32_e32 v88, s41
	v_cvt_pk_bf16_f32 v204, v32, v33
	v_cvt_pk_bf16_f32 v205, v34, v35
	s_waitcnt lgkmcnt(0)
	v_mfma_f32_16x16x32_bf16 v[68:71], v[92:95], v[96:99], v[68:71]
	v_cvt_pk_bf16_f32 v206, v64, v65
	v_cvt_pk_bf16_f32 v207, v66, v67
	s_add_u32 s0, s58, s44
	s_addc_u32 s1, s59, 0
	s_add_u32 s0, s0, 0x16e41000
	s_nop 2
	v_cndmask_b32_e64 v68, v68, v88, s[10:11]
	v_cndmask_b32_e64 v69, v69, 0, s[12:13]
	v_cndmask_b32_e64 v70, v70, 0, s[14:15]
	v_cndmask_b32_e64 v71, v71, 0, s[16:17]
	v_cvt_pk_bf16_f32 v68, v68, v69
	v_cvt_pk_bf16_f32 v69, v70, v71
	ds_write_b64 v191, v[68:69]
	ds_read_b128 v[244:247], v192 offset:56320
	ds_read_b128 v[88:91], v192 offset:56384
	ds_read_b128 v[80:83], v192 offset:56448
	ds_read_b128 v[84:87], v192 offset:56512
	s_waitcnt lgkmcnt(3)
	v_mfma_f32_16x16x32_bf16 v[68:71], v[244:247], v[248:251], 0
	s_nop 0
	s_addc_u32 s1, s1, 0
	v_cvt_pk_bf16_f32 v208, v16, v17
	s_waitcnt lgkmcnt(2)
	v_mfma_f32_16x16x32_bf16 v[68:71], v[88:91], v[252:255], v[68:71]
	s_nop 0
	v_cvt_pk_bf16_f32 v209, v18, v19
	v_cvt_pk_bf16_f32 v210, v28, v29
	s_waitcnt lgkmcnt(1)
	v_mfma_f32_16x16x32_bf16 v[68:71], v[80:83], v[72:75], v[68:71]
	v_mov_b32_e32 v72, s41
	v_cvt_pk_bf16_f32 v211, v30, v31
	v_cvt_pk_bf16_f32 v224, v44, v45
	s_waitcnt lgkmcnt(0)
	v_mfma_f32_16x16x32_bf16 v[68:71], v[84:87], v[96:99], v[68:71]
	v_cvt_pk_bf16_f32 v225, v46, v47
	v_cvt_pk_bf16_f32 v226, v52, v53
	v_cvt_pk_bf16_f32 v227, v54, v55
	v_cvt_pk_bf16_f32 v228, v56, v57
	v_cvt_pk_bf16_f32 v229, v58, v59
	s_nop 2
	v_cndmask_b32_e64 v68, v68, v72, s[18:19]
	v_cndmask_b32_e64 v69, v69, 0, s[20:21]
	v_cndmask_b32_e64 v70, v70, 0, s[22:23]
	v_cndmask_b32_e64 v71, v71, 0, s[24:25]
	v_cvt_pk_bf16_f32 v68, v68, v69
	v_cvt_pk_bf16_f32 v69, v70, v71
	ds_write_b64 v193, v[68:69]
	s_waitcnt lgkmcnt(0)
	s_barrier
	s_waitcnt lgkmcnt(0)
	ds_read_b64_tr_b16 v[70:71], v198 offset:2112
	ds_read_b64_tr_b16 v[68:69], v198
	ds_read_b64_tr_b16 v[246:247], v198 offset:2144
	ds_read_b64_tr_b16 v[244:245], v198 offset:32
	ds_read_b128 v[248:251], v194
	ds_read_b128 v[252:255], v194 offset:64
	ds_read_b128 v[92:95], v194 offset:2304
	ds_read_b128 v[96:99], v194 offset:2368
	ds_read_b128 v[128:131], v194 offset:4608
	ds_read_b64_tr_b16 v[148:149], v198 offset:16896
	ds_read_b64_tr_b16 v[150:151], v198 offset:19008
	ds_read_b128 v[156:159], v194 offset:4672
	ds_read_b64_tr_b16 v[202:203], v198 offset:19040
	ds_read_b64_tr_b16 v[200:201], v198 offset:16928
	s_waitcnt lgkmcnt(9)
	v_mfma_f32_16x16x32_bf16 v[88:91], v[68:71], v[248:251], 0
	v_cvt_pk_bf16_f32 v230, v60, v61
	v_cvt_pk_bf16_f32 v231, v62, v63
	v_mfma_f32_16x16x32_bf16 v[80:83], v[244:247], v[248:251], 0
	ds_read_b128 v[248:251], v194 offset:6912
	s_waitcnt lgkmcnt(8)
	v_mfma_f32_16x16x32_bf16 v[124:127], v[68:71], v[92:95], 0
	v_mfma_f32_16x16x32_bf16 v[92:95], v[244:247], v[92:95], 0
	s_waitcnt lgkmcnt(6)
	v_mfma_f32_16x16x32_bf16 v[160:163], v[68:71], v[128:131], 0
	s_waitcnt lgkmcnt(4)
	v_mfma_f32_16x16x32_bf16 v[88:91], v[148:151], v[252:255], v[88:91]
	s_waitcnt lgkmcnt(1)
	v_mfma_f32_16x16x32_bf16 v[80:83], v[200:203], v[252:255], v[80:83]
	ds_read_b128 v[252:255], v194 offset:6976
	v_mfma_f32_16x16x32_bf16 v[84:87], v[148:151], v[96:99], v[124:127]
	v_mfma_f32_16x16x32_bf16 v[92:95], v[200:203], v[96:99], v[92:95]
	v_mfma_f32_16x16x32_bf16 v[96:99], v[244:247], v[128:131], 0
	v_mfma_f32_16x16x32_bf16 v[124:127], v[148:151], v[156:159], v[160:163]
	ds_read2_b64 v[160:163], v236 offset0:64 offset1:68
	v_mfma_f32_16x16x32_bf16 v[96:99], v[200:203], v[156:159], v[96:99]
	s_nop 0
	s_nop 0
	s_nop 0
	s_waitcnt lgkmcnt(2)
	v_mfma_f32_16x16x32_bf16 v[68:71], v[68:71], v[248:251], 0
	v_mfma_f32_16x16x32_bf16 v[72:75], v[244:247], v[248:251], 0
	ds_read2_b64 v[244:247], v199 offset1:4
	ds_read2_b64 v[248:251], v232 offset0:32 offset1:36
	v_cvt_pk_bf16_f32 v128, v8, v9
	v_cvt_pk_bf16_f32 v129, v10, v11
	v_cvt_pk_bf16_f32 v130, v12, v13
	s_waitcnt lgkmcnt(3)
	v_mfma_f32_16x16x32_bf16 v[68:71], v[148:151], v[252:255], v[68:71]
	v_cvt_pk_bf16_f32 v131, v14, v15
	s_nop 0
	v_mfma_f32_16x16x32_bf16 v[72:75], v[200:203], v[252:255], v[72:75]
	ds_read2_b64 v[252:255], v237 offset0:96 offset1:100
	v_cvt_pk_bf16_f32 v156, v4, v5
	v_cvt_pk_bf16_f32 v157, v6, v7
	v_cvt_pk_bf16_f32 v158, v36, v37
	v_cvt_pk_bf16_f32 v159, v38, v39
	s_waitcnt lgkmcnt(2)
	v_mfma_f32_16x16x32_bf16 v[88:91], v[128:131], v[244:247], v[88:91]
	v_cvt_pk_bf16_f32 v200, v24, v25
	v_cvt_pk_bf16_f32 v201, v26, v27
	v_cvt_pk_bf16_f32 v202, v40, v41
	v_mfma_f32_16x16x32_bf16 v[80:83], v[156:159], v[244:247], v[80:83]
	ds_read2_b64 v[244:247], v199 offset0:8 offset1:12
	s_nop 0
	v_cvt_pk_bf16_f32 v203, v42, v43
	s_waitcnt lgkmcnt(2)
	v_mfma_f32_16x16x32_bf16 v[84:87], v[128:131], v[248:251], v[84:87]
	v_mfma_f32_16x16x32_bf16 v[92:95], v[156:159], v[248:251], v[92:95]
	ds_read2_b64 v[248:251], v232 offset0:40 offset1:44
	s_nop 0
	v_mfma_f32_16x16x32_bf16 v[124:127], v[128:131], v[160:163], v[124:127]
	v_mfma_f32_16x16x32_bf16 v[96:99], v[156:159], v[160:163], v[96:99]
	s_waitcnt lgkmcnt(2)
	v_mfma_f32_16x16x32_bf16 v[68:71], v[128:131], v[252:255], v[68:71]
	s_nop 0
	s_nop 0
	v_mfma_f32_16x16x32_bf16 v[148:151], v[156:159], v[252:255], v[72:75]
	ds_read2_b64 v[252:255], v236 offset0:72 offset1:76
	ds_read2_b64 v[156:159], v237 offset0:104 offset1:108
	ds_read2_b64 v[212:215], v199 offset0:16 offset1:20
	s_nop 2
	s_nop 0
	s_nop 0
	s_nop 0
	s_waitcnt lgkmcnt(4)
	v_mfma_f32_16x16x32_bf16 v[88:91], v[200:203], v[244:247], v[88:91]
	v_mfma_f32_16x16x32_bf16 v[80:83], v[204:207], v[244:247], v[80:83]
	ds_read2_b64 v[244:247], v232 offset0:48 offset1:52
	v_lshl_add_u64 v[128:129], s[0:1], 0, v[108:109]
	v_add_co_u32_e64 v130, s[0:1], s45, v128
	s_waitcnt lgkmcnt(3)
	v_mfma_f32_16x16x32_bf16 v[216:219], v[200:203], v[252:255], v[124:127]
	v_addc_co_u32_e64 v131, s[0:1], 0, v129, s[0:1]
	v_mfma_f32_16x16x32_bf16 v[96:99], v[204:207], v[252:255], v[96:99]
	ds_read2_b64 v[252:255], v236 offset0:80 offset1:84
	ds_read2_b64 v[220:223], v237 offset0:112 offset1:116
	v_add_co_u32_e64 v72, s[0:1], s50, v128
	s_nop 1
	v_addc_co_u32_e64 v73, s[0:1], 0, v129, s[0:1]
	v_mfma_f32_16x16x32_bf16 v[84:87], v[200:203], v[248:251], v[84:87]
	s_waitcnt lgkmcnt(4)
	v_mfma_f32_16x16x32_bf16 v[200:203], v[200:203], v[156:159], v[68:71]
	s_nop 2
	v_add_co_u32_e64 v68, s[0:1], s51, v128
	v_mfma_f32_16x16x32_bf16 v[92:95], v[204:207], v[248:251], v[92:95]
	ds_read2_b64 v[248:251], v199 offset0:24 offset1:28
	s_nop 0
	v_addc_co_u32_e64 v69, s[0:1], 0, v129, s[0:1]
	global_load_dwordx2 v[162:163], v[128:129], off
	global_load_dwordx2 v[152:153], v[128:129], off offset:32
	global_load_dwordx2 v[142:143], v[130:131], off
	global_load_dwordx2 v[136:137], v[130:131], off offset:32
	s_nop 0
	global_load_dwordx2 v[130:131], v[72:73], off
	global_load_dwordx2 v[128:129], v[72:73], off offset:32
	global_load_dwordx2 v[126:127], v[68:69], off
	global_load_dwordx2 v[124:125], v[68:69], off offset:32
	s_nop 0
	global_load_dwordx4 v[72:75], v[122:123], off
	global_load_dwordx4 v[68:71], v[122:123], off offset:64
	v_mfma_f32_16x16x32_bf16 v[156:159], v[204:207], v[156:159], v[148:151]
	v_cvt_pk_bf16_f32 v204, v20, v21
	v_cvt_pk_bf16_f32 v205, v22, v23
	v_cvt_pk_bf16_f32 v206, v48, v49
	v_cvt_pk_bf16_f32 v207, v50, v51
	s_waitcnt lgkmcnt(4)
	v_mfma_f32_16x16x32_bf16 v[88:91], v[208:211], v[212:215], v[88:91]
	s_nop 0
	v_mfma_f32_16x16x32_bf16 v[80:83], v[204:207], v[212:215], v[80:83]
	s_nop 0
	s_nop 0
	s_waitcnt lgkmcnt(2)
	v_mfma_f32_16x16x32_bf16 v[216:219], v[208:211], v[252:255], v[216:219]
	v_mfma_f32_16x16x32_bf16 v[212:215], v[204:207], v[252:255], v[96:99]
	s_nop 2
	s_nop 0
	ds_read2_b64 v[232:235], v232 offset0:56 offset1:60
	s_waitcnt lgkmcnt(1)
	v_mfma_f32_16x16x32_bf16 v[88:91], v[224:227], v[248:251], v[88:91]
	v_mfma_f32_16x16x32_bf16 v[84:87], v[208:211], v[244:247], v[84:87]
	v_mfma_f32_16x16x32_bf16 v[92:95], v[204:207], v[244:247], v[92:95]
	s_waitcnt vmcnt(17)
	v_lshlrev_b32_e32 v148, 16, v78
	v_and_b32_e32 v149, 0xffff0000, v78
	v_lshlrev_b32_e32 v78, 16, v79
	v_and_b32_e32 v79, 0xffff0000, v79
	s_nop 0
	v_pk_add_f32 v[150:151], v[90:91], v[78:79]
	v_mfma_f32_16x16x32_bf16 v[78:81], v[228:231], v[248:251], v[80:83]
	v_add_f32_e64 v148, v88, v148
	v_add_f32_e64 v149, v89, v149
	s_waitcnt vmcnt(16)
	v_lshlrev_b32_e32 v88, 16, v76
	v_pk_mul_f32 v[160:161], v[148:149], v[148:149]
	v_and_b32_e32 v89, 0xffff0000, v76
	v_lshlrev_b32_e32 v76, 16, v77
	v_and_b32_e32 v77, 0xffff0000, v77
	v_mfma_f32_16x16x32_bf16 v[204:207], v[204:207], v[220:223], v[156:159]
	v_mul_f32_e64 v82, v150, v150
	v_mul_f32_e64 v83, v151, v151
	s_nop 0
	v_pk_add_f32 v[158:159], v[80:81], v[76:77]
	v_add_f32_e32 v80, v160, v161
	v_pk_add_f32 v[156:157], v[78:79], v[88:89]
	v_add_f32_e32 v80, v82, v80
	v_pk_mul_f32 v[76:77], v[156:157], v[156:157]
	v_add_f32_e32 v80, v83, v80
	v_add_f32_e32 v76, v76, v80
	v_pk_mul_f32 v[78:79], v[158:159], v[158:159]
	v_add_f32_e32 v76, v77, v76
	v_add_f32_e32 v76, v78, v76
	v_add_f32_e32 v76, v79, v76
	ds_bpermute_b32 v77, v178, v76
	v_mfma_f32_16x16x32_bf16 v[200:203], v[208:211], v[220:223], v[200:203]
	ds_read2_b64 v[208:211], v236 offset0:88 offset1:92
	ds_read2_b64 v[236:239], v237 offset0:120 offset1:124
	s_waitcnt lgkmcnt(2)
	v_add_f32_e32 v160, v76, v77
	ds_bpermute_b32 v161, v179, v160
	v_mfma_f32_16x16x32_bf16 v[96:99], v[224:227], v[232:235], v[84:87]
	v_mfma_f32_16x16x32_bf16 v[92:95], v[228:231], v[232:235], v[92:95]
	s_waitcnt lgkmcnt(2)
	v_mfma_f32_16x16x32_bf16 v[88:91], v[224:227], v[208:211], v[216:219]
	v_mfma_f32_16x16x32_bf16 v[84:87], v[228:231], v[208:211], v[212:215]
	s_waitcnt lgkmcnt(1)
	v_mfma_f32_16x16x32_bf16 v[80:83], v[224:227], v[236:239], v[200:203]
	v_mfma_f32_16x16x32_bf16 v[76:79], v[228:231], v[236:239], v[204:207]
	s_and_saveexec_b64 s[0:1], s[6:7]
	s_waitcnt lgkmcnt(0)
	s_cbranch_execz .LBB0_2194
	s_waitcnt lgkmcnt(0)
	v_add_f32_e32 v160, v160, v161
	ds_write_b32 v181, v160

.LBB0_2266:
	ds_read_b128 v[138:141], v205 offset:6144
	ds_read_b128 v[142:145], v205 offset:6160
	s_waitcnt vmcnt(6)
	v_lshlrev_b32_e32 v146, 16, v98
	v_and_b32_e32 v147, 0xffff0000, v98
	v_add_u32_e32 v219, 0x9800, v216
	s_waitcnt lgkmcnt(1)
	v_mul_f32_e32 v107, 0xbfb8aa3b, v138
	v_exp_f32_e32 v108, v107
	v_mul_f32_e32 v107, 0xbfb8aa3b, v139
	v_exp_f32_e32 v109, v107
	v_mul_f32_e32 v107, 0xbfb8aa3b, v140
	v_cvt_pk_bf16_f32 v160, v10, v11
	v_cvt_pk_bf16_f32 v161, v12, v13
	v_pk_mul_f32 v[108:109], v[108:109], v[146:147]
	v_lshlrev_b32_e32 v146, 16, v99
	v_cvt_pk_bf16_f32 v98, v108, v109
	v_exp_f32_e32 v108, v107
	v_mul_f32_e32 v107, 0xbfb8aa3b, v141
	v_exp_f32_e32 v109, v107
	v_and_b32_e32 v147, 0xffff0000, v99
	s_waitcnt lgkmcnt(0)
	v_mul_f32_e32 v107, 0xbfb8aa3b, v142
	v_cvt_pk_bf16_f32 v162, v26, v27
	v_pk_mul_f32 v[108:109], v[108:109], v[146:147]
	v_lshlrev_b32_e32 v146, 16, v100
	v_cvt_pk_bf16_f32 v99, v108, v109
	v_exp_f32_e32 v108, v107
	v_mul_f32_e32 v107, 0xbfb8aa3b, v143
	v_exp_f32_e32 v109, v107
	v_and_b32_e32 v147, 0xffff0000, v100
	v_mul_f32_e32 v107, 0xbfb8aa3b, v144
	v_cvt_pk_bf16_f32 v163, v28, v29
	v_pk_mul_f32 v[108:109], v[108:109], v[146:147]
	v_lshlrev_b32_e32 v146, 16, v101
	v_cvt_pk_bf16_f32 v100, v108, v109
	v_exp_f32_e32 v108, v107
	v_mul_f32_e32 v107, 0xbfb8aa3b, v145
	v_exp_f32_e32 v109, v107
	v_and_b32_e32 v147, 0xffff0000, v101
	v_add_u32_e32 v220, 0xa800, v216
	v_add_u32_e32 v221, 0xb800, v216
	v_pk_mul_f32 v[108:109], v[108:109], v[146:147]
	v_add_u32_e32 v222, 0xc800, v216
	v_cvt_pk_bf16_f32 v101, v108, v109
	ds_write_b128 v184, v[98:101] offset:56320
	v_mul_f32_e32 v98, 0x3fb8aa3b, v138
	v_mul_f32_e32 v99, 0x3fb8aa3b, v139
	v_exp_f32_e32 v98, v98
	v_exp_f32_e32 v99, v99
	v_lshlrev_b32_e32 v100, 16, v94
	v_and_b32_e32 v101, 0xffff0000, v94
	s_waitcnt vmcnt(4)
	v_lshlrev_b32_e32 v138, 16, v90
	v_pk_mul_f32 v[98:99], v[98:99], s[48:49] op_sel_hi:[1,0]
	v_and_b32_e32 v139, 0xffff0000, v90
	v_pk_mul_f32 v[98:99], v[98:99], v[100:101]
	v_lshlrev_b32_e32 v100, 16, v95
	v_cvt_pk_bf16_f32 v94, v98, v99
	v_mul_f32_e32 v98, 0x3fb8aa3b, v140
	v_mul_f32_e32 v99, 0x3fb8aa3b, v141
	v_exp_f32_e32 v98, v98
	v_exp_f32_e32 v99, v99
	v_and_b32_e32 v101, 0xffff0000, v95
	s_mov_b32 s61, 0x8000
	s_add_u32 s74, s74, 0x60000
	v_pk_mul_f32 v[98:99], v[98:99], s[48:49] op_sel_hi:[1,0]
	s_addc_u32 s75, s75, 0
	v_pk_mul_f32 v[98:99], v[98:99], v[100:101]
	v_lshlrev_b32_e32 v100, 16, v96
	v_cvt_pk_bf16_f32 v95, v98, v99
	v_mul_f32_e32 v98, 0x3fb8aa3b, v142
	v_mul_f32_e32 v99, 0x3fb8aa3b, v143
	v_exp_f32_e32 v98, v98
	v_exp_f32_e32 v99, v99
	v_and_b32_e32 v101, 0xffff0000, v96
	s_add_i32 s60, s60, 64
	v_pk_mul_f32 v[98:99], v[98:99], s[48:49] op_sel_hi:[1,0]
	s_nop 0
	v_pk_mul_f32 v[98:99], v[98:99], v[100:101]
	v_lshlrev_b32_e32 v100, 16, v97
	v_cvt_pk_bf16_f32 v96, v98, v99
	v_mul_f32_e32 v98, 0x3fb8aa3b, v144
	v_mul_f32_e32 v99, 0x3fb8aa3b, v145
	v_exp_f32_e32 v98, v98
	v_exp_f32_e32 v99, v99
	v_and_b32_e32 v101, 0xffff0000, v97
	v_pk_mul_f32 v[98:99], v[98:99], s[48:49] op_sel_hi:[1,0]
	s_nop 0
	v_pk_mul_f32 v[98:99], v[98:99], v[100:101]
	s_nop 0
	v_cvt_pk_bf16_f32 v97, v98, v99
	ds_write_b128 v184, v[94:97] offset:38912
	ds_read_b128 v[94:97], v206 offset:6144
	ds_read_b128 v[98:101], v206 offset:6160
	s_waitcnt lgkmcnt(1)
	v_mul_f32_e32 v107, 0xbfb8aa3b, v94
	v_exp_f32_e32 v108, v107
	v_mul_f32_e32 v107, 0xbfb8aa3b, v95
	v_exp_f32_e32 v109, v107
	v_mul_f32_e32 v107, 0xbfb8aa3b, v96
	v_pk_mul_f32 v[108:109], v[108:109], v[138:139]
	s_nop 0
	v_cvt_pk_bf16_f32 v90, v108, v109
	v_exp_f32_e32 v108, v107
	v_mul_f32_e32 v107, 0xbfb8aa3b, v97
	v_exp_f32_e32 v109, v107
	v_lshlrev_b32_e32 v138, 16, v91
	v_and_b32_e32 v139, 0xffff0000, v91
	s_waitcnt lgkmcnt(0)
	v_mul_f32_e32 v107, 0xbfb8aa3b, v98
	v_pk_mul_f32 v[108:109], v[108:109], v[138:139]
	v_lshlrev_b32_e32 v138, 16, v92
	v_cvt_pk_bf16_f32 v91, v108, v109
	v_exp_f32_e32 v108, v107
	v_mul_f32_e32 v107, 0xbfb8aa3b, v99
	v_exp_f32_e32 v109, v107
	v_and_b32_e32 v139, 0xffff0000, v92
	v_mul_f32_e32 v107, 0xbfb8aa3b, v100
	v_pk_mul_f32 v[108:109], v[108:109], v[138:139]
	s_nop 0
	v_cvt_pk_bf16_f32 v92, v108, v109
	v_exp_f32_e32 v108, v107
	v_mul_f32_e32 v107, 0xbfb8aa3b, v101
	v_exp_f32_e32 v109, v107
	v_lshlrev_b32_e32 v138, 16, v93
	v_and_b32_e32 v139, 0xffff0000, v93
	v_pk_mul_f32 v[108:109], v[108:109], v[138:139]
	s_nop 0
	v_cvt_pk_bf16_f32 v93, v108, v109
	ds_write_b128 v185, v[90:93] offset:56320
	v_mul_f32_e32 v90, 0x3fb8aa3b, v94
	v_mul_f32_e32 v91, 0x3fb8aa3b, v95
	v_exp_f32_e32 v90, v90
	v_exp_f32_e32 v91, v91
	v_lshlrev_b32_e32 v92, 16, v70
	v_and_b32_e32 v93, 0xffff0000, v70
	v_pk_mul_f32 v[90:91], v[90:91], s[48:49] op_sel_hi:[1,0]
	s_nop 0
	v_pk_mul_f32 v[90:91], v[90:91], v[92:93]
	v_lshlrev_b32_e32 v92, 16, v71
	v_cvt_pk_bf16_f32 v70, v90, v91
	v_mul_f32_e32 v90, 0x3fb8aa3b, v96
	v_mul_f32_e32 v91, 0x3fb8aa3b, v97
	v_exp_f32_e32 v90, v90
	v_exp_f32_e32 v91, v91
	v_and_b32_e32 v93, 0xffff0000, v71
	v_pk_mul_f32 v[90:91], v[90:91], s[48:49] op_sel_hi:[1,0]
	s_nop 0
	v_pk_mul_f32 v[90:91], v[90:91], v[92:93]
	v_lshlrev_b32_e32 v92, 16, v72
	v_cvt_pk_bf16_f32 v71, v90, v91
	v_mul_f32_e32 v90, 0x3fb8aa3b, v98
	v_mul_f32_e32 v91, 0x3fb8aa3b, v99
	v_exp_f32_e32 v90, v90
	v_exp_f32_e32 v91, v91
	v_and_b32_e32 v93, 0xffff0000, v72
	v_pk_mul_f32 v[90:91], v[90:91], s[48:49] op_sel_hi:[1,0]
	s_nop 0
	v_pk_mul_f32 v[90:91], v[90:91], v[92:93]
	v_lshlrev_b32_e32 v92, 16, v73
	v_cvt_pk_bf16_f32 v72, v90, v91
	v_mul_f32_e32 v90, 0x3fb8aa3b, v100
	v_mul_f32_e32 v91, 0x3fb8aa3b, v101
	v_exp_f32_e32 v90, v90
	v_exp_f32_e32 v91, v91
	v_and_b32_e32 v93, 0xffff0000, v73
	v_pk_mul_f32 v[90:91], v[90:91], s[48:49] op_sel_hi:[1,0]
	s_nop 0
	v_pk_mul_f32 v[90:91], v[90:91], v[92:93]
	s_nop 0
	v_cvt_pk_bf16_f32 v73, v90, v91
	ds_write_b128 v185, v[70:73] offset:38912
	s_waitcnt vmcnt(3)
	ds_write_b128 v207, v[74:77]
	s_waitcnt vmcnt(2)
	ds_write_b128 v208, v[78:81]
	s_waitcnt vmcnt(1)
	ds_write_b128 v207, v[82:85] offset:16896
	s_waitcnt vmcnt(0)
	ds_write_b128 v209, v[86:89]
	s_waitcnt lgkmcnt(0)
	s_barrier
	s_waitcnt lgkmcnt(0)
	ds_read_b128 v[70:73], v210 offset:56320
	ds_read_b128 v[236:239], v183 offset:38912
	ds_read_b128 v[244:247], v210 offset:56384
	ds_read_b128 v[82:85], v183 offset:38976
	ds_read_b128 v[248:251], v210 offset:56448
	ds_read_b128 v[86:89], v183 offset:39040
	ds_read_b128 v[78:81], v210 offset:56512
	ds_read_b128 v[90:93], v183 offset:39104
	s_waitcnt lgkmcnt(6)
	v_mfma_f32_16x16x32_bf16 v[70:73], v[70:73], v[236:239], 0
	s_waitcnt lgkmcnt(4)
	v_mfma_f32_16x16x32_bf16 v[70:73], v[244:247], v[82:85], v[70:73]
	s_nop 0
	s_nop 0
	s_waitcnt lgkmcnt(2)
	v_mfma_f32_16x16x32_bf16 v[70:73], v[248:251], v[86:89], v[70:73]
	s_nop 0
	s_nop 0
	s_waitcnt lgkmcnt(0)
	v_mfma_f32_16x16x32_bf16 v[70:73], v[78:81], v[90:93], v[70:73]
	v_mov_b32_e32 v78, s93
	s_nop 6
	v_cndmask_b32_e64 v78, v70, v78, s[12:13]
	v_cndmask_b32_e64 v70, v78, v70, s[14:15]
	v_cndmask_b32_e64 v71, 0, v71, s[14:15]
	v_cndmask_b32_e64 v72, v72, 0, s[16:17]
	v_cndmask_b32_e64 v73, v73, 0, s[18:19]
	v_cvt_pk_bf16_f32 v70, v70, v71
	v_cvt_pk_bf16_f32 v71, v72, v73
	ds_write_b64 v211, v[70:71]
	ds_read_b128 v[252:255], v212 offset:56320
	ds_read_b128 v[244:247], v212 offset:56384
	ds_read_b128 v[248:251], v212 offset:56448
	ds_read_b128 v[74:77], v212 offset:56512
	s_waitcnt lgkmcnt(3)
	v_mfma_f32_16x16x32_bf16 v[70:73], v[252:255], v[236:239], 0
	s_nop 0
	s_waitcnt lgkmcnt(2)
	v_mfma_f32_16x16x32_bf16 v[70:73], v[244:247], v[82:85], v[70:73]
	s_nop 0
	s_waitcnt lgkmcnt(1)
	v_mfma_f32_16x16x32_bf16 v[70:73], v[248:251], v[86:89], v[70:73]
	s_nop 0
	s_waitcnt lgkmcnt(0)
	v_mfma_f32_16x16x32_bf16 v[70:73], v[74:77], v[90:93], v[70:73]
	v_mov_b32_e32 v74, s93
	s_nop 6
	v_cndmask_b32_e64 v74, v70, v74, s[20:21]
	v_cndmask_b32_e64 v70, v74, v70, s[22:23]
	v_cndmask_b32_e64 v71, 0, v71, s[22:23]
	v_cndmask_b32_e64 v72, v72, 0, s[24:25]
	v_cndmask_b32_e64 v73, v73, 0, s[26:27]
	v_cvt_pk_bf16_f32 v70, v70, v71
	v_cvt_pk_bf16_f32 v71, v72, v73
	ds_write_b64 v213, v[70:71]
	s_waitcnt lgkmcnt(0)
	s_barrier
	s_waitcnt lgkmcnt(0)
	ds_read_b64_tr_b16 v[80:81], v214 offset:2112
	ds_read_b64_tr_b16 v[78:79], v214
	ds_read_b64_tr_b16 v[82:83], v214 offset:32
	ds_read_b64_tr_b16 v[70:71], v214 offset:16896
	ds_read_b64_tr_b16 v[72:73], v214 offset:19008
	ds_read_b64_tr_b16 v[84:85], v214 offset:2144
	ds_read_b64_tr_b16 v[74:75], v214 offset:16928
	ds_read_b64_tr_b16 v[76:77], v214 offset:19040
	ds_read_b128 v[236:239], v215
	ds_read_b128 v[244:247], v215 offset:64
	ds_read_b128 v[248:251], v215 offset:2368
	ds_read_b128 v[252:255], v215 offset:4672
	ds_read_b128 v[156:159], v215 offset:6976
	ds_read2_b64 v[164:167], v219 offset1:4
	s_waitcnt lgkmcnt(5)
	v_mfma_f32_16x16x32_bf16 v[90:93], v[78:81], v[236:239], 0
	s_nop 0
	s_nop 0
	s_nop 0
	v_mfma_f32_16x16x32_bf16 v[86:89], v[82:85], v[236:239], 0
	ds_read_b128 v[236:239], v215 offset:2304
	s_waitcnt lgkmcnt(5)
	v_mfma_f32_16x16x32_bf16 v[90:93], v[70:73], v[244:247], v[90:93]
	v_mfma_f32_16x16x32_bf16 v[86:89], v[74:77], v[244:247], v[86:89]
	ds_read_b128 v[244:247], v215 offset:4608
	s_nop 0
	s_waitcnt lgkmcnt(1)
	v_mfma_f32_16x16x32_bf16 v[98:101], v[78:81], v[236:239], 0
	v_mfma_f32_16x16x32_bf16 v[94:97], v[82:85], v[236:239], 0
	ds_read_b128 v[236:239], v215 offset:6912
	v_mfma_f32_16x16x32_bf16 v[98:101], v[70:73], v[248:251], v[98:101]
	v_mfma_f32_16x16x32_bf16 v[94:97], v[74:77], v[248:251], v[94:97]
	ds_read2_b64 v[248:251], v220 offset0:32 offset1:36
	s_nop 0
	s_waitcnt lgkmcnt(2)
	v_mfma_f32_16x16x32_bf16 v[142:145], v[78:81], v[244:247], 0
	v_mfma_f32_16x16x32_bf16 v[138:141], v[82:85], v[244:247], 0
	ds_read2_b64 v[244:247], v221 offset0:64 offset1:68
	v_mfma_f32_16x16x32_bf16 v[142:145], v[70:73], v[252:255], v[142:145]
	v_mfma_f32_16x16x32_bf16 v[138:141], v[74:77], v[252:255], v[138:141]
	ds_read2_b64 v[252:255], v222 offset0:96 offset1:100
	s_nop 0
	s_waitcnt lgkmcnt(3)
	v_mfma_f32_16x16x32_bf16 v[150:153], v[78:81], v[236:239], 0
	v_mfma_f32_16x16x32_bf16 v[146:149], v[82:85], v[236:239], 0
	ds_read2_b64 v[236:239], v219 offset0:8 offset1:12
	v_mfma_f32_16x16x32_bf16 v[150:153], v[70:73], v[156:159], v[150:153]
	v_mfma_f32_16x16x32_bf16 v[146:149], v[74:77], v[156:159], v[146:149]
	v_cvt_pk_bf16_f32 v156, v6, v7
	v_cvt_pk_bf16_f32 v157, v8, v9
	v_cvt_pk_bf16_f32 v158, v22, v23
	v_cvt_pk_bf16_f32 v159, v24, v25
	v_mfma_f32_16x16x32_bf16 v[86:89], v[160:163], v[164:167], v[86:89]
	s_nop 0
	v_mfma_f32_16x16x32_bf16 v[90:93], v[156:159], v[164:167], v[90:93]
	s_nop 0
	s_waitcnt lgkmcnt(3)
	v_mfma_f32_16x16x32_bf16 v[98:101], v[156:159], v[248:251], v[98:101]
	v_mfma_f32_16x16x32_bf16 v[94:97], v[160:163], v[248:251], v[94:97]
	ds_read2_b64 v[248:251], v220 offset0:40 offset1:44
	s_nop 0
	s_waitcnt lgkmcnt(3)
	v_mfma_f32_16x16x32_bf16 v[142:145], v[156:159], v[244:247], v[142:145]
	v_mfma_f32_16x16x32_bf16 v[138:141], v[160:163], v[244:247], v[138:141]
	ds_read2_b64 v[244:247], v221 offset0:72 offset1:76
	s_nop 0
	s_waitcnt lgkmcnt(3)
	v_mfma_f32_16x16x32_bf16 v[150:153], v[156:159], v[252:255], v[150:153]
	v_cvt_pk_bf16_f32 v156, v14, v15
	v_cvt_pk_bf16_f32 v157, v16, v17
	v_cvt_pk_bf16_f32 v158, v38, v39
	v_mfma_f32_16x16x32_bf16 v[146:149], v[160:163], v[252:255], v[146:149]
	ds_read2_b64 v[252:255], v222 offset0:104 offset1:108
	v_cvt_pk_bf16_f32 v159, v40, v41
	v_cvt_pk_bf16_f32 v160, v18, v19
	v_cvt_pk_bf16_f32 v161, v20, v21
	v_cvt_pk_bf16_f32 v162, v42, v43
	v_cvt_pk_bf16_f32 v163, v44, v45
	s_nop 0
	s_waitcnt lgkmcnt(3)
	v_mfma_f32_16x16x32_bf16 v[90:93], v[156:159], v[236:239], v[90:93]
	v_mfma_f32_16x16x32_bf16 v[86:89], v[160:163], v[236:239], v[86:89]
	ds_read2_b64 v[236:239], v219 offset0:16 offset1:20
	s_nop 0
	s_waitcnt lgkmcnt(3)
	v_mfma_f32_16x16x32_bf16 v[98:101], v[156:159], v[248:251], v[98:101]
	v_mfma_f32_16x16x32_bf16 v[94:97], v[160:163], v[248:251], v[94:97]
	ds_read2_b64 v[248:251], v220 offset0:48 offset1:52
	s_nop 0
	s_waitcnt lgkmcnt(3)
	v_mfma_f32_16x16x32_bf16 v[142:145], v[156:159], v[244:247], v[142:145]
	v_mfma_f32_16x16x32_bf16 v[138:141], v[160:163], v[244:247], v[138:141]
	ds_read2_b64 v[244:247], v221 offset0:80 offset1:84
	s_nop 0
	s_waitcnt lgkmcnt(3)
	v_mfma_f32_16x16x32_bf16 v[150:153], v[156:159], v[252:255], v[150:153]
	v_cvt_pk_bf16_f32 v156, v30, v31
	v_cvt_pk_bf16_f32 v157, v32, v33
	v_cvt_pk_bf16_f32 v158, v46, v47
	v_mfma_f32_16x16x32_bf16 v[146:149], v[160:163], v[252:255], v[146:149]
	ds_read2_b64 v[252:255], v222 offset0:112 offset1:116
	v_cvt_pk_bf16_f32 v159, v48, v49
	v_cvt_pk_bf16_f32 v160, v34, v35
	v_cvt_pk_bf16_f32 v161, v36, v37
	v_cvt_pk_bf16_f32 v162, v54, v55
	v_cvt_pk_bf16_f32 v163, v56, v57
	s_nop 0
	s_waitcnt lgkmcnt(3)
	v_mfma_f32_16x16x32_bf16 v[90:93], v[156:159], v[236:239], v[90:93]
	v_mfma_f32_16x16x32_bf16 v[86:89], v[160:163], v[236:239], v[86:89]
	ds_read2_b64 v[236:239], v219 offset0:24 offset1:28
	s_nop 0
	s_waitcnt lgkmcnt(3)
	v_mfma_f32_16x16x32_bf16 v[98:101], v[156:159], v[248:251], v[98:101]
	v_mfma_f32_16x16x32_bf16 v[94:97], v[160:163], v[248:251], v[94:97]
	ds_read2_b64 v[248:251], v220 offset0:56 offset1:60
	s_nop 0
	s_waitcnt lgkmcnt(3)
	v_mfma_f32_16x16x32_bf16 v[142:145], v[156:159], v[244:247], v[142:145]
	v_mfma_f32_16x16x32_bf16 v[138:141], v[160:163], v[244:247], v[138:141]
	ds_read2_b64 v[244:247], v221 offset0:88 offset1:92
	ds_read2_b64 v[164:167], v222 offset0:120 offset1:124
	s_nop 0
	s_waitcnt lgkmcnt(4)
	v_mfma_f32_16x16x32_bf16 v[150:153], v[156:159], v[252:255], v[150:153]
	v_cvt_pk_bf16_f32 v156, v50, v51
	v_cvt_pk_bf16_f32 v157, v52, v53
	v_cvt_pk_bf16_f32 v158, v62, v63
	v_mfma_f32_16x16x32_bf16 v[146:149], v[160:163], v[252:255], v[146:149]
	ds_read_b64_tr_b16 v[254:255], v217 offset:57408
	ds_read_b64_tr_b16 v[252:253], v217 offset:56320
	v_cvt_pk_bf16_f32 v159, v64, v65
	v_cvt_pk_bf16_f32 v160, v58, v59
	v_cvt_pk_bf16_f32 v161, v60, v61
	v_cvt_pk_bf16_f32 v162, v66, v67
	v_cvt_pk_bf16_f32 v163, v68, v69
	s_nop 0
	s_waitcnt lgkmcnt(5)
	v_mfma_f32_16x16x32_bf16 v[90:93], v[156:159], v[236:239], v[90:93]
	v_mfma_f32_16x16x32_bf16 v[86:89], v[160:163], v[236:239], v[86:89]
	s_nop 0
	s_nop 5
	v_cvt_pk_bf16_f32 v90, v90, v91
	v_cvt_pk_bf16_f32 v91, v92, v93
	s_waitcnt lgkmcnt(4)
	v_mfma_f32_16x16x32_bf16 v[98:101], v[156:159], v[248:251], v[98:101]
	v_lshl_add_u64 v[92:93], s[64:65], 0, v[118:119]
	v_cvt_pk_bf16_f32 v86, v86, v87
	v_cvt_pk_bf16_f32 v87, v88, v89
	v_mfma_f32_16x16x32_bf16 v[94:97], v[160:163], v[248:251], v[94:97]
	s_nop 0
	v_add_co_u32_e32 v88, vcc, s61, v92
	s_waitcnt lgkmcnt(3)
	v_mfma_f32_16x16x32_bf16 v[142:145], v[156:159], v[244:247], v[142:145]
	global_store_dwordx2 v[92:93], v[86:87], off offset:32
	v_cvt_pk_bf16_f32 v86, v98, v99
	v_cvt_pk_bf16_f32 v87, v100, v101
	v_mfma_f32_16x16x32_bf16 v[138:141], v[160:163], v[244:247], v[138:141]
	s_nop 0
	v_addc_co_u32_e32 v89, vcc, 0, v93, vcc
	global_store_dwordx2 v[88:89], v[86:87], off
	v_cvt_pk_bf16_f32 v86, v94, v95
	v_cvt_pk_bf16_f32 v87, v96, v97
	s_mov_b32 s61, 0x10000
	s_waitcnt lgkmcnt(2)
	v_mfma_f32_16x16x32_bf16 v[150:153], v[156:159], v[164:167], v[150:153]
	global_store_dwordx2 v[88:89], v[86:87], off offset:32
	v_add_co_u32_e32 v88, vcc, s61, v92
	v_mfma_f32_16x16x32_bf16 v[146:149], v[160:163], v[164:167], v[146:149]
	v_cvt_pk_bf16_f32 v86, v142, v143
	v_cvt_pk_bf16_f32 v87, v144, v145
	v_addc_co_u32_e32 v89, vcc, 0, v93, vcc
	global_store_dwordx2 v[88:89], v[86:87], off
	v_cvt_pk_bf16_f32 v86, v138, v139
	v_cvt_pk_bf16_f32 v87, v140, v141
	global_store_dwordx2 v[88:89], v[86:87], off offset:32
	v_add_co_u32_e32 v88, vcc, s81, v92
	v_cvt_pk_bf16_f32 v86, v150, v151
	v_cvt_pk_bf16_f32 v87, v152, v153
	v_addc_co_u32_e32 v89, vcc, 0, v93, vcc
	global_store_dwordx2 v[88:89], v[86:87], off
	v_cvt_pk_bf16_f32 v86, v146, v147
	v_cvt_pk_bf16_f32 v87, v148, v149
	global_store_dwordx2 v[92:93], v[90:91], off
	ds_read_b64_tr_b16 v[90:91], v217 offset:56352
	ds_read_b64_tr_b16 v[236:237], v217 offset:65024
	ds_read_b64_tr_b16 v[238:239], v218 offset:57408
	ds_read_b64_tr_b16 v[94:95], v218 offset:57440
	ds_read_b64_tr_b16 v[92:93], v217 offset:57440
	global_store_dwordx2 v[88:89], v[86:87], off offset:32
	s_nop 0
	s_nop 0
	s_nop 0
	s_waitcnt lgkmcnt(5)
	v_mfma_f32_16x16x32_bf16 v[6:9], v[252:255], v[78:81], v[6:9]
	s_add_u32 s64, s64, 0x20000
	s_addc_u32 s65, s65, 0
	s_add_i32 s95, s95, 1
	v_mfma_f32_16x16x32_bf16 v[10:13], v[252:255], v[82:85], v[10:13]
	s_nop 0
	s_nop 0
	s_nop 0
	s_nop 0
	s_cmp_lg_u32 s74, 0x300000
	s_waitcnt lgkmcnt(2)
	v_mfma_f32_16x16x32_bf16 v[6:9], v[236:239], v[70:73], v[6:9]
	v_mfma_f32_16x16x32_bf16 v[10:13], v[236:239], v[74:77], v[10:13]
	s_waitcnt lgkmcnt(0)
	v_mfma_f32_16x16x32_bf16 v[22:25], v[90:93], v[78:81], v[22:25]
	v_mfma_f32_16x16x32_bf16 v[26:29], v[90:93], v[82:85], v[26:29]
	ds_read_b64_tr_b16 v[92:93], v217 offset:65056
	ds_read_b64_tr_b16 v[248:249], v217 offset:56384
	ds_read_b64_tr_b16 v[250:251], v217 offset:57472
	ds_read_b64_tr_b16 v[244:245], v217 offset:65088
	ds_read_b64_tr_b16 v[246:247], v218 offset:57472
	ds_read_b64_tr_b16 v[252:253], v217 offset:56416
	ds_read_b64_tr_b16 v[254:255], v217 offset:57504
	ds_read_b64_tr_b16 v[236:237], v217 offset:65120
	ds_read_b64_tr_b16 v[238:239], v218 offset:57504
	s_waitcnt lgkmcnt(6)
	v_mfma_f32_16x16x32_bf16 v[14:17], v[248:251], v[78:81], v[14:17]
	v_mfma_f32_16x16x32_bf16 v[18:21], v[248:251], v[82:85], v[18:21]
	ds_read_b64_tr_b16 v[248:249], v217 offset:56448
	ds_read_b64_tr_b16 v[250:251], v217 offset:57536
	s_nop 0
	s_nop 0
	s_waitcnt lgkmcnt(6)
	v_mfma_f32_16x16x32_bf16 v[14:17], v[244:247], v[70:73], v[14:17]
	v_mfma_f32_16x16x32_bf16 v[18:21], v[244:247], v[74:77], v[18:21]
	ds_read_b64_tr_b16 v[244:245], v217 offset:65152
	ds_read_b64_tr_b16 v[246:247], v218 offset:57536
	s_nop 0
	s_nop 0
	s_waitcnt lgkmcnt(6)
	v_mfma_f32_16x16x32_bf16 v[38:41], v[252:255], v[78:81], v[38:41]
	v_mfma_f32_16x16x32_bf16 v[42:45], v[252:255], v[82:85], v[42:45]
	ds_read_b64_tr_b16 v[252:253], v217 offset:56480
	ds_read_b64_tr_b16 v[254:255], v217 offset:57568
	s_nop 0
	s_nop 0
	s_waitcnt lgkmcnt(6)
	v_mfma_f32_16x16x32_bf16 v[38:41], v[236:239], v[70:73], v[38:41]
	v_mfma_f32_16x16x32_bf16 v[42:45], v[236:239], v[74:77], v[42:45]
	ds_read_b64_tr_b16 v[236:237], v217 offset:65184
	ds_read_b64_tr_b16 v[238:239], v218 offset:57568
	s_nop 0
	s_nop 0
	s_waitcnt lgkmcnt(6)
	v_mfma_f32_16x16x32_bf16 v[30:33], v[248:251], v[78:81], v[30:33]
	v_mfma_f32_16x16x32_bf16 v[34:37], v[248:251], v[82:85], v[34:37]
	ds_read_b64_tr_b16 v[248:249], v217 offset:56512
	ds_read_b64_tr_b16 v[250:251], v217 offset:57600
	s_nop 0
	s_nop 0
	s_waitcnt lgkmcnt(6)
	v_mfma_f32_16x16x32_bf16 v[30:33], v[244:247], v[70:73], v[30:33]
	v_mfma_f32_16x16x32_bf16 v[34:37], v[244:247], v[74:77], v[34:37]
	ds_read_b64_tr_b16 v[244:245], v217 offset:65216
	ds_read_b64_tr_b16 v[246:247], v218 offset:57600
	ds_read_b64_tr_b16 v[86:87], v217 offset:56544
	ds_read_b64_tr_b16 v[88:89], v217 offset:57632
	s_nop 0
	s_nop 0
	s_waitcnt lgkmcnt(8)
	v_mfma_f32_16x16x32_bf16 v[46:49], v[252:255], v[78:81], v[46:49]
	v_mfma_f32_16x16x32_bf16 v[54:57], v[252:255], v[82:85], v[54:57]
	s_nop 0
	s_nop 0
	s_waitcnt lgkmcnt(6)
	v_mfma_f32_16x16x32_bf16 v[46:49], v[236:239], v[70:73], v[46:49]
	v_mfma_f32_16x16x32_bf16 v[54:57], v[236:239], v[74:77], v[54:57]
	s_nop 0
	s_nop 0
	s_waitcnt lgkmcnt(4)
	v_mfma_f32_16x16x32_bf16 v[50:53], v[248:251], v[78:81], v[50:53]
	v_mfma_f32_16x16x32_bf16 v[58:61], v[248:251], v[82:85], v[58:61]
	s_nop 0
	s_nop 0
	s_waitcnt lgkmcnt(2)
	v_mfma_f32_16x16x32_bf16 v[50:53], v[244:247], v[70:73], v[50:53]
	v_mfma_f32_16x16x32_bf16 v[58:61], v[244:247], v[74:77], v[58:61]
	s_nop 0
	s_nop 0
	s_waitcnt lgkmcnt(0)
	v_mfma_f32_16x16x32_bf16 v[62:65], v[86:89], v[78:81], v[62:65]
	ds_read_b64_tr_b16 v[78:79], v217 offset:65248
	ds_read_b64_tr_b16 v[80:81], v218 offset:57632
	v_mfma_f32_16x16x32_bf16 v[66:69], v[86:89], v[82:85], v[66:69]
	v_mfma_f32_16x16x32_bf16 v[22:25], v[92:95], v[70:73], v[22:25]
	s_waitcnt lgkmcnt(0)
	v_mfma_f32_16x16x32_bf16 v[62:65], v[78:81], v[70:73], v[62:65]
	v_lshl_add_u32 v70, s49, 9, v182
	ds_read_b128 v[252:255], v70 offset:4096
	ds_read_b128 v[236:239], v70 offset:4160
	ds_read_b128 v[248:251], v70 offset:4224
	ds_read_b128 v[244:247], v70 offset:4288
	v_mfma_f32_16x16x32_bf16 v[26:29], v[92:95], v[74:77], v[26:29]
	v_mfma_f32_16x16x32_bf16 v[66:69], v[78:81], v[74:77], v[66:69]
	s_nop 0
	s_waitcnt lgkmcnt(3)
	v_mul_f32_e32 v71, 0x3fb8aa3b, v252
	v_exp_f32_e32 v72, v71
	v_mul_f32_e32 v71, 0x3fb8aa3b, v253
	v_exp_f32_e32 v73, v71
	v_mul_f32_e32 v71, 0x3fb8aa3b, v254
	v_exp_f32_e32 v74, v71
	v_mul_f32_e32 v71, 0x3fb8aa3b, v255
	ds_read_b128 v[252:255], v70 offset:4352
	v_exp_f32_e32 v75, v71
	v_pk_mul_f32 v[6:7], v[6:7], v[72:73]
	v_pk_mul_f32 v[10:11], v[10:11], v[72:73]
	v_pk_mul_f32 v[8:9], v[8:9], v[74:75]
	v_pk_mul_f32 v[12:13], v[12:13], v[74:75]
	s_nop 0
	s_waitcnt lgkmcnt(3)
	v_mul_f32_e32 v71, 0x3fb8aa3b, v236
	v_exp_f32_e32 v72, v71
	v_mul_f32_e32 v71, 0x3fb8aa3b, v237
	v_exp_f32_e32 v73, v71
	v_mul_f32_e32 v71, 0x3fb8aa3b, v238
	v_exp_f32_e32 v74, v71
	v_mul_f32_e32 v71, 0x3fb8aa3b, v239
	ds_read_b128 v[236:239], v70 offset:4416
	v_exp_f32_e32 v75, v71
	v_pk_mul_f32 v[22:23], v[22:23], v[72:73]
	v_pk_mul_f32 v[26:27], v[26:27], v[72:73]
	v_pk_mul_f32 v[24:25], v[24:25], v[74:75]
	v_pk_mul_f32 v[28:29], v[28:29], v[74:75]
	s_nop 0
	s_waitcnt lgkmcnt(3)
	v_mul_f32_e32 v71, 0x3fb8aa3b, v248
	v_exp_f32_e32 v72, v71
	v_mul_f32_e32 v71, 0x3fb8aa3b, v249
	v_exp_f32_e32 v73, v71
	v_mul_f32_e32 v71, 0x3fb8aa3b, v250
	v_exp_f32_e32 v74, v71
	v_mul_f32_e32 v71, 0x3fb8aa3b, v251
	ds_read_b128 v[248:251], v70 offset:4480
	v_exp_f32_e32 v75, v71
	v_pk_mul_f32 v[14:15], v[14:15], v[72:73]
	v_pk_mul_f32 v[18:19], v[18:19], v[72:73]
	v_pk_mul_f32 v[16:17], v[16:17], v[74:75]
	v_pk_mul_f32 v[20:21], v[20:21], v[74:75]
	s_nop 0
	s_waitcnt lgkmcnt(3)
	v_mul_f32_e32 v71, 0x3fb8aa3b, v244
	v_exp_f32_e32 v72, v71
	v_mul_f32_e32 v71, 0x3fb8aa3b, v245
	v_exp_f32_e32 v73, v71
	v_mul_f32_e32 v71, 0x3fb8aa3b, v246
	v_exp_f32_e32 v74, v71
	v_mul_f32_e32 v71, 0x3fb8aa3b, v247
	v_exp_f32_e32 v75, v71
	v_pk_mul_f32 v[38:39], v[38:39], v[72:73]
	v_pk_mul_f32 v[42:43], v[42:43], v[72:73]
	v_pk_mul_f32 v[40:41], v[40:41], v[74:75]
	v_pk_mul_f32 v[44:45], v[44:45], v[74:75]
	s_nop 0
	s_waitcnt lgkmcnt(2)
	v_mul_f32_e32 v71, 0x3fb8aa3b, v252
	v_exp_f32_e32 v72, v71
	v_mul_f32_e32 v71, 0x3fb8aa3b, v253
	v_exp_f32_e32 v73, v71
	v_mul_f32_e32 v71, 0x3fb8aa3b, v254
	v_exp_f32_e32 v74, v71
	v_mul_f32_e32 v71, 0x3fb8aa3b, v255
	v_exp_f32_e32 v75, v71
	v_pk_mul_f32 v[30:31], v[30:31], v[72:73]
	v_pk_mul_f32 v[34:35], v[34:35], v[72:73]
	v_pk_mul_f32 v[32:33], v[32:33], v[74:75]
	v_pk_mul_f32 v[36:37], v[36:37], v[74:75]
	s_nop 0
	s_waitcnt lgkmcnt(1)
	v_mul_f32_e32 v71, 0x3fb8aa3b, v236
	v_exp_f32_e32 v72, v71
	v_mul_f32_e32 v71, 0x3fb8aa3b, v237
	v_exp_f32_e32 v73, v71
	v_mul_f32_e32 v71, 0x3fb8aa3b, v238
	v_exp_f32_e32 v74, v71
	v_mul_f32_e32 v71, 0x3fb8aa3b, v239
	v_exp_f32_e32 v75, v71
	v_pk_mul_f32 v[46:47], v[46:47], v[72:73]
	v_pk_mul_f32 v[54:55], v[54:55], v[72:73]
	v_pk_mul_f32 v[48:49], v[48:49], v[74:75]
	v_pk_mul_f32 v[56:57], v[56:57], v[74:75]
	s_nop 0
	s_waitcnt lgkmcnt(0)
	v_mul_f32_e32 v71, 0x3fb8aa3b, v248
	v_exp_f32_e32 v72, v71
	v_mul_f32_e32 v71, 0x3fb8aa3b, v249
	v_exp_f32_e32 v73, v71
	v_mul_f32_e32 v71, 0x3fb8aa3b, v250
	v_exp_f32_e32 v74, v71
	v_mul_f32_e32 v71, 0x3fb8aa3b, v251
	v_exp_f32_e32 v75, v71
	v_pk_mul_f32 v[50:51], v[50:51], v[72:73]
	v_pk_mul_f32 v[58:59], v[58:59], v[72:73]
	ds_read_b128 v[70:73], v70 offset:4544
	v_pk_mul_f32 v[52:53], v[52:53], v[74:75]
	v_pk_mul_f32 v[60:61], v[60:61], v[74:75]
	s_waitcnt lgkmcnt(0)
	v_mul_f32_e32 v70, 0x3fb8aa3b, v70
	v_mul_f32_e32 v71, 0x3fb8aa3b, v71
	v_mul_f32_e32 v72, 0x3fb8aa3b, v72
	v_mul_f32_e32 v73, 0x3fb8aa3b, v73
	v_exp_f32_e32 v70, v70
	v_exp_f32_e32 v71, v71
	v_exp_f32_e32 v72, v72
	v_exp_f32_e32 v73, v73
	v_pk_mul_f32 v[62:63], v[62:63], v[70:71]
	v_pk_mul_f32 v[66:67], v[66:67], v[70:71]
	v_pk_mul_f32 v[64:65], v[64:65], v[72:73]
	v_pk_mul_f32 v[68:69], v[68:69], v[72:73]
	s_waitcnt lgkmcnt(0)
	s_cbranch_scc0 .LBB0_2275
.LBB0_2267:
	s_add_u32 s62, s92, s74
	s_addc_u32 s63, s94, s75
	s_add_u32 s49, s53, s74
	s_addc_u32 s61, s55, s75
	v_lshl_add_u64 v[70:71], s[62:63], 0, v[112:113]
	s_add_u32 s62, s49, s0
	v_add_co_u32_e32 v74, vcc, s72, v70
	s_addc_u32 s63, s61, 0
	s_nop 0
	v_addc_co_u32_e32 v75, vcc, 0, v71, vcc
	v_lshl_add_u64 v[86:87], s[62:63], 0, v[114:115]
	v_add_co_u32_e32 v78, vcc, s81, v86
	s_and_b32 s49, s95, 1
	s_add_i32 s89, s1, 0xf0
	v_addc_co_u32_e32 v79, vcc, 0, v87, vcc
	s_cmp_eq_u32 s49, 0
	v_add_co_u32_e32 v82, vcc, s72, v86
	s_cselect_b64 s[76:77], -1, 0
	s_nop 0
	v_addc_co_u32_e32 v83, vcc, 0, v87, vcc
	s_and_b64 s[62:63], s[76:77], exec
	global_load_dwordx4 v[94:97], v[70:71], off
	global_load_dwordx4 v[98:101], v[70:71], off offset:1024
	s_nop 0
	global_load_dwordx4 v[70:73], v[74:75], off
	global_load_dwordx4 v[90:93], v[74:75], off offset:1024
	s_cselect_b32 s61, 0xf0, s89
	global_load_dwordx4 v[74:77], v[86:87], off
	v_add_co_u32_e32 v86, vcc, s73, v86
	v_add3_u32 v137, s61, v180, v116
	s_nop 0
	v_addc_co_u32_e32 v87, vcc, 0, v87, vcc
	global_load_dwordx4 v[78:81], v[78:79], off
	s_nop 0
	global_load_dwordx4 v[82:85], v[82:83], off
	s_nop 0
	global_load_dwordx4 v[86:89], v[86:87], off
	s_waitcnt lgkmcnt(0)
	ds_read2_b32 v[108:109], v137 offset1:4
	ds_read2_b32 v[236:237], v137 offset0:8 offset1:12
	ds_read2_b32 v[146:147], v137 offset0:128 offset1:132
	ds_read2_b32 v[244:245], v137 offset0:64 offset1:68
	ds_read2_b32 v[248:249], v137 offset0:72 offset1:76
	ds_read2_b32 v[252:253], v137 offset0:136 offset1:140
	s_waitcnt lgkmcnt(5)
	v_mfma_f32_16x16x4_f32 v[138:141], v108, v102, 0
	s_nop 0
	v_mfma_f32_16x16x4_f32 v[138:141], v109, v103, v[138:141]
	s_waitcnt lgkmcnt(4)
	v_mfma_f32_16x16x4_f32 v[138:141], v236, v104, v[138:141]
	v_mfma_f32_16x16x4_f32 v[138:141], v237, v105, v[138:141]
	ds_read2_b32 v[236:237], v137 offset0:192 offset1:196
	s_nop 0
	s_nop 8
	v_add_f32_e32 v108, v106, v138
	v_min_f32_e32 v107, 0, v108
	v_mul_f32_e64 v108, |v108|, s66
	v_exp_f32_e32 v108, v108
	v_add_f32_e32 v109, v106, v139
	v_add_f32_e32 v135, v106, v140
	v_add_f32_e32 v138, v106, v141
	v_add_f32_e32 v108, 1.0, v108
	v_log_f32_e32 v108, v108
	s_nop 0
	v_fmac_f32_e32 v107, 0xbf317218, v108
	v_min_f32_e32 v108, 0, v109
	v_mul_f32_e64 v109, |v109|, s66
	v_exp_f32_e32 v109, v109
	v_fma_f32 v107, v107, s67, 0
	v_add_f32_e32 v109, 1.0, v109
	v_log_f32_e32 v109, v109
	s_nop 0
	v_fmac_f32_e32 v108, 0xbf317218, v109
	v_min_f32_e32 v109, 0, v135
	v_mul_f32_e64 v135, |v135|, s66
	v_exp_f32_e32 v135, v135
	v_fmamk_f32 v108, v108, 0x3d800000, v107
	v_add_f32_e32 v135, 1.0, v135
	v_log_f32_e32 v135, v135
	s_nop 0
	v_fmac_f32_e32 v109, 0xbf317218, v135
	v_min_f32_e32 v135, 0, v138
	v_mul_f32_e64 v138, |v138|, s66
	v_exp_f32_e32 v138, v138
	v_fmamk_f32 v109, v109, 0x3d800000, v108
	v_add_f32_e32 v138, 1.0, v138
	v_log_f32_e32 v138, v138
	s_nop 0
	v_fmac_f32_e32 v135, 0xbf317218, v138
	s_waitcnt lgkmcnt(3)
	v_mfma_f32_16x16x4_f32 v[138:141], v244, v102, 0
	v_fmamk_f32 v135, v135, 0x3d800000, v109
	v_mfma_f32_16x16x4_f32 v[138:141], v245, v103, v[138:141]
	ds_read2_b32 v[244:245], v137 offset0:200 offset1:204
	s_nop 0
	s_waitcnt lgkmcnt(3)
	v_mfma_f32_16x16x4_f32 v[138:141], v248, v104, v[138:141]
	v_mfma_f32_16x16x4_f32 v[138:141], v249, v105, v[138:141]
	s_nop 9
	v_add_f32_e32 v142, v106, v138
	v_min_f32_e32 v138, 0, v142
	v_mul_f32_e64 v142, |v142|, s66
	v_exp_f32_e32 v142, v142
	s_nop 0
	v_add_f32_e32 v142, 1.0, v142
	v_log_f32_e32 v142, v142
	s_nop 0
	v_fmac_f32_e32 v138, 0xbf317218, v142
	v_add_f32_e32 v142, v106, v139
	v_min_f32_e32 v139, 0, v142
	v_mul_f32_e64 v142, |v142|, s66
	v_exp_f32_e32 v142, v142
	s_nop 0
	v_add_f32_e32 v142, 1.0, v142
	v_log_f32_e32 v142, v142
	s_nop 0
	v_fmac_f32_e32 v139, 0xbf317218, v142
	v_add_f32_e32 v142, v106, v140
	v_min_f32_e32 v140, 0, v142
	v_mul_f32_e64 v142, |v142|, s66
	v_exp_f32_e32 v142, v142
	s_nop 0
	v_add_f32_e32 v142, 1.0, v142
	v_log_f32_e32 v142, v142
	s_nop 0
	v_fmac_f32_e32 v140, 0xbf317218, v142
	v_add_f32_e32 v142, v106, v141
	v_min_f32_e32 v141, 0, v142
	v_mul_f32_e64 v142, |v142|, s66
	v_exp_f32_e32 v142, v142
	s_nop 0
	v_add_f32_e32 v142, 1.0, v142
	v_log_f32_e32 v142, v142
	s_nop 0
	v_fmac_f32_e32 v141, 0xbf317218, v142
	v_mfma_f32_16x16x4_f32 v[142:145], v146, v102, 0
	v_mfma_f32_16x16x4_f32 v[142:145], v147, v103, v[142:145]
	s_nop 0
	s_waitcnt lgkmcnt(2)
	v_mfma_f32_16x16x4_f32 v[142:145], v252, v104, v[142:145]
	v_mfma_f32_16x16x4_f32 v[142:145], v253, v105, v[142:145]
	s_nop 0
	s_nop 8
	v_add_f32_e32 v142, v106, v142
	v_min_f32_e32 v148, 0, v142
	v_mul_f32_e64 v142, |v142|, s66
	v_exp_f32_e32 v142, v142
	s_nop 0
	v_add_f32_e32 v142, 1.0, v142
	v_log_f32_e32 v142, v142
	s_nop 0
	v_fmac_f32_e32 v148, 0xbf317218, v142
	v_add_f32_e32 v142, v106, v143
	v_min_f32_e32 v149, 0, v142
	v_mul_f32_e64 v142, |v142|, s66
	v_exp_f32_e32 v142, v142
	s_nop 0
	v_add_f32_e32 v142, 1.0, v142
	v_log_f32_e32 v142, v142
	s_nop 0
	v_fmac_f32_e32 v149, 0xbf317218, v142
	v_add_f32_e32 v142, v106, v144
	v_min_f32_e32 v150, 0, v142
	v_mul_f32_e64 v142, |v142|, s66
	v_exp_f32_e32 v142, v142
	s_nop 0
	v_add_f32_e32 v142, 1.0, v142
	v_log_f32_e32 v142, v142
	s_nop 0
	v_fmac_f32_e32 v150, 0xbf317218, v142
	v_add_f32_e32 v142, v106, v145
	v_min_f32_e32 v151, 0, v142
	v_mul_f32_e64 v142, |v142|, s66
	v_exp_f32_e32 v142, v142
	s_nop 0
	v_add_f32_e32 v142, 1.0, v142
	v_log_f32_e32 v142, v142
	s_nop 0
	v_fmac_f32_e32 v151, 0xbf317218, v142
	s_waitcnt lgkmcnt(1)
	v_mfma_f32_16x16x4_f32 v[142:145], v236, v102, 0
	v_mfma_f32_16x16x4_f32 v[142:145], v237, v103, v[142:145]
	s_nop 0
	s_waitcnt lgkmcnt(0)
	v_mfma_f32_16x16x4_f32 v[142:145], v244, v104, v[142:145]
	v_mfma_f32_16x16x4_f32 v[142:145], v245, v105, v[142:145]
	s_nop 9
	v_add_f32_e32 v137, v106, v142
	v_min_f32_e32 v142, 0, v137
	v_mul_f32_e64 v137, |v137|, s66
	v_exp_f32_e32 v137, v137
	s_nop 0
	v_add_f32_e32 v137, 1.0, v137
	v_log_f32_e32 v137, v137
	s_nop 0
	v_fmac_f32_e32 v142, 0xbf317218, v137
	v_add_f32_e32 v137, v106, v143
	v_min_f32_e32 v143, 0, v137
	v_mul_f32_e64 v137, |v137|, s66
	v_exp_f32_e32 v137, v137
	s_nop 0
	v_add_f32_e32 v137, 1.0, v137
	v_log_f32_e32 v137, v137
	s_nop 0
	v_fmac_f32_e32 v143, 0xbf317218, v137
	v_add_f32_e32 v137, v106, v144
	v_min_f32_e32 v144, 0, v137
	v_mul_f32_e64 v137, |v137|, s66
	v_exp_f32_e32 v137, v137
	s_nop 0
	v_add_f32_e32 v137, 1.0, v137
	v_log_f32_e32 v137, v137
	s_nop 0
	v_fmac_f32_e32 v144, 0xbf317218, v137
	v_add_f32_e32 v137, v106, v145
	v_min_f32_e32 v145, 0, v137
	v_mul_f32_e64 v137, |v137|, s66
	v_exp_f32_e32 v137, v137
	s_nop 0
	v_add_f32_e32 v137, 1.0, v137
	v_log_f32_e32 v137, v137
	s_nop 0
	v_fmac_f32_e32 v145, 0xbf317218, v137
	v_fmamk_f32 v137, v138, 0x3d800000, v135
	v_fmamk_f32 v138, v139, 0x3d800000, v137
	v_fmamk_f32 v139, v140, 0x3d800000, v138
	v_fmamk_f32 v140, v141, 0x3d800000, v139
	v_fmamk_f32 v141, v148, 0x3d800000, v140
	v_fmamk_f32 v146, v149, 0x3d800000, v141
	v_fmamk_f32 v147, v150, 0x3d800000, v146
	v_fmamk_f32 v148, v151, 0x3d800000, v147
	v_fmamk_f32 v142, v142, 0x3d800000, v148
	v_fmamk_f32 v143, v143, 0x3d800000, v142
	v_fmamk_f32 v144, v144, 0x3d800000, v143
	v_fmamk_f32 v145, v145, 0x3d800000, v144
	ds_bpermute_b32 v149, v190, v145
	ds_bpermute_b32 v150, v191, v145
	ds_bpermute_b32 v151, v192, v145
	s_waitcnt lgkmcnt(2)
	v_cndmask_b32_e64 v149, v149, 0, s[4:5]
	s_waitcnt lgkmcnt(1)
	v_cndmask_b32_e64 v150, 0, v150, s[6:7]
	v_add_f32_e32 v149, v149, v150
	s_waitcnt lgkmcnt(0)
	v_cndmask_b32_e64 v150, 0, v151, s[8:9]
	v_add_f32_e32 v149, v149, v150
	v_add_f32_e32 v107, v107, v149
	v_add_f32_e32 v108, v108, v149
	ds_write2st64_b32 v204, v107, v108 offset0:24 offset1:26
	v_add_f32_e32 v107, v109, v149
	v_add_f32_e32 v108, v135, v149
	ds_write2st64_b32 v204, v107, v108 offset0:28 offset1:30
	v_add_f32_e32 v107, v137, v149
	v_add_f32_e32 v108, v138, v149
	ds_write2st64_b32 v204, v107, v108 offset0:32 offset1:34
	v_add_f32_e32 v107, v139, v149
	v_add_f32_e32 v108, v140, v149
	ds_write2st64_b32 v204, v107, v108 offset0:36 offset1:38
	v_add_f32_e32 v107, v141, v149
	v_add_f32_e32 v108, v146, v149
	ds_write2st64_b32 v204, v107, v108 offset0:40 offset1:42
	v_add_f32_e32 v107, v149, v147
	v_add_f32_e32 v108, v149, v148
	ds_write2st64_b32 v204, v107, v108 offset0:44 offset1:46
	v_add_f32_e32 v107, v149, v142
	v_add_f32_e32 v108, v149, v143
	ds_write2st64_b32 v204, v107, v108 offset0:48 offset1:50
	v_add_f32_e32 v107, v149, v144
	v_add_f32_e32 v108, v149, v145
	ds_write2st64_b32 v204, v107, v108 offset0:52 offset1:54
	s_waitcnt lgkmcnt(0)
	s_barrier
	s_and_saveexec_b64 s[62:63], s[10:11]
	s_cbranch_execz .LBB0_2269
	ds_read_b32 v107, v181 offset:38400
	v_lshl_add_u32 v108, s49, 9, v181
	s_waitcnt lgkmcnt(0)
	ds_write_b32 v108, v107 offset:4096

.LBB0_2282:
	s_or_b64 exec, exec, s[60:61]
	s_waitcnt lgkmcnt(0)
	s_barrier
	s_waitcnt lgkmcnt(0)
	ds_read_b128 v[140:143], v188
	ds_read_b128 v[146:149], v188 offset:16
	s_waitcnt vmcnt(8)
	v_lshlrev_b32_e32 v160, 16, v170
	v_and_b32_e32 v161, 0xffff0000, v170
	v_lshlrev_b32_e32 v170, 16, v171
	s_waitcnt lgkmcnt(1)
	v_mov_b32_e32 v81, v142
	v_lshlrev_b32_e32 v142, 16, v172
	v_mov_b32_e32 v80, v141
	v_mov_b32_e32 v141, v143
	v_and_b32_e32 v143, 0xffff0000, v172
	v_mul_f32_e32 v0, 0xbfb8aa3b, v142
	v_exp_f32_e32 v0, v0
	v_mul_f32_e32 v135, 0xbfb8aa3b, v143
	v_exp_f32_e32 v135, v135
	v_pk_add_f32 v[80:81], v[80:81], v[140:141]
	s_waitcnt lgkmcnt(0)
	v_mov_b32_e32 v140, v148
	v_mov_b32_e32 v141, v146
	v_mov_b32_e32 v146, v149
	v_add_f32_e32 v0, 1.0, v0
	v_pk_add_f32 v[150:151], v[140:141], v[146:147]
	v_rcp_f32_e32 v140, v0
	v_add_f32_e32 v0, 1.0, v135
	v_lshlrev_b32_e32 v146, 16, v173
	v_rcp_f32_e32 v141, v0
	v_and_b32_e32 v147, 0xffff0000, v173
	v_mul_f32_e32 v0, 0xbfb8aa3b, v146
	v_exp_f32_e32 v0, v0
	v_mul_f32_e32 v135, 0xbfb8aa3b, v147
	v_exp_f32_e32 v135, v135
	v_pk_mul_f32 v[152:153], v[140:141], v[142:143]
	v_add_f32_e32 v0, 1.0, v0
	v_rcp_f32_e32 v140, v0
	v_add_f32_e32 v0, 1.0, v135
	v_rcp_f32_e32 v141, v0
	v_mul_f32_e32 v0, 0xbfb8aa3b, v160
	v_exp_f32_e32 v0, v0
	v_mul_f32_e32 v135, 0xbfb8aa3b, v161
	v_exp_f32_e32 v135, v135
	v_pk_mul_f32 v[172:173], v[140:141], v[146:147]
	ds_read_b128 v[140:143], v188 offset:512
	ds_read_b128 v[146:149], v188 offset:528
	v_add_f32_e32 v0, 1.0, v0
	v_rcp_f32_e32 v228, v0
	v_add_f32_e32 v0, 1.0, v135
	v_rcp_f32_e32 v229, v0
	v_mul_f32_e32 v0, 0xbfb8aa3b, v170
	v_and_b32_e32 v171, 0xffff0000, v171
	s_waitcnt lgkmcnt(1)
	v_mov_b32_e32 v232, v141
	v_mov_b32_e32 v233, v142
	v_mov_b32_e32 v141, v143
	v_exp_f32_e32 v0, v0
	v_mul_f32_e32 v135, 0xbfb8aa3b, v171
	v_pk_add_f32 v[140:141], v[232:233], v[140:141]
	s_waitcnt lgkmcnt(0)
	v_mov_b32_e32 v142, v148
	v_mov_b32_e32 v143, v146
	v_mov_b32_e32 v146, v149
	v_exp_f32_e32 v135, v135
	v_pk_add_f32 v[142:143], v[142:143], v[146:147]
	v_mov_b32_e32 v146, v140
	v_mov_b32_e32 v147, v80
	v_mov_b32_e32 v80, v141
	v_pk_add_f32 v[80:81], v[146:147], v[80:81]
	v_mov_b32_e32 v140, v143
	v_mov_b32_e32 v141, v151
	v_pk_add_f32 v[80:81], v[80:81], v[140:141]
	v_mov_b32_e32 v143, v150
	s_mov_b32 s60, 0x358637bd
	v_add_f32_e32 v0, 1.0, v0
	v_pk_add_f32 v[140:141], v[142:143], v[80:81]
	v_mov_b64_e32 v[80:81], s[60:61]
	v_rcp_f32_e32 v230, v0
	v_add_f32_e32 v0, 1.0, v135
	v_pk_fma_f32 v[140:141], v[140:141], s[50:51], v[80:81] op_sel_hi:[1,0,0]
	v_rcp_f32_e32 v231, v0
	v_mul_f32_e32 v0, 0x4b800000, v141
	v_cmp_gt_f32_e32 vcc, s80, v141
	v_pk_mul_f32 v[146:147], v[228:229], v[160:161]
	v_pk_mul_f32 v[148:149], v[230:231], v[170:171]
	v_cndmask_b32_e32 v0, v141, v0, vcc
	v_rsq_f32_e32 v0, v0
	v_lshl_add_u64 v[142:143], s[54:55], 0, v[118:119]
	s_waitcnt vmcnt(4)
	v_lshlrev_b32_e32 v150, 16, v163
	v_and_b32_e32 v151, 0xffff0000, v163
	v_mul_f32_e32 v135, 0x45800000, v0
	v_cndmask_b32_e32 v0, v0, v135, vcc
	v_pk_mul_f32 v[106:107], v[106:107], v[0:1] op_sel_hi:[1,0]
	v_pk_mul_f32 v[108:109], v[108:109], v[0:1] op_sel_hi:[1,0]
	v_pk_mul_f32 v[102:103], v[102:103], v[0:1] op_sel_hi:[1,0]
	v_pk_mul_f32 v[104:105], v[104:105], v[0:1] op_sel_hi:[1,0]
	v_mul_f32_e32 v0, 0x4b800000, v140
	v_cmp_gt_f32_e32 vcc, s80, v140
	s_waitcnt vmcnt(0)
	v_pk_mul_f32 v[102:103], v[70:71], v[102:103]
	v_pk_mul_f32 v[104:105], v[72:73], v[104:105]
	v_cndmask_b32_e32 v0, v140, v0, vcc
	v_pk_mul_f32 v[102:103], v[146:147], v[102:103]
	v_pk_mul_f32 v[104:105], v[148:149], v[104:105]
	v_rsq_f32_e32 v0, v0
	v_cvt_pk_bf16_f32 v102, v102, v103
	v_cvt_pk_bf16_f32 v103, v104, v105
	global_store_dwordx2 v[142:143], v[102:103], off offset:32
	v_lshlrev_b32_e32 v102, 16, v168
	v_mul_f32_e32 v103, 0xbfb8aa3b, v102
	v_exp_f32_e32 v104, v103
	v_mul_f32_e32 v103, 0x45800000, v0
	v_cndmask_b32_e32 v0, v0, v103, vcc
	v_and_b32_e32 v103, 0xffff0000, v168
	v_mul_f32_e32 v105, 0xbfb8aa3b, v103
	v_exp_f32_e32 v105, v105
	v_pk_mul_f32 v[106:107], v[74:75], v[106:107]
	v_pk_mul_f32 v[108:109], v[76:77], v[108:109]
	v_pk_mul_f32 v[106:107], v[152:153], v[106:107]
	v_pk_mul_f32 v[108:109], v[172:173], v[108:109]
	v_cvt_pk_bf16_f32 v106, v106, v107
	v_cvt_pk_bf16_f32 v107, v108, v109
	v_lshlrev_b32_e32 v108, 16, v169
	v_and_b32_e32 v109, 0xffff0000, v169
	v_add_f32_e32 v104, 1.0, v104
	v_add_f32_e32 v105, 1.0, v105
	v_mul_f32_e32 v135, 0xbfb8aa3b, v108
	v_mul_f32_e32 v137, 0xbfb8aa3b, v109
	v_rcp_f32_e32 v104, v104
	v_rcp_f32_e32 v105, v105
	v_exp_f32_e32 v135, v135
	v_exp_f32_e32 v137, v137
	global_store_dwordx2 v[142:143], v[106:107], off
	v_pk_mul_f32 v[102:103], v[104:105], v[102:103]
	v_add_f32_e32 v104, 1.0, v135
	v_add_f32_e32 v105, 1.0, v137
	v_rcp_f32_e32 v104, v104
	v_rcp_f32_e32 v105, v105
	v_pk_mul_f32 v[106:107], v[158:159], v[0:1] op_sel_hi:[1,0]
	v_pk_mul_f32 v[100:101], v[100:101], v[0:1] op_sel_hi:[1,0]
	v_pk_mul_f32 v[106:107], v[74:75], v[106:107]
	v_pk_mul_f32 v[100:101], v[76:77], v[100:101]
	v_pk_mul_f32 v[104:105], v[104:105], v[108:109]
	v_pk_mul_f32 v[102:103], v[102:103], v[106:107]
	v_pk_mul_f32 v[100:101], v[104:105], v[100:101]
	v_cvt_pk_bf16_f32 v102, v102, v103
	v_cvt_pk_bf16_f32 v103, v100, v101
	v_lshlrev_b32_e32 v100, 16, v166
	v_mul_f32_e32 v101, 0xbfb8aa3b, v100
	v_exp_f32_e32 v106, v101
	v_lshl_add_u64 v[104:105], s[54:55], 0, v[122:123]
	v_and_b32_e32 v101, 0xffff0000, v166
	global_store_dwordx2 v[104:105], v[102:103], off
	v_mul_f32_e32 v103, 0xbfb8aa3b, v101
	v_exp_f32_e32 v103, v103
	v_lshlrev_b32_e32 v104, 16, v167
	v_and_b32_e32 v105, 0xffff0000, v167
	v_add_f32_e32 v102, 1.0, v106
	v_add_f32_e32 v103, 1.0, v103
	v_mul_f32_e32 v106, 0xbfb8aa3b, v104
	v_mul_f32_e32 v107, 0xbfb8aa3b, v105
	v_rcp_f32_e32 v102, v102
	v_rcp_f32_e32 v103, v103
	v_exp_f32_e32 v106, v106
	v_exp_f32_e32 v107, v107
	v_pk_mul_f32 v[98:99], v[98:99], v[0:1] op_sel_hi:[1,0]
	v_pk_mul_f32 v[100:101], v[102:103], v[100:101]
	v_add_f32_e32 v102, 1.0, v106
	v_add_f32_e32 v103, 1.0, v107
	v_rcp_f32_e32 v102, v102
	v_rcp_f32_e32 v103, v103
	v_pk_mul_f32 v[98:99], v[70:71], v[98:99]
	v_pk_mul_f32 v[96:97], v[96:97], v[0:1] op_sel_hi:[1,0]
	v_pk_mul_f32 v[98:99], v[100:101], v[98:99]
	v_pk_mul_f32 v[96:97], v[72:73], v[96:97]
	v_pk_mul_f32 v[100:101], v[102:103], v[104:105]
	v_cvt_pk_bf16_f32 v102, v98, v99
	v_pk_mul_f32 v[100:101], v[100:101], v[96:97]
	ds_read_b128 v[96:99], v188 offset:1024
	v_cvt_pk_bf16_f32 v103, v100, v101
	v_lshl_add_u64 v[100:101], s[54:55], 0, v[124:125]
	global_store_dwordx2 v[100:101], v[102:103], off
	ds_read_b128 v[100:103], v188 offset:1040
	s_waitcnt lgkmcnt(1)
	v_mov_b32_e32 v105, v98
	v_lshlrev_b32_e32 v98, 16, v164
	v_mov_b32_e32 v104, v97
	v_mov_b32_e32 v97, v99
	v_and_b32_e32 v99, 0xffff0000, v164
	v_mul_f32_e32 v0, 0xbfb8aa3b, v98
	v_pk_add_f32 v[104:105], v[104:105], v[96:97]
	v_exp_f32_e32 v0, v0
	v_mul_f32_e32 v97, 0xbfb8aa3b, v99
	s_waitcnt lgkmcnt(0)
	v_mov_b32_e32 v96, v102
	v_exp_f32_e32 v102, v97
	v_lshlrev_b32_e32 v108, 16, v165
	v_mov_b32_e32 v97, v100
	v_add_f32_e32 v0, 1.0, v0
	v_and_b32_e32 v109, 0xffff0000, v165
	v_mul_f32_e32 v100, 0xbfb8aa3b, v108
	v_rcp_f32_e32 v106, v0
	v_add_f32_e32 v0, 1.0, v102
	v_exp_f32_e32 v100, v100
	v_mul_f32_e32 v102, 0xbfb8aa3b, v109
	v_exp_f32_e32 v102, v102
	v_rcp_f32_e32 v107, v0
	v_add_f32_e32 v0, 1.0, v100
	v_rcp_f32_e32 v140, v0
	v_add_f32_e32 v0, 1.0, v102
	v_rcp_f32_e32 v141, v0
	v_mov_b32_e32 v100, v103
	v_pk_add_f32 v[142:143], v[96:97], v[100:101]
	v_pk_mul_f32 v[106:107], v[106:107], v[98:99]
	v_pk_mul_f32 v[108:109], v[140:141], v[108:109]
	v_lshlrev_b32_e32 v140, 16, v162
	v_and_b32_e32 v141, 0xffff0000, v162
	v_mul_f32_e32 v0, 0xbfb8aa3b, v140
	v_exp_f32_e32 v0, v0
	v_mul_f32_e32 v96, 0xbfb8aa3b, v141
	v_exp_f32_e32 v96, v96
	v_lshl_add_u64 v[146:147], s[54:55], 0, v[126:127]
	v_add_f32_e32 v0, 1.0, v0
	v_rcp_f32_e32 v148, v0
	v_add_f32_e32 v0, 1.0, v96
	v_rcp_f32_e32 v149, v0
	v_mul_f32_e32 v0, 0xbfb8aa3b, v150
	v_exp_f32_e32 v0, v0
	v_mul_f32_e32 v96, 0xbfb8aa3b, v151
	v_exp_f32_e32 v100, v96
	ds_read_b128 v[96:99], v188 offset:1536
	v_add_f32_e32 v0, 1.0, v0
	v_rcp_f32_e32 v152, v0
	v_add_f32_e32 v0, 1.0, v100
	ds_read_b128 v[100:103], v188 offset:1552
	ds_read_b64_tr_b16 v[238:239], v217 offset:57408
	ds_read_b64_tr_b16 v[236:237], v217 offset:56320
	s_waitcnt lgkmcnt(3)
	v_mov_b32_e32 v158, v97
	v_mov_b32_e32 v159, v98
	v_mov_b32_e32 v97, v99
	v_pk_add_f32 v[96:97], v[158:159], v[96:97]
	s_waitcnt lgkmcnt(2)
	v_mov_b32_e32 v98, v102
	v_mov_b32_e32 v99, v100
	v_mov_b32_e32 v100, v103
	v_pk_add_f32 v[98:99], v[98:99], v[100:101]
	v_mov_b32_e32 v100, v96
	v_mov_b32_e32 v101, v104
	v_mov_b32_e32 v104, v97
	v_pk_add_f32 v[96:97], v[100:101], v[104:105]
	v_mov_b32_e32 v100, v99
	v_mov_b32_e32 v101, v143
	v_pk_add_f32 v[96:97], v[96:97], v[100:101]
	v_mov_b32_e32 v99, v142
	v_pk_add_f32 v[96:97], v[98:99], v[96:97]
	v_rcp_f32_e32 v153, v0
	v_pk_fma_f32 v[80:81], v[96:97], s[50:51], v[80:81] op_sel_hi:[1,0,0]
	v_pk_mul_f32 v[96:97], v[148:149], v[140:141]
	v_mul_f32_e32 v0, 0x4b800000, v81
	v_cmp_gt_f32_e32 vcc, s80, v81
	v_pk_mul_f32 v[170:171], v[152:153], v[150:151]
	v_lshl_add_u64 v[172:173], s[54:55], 0, v[128:129]
	v_cndmask_b32_e32 v0, v81, v0, vcc
	v_rsq_f32_e32 v0, v0
	s_add_i32 s74, s74, 1
	s_add_u32 s58, s58, 0xfffa0000
	s_addc_u32 s59, s59, -1
	v_mul_f32_e32 v81, 0x45800000, v0
	v_cndmask_b32_e32 v0, v0, v81, vcc
	v_pk_mul_f32 v[90:91], v[90:91], v[0:1] op_sel_hi:[1,0]
	v_pk_mul_f32 v[94:95], v[94:95], v[0:1] op_sel_hi:[1,0]
	v_pk_mul_f32 v[90:91], v[74:75], v[90:91]
	v_pk_mul_f32 v[94:95], v[76:77], v[94:95]
	v_pk_mul_f32 v[90:91], v[106:107], v[90:91]
	v_pk_mul_f32 v[94:95], v[108:109], v[94:95]
	v_cvt_pk_bf16_f32 v90, v90, v91
	v_cvt_pk_bf16_f32 v91, v94, v95
	ds_read_b64_tr_b16 v[94:95], v214 offset:2112
	global_store_dwordx2 v[146:147], v[90:91], off
	v_pk_mul_f32 v[90:91], v[92:93], v[0:1] op_sel_hi:[1,0]
	ds_read_b64_tr_b16 v[92:93], v214
	ds_read_b64_tr_b16 v[98:99], v214 offset:2144
	v_pk_mul_f32 v[88:89], v[88:89], v[0:1] op_sel_hi:[1,0]
	v_mul_f32_e32 v0, 0x4b800000, v80
	v_cmp_gt_f32_e32 vcc, s80, v80
	v_pk_mul_f32 v[90:91], v[70:71], v[90:91]
	v_pk_mul_f32 v[228:229], v[72:73], v[88:89]
	v_cndmask_b32_e32 v0, v80, v0, vcc
	v_pk_mul_f32 v[108:109], v[96:97], v[90:91]
	ds_read_b64_tr_b16 v[96:97], v214 offset:32
	ds_read_b64_tr_b16 v[100:101], v217 offset:56352
	ds_read_b64_tr_b16 v[104:105], v217 offset:56384
	ds_read_b64_tr_b16 v[140:141], v217 offset:56416
	ds_read_b64_tr_b16 v[102:103], v217 offset:57440
	ds_read_b64_tr_b16 v[106:107], v217 offset:57472
	ds_read_b64_tr_b16 v[142:143], v217 offset:57504
	ds_read_b64_tr_b16 v[146:147], v217 offset:65024
	ds_read_b64_tr_b16 v[148:149], v218 offset:57408
	ds_read_b64_tr_b16 v[150:151], v214 offset:16896
	ds_read_b64_tr_b16 v[152:153], v214 offset:19008
	ds_read_b64_tr_b16 v[160:161], v214 offset:19040
	ds_read_b64_tr_b16 v[158:159], v214 offset:16928
	ds_read_b64_tr_b16 v[244:245], v217 offset:65056
	ds_read_b64_tr_b16 v[162:163], v217 offset:65088
	ds_read_b64_tr_b16 v[166:167], v217 offset:65120
	ds_read_b64_tr_b16 v[246:247], v218 offset:57440
	ds_read_b64_tr_b16 v[164:165], v218 offset:57472
	ds_read_b64_tr_b16 v[168:169], v218 offset:57504
	ds_read_b64_tr_b16 v[248:249], v217 offset:56448
	ds_read_b64_tr_b16 v[250:251], v217 offset:57536
	s_nop 0
	s_nop 0
	s_nop 0
	s_nop 0
	s_nop 0
	s_nop 0
	s_nop 0
	s_nop 0
	s_nop 0
	s_nop 0
	s_nop 0
	s_nop 0
	v_rsq_f32_e32 v0, v0
	s_nop 0
	s_nop 0
	s_nop 0
	s_nop 0
	s_nop 0
	s_nop 0
	s_waitcnt lgkmcnt(15)
	v_mfma_f32_16x16x32_bf16 v[10:13], v[100:103], v[92:95], v[10:13]
	v_and_b32_e32 v81, 0xffff0000, v156
	v_mul_f32_e32 v80, 0x45800000, v0
	v_cndmask_b32_e32 v0, v0, v80, vcc
	v_mfma_f32_16x16x32_bf16 v[18:21], v[100:103], v[96:99], v[18:21]
	v_lshlrev_b32_e32 v80, 16, v156
	v_mul_f32_e32 v100, 0xbfb8aa3b, v80
	v_mul_f32_e32 v101, 0xbfb8aa3b, v81
	v_mfma_f32_16x16x32_bf16 v[30:33], v[236:239], v[92:95], v[30:33]
	v_exp_f32_e32 v100, v100
	v_pk_mul_f32 v[86:87], v[86:87], v[0:1] op_sel_hi:[1,0]
	v_pk_mul_f32 v[170:171], v[170:171], v[228:229]
	v_mfma_f32_16x16x32_bf16 v[6:9], v[236:239], v[96:99], v[6:9]
	s_nop 0
	s_nop 0
	s_nop 0
	s_nop 0
	s_nop 0
	s_nop 0
	v_pk_mul_f32 v[74:75], v[74:75], v[86:87]
	v_lshlrev_b32_e32 v86, 16, v157
	s_waitcnt lgkmcnt(4)
	v_mfma_f32_16x16x32_bf16 v[10:13], v[244:247], v[150:153], v[10:13]
	v_mul_f32_e32 v87, 0xbfb8aa3b, v86
	v_cvt_pk_bf16_f32 v108, v108, v109
	v_cvt_pk_bf16_f32 v109, v170, v171
	v_mfma_f32_16x16x32_bf16 v[18:21], v[244:247], v[158:161], v[18:21]
	v_exp_f32_e32 v89, v101
	v_add_f32_e32 v88, 1.0, v100
	v_rcp_f32_e32 v88, v88
	global_store_dwordx2 v[172:173], v[108:109], off
	v_add_f32_e32 v89, 1.0, v89
	v_rcp_f32_e32 v89, v89
	v_mfma_f32_16x16x32_bf16 v[14:17], v[104:107], v[92:95], v[14:17]
	v_mul_f32_e64 v82, v82, v0
	v_mul_f32_e64 v83, v83, v0
	v_pk_mul_f32 v[78:79], v[78:79], v[0:1] op_sel_hi:[1,0]
	v_pk_mul_f32 v[80:81], v[88:89], v[80:81]
	v_exp_f32_e32 v88, v87
	v_pk_mul_f32 v[80:81], v[80:81], v[74:75]
	v_and_b32_e32 v87, 0xffff0000, v157
	v_mfma_f32_16x16x32_bf16 v[26:29], v[104:107], v[96:99], v[26:29]
	v_add_f32_e32 v74, 1.0, v88
	v_rcp_f32_e32 v88, v74
	v_mul_f32_e32 v74, 0xbfb8aa3b, v87
	v_exp_f32_e32 v89, v74
	v_pk_mul_f32 v[74:75], v[84:85], v[0:1] op_sel_hi:[1,0]
	ds_read_b64_tr_b16 v[84:85], v217 offset:56480
	v_mfma_f32_16x16x32_bf16 v[38:41], v[140:143], v[92:95], v[38:41]
	v_mul_f32_e64 v108, v76, v74
	v_mul_f32_e64 v109, v77, v75
	v_add_f32_e32 v74, 1.0, v89
	v_rcp_f32_e32 v89, v74
	s_nop 0
	s_nop 0
	v_mfma_f32_16x16x32_bf16 v[50:53], v[140:143], v[96:99], v[50:53]
	v_cvt_pk_bf16_f32 v80, v80, v81
	v_pk_mul_f32 v[140:141], v[88:89], v[86:87]
	ds_read_b64_tr_b16 v[88:89], v217 offset:56512
	ds_read_b64_tr_b16 v[100:101], v217 offset:56544
	ds_read_b64_tr_b16 v[86:87], v217 offset:57568
	ds_read_b64_tr_b16 v[90:91], v217 offset:57600
	ds_read_b64_tr_b16 v[102:103], v217 offset:57632
	ds_read_b64_tr_b16 v[104:105], v217 offset:65152
	ds_read_b64_tr_b16 v[106:107], v218 offset:57536
	ds_read_b64_tr_b16 v[252:253], v217 offset:65184
	s_nop 0
	s_nop 0
	s_nop 0
	s_nop 0
	s_nop 0
	s_nop 0
	s_nop 0
	s_nop 0
	s_waitcnt lgkmcnt(9)
	v_mfma_f32_16x16x32_bf16 v[22:25], v[248:251], v[92:95], v[22:25]
	v_mul_f32_e64 v108, v140, v108
	v_mul_f32_e64 v109, v141, v109
	ds_read_b64_tr_b16 v[140:141], v217 offset:65216
	v_pk_mul_f32 v[70:71], v[70:71], v[82:83]
	v_cvt_pk_bf16_f32 v81, v108, v109
	v_mfma_f32_16x16x32_bf16 v[34:37], v[248:251], v[96:99], v[34:37]
	v_lshl_add_u64 v[108:109], s[54:55], 0, v[130:131]
	v_pk_mul_f32 v[72:73], v[72:73], v[78:79]
	v_lshl_add_u32 v0, s68, 9, v182
	v_mfma_f32_16x16x32_bf16 v[30:33], v[146:149], v[150:153], v[30:33]
	s_sub_i32 s52, s52, 64
	v_mfma_f32_16x16x32_bf16 v[6:9], v[146:149], v[158:161], v[6:9]
	ds_read_b64_tr_b16 v[146:147], v217 offset:65248
	ds_read_b64_tr_b16 v[254:255], v218 offset:57568
	ds_read_b64_tr_b16 v[142:143], v218 offset:57600
	ds_read_b64_tr_b16 v[148:149], v218 offset:57632
	ds_read_b128 v[236:239], v0 offset:4096
	ds_read_b128 v[244:247], v0 offset:4160
	ds_read_b128 v[248:251], v0 offset:4224
	s_nop 0
	s_nop 0
	s_nop 0
	s_nop 0
	s_nop 0
	s_nop 0
	global_store_dwordx2 v[108:109], v[80:81], off
	v_lshlrev_b32_e32 v80, 16, v144
	v_and_b32_e32 v81, 0xffff0000, v144
	s_waitcnt lgkmcnt(9)
	v_mfma_f32_16x16x32_bf16 v[22:25], v[104:107], v[150:153], v[22:25]
	v_mfma_f32_16x16x32_bf16 v[34:37], v[104:107], v[158:161], v[34:37]
	v_mul_f32_e32 v104, 0xbfb8aa3b, v80
	v_mul_f32_e32 v105, 0xbfb8aa3b, v81
	v_exp_f32_e32 v104, v104
	v_mfma_f32_16x16x32_bf16 v[42:45], v[84:87], v[92:95], v[42:45]
	v_mfma_f32_16x16x32_bf16 v[54:57], v[84:87], v[96:99], v[54:57]
	v_exp_f32_e32 v85, v105
	v_add_f32_e32 v84, 1.0, v104
	v_rcp_f32_e32 v84, v84
	s_waitcnt lgkmcnt(5)
	v_mfma_f32_16x16x32_bf16 v[42:45], v[252:255], v[150:153], v[42:45]
	v_add_f32_e32 v85, 1.0, v85
	v_rcp_f32_e32 v85, v85
	v_mfma_f32_16x16x32_bf16 v[54:57], v[252:255], v[158:161], v[54:57]
	ds_read_b128 v[252:255], v0 offset:4288
	v_mul_f32_e64 v74, v84, v80
	v_mul_f32_e64 v75, v85, v81
	v_pk_mul_f32 v[70:71], v[74:75], v[70:71]
	v_lshlrev_b32_e32 v74, 16, v145
	v_and_b32_e32 v75, 0xffff0000, v145
	v_mul_f32_e32 v76, 0xbfb8aa3b, v74
	v_mul_f32_e32 v77, 0xbfb8aa3b, v75
	v_exp_f32_e32 v76, v76
	v_exp_f32_e32 v77, v77
	v_cvt_pk_bf16_f32 v78, v70, v71
	v_lshl_add_u64 v[80:81], s[54:55], 0, v[132:133]
	v_add_f32_e32 v76, 1.0, v76
	v_add_f32_e32 v77, 1.0, v77
	v_rcp_f32_e32 v76, v76
	v_rcp_f32_e32 v77, v77
	v_mfma_f32_16x16x32_bf16 v[14:17], v[162:165], v[150:153], v[14:17]
	s_add_u32 s54, s54, 0xfffe0000
	s_addc_u32 s55, s55, -1
	v_pk_mul_f32 v[74:75], v[76:77], v[74:75]
	v_mfma_f32_16x16x32_bf16 v[26:29], v[162:165], v[158:161], v[26:29]
	v_mul_f32_e64 v74, v74, v72
	v_mul_f32_e64 v75, v75, v73
	s_nop 0
	v_cvt_pk_bf16_f32 v79, v74, v75
	s_nop 0
	global_store_dwordx2 v[80:81], v[78:79], off
	v_mfma_f32_16x16x32_bf16 v[38:41], v[166:169], v[150:153], v[38:41]
	s_waitcnt lgkmcnt(3)
	v_mul_f32_e32 v70, 0x3fb8aa3b, v236
	v_exp_f32_e32 v82, v70
	v_mul_f32_e32 v83, 0x3fb8aa3b, v237
	v_mul_f32_e32 v70, 0x3fb8aa3b, v238
	v_mul_f32_e32 v71, 0x3fb8aa3b, v239
	ds_read_b128 v[236:239], v0 offset:4352
	v_exp_f32_e32 v70, v70
	v_exp_f32_e32 v71, v71
	v_exp_f32_e32 v83, v83
	v_mfma_f32_16x16x32_bf16 v[50:53], v[166:169], v[158:161], v[50:53]
	s_add_u32 s56, s56, 0xfffe0000
	v_pk_mul_f32 v[32:33], v[32:33], v[70:71]
	v_pk_mul_f32 v[8:9], v[8:9], v[70:71]
	s_waitcnt lgkmcnt(3)
	v_mul_f32_e32 v70, 0x3fb8aa3b, v244
	v_mul_f32_e32 v71, 0x3fb8aa3b, v246
	v_exp_f32_e32 v78, v70
	v_mul_f32_e32 v70, 0x3fb8aa3b, v245
	v_exp_f32_e32 v80, v71
	v_mul_f32_e32 v71, 0x3fb8aa3b, v247
	ds_read_b128 v[244:247], v0 offset:4416
	v_exp_f32_e32 v81, v71
	v_exp_f32_e32 v79, v70
	s_nop 0
	s_nop 0
	v_pk_mul_f32 v[30:31], v[30:31], v[82:83]
	v_pk_mul_f32 v[6:7], v[6:7], v[82:83]
	v_pk_mul_f32 v[12:13], v[12:13], v[80:81]
	s_waitcnt lgkmcnt(3)
	v_mul_f32_e32 v70, 0x3fb8aa3b, v248
	v_exp_f32_e32 v82, v70
	v_mul_f32_e32 v83, 0x3fb8aa3b, v249
	v_mul_f32_e32 v70, 0x3fb8aa3b, v250
	v_mul_f32_e32 v71, 0x3fb8aa3b, v251
	ds_read_b128 v[248:251], v0 offset:4480
	v_exp_f32_e32 v70, v70
	v_exp_f32_e32 v71, v71
	v_pk_mul_f32 v[10:11], v[10:11], v[78:79]
	v_pk_mul_f32 v[20:21], v[20:21], v[80:81]
	v_pk_mul_f32 v[18:19], v[18:19], v[78:79]
	v_pk_mul_f32 v[16:17], v[16:17], v[70:71]
	v_pk_mul_f32 v[28:29], v[28:29], v[70:71]
	s_waitcnt lgkmcnt(3)
	v_mul_f32_e32 v70, 0x3fb8aa3b, v252
	v_mul_f32_e32 v71, 0x3fb8aa3b, v254
	v_exp_f32_e32 v78, v70
	v_mul_f32_e32 v70, 0x3fb8aa3b, v253
	v_exp_f32_e32 v80, v71
	v_mul_f32_e32 v71, 0x3fb8aa3b, v255
	ds_read_b128 v[252:255], v0 offset:4544
	v_exp_f32_e32 v81, v71
	v_exp_f32_e32 v79, v70
	s_nop 0
	s_nop 0
	v_exp_f32_e32 v83, v83
	v_pk_mul_f32 v[40:41], v[40:41], v[80:81]
	v_pk_mul_f32 v[38:39], v[38:39], v[78:79]
	s_waitcnt lgkmcnt(3)
	v_mul_f32_e32 v70, 0x3fb8aa3b, v236
	v_pk_mul_f32 v[14:15], v[14:15], v[82:83]
	v_pk_mul_f32 v[26:27], v[26:27], v[82:83]
	v_exp_f32_e32 v82, v70
	v_mul_f32_e32 v83, 0x3fb8aa3b, v237
	v_mul_f32_e32 v70, 0x3fb8aa3b, v238
	v_mul_f32_e32 v71, 0x3fb8aa3b, v239
	v_exp_f32_e32 v70, v70
	v_exp_f32_e32 v71, v71
	v_pk_mul_f32 v[52:53], v[52:53], v[80:81]
	v_pk_mul_f32 v[50:51], v[50:51], v[78:79]
	v_mfma_f32_16x16x32_bf16 v[46:49], v[88:91], v[92:95], v[46:49]
	v_mul_f32_e64 v24, v24, v70
	v_mul_f32_e64 v25, v25, v71
	v_pk_mul_f32 v[36:37], v[36:37], v[70:71]
	s_waitcnt lgkmcnt(2)
	v_mul_f32_e32 v70, 0x3fb8aa3b, v244
	v_mul_f32_e32 v71, 0x3fb8aa3b, v246
	v_exp_f32_e32 v78, v70
	v_mul_f32_e32 v70, 0x3fb8aa3b, v245
	v_exp_f32_e32 v80, v71
	v_mul_f32_e32 v71, 0x3fb8aa3b, v247
	v_exp_f32_e32 v81, v71
	v_exp_f32_e32 v79, v70
	s_nop 0
	s_nop 0
	v_mfma_f32_16x16x32_bf16 v[62:65], v[88:91], v[96:99], v[62:65]
	v_exp_f32_e32 v83, v83
	s_addc_u32 s57, s57, -1
	s_waitcnt lgkmcnt(1)
	v_mul_f32_e32 v0, 0x3fb8aa3b, v248
	v_exp_f32_e32 v70, v0
	v_mul_f32_e32 v0, 0x3fb8aa3b, v249
	v_mul_f32_e32 v71, 0x3fb8aa3b, v250
	v_mfma_f32_16x16x32_bf16 v[58:61], v[100:103], v[92:95], v[58:61]
	v_exp_f32_e32 v72, v71
	v_mul_f32_e32 v71, 0x3fb8aa3b, v251
	v_exp_f32_e32 v73, v71
	v_mfma_f32_16x16x32_bf16 v[66:69], v[100:103], v[96:99], v[66:69]
	v_exp_f32_e32 v71, v0
	s_waitcnt lgkmcnt(0)
	v_mul_f32_e32 v0, 0x3fb8aa3b, v252
	v_exp_f32_e32 v74, v0
	v_mul_f32_e32 v0, 0x3fb8aa3b, v253
	v_mul_f32_e32 v75, 0x3fb8aa3b, v254
	v_exp_f32_e32 v76, v75
	v_mul_f32_e32 v75, 0x3fb8aa3b, v255
	v_mfma_f32_16x16x32_bf16 v[46:49], v[140:143], v[150:153], v[46:49]
	v_exp_f32_e32 v77, v75
	v_exp_f32_e32 v75, v0
	v_pk_mul_f32 v[22:23], v[22:23], v[82:83]
	v_mfma_f32_16x16x32_bf16 v[62:65], v[140:143], v[158:161], v[62:65]
	v_mul_f32_e64 v34, v34, v82
	v_mul_f32_e64 v35, v35, v83
	v_pk_mul_f32 v[44:45], v[44:45], v[80:81]
	v_pk_mul_f32 v[42:43], v[42:43], v[78:79]
	v_mfma_f32_16x16x32_bf16 v[58:61], v[146:149], v[150:153], v[58:61]
	v_mul_f32_e64 v56, v56, v80
	v_mul_f32_e64 v57, v57, v81
	v_pk_mul_f32 v[54:55], v[54:55], v[78:79]
	v_pk_mul_f32 v[48:49], v[48:49], v[72:73]
	v_mfma_f32_16x16x32_bf16 v[66:69], v[146:149], v[158:161], v[66:69]
	v_mul_f32_e64 v46, v46, v70
	v_mul_f32_e64 v47, v47, v71
	v_pk_mul_f32 v[64:65], v[64:65], v[72:73]
	v_pk_mul_f32 v[62:63], v[62:63], v[70:71]
	v_pk_mul_f32 v[60:61], v[60:61], v[76:77]
	v_pk_mul_f32 v[58:59], v[58:59], v[74:75]
	s_nop 1
	v_pk_mul_f32 v[68:69], v[68:69], v[76:77]
	s_cmp_lg_u32 s74, 8
	v_pk_mul_f32 v[66:67], v[66:67], v[74:75]
	s_waitcnt lgkmcnt(0)
	s_cbranch_scc0 .LBB0_2257
.LBB0_2283:
	s_add_u32 s60, s70, s58
	s_addc_u32 s61, s71, s59
	s_add_u32 s49, s64, s58
	s_addc_u32 s69, s65, s59
	s_add_u32 s53, s49, s0
	v_lshl_add_u64 v[70:71], s[60:61], 0, v[112:113]
	s_addc_u32 s61, s69, 0
	s_add_u32 s60, s53, 0xafc0800
	v_add_co_u32_e32 v74, vcc, s72, v70
	s_addc_u32 s61, s61, 0
	s_nop 0
	v_addc_co_u32_e32 v75, vcc, 0, v71, vcc
	v_lshl_add_u64 v[86:87], s[60:61], 0, v[114:115]
	v_add_co_u32_e32 v78, vcc, s81, v86
	s_and_b32 s68, s74, 1
	s_nop 0
	v_addc_co_u32_e32 v79, vcc, 0, v87, vcc
	s_cmp_eq_u32 s68, 0
	v_add_co_u32_e32 v82, vcc, s72, v86
	s_cselect_b64 s[60:61], -1, 0
	s_nop 0
	v_addc_co_u32_e32 v83, vcc, 0, v87, vcc
	s_and_b64 s[62:63], s[60:61], exec
	global_load_dwordx4 v[94:97], v[70:71], off
	global_load_dwordx4 v[98:101], v[70:71], off offset:1024
	s_nop 0
	global_load_dwordx4 v[70:73], v[74:75], off
	global_load_dwordx4 v[90:93], v[74:75], off offset:1024
	s_cselect_b32 s53, 0xf0, s89
	global_load_dwordx4 v[74:77], v[86:87], off
	v_add_co_u32_e32 v86, vcc, s73, v86
	v_add3_u32 v105, s53, v180, v116
	s_nop 0
	v_addc_co_u32_e32 v87, vcc, 0, v87, vcc
	global_load_dwordx4 v[78:81], v[78:79], off
	s_nop 0
	global_load_dwordx4 v[82:85], v[82:83], off
	s_nop 0
	global_load_dwordx4 v[86:89], v[86:87], off
	s_waitcnt lgkmcnt(0)
	ds_read2_b32 v[102:103], v105 offset1:4
	ds_read2_b32 v[236:237], v105 offset0:8 offset1:12
	ds_read2_b32 v[144:145], v105 offset0:128 offset1:132
	ds_read2_b32 v[244:245], v105 offset0:64 offset1:68
	ds_read2_b32 v[248:249], v105 offset0:72 offset1:76
	ds_read2_b32 v[252:253], v105 offset0:136 offset1:140
	s_waitcnt vmcnt(12)
	s_waitcnt lgkmcnt(5)
	v_mfma_f32_16x16x4_f32 v[106:109], v102, v223, 0
	s_nop 0
	s_waitcnt vmcnt(11)
	v_mfma_f32_16x16x4_f32 v[106:109], v103, v224, v[106:109]
	s_waitcnt vmcnt(10)
	s_waitcnt lgkmcnt(4)
	v_mfma_f32_16x16x4_f32 v[106:109], v236, v225, v[106:109]
	s_waitcnt vmcnt(9)
	v_mfma_f32_16x16x4_f32 v[106:109], v237, v226, v[106:109]
	ds_read2_b32 v[236:237], v105 offset0:192 offset1:196
	s_nop 0
	s_waitcnt vmcnt(8)
	s_nop 7
	v_add_f32_e32 v102, v227, v106
	v_min_f32_e32 v0, 0, v102
	v_mul_f32_e64 v102, |v102|, s66
	v_exp_f32_e32 v102, v102
	v_add_f32_e32 v103, v227, v107
	v_add_f32_e32 v104, v227, v108
	v_add_f32_e32 v106, v227, v109
	v_add_f32_e32 v102, 1.0, v102
	v_log_f32_e32 v102, v102
	s_nop 0
	v_fmac_f32_e32 v0, 0xbf317218, v102
	v_min_f32_e32 v102, 0, v103
	v_mul_f32_e64 v103, |v103|, s66
	v_exp_f32_e32 v103, v103
	s_nop 0
	v_add_f32_e32 v103, 1.0, v103
	v_log_f32_e32 v103, v103
	s_nop 0
	v_fmac_f32_e32 v102, 0xbf317218, v103
	v_min_f32_e32 v103, 0, v104
	v_mul_f32_e64 v104, |v104|, s66
	v_exp_f32_e32 v104, v104
	s_nop 0
	v_add_f32_e32 v104, 1.0, v104
	v_log_f32_e32 v104, v104
	s_nop 0
	v_fmac_f32_e32 v103, 0xbf317218, v104
	v_min_f32_e32 v104, 0, v106
	v_mul_f32_e64 v106, |v106|, s66
	v_exp_f32_e32 v106, v106
	s_nop 0
	v_add_f32_e32 v106, 1.0, v106
	v_log_f32_e32 v106, v106
	s_nop 0
	v_fmac_f32_e32 v104, 0xbf317218, v106
	s_waitcnt lgkmcnt(3)
	v_mfma_f32_16x16x4_f32 v[106:109], v244, v223, 0
	v_mfma_f32_16x16x4_f32 v[106:109], v245, v224, v[106:109]
	ds_read2_b32 v[244:245], v105 offset0:200 offset1:204
	s_nop 0
	s_waitcnt lgkmcnt(3)
	v_mfma_f32_16x16x4_f32 v[106:109], v248, v225, v[106:109]
	v_mfma_f32_16x16x4_f32 v[106:109], v249, v226, v[106:109]
	v_mfma_f32_16x16x4_f32 v[140:143], v144, v223, 0
	s_nop 8
	v_add_f32_e32 v135, v227, v106
	v_min_f32_e32 v106, 0, v135
	v_mul_f32_e64 v135, |v135|, s66
	v_exp_f32_e32 v135, v135
	s_nop 0
	v_add_f32_e32 v135, 1.0, v135
	v_log_f32_e32 v135, v135
	v_mfma_f32_16x16x4_f32 v[140:143], v145, v224, v[140:143]
	s_nop 0
	v_fmac_f32_e32 v106, 0xbf317218, v135
	v_add_f32_e32 v135, v227, v107
	v_min_f32_e32 v107, 0, v135
	v_mul_f32_e64 v135, |v135|, s66
	v_exp_f32_e32 v135, v135
	s_waitcnt lgkmcnt(2)
	v_mfma_f32_16x16x4_f32 v[140:143], v252, v225, v[140:143]
	v_add_f32_e32 v135, 1.0, v135
	v_log_f32_e32 v135, v135
	s_nop 0
	v_fmac_f32_e32 v107, 0xbf317218, v135
	v_add_f32_e32 v135, v227, v108
	v_min_f32_e32 v108, 0, v135
	v_mul_f32_e64 v135, |v135|, s66
	v_exp_f32_e32 v135, v135
	v_mfma_f32_16x16x4_f32 v[140:143], v253, v226, v[140:143]
	s_nop 0
	v_add_f32_e32 v135, 1.0, v135
	v_log_f32_e32 v135, v135
	s_nop 0
	v_fmac_f32_e32 v108, 0xbf317218, v135
	v_add_f32_e32 v135, v227, v109
	v_min_f32_e32 v109, 0, v135
	v_mul_f32_e64 v135, |v135|, s66
	v_exp_f32_e32 v135, v135
	s_nop 0
	v_add_f32_e32 v135, 1.0, v135
	v_log_f32_e32 v135, v135
	s_nop 0
	v_fmac_f32_e32 v109, 0xbf317218, v135
	v_add_f32_e32 v135, v227, v140
	v_min_f32_e32 v137, 0, v135
	v_mul_f32_e64 v135, |v135|, s66
	v_exp_f32_e32 v135, v135
	s_nop 0
	v_add_f32_e32 v135, 1.0, v135
	v_log_f32_e32 v135, v135
	s_nop 0
	v_fmac_f32_e32 v137, 0xbf317218, v135
	v_add_f32_e32 v135, v227, v141
	v_min_f32_e32 v146, 0, v135
	v_mul_f32_e64 v135, |v135|, s66
	v_exp_f32_e32 v135, v135
	s_nop 0
	v_add_f32_e32 v135, 1.0, v135
	v_log_f32_e32 v135, v135
	s_nop 0
	v_fmac_f32_e32 v146, 0xbf317218, v135
	v_add_f32_e32 v135, v227, v142
	v_min_f32_e32 v147, 0, v135
	v_mul_f32_e64 v135, |v135|, s66
	v_exp_f32_e32 v135, v135
	s_nop 0
	v_add_f32_e32 v135, 1.0, v135
	v_log_f32_e32 v135, v135
	s_nop 0
	v_fmac_f32_e32 v147, 0xbf317218, v135
	v_add_f32_e32 v135, v227, v143
	s_waitcnt lgkmcnt(1)
	v_mfma_f32_16x16x4_f32 v[140:143], v236, v223, 0
	v_min_f32_e32 v148, 0, v135
	v_mul_f32_e64 v135, |v135|, s66
	v_exp_f32_e32 v135, v135
	s_nop 0
	v_add_f32_e32 v135, 1.0, v135
	v_mfma_f32_16x16x4_f32 v[140:143], v237, v224, v[140:143]
	s_nop 0
	v_log_f32_e32 v135, v135
	s_nop 0
	v_fmac_f32_e32 v148, 0xbf317218, v135
	s_waitcnt lgkmcnt(0)
	v_mfma_f32_16x16x4_f32 v[140:143], v244, v225, v[140:143]
	v_mfma_f32_16x16x4_f32 v[140:143], v245, v226, v[140:143]
	s_nop 9
	v_add_f32_e32 v105, v227, v140
	v_min_f32_e32 v135, 0, v105
	v_mul_f32_e64 v105, |v105|, s66
	v_exp_f32_e32 v105, v105
	s_nop 0
	v_add_f32_e32 v105, 1.0, v105
	v_log_f32_e32 v105, v105
	s_nop 0
	v_fmac_f32_e32 v135, 0xbf317218, v105
	v_add_f32_e32 v105, v227, v141
	v_min_f32_e32 v140, 0, v105
	v_mul_f32_e64 v105, |v105|, s66
	v_exp_f32_e32 v105, v105
	s_nop 0
	v_add_f32_e32 v105, 1.0, v105
	v_log_f32_e32 v105, v105
	s_nop 0
	v_fmac_f32_e32 v140, 0xbf317218, v105
	v_add_f32_e32 v105, v227, v142
	v_min_f32_e32 v141, 0, v105
	v_mul_f32_e64 v105, |v105|, s66
	v_exp_f32_e32 v105, v105
	s_nop 0
	v_add_f32_e32 v105, 1.0, v105
	v_log_f32_e32 v105, v105
	s_nop 0
	v_fmac_f32_e32 v141, 0xbf317218, v105
	v_add_f32_e32 v105, v227, v143
	v_min_f32_e32 v142, 0, v105
	v_mul_f32_e64 v105, |v105|, s66
	v_exp_f32_e32 v105, v105
	s_nop 0
	v_add_f32_e32 v105, 1.0, v105
	v_log_f32_e32 v105, v105
	s_nop 0
	v_fmac_f32_e32 v142, 0xbf317218, v105
	v_fma_f32 v105, v142, s67, 0
	v_fmamk_f32 v141, v141, 0x3d800000, v105
	v_fmamk_f32 v140, v140, 0x3d800000, v141
	v_fmamk_f32 v135, v135, 0x3d800000, v140
	v_fmamk_f32 v142, v148, 0x3d800000, v135
	v_fmamk_f32 v143, v147, 0x3d800000, v142
	v_fmamk_f32 v144, v146, 0x3d800000, v143
	v_fmamk_f32 v137, v137, 0x3d800000, v144
	v_fmamk_f32 v109, v109, 0x3d800000, v137
	v_fmamk_f32 v108, v108, 0x3d800000, v109
	v_fmamk_f32 v107, v107, 0x3d800000, v108
	v_fmamk_f32 v106, v106, 0x3d800000, v107
	v_fmamk_f32 v104, v104, 0x3d800000, v106
	v_fmamk_f32 v103, v103, 0x3d800000, v104
	v_fmamk_f32 v102, v102, 0x3d800000, v103
	v_fmamk_f32 v0, v0, 0x3d800000, v102
	ds_bpermute_b32 v146, v192, v0
	ds_bpermute_b32 v147, v193, v0
	ds_bpermute_b32 v145, v191, v0
	s_waitcnt lgkmcnt(2)
	v_cndmask_b32_e64 v146, 0, v146, s[28:29]
	s_waitcnt lgkmcnt(1)
	v_cndmask_b32_e64 v147, v147, 0, s[8:9]
	v_add_f32_e32 v146, v146, v147
	s_waitcnt lgkmcnt(0)
	v_cndmask_b32_e64 v145, 0, v145, s[4:5]
	v_add_f32_e32 v145, v145, v146
	v_add_f32_e32 v0, v145, v0
	v_add_f32_e32 v102, v145, v102
	ds_write2st64_b32 v204, v0, v102 offset0:24 offset1:26
	v_add_f32_e32 v0, v145, v103
	v_add_f32_e32 v102, v145, v104
	ds_write2st64_b32 v204, v0, v102 offset0:28 offset1:30
	v_add_f32_e32 v0, v145, v106
	v_add_f32_e32 v102, v145, v107
	ds_write2st64_b32 v204, v0, v102 offset0:32 offset1:34
	v_add_f32_e32 v0, v145, v108
	v_add_f32_e32 v102, v145, v109
	ds_write2st64_b32 v204, v0, v102 offset0:36 offset1:38
	v_add_f32_e32 v0, v145, v137
	v_add_f32_e32 v102, v145, v144
	ds_write2st64_b32 v204, v0, v102 offset0:40 offset1:42
	v_add_f32_e32 v0, v145, v143
	v_add_f32_e32 v102, v145, v142
	ds_write2st64_b32 v204, v0, v102 offset0:44 offset1:46
	v_add_f32_e32 v0, v145, v135
	v_add_f32_e32 v102, v145, v140
	ds_write2st64_b32 v204, v0, v102 offset0:48 offset1:50
	v_add_f32_e32 v0, v145, v141
	v_add_f32_e32 v102, v145, v105
	ds_write2st64_b32 v204, v0, v102 offset0:52 offset1:54
	s_waitcnt lgkmcnt(0)
	s_barrier
	s_and_saveexec_b64 s[62:63], s[10:11]
	s_cbranch_execz .LBB0_2285
	ds_read_b32 v0, v181 offset:6144
	v_lshl_add_u32 v102, s68, 9, v181
	s_waitcnt lgkmcnt(0)
	ds_write_b32 v102, v0 offset:4096

.LBB0_2292:
	ds_read_b128 v[102:105], v205 offset:6144
	ds_read_b128 v[106:109], v205 offset:6160
	s_waitcnt vmcnt(6)
	v_lshlrev_b32_e32 v142, 16, v98
	v_and_b32_e32 v143, 0xffff0000, v98
	s_waitcnt lgkmcnt(1)
	v_mul_f32_e32 v0, 0xbfb8aa3b, v102
	v_exp_f32_e32 v140, v0
	v_mul_f32_e32 v0, 0xbfb8aa3b, v103
	v_exp_f32_e32 v141, v0
	v_mul_f32_e32 v0, 0xbfb8aa3b, v104
	v_pk_mul_f32 v[140:141], v[140:141], v[142:143]
	s_nop 0
	v_cvt_pk_bf16_f32 v98, v140, v141
	v_exp_f32_e32 v140, v0
	v_mul_f32_e32 v0, 0xbfb8aa3b, v105
	v_exp_f32_e32 v141, v0
	v_lshlrev_b32_e32 v142, 16, v99
	v_and_b32_e32 v143, 0xffff0000, v99
	s_waitcnt lgkmcnt(0)
	v_mul_f32_e32 v0, 0xbfb8aa3b, v106
	v_pk_mul_f32 v[140:141], v[140:141], v[142:143]
	v_lshlrev_b32_e32 v142, 16, v100
	v_cvt_pk_bf16_f32 v99, v140, v141
	v_exp_f32_e32 v140, v0
	v_mul_f32_e32 v0, 0xbfb8aa3b, v107
	v_exp_f32_e32 v141, v0
	v_and_b32_e32 v143, 0xffff0000, v100
	v_mul_f32_e32 v0, 0xbfb8aa3b, v108
	v_pk_mul_f32 v[140:141], v[140:141], v[142:143]
	s_nop 0
	v_cvt_pk_bf16_f32 v100, v140, v141
	v_exp_f32_e32 v140, v0
	v_mul_f32_e32 v0, 0xbfb8aa3b, v109
	v_exp_f32_e32 v141, v0
	v_lshlrev_b32_e32 v142, 16, v101
	v_and_b32_e32 v143, 0xffff0000, v101
	v_mul_f32_e32 v0, 0x3fb8aa3b, v102
	v_pk_mul_f32 v[140:141], v[140:141], v[142:143]
	s_nop 0
	v_cvt_pk_bf16_f32 v101, v140, v141
	ds_write_b128 v184, v[98:101] offset:56320
	v_exp_f32_e32 v98, v0
	v_mul_f32_e32 v0, 0x3fb8aa3b, v103
	v_exp_f32_e32 v99, v0
	v_lshlrev_b32_e32 v100, 16, v94
	v_and_b32_e32 v101, 0xffff0000, v94
	v_mul_f32_e32 v0, 0x3fb8aa3b, v104
	v_pk_mul_f32 v[98:99], v[98:99], s[48:49] op_sel_hi:[1,0]
	s_waitcnt vmcnt(4)
	v_lshlrev_b32_e32 v104, 16, v90
	v_pk_mul_f32 v[98:99], v[98:99], v[100:101]
	v_lshlrev_b32_e32 v100, 16, v95
	v_cvt_pk_bf16_f32 v94, v98, v99
	v_exp_f32_e32 v98, v0
	v_mul_f32_e32 v0, 0x3fb8aa3b, v105
	v_exp_f32_e32 v99, v0
	v_and_b32_e32 v101, 0xffff0000, v95
	v_mul_f32_e32 v0, 0x3fb8aa3b, v106
	v_and_b32_e32 v105, 0xffff0000, v90
	v_pk_mul_f32 v[98:99], v[98:99], s[48:49] op_sel_hi:[1,0]
	s_nop 0
	v_pk_mul_f32 v[98:99], v[98:99], v[100:101]
	v_lshlrev_b32_e32 v100, 16, v96
	v_cvt_pk_bf16_f32 v95, v98, v99
	v_exp_f32_e32 v98, v0
	v_mul_f32_e32 v0, 0x3fb8aa3b, v107
	v_exp_f32_e32 v99, v0
	v_and_b32_e32 v101, 0xffff0000, v96
	v_mul_f32_e32 v0, 0x3fb8aa3b, v108
	v_pk_mul_f32 v[98:99], v[98:99], s[48:49] op_sel_hi:[1,0]
	s_nop 0
	v_pk_mul_f32 v[98:99], v[98:99], v[100:101]
	v_lshlrev_b32_e32 v100, 16, v97
	v_cvt_pk_bf16_f32 v96, v98, v99
	v_exp_f32_e32 v98, v0
	v_mul_f32_e32 v0, 0x3fb8aa3b, v109
	v_exp_f32_e32 v99, v0
	v_and_b32_e32 v101, 0xffff0000, v97
	v_pk_mul_f32 v[98:99], v[98:99], s[48:49] op_sel_hi:[1,0]
	s_nop 0
	v_pk_mul_f32 v[98:99], v[98:99], v[100:101]
	s_nop 0
	v_cvt_pk_bf16_f32 v97, v98, v99
	ds_write_b128 v184, v[94:97] offset:38912
	ds_read_b128 v[94:97], v206 offset:6144
	ds_read_b128 v[98:101], v206 offset:6160
	s_waitcnt lgkmcnt(1)
	v_mul_f32_e32 v0, 0xbfb8aa3b, v94
	v_exp_f32_e32 v102, v0
	v_mul_f32_e32 v0, 0xbfb8aa3b, v95
	v_exp_f32_e32 v103, v0
	v_mul_f32_e32 v0, 0xbfb8aa3b, v96
	v_pk_mul_f32 v[102:103], v[102:103], v[104:105]
	s_nop 0
	v_cvt_pk_bf16_f32 v90, v102, v103
	v_exp_f32_e32 v102, v0
	v_mul_f32_e32 v0, 0xbfb8aa3b, v97
	v_exp_f32_e32 v103, v0
	v_lshlrev_b32_e32 v104, 16, v91
	v_and_b32_e32 v105, 0xffff0000, v91
	s_waitcnt lgkmcnt(0)
	v_mul_f32_e32 v0, 0xbfb8aa3b, v98
	v_pk_mul_f32 v[102:103], v[102:103], v[104:105]
	v_lshlrev_b32_e32 v104, 16, v92
	v_cvt_pk_bf16_f32 v91, v102, v103
	v_exp_f32_e32 v102, v0
	v_mul_f32_e32 v0, 0xbfb8aa3b, v99
	v_exp_f32_e32 v103, v0
	v_and_b32_e32 v105, 0xffff0000, v92
	v_mul_f32_e32 v0, 0xbfb8aa3b, v100
	v_pk_mul_f32 v[102:103], v[102:103], v[104:105]
	s_nop 0
	v_cvt_pk_bf16_f32 v92, v102, v103
	v_exp_f32_e32 v102, v0
	v_mul_f32_e32 v0, 0xbfb8aa3b, v101
	v_exp_f32_e32 v103, v0
	v_lshlrev_b32_e32 v104, 16, v93
	v_and_b32_e32 v105, 0xffff0000, v93
	v_mul_f32_e32 v0, 0x3fb8aa3b, v94
	v_pk_mul_f32 v[102:103], v[102:103], v[104:105]
	s_nop 0
	v_cvt_pk_bf16_f32 v93, v102, v103
	ds_write_b128 v185, v[90:93] offset:56320
	v_exp_f32_e32 v90, v0
	v_mul_f32_e32 v0, 0x3fb8aa3b, v95
	v_exp_f32_e32 v91, v0
	v_lshlrev_b32_e32 v92, 16, v70
	v_and_b32_e32 v93, 0xffff0000, v70
	v_mul_f32_e32 v0, 0x3fb8aa3b, v96
	v_pk_mul_f32 v[90:91], v[90:91], s[48:49] op_sel_hi:[1,0]
	s_nop 0
	v_pk_mul_f32 v[90:91], v[90:91], v[92:93]
	v_lshlrev_b32_e32 v92, 16, v71
	v_cvt_pk_bf16_f32 v70, v90, v91
	v_exp_f32_e32 v90, v0
	v_mul_f32_e32 v0, 0x3fb8aa3b, v97
	v_exp_f32_e32 v91, v0
	v_and_b32_e32 v93, 0xffff0000, v71
	v_mul_f32_e32 v0, 0x3fb8aa3b, v98
	v_pk_mul_f32 v[90:91], v[90:91], s[48:49] op_sel_hi:[1,0]
	s_nop 0
	v_pk_mul_f32 v[90:91], v[90:91], v[92:93]
	v_lshlrev_b32_e32 v92, 16, v72
	v_cvt_pk_bf16_f32 v71, v90, v91
	v_exp_f32_e32 v90, v0
	v_mul_f32_e32 v0, 0x3fb8aa3b, v99
	v_exp_f32_e32 v91, v0
	v_and_b32_e32 v93, 0xffff0000, v72
	v_mul_f32_e32 v0, 0x3fb8aa3b, v100
	v_pk_mul_f32 v[90:91], v[90:91], s[48:49] op_sel_hi:[1,0]
	s_nop 0
	v_pk_mul_f32 v[90:91], v[90:91], v[92:93]
	v_lshlrev_b32_e32 v92, 16, v73
	v_cvt_pk_bf16_f32 v72, v90, v91
	v_exp_f32_e32 v90, v0
	v_mul_f32_e32 v0, 0x3fb8aa3b, v101
	v_exp_f32_e32 v91, v0
	v_and_b32_e32 v93, 0xffff0000, v73
	v_pk_mul_f32 v[90:91], v[90:91], s[48:49] op_sel_hi:[1,0]
	s_nop 0
	v_pk_mul_f32 v[90:91], v[90:91], v[92:93]
	s_nop 0
	v_cvt_pk_bf16_f32 v73, v90, v91
	ds_write_b128 v185, v[70:73] offset:38912
	s_waitcnt vmcnt(3)
	ds_write_b128 v207, v[74:77]
	s_waitcnt vmcnt(2)
	ds_write_b128 v208, v[78:81]
	s_waitcnt vmcnt(1)
	ds_write_b128 v207, v[82:85] offset:16896
	s_waitcnt vmcnt(0)
	ds_write_b128 v209, v[86:89]
	v_lshl_add_u64 v[70:71], s[56:57], 0, v[118:119]
	v_lshl_add_u64 v[72:73], s[56:57], 0, v[122:123]
	v_lshl_add_u64 v[74:75], s[56:57], 0, v[124:125]
	global_load_dwordx2 v[160:161], v[70:71], off
	global_load_dwordx2 v[158:159], v[70:71], off offset:32
	global_load_dwordx2 v[152:153], v[72:73], off
	global_load_dwordx2 v[150:151], v[74:75], off
	v_lshl_add_u64 v[70:71], s[56:57], 0, v[126:127]
	v_lshl_add_u64 v[72:73], s[56:57], 0, v[128:129]
	v_lshl_add_u64 v[74:75], s[56:57], 0, v[130:131]
	v_lshl_add_u64 v[76:77], s[56:57], 0, v[132:133]
	global_load_dwordx2 v[148:149], v[70:71], off
	global_load_dwordx2 v[146:147], v[72:73], off
	global_load_dwordx2 v[142:143], v[74:75], off
	global_load_dwordx2 v[140:141], v[76:77], off
	s_waitcnt lgkmcnt(0)
	s_barrier
	s_waitcnt lgkmcnt(0)
	ds_read_b128 v[70:73], v210 offset:56320
	ds_read_b128 v[236:239], v183 offset:38912
	ds_read_b128 v[244:247], v210 offset:56384
	ds_read_b128 v[82:85], v183 offset:38976
	ds_read_b128 v[248:251], v210 offset:56448
	ds_read_b128 v[86:89], v183 offset:39040
	ds_read_b128 v[78:81], v210 offset:56512
	ds_read_b128 v[90:93], v183 offset:39104
	s_waitcnt lgkmcnt(6)
	v_mfma_f32_16x16x32_bf16 v[70:73], v[70:73], v[236:239], 0
	v_mov_b32_e32 v0, s93
	v_cvt_pk_bf16_f32 v170, v62, v63
	v_cvt_pk_bf16_f32 v171, v64, v65
	s_waitcnt lgkmcnt(4)
	v_mfma_f32_16x16x32_bf16 v[70:73], v[244:247], v[82:85], v[70:73]
	s_nop 0
	s_nop 0
	v_cvt_pk_bf16_f32 v172, v66, v67
	v_cvt_pk_bf16_f32 v173, v68, v69
	s_waitcnt lgkmcnt(2)
	v_mfma_f32_16x16x32_bf16 v[70:73], v[248:251], v[86:89], v[70:73]
	s_nop 0
	s_nop 0
	s_add_u32 s49, s49, s0
	s_addc_u32 s53, s69, 0
	s_waitcnt lgkmcnt(0)
	v_mfma_f32_16x16x32_bf16 v[70:73], v[78:81], v[90:93], v[70:73]
	s_add_u32 s60, s49, 0xafc1000
	s_addc_u32 s61, s53, 0
	s_waitcnt vmcnt(7)
	v_lshlrev_b32_e32 v228, 16, v160
	s_nop 3
	v_cndmask_b32_e64 v0, v70, v0, s[14:15]
	v_cndmask_b32_e64 v70, v71, 0, s[30:31]
	v_cndmask_b32_e64 v71, v72, 0, s[34:35]
	v_cndmask_b32_e64 v72, v73, 0, s[36:37]
	v_cvt_pk_bf16_f32 v70, v0, v70
	v_cvt_pk_bf16_f32 v71, v71, v72
	ds_write_b64 v211, v[70:71]
	ds_read_b128 v[252:255], v212 offset:56320
	ds_read_b128 v[244:247], v212 offset:56384
	ds_read_b128 v[248:251], v212 offset:56448
	ds_read_b128 v[74:77], v212 offset:56512
	s_waitcnt lgkmcnt(3)
	v_mfma_f32_16x16x32_bf16 v[70:73], v[252:255], v[236:239], 0
	s_nop 0
	v_mov_b32_e32 v0, s93
	v_and_b32_e32 v229, 0xffff0000, v160
	s_waitcnt lgkmcnt(2)
	v_mfma_f32_16x16x32_bf16 v[70:73], v[244:247], v[82:85], v[70:73]
	s_nop 0
	v_lshlrev_b32_e32 v160, 16, v161
	v_and_b32_e32 v161, 0xffff0000, v161
	s_waitcnt lgkmcnt(1)
	v_mfma_f32_16x16x32_bf16 v[70:73], v[248:251], v[86:89], v[70:73]
	s_nop 0
	s_waitcnt vmcnt(6)
	v_lshlrev_b32_e32 v230, 16, v158
	v_and_b32_e32 v231, 0xffff0000, v158
	s_waitcnt lgkmcnt(0)
	v_mfma_f32_16x16x32_bf16 v[70:73], v[74:77], v[90:93], v[70:73]
	v_lshlrev_b32_e32 v158, 16, v159
	v_and_b32_e32 v159, 0xffff0000, v159
	s_nop 5
	v_cndmask_b32_e64 v0, v70, v0, s[22:23]
	v_cndmask_b32_e64 v70, v71, 0, s[38:39]
	v_cndmask_b32_e64 v71, v72, 0, s[40:41]
	v_cndmask_b32_e64 v72, v73, 0, s[42:43]
	v_cvt_pk_bf16_f32 v70, v0, v70
	v_cvt_pk_bf16_f32 v71, v71, v72
	ds_write_b64 v213, v[70:71]
	s_waitcnt lgkmcnt(0)
	s_barrier
	s_waitcnt lgkmcnt(0)
	ds_read_b64_tr_b16 v[72:73], v214 offset:2112
	ds_read_b64_tr_b16 v[70:71], v214
	ds_read_b64_tr_b16 v[236:237], v214 offset:32
	ds_read_b64_tr_b16 v[244:245], v214 offset:16896
	ds_read_b64_tr_b16 v[246:247], v214 offset:19008
	ds_read_b64_tr_b16 v[238:239], v214 offset:2144
	ds_read_b64_tr_b16 v[248:249], v214 offset:16928
	ds_read_b64_tr_b16 v[250:251], v214 offset:19040
	ds_read_b128 v[252:255], v215
	ds_read_b128 v[94:97], v215 offset:64
	ds_read_b128 v[102:105], v215 offset:2368
	ds_read_b128 v[162:165], v215 offset:4672
	s_waitcnt lgkmcnt(3)
	v_mfma_f32_16x16x32_bf16 v[90:93], v[70:73], v[252:255], 0
	s_nop 0
	v_mfma_f32_16x16x32_bf16 v[86:89], v[236:239], v[252:255], 0
	ds_read_b128 v[252:255], v215 offset:2304
	s_waitcnt lgkmcnt(3)
	v_mfma_f32_16x16x32_bf16 v[90:93], v[244:247], v[94:97], v[90:93]
	v_mfma_f32_16x16x32_bf16 v[86:89], v[248:251], v[94:97], v[86:89]
	s_nop 0
	s_waitcnt lgkmcnt(0)
	v_mfma_f32_16x16x32_bf16 v[98:101], v[70:73], v[252:255], 0
	v_mfma_f32_16x16x32_bf16 v[94:97], v[236:239], v[252:255], 0
	ds_read_b128 v[252:255], v215 offset:4608
	v_mfma_f32_16x16x32_bf16 v[98:101], v[244:247], v[102:105], v[98:101]
	v_mfma_f32_16x16x32_bf16 v[94:97], v[248:251], v[102:105], v[94:97]
	s_nop 0
	s_waitcnt lgkmcnt(0)
	v_mfma_f32_16x16x32_bf16 v[106:109], v[70:73], v[252:255], 0
	v_mfma_f32_16x16x32_bf16 v[102:105], v[236:239], v[252:255], 0
	ds_read_b128 v[252:255], v215 offset:6912
	v_mfma_f32_16x16x32_bf16 v[106:109], v[244:247], v[162:165], v[106:109]
	v_mfma_f32_16x16x32_bf16 v[102:105], v[248:251], v[162:165], v[102:105]
	s_nop 0
	s_waitcnt lgkmcnt(0)
	v_mfma_f32_16x16x32_bf16 v[70:73], v[70:73], v[252:255], 0
	v_mfma_f32_16x16x32_bf16 v[74:77], v[236:239], v[252:255], 0
	ds_read_b128 v[236:239], v215 offset:6976
	ds_read2_b64 v[252:255], v219 offset1:4
	s_waitcnt lgkmcnt(1)
	v_mfma_f32_16x16x32_bf16 v[70:73], v[244:247], v[236:239], v[70:73]
	ds_read2_b64 v[244:247], v220 offset0:32 offset1:36
	v_cvt_pk_bf16_f32 v78, v30, v31
	v_cvt_pk_bf16_f32 v79, v32, v33
	v_cvt_pk_bf16_f32 v80, v10, v11
	v_mfma_f32_16x16x32_bf16 v[74:77], v[248:251], v[236:239], v[74:77]
	ds_read2_b64 v[236:239], v221 offset0:64 offset1:68
	ds_read2_b64 v[248:251], v222 offset0:96 offset1:100
	v_cvt_pk_bf16_f32 v81, v12, v13
	v_cvt_pk_bf16_f32 v82, v6, v7
	v_cvt_pk_bf16_f32 v83, v8, v9
	v_cvt_pk_bf16_f32 v84, v18, v19
	v_cvt_pk_bf16_f32 v85, v20, v21
	s_nop 0
	s_waitcnt lgkmcnt(3)
	v_mfma_f32_16x16x32_bf16 v[90:93], v[78:81], v[252:255], v[90:93]
	v_mfma_f32_16x16x32_bf16 v[86:89], v[82:85], v[252:255], v[86:89]
	ds_read2_b64 v[252:255], v219 offset0:8 offset1:12
	s_nop 0
	s_waitcnt lgkmcnt(3)
	v_mfma_f32_16x16x32_bf16 v[98:101], v[78:81], v[244:247], v[98:101]
	v_mfma_f32_16x16x32_bf16 v[94:97], v[82:85], v[244:247], v[94:97]
	ds_read2_b64 v[244:247], v220 offset0:40 offset1:44
	s_nop 0
	s_waitcnt lgkmcnt(3)
	v_mfma_f32_16x16x32_bf16 v[106:109], v[78:81], v[236:239], v[106:109]
	v_mfma_f32_16x16x32_bf16 v[102:105], v[82:85], v[236:239], v[102:105]
	ds_read2_b64 v[236:239], v221 offset0:72 offset1:76
	s_nop 0
	s_waitcnt lgkmcnt(3)
	v_mfma_f32_16x16x32_bf16 v[70:73], v[78:81], v[248:251], v[70:73]
	v_cvt_pk_bf16_f32 v78, v14, v15
	v_cvt_pk_bf16_f32 v79, v16, v17
	v_cvt_pk_bf16_f32 v80, v38, v39
	v_mfma_f32_16x16x32_bf16 v[74:77], v[82:85], v[248:251], v[74:77]
	ds_read2_b64 v[248:251], v222 offset0:104 offset1:108
	v_cvt_pk_bf16_f32 v81, v40, v41
	v_cvt_pk_bf16_f32 v82, v26, v27
	v_cvt_pk_bf16_f32 v83, v28, v29
	v_cvt_pk_bf16_f32 v84, v50, v51
	v_cvt_pk_bf16_f32 v85, v52, v53
	s_nop 0
	s_waitcnt lgkmcnt(3)
	v_mfma_f32_16x16x32_bf16 v[90:93], v[78:81], v[252:255], v[90:93]
	v_mfma_f32_16x16x32_bf16 v[86:89], v[82:85], v[252:255], v[86:89]
	ds_read2_b64 v[252:255], v219 offset0:16 offset1:20
	s_nop 0
	s_waitcnt lgkmcnt(3)
	v_mfma_f32_16x16x32_bf16 v[98:101], v[78:81], v[244:247], v[98:101]
	v_mfma_f32_16x16x32_bf16 v[94:97], v[82:85], v[244:247], v[94:97]
	ds_read2_b64 v[244:247], v220 offset0:48 offset1:52
	s_nop 0
	s_waitcnt lgkmcnt(3)
	v_mfma_f32_16x16x32_bf16 v[106:109], v[78:81], v[236:239], v[106:109]
	v_mfma_f32_16x16x32_bf16 v[102:105], v[82:85], v[236:239], v[102:105]
	ds_read2_b64 v[236:239], v221 offset0:80 offset1:84
	s_nop 0
	s_waitcnt lgkmcnt(3)
	v_mfma_f32_16x16x32_bf16 v[70:73], v[78:81], v[248:251], v[70:73]
	v_cvt_pk_bf16_f32 v78, v22, v23
	v_cvt_pk_bf16_f32 v79, v24, v25
	v_cvt_pk_bf16_f32 v80, v42, v43
	v_mfma_f32_16x16x32_bf16 v[74:77], v[82:85], v[248:251], v[74:77]
	ds_read2_b64 v[248:251], v222 offset0:112 offset1:116
	v_cvt_pk_bf16_f32 v81, v44, v45
	v_cvt_pk_bf16_f32 v82, v34, v35
	v_cvt_pk_bf16_f32 v83, v36, v37
	v_cvt_pk_bf16_f32 v84, v54, v55
	v_cvt_pk_bf16_f32 v85, v56, v57
	s_nop 0
	s_waitcnt lgkmcnt(3)
	v_mfma_f32_16x16x32_bf16 v[90:93], v[78:81], v[252:255], v[90:93]
	v_mfma_f32_16x16x32_bf16 v[86:89], v[82:85], v[252:255], v[86:89]
	ds_read2_b64 v[252:255], v219 offset0:24 offset1:28
	s_nop 0
	s_waitcnt lgkmcnt(3)
	v_mfma_f32_16x16x32_bf16 v[98:101], v[78:81], v[244:247], v[98:101]
	v_mfma_f32_16x16x32_bf16 v[94:97], v[82:85], v[244:247], v[94:97]
	ds_read2_b64 v[244:247], v220 offset0:56 offset1:60
	s_nop 0
	s_waitcnt lgkmcnt(3)
	v_mfma_f32_16x16x32_bf16 v[166:169], v[78:81], v[236:239], v[106:109]
	v_mfma_f32_16x16x32_bf16 v[162:165], v[82:85], v[236:239], v[102:105]
	ds_read2_b64 v[236:239], v221 offset0:88 offset1:92
	s_nop 2
	s_nop 0
	s_waitcnt lgkmcnt(3)
	v_mfma_f32_16x16x32_bf16 v[70:73], v[78:81], v[248:251], v[70:73]
	v_cvt_pk_bf16_f32 v78, v46, v47
	v_cvt_pk_bf16_f32 v79, v48, v49
	v_cvt_pk_bf16_f32 v80, v58, v59
	v_mfma_f32_16x16x32_bf16 v[74:77], v[82:85], v[248:251], v[74:77]
	ds_read2_b64 v[248:251], v222 offset0:120 offset1:124
	v_cvt_pk_bf16_f32 v81, v60, v61
	s_nop 0
	s_waitcnt lgkmcnt(3)
	v_mfma_f32_16x16x32_bf16 v[106:109], v[78:81], v[252:255], v[90:93]
	v_mfma_f32_16x16x32_bf16 v[102:105], v[170:173], v[252:255], v[86:89]
	s_nop 0
	s_nop 5
	v_pk_add_f32 v[106:107], v[106:107], v[228:229]
	v_pk_add_f32 v[108:109], v[108:109], v[160:161]
	s_waitcnt lgkmcnt(2)
	v_mfma_f32_16x16x32_bf16 v[98:101], v[78:81], v[244:247], v[98:101]
	v_mul_f32_e64 v160, v106, v106
	v_mul_f32_e64 v161, v107, v107
	v_pk_mul_f32 v[228:229], v[108:109], v[108:109]
	v_add_f32_e32 v0, v160, v161
	v_mfma_f32_16x16x32_bf16 v[94:97], v[170:173], v[244:247], v[94:97]
	s_nop 0
	v_pk_add_f32 v[102:103], v[102:103], v[230:231]
	v_add_f32_e32 v0, v228, v0
	s_waitcnt lgkmcnt(1)
	v_mfma_f32_16x16x32_bf16 v[86:89], v[170:173], v[236:239], v[162:165]
	v_add_f32_e64 v104, v104, v158
	v_add_f32_e64 v105, v105, v159
	s_nop 0
	s_nop 0
	v_pk_mul_f32 v[158:159], v[102:103], v[102:103]
	v_mfma_f32_16x16x32_bf16 v[90:93], v[78:81], v[236:239], v[166:169]
	v_add_f32_e32 v0, v229, v0
	v_add_f32_e32 v0, v158, v0
	v_pk_mul_f32 v[230:231], v[104:105], v[104:105]
	s_waitcnt lgkmcnt(0)
	v_mfma_f32_16x16x32_bf16 v[82:85], v[78:81], v[248:251], v[70:73]
	v_add_f32_e32 v0, v159, v0
	v_add_f32_e32 v0, v230, v0
	v_add_f32_e32 v0, v231, v0
	v_lshl_add_u64 v[70:71], s[60:61], 0, v[120:121]
	v_add_co_u32_e32 v72, vcc, s81, v70
	v_mfma_f32_16x16x32_bf16 v[78:81], v[170:173], v[248:251], v[74:77]
	s_nop 0
	v_addc_co_u32_e32 v73, vcc, 0, v71, vcc
	global_load_dwordx2 v[172:173], v[70:71], off
	global_load_dwordx2 v[170:171], v[70:71], off offset:32
	global_load_dwordx2 v[168:169], v[72:73], off
	global_load_dwordx2 v[166:167], v[72:73], off offset:32
	v_add_co_u32_e32 v72, vcc, s72, v70
	ds_bpermute_b32 v135, v194, v0
	s_nop 0
	v_addc_co_u32_e32 v73, vcc, 0, v71, vcc
	v_add_co_u32_e32 v70, vcc, s73, v70
	global_load_dwordx2 v[164:165], v[72:73], off
	global_load_dwordx2 v[162:163], v[72:73], off offset:32
	v_addc_co_u32_e32 v71, vcc, 0, v71, vcc
	global_load_dwordx2 v[156:157], v[70:71], off
	global_load_dwordx2 v[144:145], v[70:71], off offset:32
	global_load_dwordx4 v[74:77], v[138:139], off
	s_nop 0
	global_load_dwordx4 v[70:73], v[138:139], off offset:64
	s_waitcnt lgkmcnt(0)
	v_add_f32_e32 v0, v0, v135
	ds_bpermute_b32 v135, v195, v0
	s_and_saveexec_b64 s[60:61], s[4:5]
	s_waitcnt lgkmcnt(0)
	s_cbranch_execz .LBB0_2294
	s_waitcnt lgkmcnt(0)
	v_add_f32_e32 v0, v0, v135
	ds_write_b32 v189, v0
